# v24: v23 + lever 7 instruction trimming: 527 inline-asm s_nop 0 before v_cvt_pk_bf16_f32 removed (kept where a transcendental precedes), second-K-tile LDS bases folded into ds_read offsets
# baseline (speedup 1.0000x reference)
; #define PG8_STAGE(bufoff, gbase, voff) do { _Pragma("unroll") for (int _i = 0; _i < 2; ++_i) \
;         __builtin_amdgcn_global_load_lds((const unsigned*)((const char*)(gbase) + (voff)[_i]), (PG8_LAS unsigned*)(lds + (bufoff) + ldsw + _i * 8192), 16, 0, 0); } while (0)
; #define PG8_LDA(dst, b, h) do { _Pragma("unroll") for (int m = 0; m < 4; ++m) _Pragma("unroll") for (int k = 0; k < 2; ++k) dst[m][k] = *(const PG8_LAS bf16x8*)(lds + PG8_SA(b, h) + aoff + m * 2048 + k * 1024); } while (0)
; #define PG8_LDB(dst, b, h) do { _Pragma("unroll") for (int n = 0; n < 2; ++n) _Pragma("unroll") for (int k = 0; k < 2; ++k) dst[n][k] = *(const PG8_LAS bf16x8*)(lds + PG8_SB(b, h) + boff + n * 2048 + k * 1024); } while (0)
; #define PG8_MMA(ai, bj, At, Bt) do { __builtin_amdgcn_s_setprio(1); _Pragma("unroll") for (int m = 0; m < 4; ++m) _Pragma("unroll") for (int n = 0; n < 2; ++n) _Pragma("unroll") for (int k = 0; k < 2; ++k) \
;         acc[ai][bj][m][n] = mma_<I8>(Bt[n][k], At[m][k], acc[ai][bj][m][n]); __builtin_amdgcn_s_setprio(0); } while (0)
; #define PG8_WAIT_V(n) asm volatile("s_waitcnt vmcnt(" #n ")" ::: "memory")
; #define PG8_WAIT_L(n) asm volatile("s_waitcnt lgkmcnt(" #n ")" ::: "memory")
; #define PG8_BAR __builtin_amdgcn_s_barrier()
; #define PG8_SCHED __builtin_amdgcn_sched_barrier(0)
; template <class Epi, class Sched, bool ALIGN_EPI = false, bool SP2 = false, bool I8 = false>
; __device__ __forceinline__ void gemm_phase(PG8_LAS unsigned char* lds, const Gemm g, const Sched& S, const Epi& E) {
;     ...
;             PG8_LDB(B0, 0, 0); PG8_LDB(B1, 0, 1); PG8_SCHED; PG8_LDA(At, 0, 0); PG8_STAGE(PG8_SA(1, 1), a1 + hstepA, voffA);
;             PG8_WAIT_V(8); PG8_WAIT_L(0); PG8_BAR; PG8_MMA(0, 0, At, B0); PG8_MMA(0, 1, At, B1); PG8_BAR; PG8_SCHED;
;             PG8_LDA(At, 0, 1); PG8_STAGE(PG8_SB(0, 0), b2, voffB); PG8_STAGE(PG8_SB(0, 1), b2 + hstepB, voffB); PG8_STAGE(PG8_SA(0, 0), a2, voffA);
;             PG8_WAIT_V(8); PG8_WAIT_L(0); PG8_BAR; PG8_MMA(1, 0, At, B0); PG8_MMA(1, 1, At, B1); PG8_BAR; PG8_SCHED;
.LBB0_483:
	ds_read_b128 v[58:61], v187
	ds_read_b128 v[62:65], v187 offset:1024
	ds_read_b128 v[74:77], v187 offset:2048
	ds_read_b128 v[78:81], v187 offset:3072
	ds_read_b128 v[162:165], v188
	ds_read_b128 v[166:169], v188 offset:1024
	ds_read_b128 v[170:173], v188 offset:2048
	ds_read_b128 v[190:193], v188 offset:3072
	s_add_u32 s34, s2, 0xfff80080
	s_addc_u32 s35, s3, -1
	s_cmp_eq_u32 s40, 28
	s_cselect_b32 s37, s7, s35
	s_cselect_b32 s36, s25, s34
	s_cselect_b32 s35, s23, s39
	s_cselect_b32 s34, s33, s38
	s_add_i32 m0, s31, 0xc000
	ds_read_b128 v[194:197], v189
	ds_read_b128 v[198:201], v189 offset:1024
	ds_read_b128 v[202:205], v189 offset:2048
	ds_read_b128 v[206:209], v189 offset:3072
	ds_read_b128 v[210:213], v189 offset:4096
	ds_read_b128 v[214:217], v189 offset:5120
	ds_read_b128 v[218:221], v189 offset:6144
	ds_read_b128 v[222:225], v189 offset:7168
	global_load_lds_dwordx4 v154, s[2:3]
	s_add_i32 m0, s31, 0xe000
	s_nop 0
	global_load_lds_dwordx4 v156, s[2:3]
	s_waitcnt vmcnt(8) lgkmcnt(0)
	s_barrier
	v_mfma_i32_16x16x64_i8 v[142:145], v[58:61], v[194:197], v[142:145]
	v_mfma_i32_16x16x64_i8 v[138:141], v[74:77], v[194:197], v[138:141]
	v_mfma_i32_16x16x64_i8 v[126:129], v[58:61], v[202:205], v[126:129]
	v_mfma_i32_16x16x64_i8 v[122:125], v[74:77], v[202:205], v[122:125]
	v_mfma_i32_16x16x64_i8 v[110:113], v[58:61], v[210:213], v[110:113]
	v_mfma_i32_16x16x64_i8 v[106:109], v[74:77], v[210:213], v[106:109]
	v_mfma_i32_16x16x64_i8 v[94:97], v[58:61], v[218:221], v[94:97]
	v_mfma_i32_16x16x64_i8 v[90:93], v[74:77], v[218:221], v[90:93]
	v_mfma_i32_16x16x64_i8 v[142:145], v[62:65], v[198:201], v[142:145]
	v_mfma_i32_16x16x64_i8 v[138:141], v[78:81], v[198:201], v[138:141]
	v_mfma_i32_16x16x64_i8 v[126:129], v[62:65], v[206:209], v[126:129]
	v_mfma_i32_16x16x64_i8 v[122:125], v[78:81], v[206:209], v[122:125]
	v_mfma_i32_16x16x64_i8 v[110:113], v[62:65], v[214:217], v[110:113]
	v_mfma_i32_16x16x64_i8 v[106:109], v[78:81], v[214:217], v[106:109]
	v_mfma_i32_16x16x64_i8 v[94:97], v[62:65], v[222:225], v[94:97]
	v_mfma_i32_16x16x64_i8 v[90:93], v[78:81], v[222:225], v[90:93]
	v_mfma_i32_16x16x64_i8 v[134:137], v[162:165], v[194:197], v[134:137]
	v_mfma_i32_16x16x64_i8 v[130:133], v[170:173], v[194:197], v[130:133]
	v_mfma_i32_16x16x64_i8 v[118:121], v[162:165], v[202:205], v[118:121]
	v_mfma_i32_16x16x64_i8 v[114:117], v[170:173], v[202:205], v[114:117]
	v_mfma_i32_16x16x64_i8 v[102:105], v[162:165], v[210:213], v[102:105]
	v_mfma_i32_16x16x64_i8 v[98:101], v[170:173], v[210:213], v[98:101]
	v_mfma_i32_16x16x64_i8 v[86:89], v[162:165], v[218:221], v[86:89]
	v_mfma_i32_16x16x64_i8 v[82:85], v[170:173], v[218:221], v[82:85]
	v_mfma_i32_16x16x64_i8 v[134:137], v[166:169], v[198:201], v[134:137]
	v_mfma_i32_16x16x64_i8 v[130:133], v[190:193], v[198:201], v[130:133]
	v_mfma_i32_16x16x64_i8 v[118:121], v[166:169], v[206:209], v[118:121]
	v_mfma_i32_16x16x64_i8 v[114:117], v[190:193], v[206:209], v[114:117]
	v_mfma_i32_16x16x64_i8 v[102:105], v[166:169], v[214:217], v[102:105]
	v_mfma_i32_16x16x64_i8 v[98:101], v[190:193], v[214:217], v[98:101]
	v_mfma_i32_16x16x64_i8 v[86:89], v[166:169], v[222:225], v[86:89]
	v_mfma_i32_16x16x64_i8 v[82:85], v[190:193], v[222:225], v[82:85]
	s_barrier
	s_add_i32 s41, s8, s68
	s_mov_b64 s[98:99], s[34:35]
	s_mov_b32 m0, s41
	ds_read_b128 v[194:197], v189 offset:16384
	ds_read_b128 v[198:201], v189 offset:17408
	ds_read_b128 v[202:205], v189 offset:18432
	ds_read_b128 v[206:209], v189 offset:19456
	ds_read_b128 v[210:213], v189 offset:20480
	ds_read_b128 v[214:217], v189 offset:21504
	ds_read_b128 v[218:221], v189 offset:22528
	ds_read_b128 v[222:225], v189 offset:23552
	global_load_lds_dwordx4 v148, s[34:35]
	s_add_i32 m0, s41, 0x2000
	s_add_u32 vcc_lo, s34, 0x80000
	s_mov_b64 s[98:99], s[34:35]
	s_addc_u32 vcc_hi, s35, 0
	s_add_i32 s41, s9, s68
	global_load_lds_dwordx4 v152, s[34:35]
	s_mov_b32 m0, s41
	s_mov_b64 s[100:101], s[36:37]
	global_load_lds_dwordx4 v148, vcc
	s_add_i32 m0, s41, 0x2000
	s_nop 0
	global_load_lds_dwordx4 v152, vcc
	s_mov_b64 s[100:101], s[36:37]
	s_mov_b32 m0, s31
	s_nop 0
	global_load_lds_dwordx4 v146, s[36:37]
	s_mov_b32 m0, s69
	s_nop 0
	global_load_lds_dwordx4 v150, s[36:37]
	s_waitcnt vmcnt(8) lgkmcnt(0)
	s_barrier
	v_mfma_i32_16x16x64_i8 v[70:73], v[58:61], v[194:197], v[70:73]
	v_mfma_i32_16x16x64_i8 v[66:69], v[74:77], v[194:197], v[66:69]
	v_mfma_i32_16x16x64_i8 v[46:49], v[58:61], v[202:205], v[46:49]
	v_mfma_i32_16x16x64_i8 v[42:45], v[74:77], v[202:205], v[42:45]
	v_mfma_i32_16x16x64_i8 v[30:33], v[58:61], v[210:213], v[30:33]
	v_mfma_i32_16x16x64_i8 v[26:29], v[74:77], v[210:213], v[26:29]
	v_mfma_i32_16x16x64_i8 v[14:17], v[58:61], v[218:221], v[14:17]
	v_mfma_i32_16x16x64_i8 v[10:13], v[74:77], v[218:221], v[10:13]
	v_mfma_i32_16x16x64_i8 v[70:73], v[62:65], v[198:201], v[70:73]
	v_mfma_i32_16x16x64_i8 v[66:69], v[78:81], v[198:201], v[66:69]
	v_mfma_i32_16x16x64_i8 v[46:49], v[62:65], v[206:209], v[46:49]
	v_mfma_i32_16x16x64_i8 v[42:45], v[78:81], v[206:209], v[42:45]
	v_mfma_i32_16x16x64_i8 v[30:33], v[62:65], v[214:217], v[30:33]
	v_mfma_i32_16x16x64_i8 v[26:29], v[78:81], v[214:217], v[26:29]
	v_mfma_i32_16x16x64_i8 v[14:17], v[62:65], v[222:225], v[14:17]
	v_mfma_i32_16x16x64_i8 v[10:13], v[78:81], v[222:225], v[10:13]
	v_mfma_i32_16x16x64_i8 v[54:57], v[162:165], v[194:197], v[54:57]
	v_mfma_i32_16x16x64_i8 v[50:53], v[170:173], v[194:197], v[50:53]
	v_mfma_i32_16x16x64_i8 v[38:41], v[162:165], v[202:205], v[38:41]
	v_mfma_i32_16x16x64_i8 v[34:37], v[170:173], v[202:205], v[34:37]
	v_mfma_i32_16x16x64_i8 v[22:25], v[162:165], v[210:213], v[22:25]
	v_mfma_i32_16x16x64_i8 v[18:21], v[170:173], v[210:213], v[18:21]
	v_mfma_i32_16x16x64_i8 v[6:9], v[162:165], v[218:221], v[6:9]
	v_mfma_i32_16x16x64_i8 v[2:5], v[170:173], v[218:221], v[2:5]
	v_mfma_i32_16x16x64_i8 v[54:57], v[166:169], v[198:201], v[54:57]
	v_mfma_i32_16x16x64_i8 v[50:53], v[190:193], v[198:201], v[50:53]
	v_mfma_i32_16x16x64_i8 v[38:41], v[166:169], v[206:209], v[38:41]
	v_mfma_i32_16x16x64_i8 v[34:37], v[190:193], v[206:209], v[34:37]
	v_mfma_i32_16x16x64_i8 v[22:25], v[166:169], v[214:217], v[22:25]
	v_mfma_i32_16x16x64_i8 v[18:21], v[190:193], v[214:217], v[18:21]
	v_mfma_i32_16x16x64_i8 v[6:9], v[166:169], v[222:225], v[6:9]
	v_mfma_i32_16x16x64_i8 v[2:5], v[190:193], v[222:225], v[2:5]
	s_barrier
; #define PG8_STAGE(bufoff, gbase, voff) do { _Pragma("unroll") for (int _i = 0; _i < 2; ++_i) \
;         __builtin_amdgcn_global_load_lds((const unsigned*)((const char*)(gbase) + (voff)[_i]), (PG8_LAS unsigned*)(lds + (bufoff) + ldsw + _i * 8192), 16, 0, 0); } while (0)
; #define PG8_LDA(dst, b, h) do { _Pragma("unroll") for (int m = 0; m < 4; ++m) _Pragma("unroll") for (int k = 0; k < 2; ++k) dst[m][k] = *(const PG8_LAS bf16x8*)(lds + PG8_SA(b, h) + aoff + m * 2048 + k * 1024); } while (0)
; #define PG8_LDB(dst, b, h) do { _Pragma("unroll") for (int n = 0; n < 2; ++n) _Pragma("unroll") for (int k = 0; k < 2; ++k) dst[n][k] = *(const PG8_LAS bf16x8*)(lds + PG8_SB(b, h) + boff + n * 2048 + k * 1024); } while (0)
; #define PG8_MMA(ai, bj, At, Bt) do { __builtin_amdgcn_s_setprio(1); _Pragma("unroll") for (int m = 0; m < 4; ++m) _Pragma("unroll") for (int n = 0; n < 2; ++n) _Pragma("unroll") for (int k = 0; k < 2; ++k) \
;         acc[ai][bj][m][n] = mma_<I8>(Bt[n][k], At[m][k], acc[ai][bj][m][n]); __builtin_amdgcn_s_setprio(0); } while (0)
; #define PG8_WAIT_V(n) asm volatile("s_waitcnt vmcnt(" #n ")" ::: "memory")
; #define PG8_WAIT_L(n) asm volatile("s_waitcnt lgkmcnt(" #n ")" ::: "memory")
; #define PG8_BAR __builtin_amdgcn_s_barrier()
; #define PG8_SCHED __builtin_amdgcn_sched_barrier(0)
; template <class Epi, class Sched, bool ALIGN_EPI = false, bool SP2 = false, bool I8 = false>
; __device__ __forceinline__ void gemm_phase(PG8_LAS unsigned char* lds, const Gemm g, const Sched& S, const Epi& E) {
;     ...
;         for (int t = 0; t < nt; t += 2) {
;             const bool last = (t == nt - 2);
;             const char* a1 = cA + (size_t)(t + 1) * kstep;
;             const char* a2 = last ? nA : cA + (size_t)(t + 2) * kstep; const char* b2 = last ? nB : cB + (size_t)(t + 2) * kstep;
;             const char* a3 = a2 + kstep; const char* b3 = b2 + kstep;
;     ...
;             PG8_LDB(B0, 1, 0); PG8_LDB(B1, 1, 1); PG8_SCHED; PG8_LDA(At, 1, 0); PG8_STAGE(PG8_SA(0, 1), a2 + hstepA, voffA);
;             PG8_WAIT_V(8); PG8_WAIT_L(0); PG8_BAR; PG8_MMA(0, 0, At, B0); PG8_MMA(0, 1, At, B1); PG8_BAR; PG8_SCHED;
;             PG8_LDA(At, 1, 1); PG8_STAGE(PG8_SB(1, 0), b3, voffB); PG8_STAGE(PG8_SB(1, 1), b3 + hstepB, voffB); PG8_STAGE(PG8_SA(1, 0), a3, voffA);
;             PG8_WAIT_V(8); PG8_WAIT_L(0); PG8_BAR; PG8_MMA(1, 0, At, B0); PG8_MMA(1, 1, At, B1); PG8_BAR; PG8_SCHED;
	s_add_i32 s41, 0, 0x18000
	s_add_i32 s95, 0, 0x1c000
	ds_read_b128 v[58:61], v188 offset:16384
	ds_read_b128 v[62:65], v188 offset:17408
	ds_read_b128 v[74:77], v188 offset:18432
	ds_read_b128 v[78:81], v188 offset:19456
	ds_read_b128 v[162:165], v188 offset:32768
	ds_read_b128 v[166:169], v188 offset:33792
	ds_read_b128 v[170:173], v188 offset:34816
	ds_read_b128 v[190:193], v188 offset:35840
	s_add_u32 s36, s36, 0x80000
	s_addc_u32 s37, s37, 0
	s_mov_b32 m0, s70
	ds_read_b128 v[194:197], v189 offset:32768
	ds_read_b128 v[198:201], v189 offset:33792
	ds_read_b128 v[202:205], v189 offset:34816
	ds_read_b128 v[206:209], v189 offset:35840
	ds_read_b128 v[210:213], v189 offset:36864
	ds_read_b128 v[214:217], v189 offset:37888
	ds_read_b128 v[218:221], v189 offset:38912
	ds_read_b128 v[222:225], v189 offset:39936
	global_load_lds_dwordx4 v146, s[36:37]
	s_mov_b32 m0, s71
	s_nop 0
	global_load_lds_dwordx4 v150, s[36:37]
	s_waitcnt vmcnt(8) lgkmcnt(0)
	s_barrier
	v_mfma_i32_16x16x64_i8 v[142:145], v[58:61], v[194:197], v[142:145]
	v_mfma_i32_16x16x64_i8 v[138:141], v[74:77], v[194:197], v[138:141]
	v_mfma_i32_16x16x64_i8 v[126:129], v[58:61], v[202:205], v[126:129]
	v_mfma_i32_16x16x64_i8 v[122:125], v[74:77], v[202:205], v[122:125]
	v_mfma_i32_16x16x64_i8 v[110:113], v[58:61], v[210:213], v[110:113]
	v_mfma_i32_16x16x64_i8 v[106:109], v[74:77], v[210:213], v[106:109]
	v_mfma_i32_16x16x64_i8 v[94:97], v[58:61], v[218:221], v[94:97]
	v_mfma_i32_16x16x64_i8 v[90:93], v[74:77], v[218:221], v[90:93]
	v_mfma_i32_16x16x64_i8 v[142:145], v[62:65], v[198:201], v[142:145]
	v_mfma_i32_16x16x64_i8 v[138:141], v[78:81], v[198:201], v[138:141]
	v_mfma_i32_16x16x64_i8 v[126:129], v[62:65], v[206:209], v[126:129]
	v_mfma_i32_16x16x64_i8 v[122:125], v[78:81], v[206:209], v[122:125]
	v_mfma_i32_16x16x64_i8 v[110:113], v[62:65], v[214:217], v[110:113]
	v_mfma_i32_16x16x64_i8 v[106:109], v[78:81], v[214:217], v[106:109]
	v_mfma_i32_16x16x64_i8 v[94:97], v[62:65], v[222:225], v[94:97]
	v_mfma_i32_16x16x64_i8 v[90:93], v[78:81], v[222:225], v[90:93]
	v_mfma_i32_16x16x64_i8 v[134:137], v[162:165], v[194:197], v[134:137]
	v_mfma_i32_16x16x64_i8 v[130:133], v[170:173], v[194:197], v[130:133]
	v_mfma_i32_16x16x64_i8 v[118:121], v[162:165], v[202:205], v[118:121]
	v_mfma_i32_16x16x64_i8 v[114:117], v[170:173], v[202:205], v[114:117]
	v_mfma_i32_16x16x64_i8 v[102:105], v[162:165], v[210:213], v[102:105]
	v_mfma_i32_16x16x64_i8 v[98:101], v[170:173], v[210:213], v[98:101]
	v_mfma_i32_16x16x64_i8 v[86:89], v[162:165], v[218:221], v[86:89]
	v_mfma_i32_16x16x64_i8 v[82:85], v[170:173], v[218:221], v[82:85]
	v_mfma_i32_16x16x64_i8 v[134:137], v[166:169], v[198:201], v[134:137]
	v_mfma_i32_16x16x64_i8 v[130:133], v[190:193], v[198:201], v[130:133]
	v_mfma_i32_16x16x64_i8 v[118:121], v[166:169], v[206:209], v[118:121]
	v_mfma_i32_16x16x64_i8 v[114:117], v[190:193], v[206:209], v[114:117]
	v_mfma_i32_16x16x64_i8 v[102:105], v[166:169], v[214:217], v[102:105]
	v_mfma_i32_16x16x64_i8 v[98:101], v[190:193], v[214:217], v[98:101]
	v_mfma_i32_16x16x64_i8 v[86:89], v[166:169], v[222:225], v[86:89]
	v_mfma_i32_16x16x64_i8 v[82:85], v[190:193], v[222:225], v[82:85]
	s_barrier
	s_add_i32 s36, s41, s68
	s_add_i32 m0, s36, 0xffffff80
	ds_read_b128 v[194:197], v189 offset:49152
	ds_read_b128 v[198:201], v189 offset:50176
	ds_read_b128 v[202:205], v189 offset:51200
	ds_read_b128 v[206:209], v189 offset:52224
	ds_read_b128 v[210:213], v189 offset:53248
	ds_read_b128 v[214:217], v189 offset:54272
	ds_read_b128 v[218:221], v189 offset:55296
	ds_read_b128 v[222:225], v189 offset:56320
	global_load_lds_dwordx4 v148, s[98:99] offset:128
	s_add_i32 m0, s36, 0x1f80
	s_add_u32 s34, s34, 0x80080
	s_addc_u32 s35, s35, 0
	s_add_i32 s36, s95, s68
	global_load_lds_dwordx4 v152, s[98:99] offset:128
	s_mov_b32 m0, s36
	s_nop 0
	global_load_lds_dwordx4 v148, s[34:35]
	s_add_i32 m0, s36, 0x2000
	s_nop 0
	global_load_lds_dwordx4 v152, s[34:35]
	s_add_i32 m0, s89, 0xffffff80
	s_nop 0
	global_load_lds_dwordx4 v146, s[100:101] offset:128
	s_add_i32 m0, s92, 0xffffff80
	s_nop 0
	global_load_lds_dwordx4 v150, s[100:101] offset:128
	s_waitcnt vmcnt(8) lgkmcnt(0)
	s_barrier
	v_mfma_i32_16x16x64_i8 v[70:73], v[58:61], v[194:197], v[70:73]
	v_mfma_i32_16x16x64_i8 v[66:69], v[74:77], v[194:197], v[66:69]
	v_mfma_i32_16x16x64_i8 v[46:49], v[58:61], v[202:205], v[46:49]
	v_mfma_i32_16x16x64_i8 v[42:45], v[74:77], v[202:205], v[42:45]
	v_mfma_i32_16x16x64_i8 v[30:33], v[58:61], v[210:213], v[30:33]
	v_mfma_i32_16x16x64_i8 v[26:29], v[74:77], v[210:213], v[26:29]
	v_mfma_i32_16x16x64_i8 v[14:17], v[58:61], v[218:221], v[14:17]
	v_mfma_i32_16x16x64_i8 v[10:13], v[74:77], v[218:221], v[10:13]
	v_mfma_i32_16x16x64_i8 v[70:73], v[62:65], v[198:201], v[70:73]
	v_mfma_i32_16x16x64_i8 v[66:69], v[78:81], v[198:201], v[66:69]
	v_mfma_i32_16x16x64_i8 v[46:49], v[62:65], v[206:209], v[46:49]
	v_mfma_i32_16x16x64_i8 v[42:45], v[78:81], v[206:209], v[42:45]
	v_mfma_i32_16x16x64_i8 v[30:33], v[62:65], v[214:217], v[30:33]
	v_mfma_i32_16x16x64_i8 v[26:29], v[78:81], v[214:217], v[26:29]
	v_mfma_i32_16x16x64_i8 v[14:17], v[62:65], v[222:225], v[14:17]
	v_mfma_i32_16x16x64_i8 v[10:13], v[78:81], v[222:225], v[10:13]
	v_mfma_i32_16x16x64_i8 v[54:57], v[162:165], v[194:197], v[54:57]
	v_mfma_i32_16x16x64_i8 v[50:53], v[170:173], v[194:197], v[50:53]
	v_mfma_i32_16x16x64_i8 v[38:41], v[162:165], v[202:205], v[38:41]
	v_mfma_i32_16x16x64_i8 v[34:37], v[170:173], v[202:205], v[34:37]
	v_mfma_i32_16x16x64_i8 v[22:25], v[162:165], v[210:213], v[22:25]
	v_mfma_i32_16x16x64_i8 v[18:21], v[170:173], v[210:213], v[18:21]
	v_mfma_i32_16x16x64_i8 v[6:9], v[162:165], v[218:221], v[6:9]
	v_mfma_i32_16x16x64_i8 v[2:5], v[170:173], v[218:221], v[2:5]
	v_mfma_i32_16x16x64_i8 v[54:57], v[166:169], v[198:201], v[54:57]
	v_mfma_i32_16x16x64_i8 v[50:53], v[190:193], v[198:201], v[50:53]
	v_mfma_i32_16x16x64_i8 v[38:41], v[166:169], v[206:209], v[38:41]
	v_mfma_i32_16x16x64_i8 v[34:37], v[190:193], v[206:209], v[34:37]
	v_mfma_i32_16x16x64_i8 v[22:25], v[166:169], v[214:217], v[22:25]
	v_mfma_i32_16x16x64_i8 v[18:21], v[190:193], v[214:217], v[18:21]
	v_mfma_i32_16x16x64_i8 v[6:9], v[166:169], v[222:225], v[6:9]
	v_mfma_i32_16x16x64_i8 v[2:5], v[190:193], v[222:225], v[2:5]
	s_barrier
	s_add_i32 s40, s40, 2
	s_add_u32 s2, s2, 0x100
	s_addc_u32 s3, s3, 0
	s_add_u32 s38, s38, 0x100
	s_addc_u32 s39, s39, 0
	s_cmp_gt_u32 s40, 29
	s_cbranch_scc0 .LBB0_483
	s_and_b64 vcc, exec, s[20:21]
	s_cbranch_vccz .LBB0_486
	s_barrier

; __device__ __forceinline__ unsigned cvt_pk_bf16(float lo, float hi) { unsigned r; asm volatile("s_nop 0\n\tv_cvt_pk_bf16_f32 %0, %1, %2" : "=v"(r) : "v"(lo), "v"(hi)); return r; }
; __device__ __forceinline__ float sigmoidf_(float x) { return __builtin_amdgcn_rcpf(1.0f + __builtin_amdgcn_exp2f(-1.4426950408889634f * x)); }
; __device__ __forceinline__ u32x4 pack8(const f32x4 v0, const f32x4 v1) { u32x4 w; w.x = cvt_pk_bf16(v0[0], v0[1]); w.y = cvt_pk_bf16(v0[2], v0[3]); w.z = cvt_pk_bf16(v1[0], v1[1]); w.w = cvt_pk_bf16(v1[2], v1[3]); return w; }
; __device__ __forceinline__ void unpack8(const u32x4 w, f32x4& v0, f32x4& v1) { v0 = (f32x4){bf_lo(w.x), bf_hi(w.x), bf_lo(w.y), bf_hi(w.y)}; v1 = (f32x4){bf_lo(w.z), bf_hi(w.z), bf_lo(w.w), bf_hi(w.w)}; }
; __device__ __forceinline__ f32x4 sig4(const f32x4 v) { return (f32x4){sigmoidf_(v[0]), sigmoidf_(v[1]), sigmoidf_(v[2]), sigmoidf_(v[3])}; }
;     __device__ __forceinline__ void operator()(const i32x4 (&acc)[2][2][4][2], const Unit& uu, int wr, int wc, int fr, int fq) const {
;     ...
; #pragma unroll
;         for (int ai = 0; ai < 2; ++ai)
; #pragma unroll
;             for (int m = 0; m < 4; ++m) { const int r = row0 + ai * HALF + m * 16; const float rs = rsv[ai][m]; bf16_t* rowp = base + (size_t)r * ldc + col0;
; #pragma unroll
;                 for (int bj = 0; bj < 2; ++bj) { f32x4 v0 = __builtin_convertvector(acc[ai][bj][m][0], f32x4) * rs * sv[bj][0], v1 = __builtin_convertvector(acc[ai][bj][m][1], f32x4) * rs * sv[bj][1];
;                     if (sg) { v0 = sig4(v0); v1 = sig4(v1); }
;                     *(u32x4*)(rowp + bj * HALF) = pack8(v0, v1); } }
.LBB0_496:
	v_cvt_f32_i32_e32 v135, v135
	v_cvt_f32_i32_e32 v137, v137
	v_cvt_f32_i32_e32 v136, v136
	v_cvt_f32_i32_e32 v134, v134
	v_cvt_f32_i32_e32 v131, v131
	v_cvt_f32_i32_e32 v133, v133
	v_cvt_f32_i32_e32 v132, v132
	v_cvt_f32_i32_e32 v130, v130
	v_add_u32_e32 v138, s23, v204
	v_ashrrev_i32_e32 v139, 31, v138
	v_mov_b32_e32 v143, v142
	v_lshl_add_u64 v[138:139], v[138:139], 1, s[34:35]
	v_mul_lo_u32 v204, s3, v162
	v_mul_lo_u32 v163, s2, v163
	v_mad_u64_u32 v[140:141], s[34:35], s2, v162, 0
	v_cvt_pk_bf16_f32 v172, v172, v173
	v_cvt_pk_bf16_f32 v173, v170, v171
	v_cvt_pk_bf16_f32 v174, v174, v175
	v_cvt_pk_bf16_f32 v175, v144, v145
	v_mov_b32_e32 v144, v142
	v_mov_b32_e32 v145, v142
	v_add3_u32 v141, v141, v163, v204
	v_pk_mul_f32 v[136:137], v[144:145], v[136:137]
	v_pk_mul_f32 v[170:171], v[142:143], v[134:135]
	v_pk_mul_f32 v[132:133], v[144:145], v[132:133]
	v_pk_mul_f32 v[130:131], v[142:143], v[130:131]
	v_lshl_add_u64 v[140:141], v[140:141], 1, v[138:139]
	v_pk_mul_f32 v[134:135], v[64:65], v[136:137]
	v_pk_mul_f32 v[136:137], v[62:63], v[170:171]
	v_pk_mul_f32 v[132:133], v[60:61], v[132:133]
	s_and_b64 vcc, exec, s[6:7]
	v_pk_mul_f32 v[142:143], v[58:59], v[130:131]
	global_store_dwordx4 v[140:141], v[172:175], off
	s_cbranch_vccnz .LBB0_498
	v_mul_f32_e32 v130, 0xbfb8aa3b, v136
	v_exp_f32_e32 v130, v130
	v_mul_f32_e32 v131, 0xbfb8aa3b, v137
	v_exp_f32_e32 v131, v131
	v_add_f32_e32 v130, 1.0, v130
	v_rcp_f32_e32 v136, v130
	v_mul_f32_e32 v130, 0xbfb8aa3b, v134
	v_add_f32_e32 v131, 1.0, v131
	v_exp_f32_e32 v130, v130
	v_mul_f32_e32 v134, 0xbfb8aa3b, v135
	v_exp_f32_e32 v135, v134
	v_rcp_f32_e32 v137, v131
	v_mul_f32_e32 v131, 0xbfb8aa3b, v142
	v_exp_f32_e32 v131, v131
	v_add_f32_e32 v130, 1.0, v130
	v_rcp_f32_e32 v134, v130
	v_add_f32_e32 v130, 1.0, v135
	v_mul_f32_e32 v135, 0xbfb8aa3b, v143
	v_exp_f32_e32 v143, v135
	v_rcp_f32_e32 v135, v130
	v_add_f32_e32 v130, 1.0, v131
	v_mul_f32_e32 v131, 0xbfb8aa3b, v132
	v_exp_f32_e32 v131, v131
	v_mul_f32_e32 v132, 0xbfb8aa3b, v133
	v_exp_f32_e32 v133, v132
	v_rcp_f32_e32 v142, v130
	v_add_f32_e32 v130, 1.0, v143
	v_rcp_f32_e32 v143, v130
	v_add_f32_e32 v130, 1.0, v131
	v_rcp_f32_e32 v132, v130
	v_add_f32_e32 v130, 1.0, v133
	v_rcp_f32_e32 v133, v130
.LBB0_498:
	v_cvt_f32_i32_e32 v129, v129
	v_cvt_f32_i32_e32 v128, v128
	v_cvt_pk_bf16_f32 v170, v136, v137
	v_cvt_pk_bf16_f32 v171, v134, v135
	v_cvt_pk_bf16_f32 v172, v142, v143
	v_cvt_f32_i32_e32 v127, v127
	v_cvt_f32_i32_e32 v126, v126
	v_cvt_pk_bf16_f32 v173, v132, v133
	v_cvt_f32_i32_e32 v133, v125
	v_cvt_f32_i32_e32 v123, v123
	v_cvt_f32_i32_e32 v122, v122
	v_cvt_f32_i32_e32 v132, v124
	v_mul_f32_e32 v130, v202, v203
	v_pk_mul_f32 v[128:129], v[130:131], v[128:129] op_sel_hi:[0,1]
	v_pk_mul_f32 v[126:127], v[130:131], v[126:127] op_sel_hi:[0,1]
	v_pk_mul_f32 v[124:125], v[80:81], v[128:129]
	v_pk_mul_f32 v[122:123], v[130:131], v[122:123] op_sel_hi:[0,1]
	v_pk_mul_f32 v[128:129], v[130:131], v[132:133] op_sel_hi:[0,1]
	v_pk_mul_f32 v[126:127], v[78:79], v[126:127]
	v_pk_mul_f32 v[128:129], v[76:77], v[128:129]
	s_and_b64 vcc, exec, s[6:7]
	v_pk_mul_f32 v[132:133], v[74:75], v[122:123]
	global_store_dwordx4 v[140:141], v[170:173], off offset:256
	s_cbranch_vccnz .LBB0_500
	v_mul_f32_e32 v122, 0xbfb8aa3b, v126
	v_exp_f32_e32 v122, v122
	v_mul_f32_e32 v123, 0xbfb8aa3b, v127
	v_exp_f32_e32 v123, v123
	v_add_f32_e32 v122, 1.0, v122
	v_rcp_f32_e32 v126, v122
	v_mul_f32_e32 v122, 0xbfb8aa3b, v124
	v_add_f32_e32 v123, 1.0, v123
	v_exp_f32_e32 v122, v122
	v_mul_f32_e32 v124, 0xbfb8aa3b, v125
	v_exp_f32_e32 v125, v124
	v_rcp_f32_e32 v127, v123
	v_mul_f32_e32 v123, 0xbfb8aa3b, v132
	v_exp_f32_e32 v123, v123
	v_add_f32_e32 v122, 1.0, v122
	v_rcp_f32_e32 v124, v122
	v_add_f32_e32 v122, 1.0, v125
	v_mul_f32_e32 v125, 0xbfb8aa3b, v133
	v_exp_f32_e32 v131, v125
	v_rcp_f32_e32 v125, v122
	v_add_f32_e32 v122, 1.0, v123
	v_mul_f32_e32 v123, 0xbfb8aa3b, v128
	v_exp_f32_e32 v123, v123
	v_mul_f32_e32 v128, 0xbfb8aa3b, v129
	v_exp_f32_e32 v129, v128
	v_rcp_f32_e32 v132, v122
	v_add_f32_e32 v122, 1.0, v131
	v_rcp_f32_e32 v133, v122
	v_add_f32_e32 v122, 1.0, v123
	v_rcp_f32_e32 v128, v122
	v_add_f32_e32 v122, 1.0, v129
	v_rcp_f32_e32 v129, v122
.LBB0_500:
	v_cvt_f32_i32_e32 v119, v119
	v_cvt_f32_i32_e32 v121, v121
	v_cvt_f32_i32_e32 v120, v120
	v_cvt_f32_i32_e32 v118, v118
	v_cvt_f32_i32_e32 v115, v115
	v_cvt_f32_i32_e32 v117, v117
	v_cvt_f32_i32_e32 v116, v116
	v_cvt_f32_i32_e32 v114, v114
	v_mul_lo_u32 v134, s3, v168
	v_mul_lo_u32 v135, s2, v169
	v_mad_u64_u32 v[122:123], s[34:35], s2, v168, 0
	v_mov_b32_e32 v131, v130
	v_add3_u32 v123, v123, v135, v134
	v_cvt_pk_bf16_f32 v134, v126, v127
	v_cvt_pk_bf16_f32 v135, v124, v125
	v_mov_b32_e32 v124, v130
	v_mov_b32_e32 v125, v130
	v_pk_mul_f32 v[120:121], v[124:125], v[120:121]
	v_pk_mul_f32 v[126:127], v[130:131], v[118:119]
	v_pk_mul_f32 v[116:117], v[124:125], v[116:117]
	v_pk_mul_f32 v[114:115], v[130:131], v[114:115]
	v_lshl_add_u64 v[122:123], v[122:123], 1, v[138:139]
	v_pk_mul_f32 v[118:119], v[64:65], v[120:121]
	v_pk_mul_f32 v[120:121], v[62:63], v[126:127]
	v_pk_mul_f32 v[116:117], v[60:61], v[116:117]
	s_and_b64 vcc, exec, s[6:7]
	v_pk_mul_f32 v[124:125], v[58:59], v[114:115]
	v_cvt_pk_bf16_f32 v136, v132, v133
	v_cvt_pk_bf16_f32 v137, v128, v129
	global_store_dwordx4 v[122:123], v[134:137], off
	s_cbranch_vccnz .LBB0_502
	v_mul_f32_e32 v114, 0xbfb8aa3b, v120
	v_exp_f32_e32 v114, v114
	v_mul_f32_e32 v115, 0xbfb8aa3b, v121
	v_exp_f32_e32 v115, v115
	v_add_f32_e32 v114, 1.0, v114
	v_rcp_f32_e32 v120, v114
	v_mul_f32_e32 v114, 0xbfb8aa3b, v118
	v_add_f32_e32 v115, 1.0, v115
	v_exp_f32_e32 v114, v114
	v_mul_f32_e32 v118, 0xbfb8aa3b, v119
	v_exp_f32_e32 v119, v118
	v_rcp_f32_e32 v121, v115
	v_mul_f32_e32 v115, 0xbfb8aa3b, v124
	v_exp_f32_e32 v115, v115
	v_add_f32_e32 v114, 1.0, v114
	v_rcp_f32_e32 v118, v114
	v_add_f32_e32 v114, 1.0, v119
	v_mul_f32_e32 v119, 0xbfb8aa3b, v125
	v_exp_f32_e32 v125, v119
	v_rcp_f32_e32 v119, v114
	v_add_f32_e32 v114, 1.0, v115
	v_mul_f32_e32 v115, 0xbfb8aa3b, v116
	v_exp_f32_e32 v115, v115
	v_mul_f32_e32 v116, 0xbfb8aa3b, v117
	v_exp_f32_e32 v117, v116
	v_rcp_f32_e32 v124, v114
	v_add_f32_e32 v114, 1.0, v125
	v_rcp_f32_e32 v125, v114
	v_add_f32_e32 v114, 1.0, v115
	v_rcp_f32_e32 v116, v114
	v_add_f32_e32 v114, 1.0, v117
	v_rcp_f32_e32 v117, v114
; __device__ __forceinline__ unsigned cvt_pk_bf16(float lo, float hi) { unsigned r; asm volatile("s_nop 0\n\tv_cvt_pk_bf16_f32 %0, %1, %2" : "=v"(r) : "v"(lo), "v"(hi)); return r; }
; __device__ __forceinline__ float sigmoidf_(float x) { return __builtin_amdgcn_rcpf(1.0f + __builtin_amdgcn_exp2f(-1.4426950408889634f * x)); }
; __device__ __forceinline__ u32x4 pack8(const f32x4 v0, const f32x4 v1) { u32x4 w; w.x = cvt_pk_bf16(v0[0], v0[1]); w.y = cvt_pk_bf16(v0[2], v0[3]); w.z = cvt_pk_bf16(v1[0], v1[1]); w.w = cvt_pk_bf16(v1[2], v1[3]); return w; }
; __device__ __forceinline__ void unpack8(const u32x4 w, f32x4& v0, f32x4& v1) { v0 = (f32x4){bf_lo(w.x), bf_hi(w.x), bf_lo(w.y), bf_hi(w.y)}; v1 = (f32x4){bf_lo(w.z), bf_hi(w.z), bf_lo(w.w), bf_hi(w.w)}; }
; __device__ __forceinline__ f32x4 sig4(const f32x4 v) { return (f32x4){sigmoidf_(v[0]), sigmoidf_(v[1]), sigmoidf_(v[2]), sigmoidf_(v[3])}; }
;     __device__ __forceinline__ void operator()(const i32x4 (&acc)[2][2][4][2], const Unit& uu, int wr, int wc, int fr, int fq) const {
;     ...
; #pragma unroll
;         for (int ai = 0; ai < 2; ++ai)
; #pragma unroll
;             for (int m = 0; m < 4; ++m) { const int r = row0 + ai * HALF + m * 16; const float rs = rsv[ai][m]; bf16_t* rowp = base + (size_t)r * ldc + col0;
; #pragma unroll
;                 for (int bj = 0; bj < 2; ++bj) { f32x4 v0 = __builtin_convertvector(acc[ai][bj][m][0], f32x4) * rs * sv[bj][0], v1 = __builtin_convertvector(acc[ai][bj][m][1], f32x4) * rs * sv[bj][1];
;                     if (sg) { v0 = sig4(v0); v1 = sig4(v1); }
;                     *(u32x4*)(rowp + bj * HALF) = pack8(v0, v1); } }
.LBB0_502:
	v_cvt_f32_i32_e32 v113, v113
	v_cvt_f32_i32_e32 v112, v112
	v_cvt_pk_bf16_f32 v126, v120, v121
	v_cvt_pk_bf16_f32 v127, v118, v119
	v_cvt_pk_bf16_f32 v128, v124, v125
	v_cvt_f32_i32_e32 v111, v111
	v_cvt_f32_i32_e32 v110, v110
	v_cvt_pk_bf16_f32 v129, v116, v117
	v_cvt_f32_i32_e32 v117, v109
	v_cvt_f32_i32_e32 v107, v107
	v_cvt_f32_i32_e32 v106, v106
	v_cvt_f32_i32_e32 v116, v108
	v_mul_f32_e32 v114, v200, v201
	v_pk_mul_f32 v[112:113], v[114:115], v[112:113] op_sel_hi:[0,1]
	v_pk_mul_f32 v[110:111], v[114:115], v[110:111] op_sel_hi:[0,1]
	v_pk_mul_f32 v[108:109], v[80:81], v[112:113]
	v_pk_mul_f32 v[106:107], v[114:115], v[106:107] op_sel_hi:[0,1]
	v_pk_mul_f32 v[112:113], v[114:115], v[116:117] op_sel_hi:[0,1]
	v_pk_mul_f32 v[110:111], v[78:79], v[110:111]
	v_pk_mul_f32 v[112:113], v[76:77], v[112:113]
	s_and_b64 vcc, exec, s[6:7]
	v_pk_mul_f32 v[116:117], v[74:75], v[106:107]
	global_store_dwordx4 v[122:123], v[126:129], off offset:256
	s_cbranch_vccnz .LBB0_504
	v_mul_f32_e32 v106, 0xbfb8aa3b, v110
	v_exp_f32_e32 v106, v106
	v_mul_f32_e32 v107, 0xbfb8aa3b, v111
	v_exp_f32_e32 v107, v107
	v_add_f32_e32 v106, 1.0, v106
	v_rcp_f32_e32 v110, v106
	v_mul_f32_e32 v106, 0xbfb8aa3b, v108
	v_add_f32_e32 v107, 1.0, v107
	v_exp_f32_e32 v106, v106
	v_mul_f32_e32 v108, 0xbfb8aa3b, v109
	v_exp_f32_e32 v109, v108
	v_rcp_f32_e32 v111, v107
	v_mul_f32_e32 v107, 0xbfb8aa3b, v116
	v_exp_f32_e32 v107, v107
	v_add_f32_e32 v106, 1.0, v106
	v_rcp_f32_e32 v108, v106
	v_add_f32_e32 v106, 1.0, v109
	v_mul_f32_e32 v109, 0xbfb8aa3b, v117
	v_exp_f32_e32 v115, v109
	v_rcp_f32_e32 v109, v106
	v_add_f32_e32 v106, 1.0, v107
	v_mul_f32_e32 v107, 0xbfb8aa3b, v112
	v_exp_f32_e32 v107, v107
	v_mul_f32_e32 v112, 0xbfb8aa3b, v113
	v_exp_f32_e32 v113, v112
	v_rcp_f32_e32 v116, v106
	v_add_f32_e32 v106, 1.0, v115
	v_rcp_f32_e32 v117, v106
	v_add_f32_e32 v106, 1.0, v107
	v_rcp_f32_e32 v112, v106
	v_add_f32_e32 v106, 1.0, v113
	v_rcp_f32_e32 v113, v106
.LBB0_504:
	v_cvt_f32_i32_e32 v103, v103
	v_cvt_f32_i32_e32 v105, v105
	v_cvt_f32_i32_e32 v104, v104
	v_cvt_f32_i32_e32 v102, v102
	v_cvt_f32_i32_e32 v99, v99
	v_cvt_f32_i32_e32 v101, v101
	v_cvt_f32_i32_e32 v100, v100
	v_cvt_f32_i32_e32 v98, v98
	v_mul_lo_u32 v118, s3, v166
	v_mul_lo_u32 v119, s2, v167
	v_mad_u64_u32 v[106:107], s[34:35], s2, v166, 0
	v_mov_b32_e32 v115, v114
	v_add3_u32 v107, v107, v119, v118
	v_cvt_pk_bf16_f32 v118, v110, v111
	v_cvt_pk_bf16_f32 v119, v108, v109
	v_mov_b32_e32 v108, v114
	v_mov_b32_e32 v109, v114
	v_pk_mul_f32 v[104:105], v[108:109], v[104:105]
	v_pk_mul_f32 v[110:111], v[114:115], v[102:103]
	v_pk_mul_f32 v[100:101], v[108:109], v[100:101]
	v_pk_mul_f32 v[98:99], v[114:115], v[98:99]
	v_lshl_add_u64 v[106:107], v[106:107], 1, v[138:139]
	v_pk_mul_f32 v[102:103], v[64:65], v[104:105]
	v_pk_mul_f32 v[104:105], v[62:63], v[110:111]
	v_pk_mul_f32 v[100:101], v[60:61], v[100:101]
	s_and_b64 vcc, exec, s[6:7]
	v_pk_mul_f32 v[108:109], v[58:59], v[98:99]
	v_cvt_pk_bf16_f32 v120, v116, v117
	v_cvt_pk_bf16_f32 v121, v112, v113
	global_store_dwordx4 v[106:107], v[118:121], off
	s_cbranch_vccnz .LBB0_506
	v_mul_f32_e32 v98, 0xbfb8aa3b, v104
	v_exp_f32_e32 v98, v98
	v_mul_f32_e32 v99, 0xbfb8aa3b, v105
	v_exp_f32_e32 v99, v99
	v_add_f32_e32 v98, 1.0, v98
	v_rcp_f32_e32 v104, v98
	v_mul_f32_e32 v98, 0xbfb8aa3b, v102
	v_add_f32_e32 v99, 1.0, v99
	v_exp_f32_e32 v98, v98
	v_mul_f32_e32 v102, 0xbfb8aa3b, v103
	v_exp_f32_e32 v103, v102
	v_rcp_f32_e32 v105, v99
	v_mul_f32_e32 v99, 0xbfb8aa3b, v108
	v_exp_f32_e32 v99, v99
	v_add_f32_e32 v98, 1.0, v98
	v_rcp_f32_e32 v102, v98
	v_add_f32_e32 v98, 1.0, v103
	v_mul_f32_e32 v103, 0xbfb8aa3b, v109
	v_exp_f32_e32 v109, v103
	v_rcp_f32_e32 v103, v98
	v_add_f32_e32 v98, 1.0, v99
	v_mul_f32_e32 v99, 0xbfb8aa3b, v100
	v_exp_f32_e32 v99, v99
	v_mul_f32_e32 v100, 0xbfb8aa3b, v101
	v_exp_f32_e32 v101, v100
	v_rcp_f32_e32 v108, v98
	v_add_f32_e32 v98, 1.0, v109
	v_rcp_f32_e32 v109, v98
	v_add_f32_e32 v98, 1.0, v99
	v_rcp_f32_e32 v100, v98
	v_add_f32_e32 v98, 1.0, v101
	v_rcp_f32_e32 v101, v98
.LBB0_506:
	v_cvt_f32_i32_e32 v97, v97
	v_cvt_f32_i32_e32 v96, v96
	v_cvt_pk_bf16_f32 v110, v104, v105
	v_cvt_pk_bf16_f32 v111, v102, v103
	v_cvt_pk_bf16_f32 v112, v108, v109
	v_cvt_f32_i32_e32 v95, v95
	v_cvt_f32_i32_e32 v94, v94
	v_cvt_pk_bf16_f32 v113, v100, v101
	v_cvt_f32_i32_e32 v101, v93
	v_cvt_f32_i32_e32 v91, v91
	v_cvt_f32_i32_e32 v90, v90
	v_cvt_f32_i32_e32 v100, v92
	v_mul_f32_e32 v98, v198, v199
	v_pk_mul_f32 v[96:97], v[98:99], v[96:97] op_sel_hi:[0,1]
	v_pk_mul_f32 v[94:95], v[98:99], v[94:95] op_sel_hi:[0,1]
	v_pk_mul_f32 v[92:93], v[80:81], v[96:97]
	v_pk_mul_f32 v[90:91], v[98:99], v[90:91] op_sel_hi:[0,1]
	v_pk_mul_f32 v[96:97], v[98:99], v[100:101] op_sel_hi:[0,1]
	v_pk_mul_f32 v[94:95], v[78:79], v[94:95]
	v_pk_mul_f32 v[96:97], v[76:77], v[96:97]
	s_and_b64 vcc, exec, s[6:7]
	v_pk_mul_f32 v[100:101], v[74:75], v[90:91]
	global_store_dwordx4 v[106:107], v[110:113], off offset:256
	s_cbranch_vccnz .LBB0_508
	v_mul_f32_e32 v90, 0xbfb8aa3b, v94
	v_exp_f32_e32 v90, v90
	v_mul_f32_e32 v91, 0xbfb8aa3b, v95
	v_exp_f32_e32 v91, v91
	v_add_f32_e32 v90, 1.0, v90
	v_rcp_f32_e32 v94, v90
	v_mul_f32_e32 v90, 0xbfb8aa3b, v92
	v_add_f32_e32 v91, 1.0, v91
	v_exp_f32_e32 v90, v90
	v_mul_f32_e32 v92, 0xbfb8aa3b, v93
	v_exp_f32_e32 v93, v92
	v_rcp_f32_e32 v95, v91
	v_mul_f32_e32 v91, 0xbfb8aa3b, v100
	v_exp_f32_e32 v91, v91
	v_add_f32_e32 v90, 1.0, v90
	v_rcp_f32_e32 v92, v90
	v_add_f32_e32 v90, 1.0, v93
	v_mul_f32_e32 v93, 0xbfb8aa3b, v101
	v_exp_f32_e32 v99, v93
	v_rcp_f32_e32 v93, v90
	v_add_f32_e32 v90, 1.0, v91
	v_mul_f32_e32 v91, 0xbfb8aa3b, v96
	v_exp_f32_e32 v91, v91
	v_mul_f32_e32 v96, 0xbfb8aa3b, v97
	v_exp_f32_e32 v97, v96
	v_rcp_f32_e32 v100, v90
	v_add_f32_e32 v90, 1.0, v99
	v_rcp_f32_e32 v101, v90
	v_add_f32_e32 v90, 1.0, v91
	v_rcp_f32_e32 v96, v90
	v_add_f32_e32 v90, 1.0, v97
	v_rcp_f32_e32 v97, v90
; __device__ __forceinline__ unsigned cvt_pk_bf16(float lo, float hi) { unsigned r; asm volatile("s_nop 0\n\tv_cvt_pk_bf16_f32 %0, %1, %2" : "=v"(r) : "v"(lo), "v"(hi)); return r; }
; __device__ __forceinline__ float sigmoidf_(float x) { return __builtin_amdgcn_rcpf(1.0f + __builtin_amdgcn_exp2f(-1.4426950408889634f * x)); }
; __device__ __forceinline__ u32x4 pack8(const f32x4 v0, const f32x4 v1) { u32x4 w; w.x = cvt_pk_bf16(v0[0], v0[1]); w.y = cvt_pk_bf16(v0[2], v0[3]); w.z = cvt_pk_bf16(v1[0], v1[1]); w.w = cvt_pk_bf16(v1[2], v1[3]); return w; }
; __device__ __forceinline__ void unpack8(const u32x4 w, f32x4& v0, f32x4& v1) { v0 = (f32x4){bf_lo(w.x), bf_hi(w.x), bf_lo(w.y), bf_hi(w.y)}; v1 = (f32x4){bf_lo(w.z), bf_hi(w.z), bf_lo(w.w), bf_hi(w.w)}; }
; __device__ __forceinline__ f32x4 sig4(const f32x4 v) { return (f32x4){sigmoidf_(v[0]), sigmoidf_(v[1]), sigmoidf_(v[2]), sigmoidf_(v[3])}; }
;     __device__ __forceinline__ void operator()(const i32x4 (&acc)[2][2][4][2], const Unit& uu, int wr, int wc, int fr, int fq) const {
;     ...
; #pragma unroll
;         for (int ai = 0; ai < 2; ++ai)
; #pragma unroll
;             for (int m = 0; m < 4; ++m) { const int r = row0 + ai * HALF + m * 16; const float rs = rsv[ai][m]; bf16_t* rowp = base + (size_t)r * ldc + col0;
; #pragma unroll
;                 for (int bj = 0; bj < 2; ++bj) { f32x4 v0 = __builtin_convertvector(acc[ai][bj][m][0], f32x4) * rs * sv[bj][0], v1 = __builtin_convertvector(acc[ai][bj][m][1], f32x4) * rs * sv[bj][1];
;                     if (sg) { v0 = sig4(v0); v1 = sig4(v1); }
;                     *(u32x4*)(rowp + bj * HALF) = pack8(v0, v1); } }
.LBB0_508:
	v_cvt_f32_i32_e32 v87, v87
	v_cvt_f32_i32_e32 v89, v89
	v_cvt_f32_i32_e32 v88, v88
	v_cvt_f32_i32_e32 v86, v86
	v_cvt_f32_i32_e32 v83, v83
	v_cvt_f32_i32_e32 v85, v85
	v_cvt_f32_i32_e32 v84, v84
	v_cvt_f32_i32_e32 v82, v82
	v_mul_lo_u32 v102, s3, v164
	v_mul_lo_u32 v103, s2, v165
	v_mad_u64_u32 v[90:91], s[34:35], s2, v164, 0
	v_mov_b32_e32 v99, v98
	v_add3_u32 v91, v91, v103, v102
	v_cvt_pk_bf16_f32 v102, v94, v95
	v_cvt_pk_bf16_f32 v103, v92, v93
	v_mov_b32_e32 v92, v98
	v_mov_b32_e32 v93, v98
	v_pk_mul_f32 v[88:89], v[92:93], v[88:89]
	v_pk_mul_f32 v[94:95], v[98:99], v[86:87]
	v_pk_mul_f32 v[84:85], v[92:93], v[84:85]
	v_pk_mul_f32 v[82:83], v[98:99], v[82:83]
	v_lshl_add_u64 v[90:91], v[90:91], 1, v[138:139]
	v_pk_mul_f32 v[86:87], v[64:65], v[88:89]
	v_pk_mul_f32 v[88:89], v[62:63], v[94:95]
	v_pk_mul_f32 v[84:85], v[60:61], v[84:85]
	s_and_b64 vcc, exec, s[6:7]
	v_pk_mul_f32 v[92:93], v[58:59], v[82:83]
	v_cvt_pk_bf16_f32 v104, v100, v101
	v_cvt_pk_bf16_f32 v105, v96, v97
	global_store_dwordx4 v[90:91], v[102:105], off
	s_cbranch_vccnz .LBB0_510
	v_mul_f32_e32 v82, 0xbfb8aa3b, v88
	v_exp_f32_e32 v82, v82
	v_mul_f32_e32 v83, 0xbfb8aa3b, v89
	v_exp_f32_e32 v83, v83
	v_add_f32_e32 v82, 1.0, v82
	v_rcp_f32_e32 v88, v82
	v_mul_f32_e32 v82, 0xbfb8aa3b, v86
	v_add_f32_e32 v83, 1.0, v83
	v_exp_f32_e32 v82, v82
	v_mul_f32_e32 v86, 0xbfb8aa3b, v87
	v_exp_f32_e32 v87, v86
	v_rcp_f32_e32 v89, v83
	v_mul_f32_e32 v83, 0xbfb8aa3b, v92
	v_exp_f32_e32 v83, v83
	v_add_f32_e32 v82, 1.0, v82
	v_rcp_f32_e32 v86, v82
	v_add_f32_e32 v82, 1.0, v87
	v_mul_f32_e32 v87, 0xbfb8aa3b, v93
	v_exp_f32_e32 v93, v87
	v_rcp_f32_e32 v87, v82
	v_add_f32_e32 v82, 1.0, v83
	v_mul_f32_e32 v83, 0xbfb8aa3b, v84
	v_exp_f32_e32 v83, v83
	v_mul_f32_e32 v84, 0xbfb8aa3b, v85
	v_exp_f32_e32 v85, v84
	v_rcp_f32_e32 v92, v82
	v_add_f32_e32 v82, 1.0, v93
	v_rcp_f32_e32 v93, v82
	v_add_f32_e32 v82, 1.0, v83
	v_rcp_f32_e32 v84, v82
	v_add_f32_e32 v82, 1.0, v85
	v_rcp_f32_e32 v85, v82
.LBB0_510:
	v_cvt_f32_i32_e32 v73, v73
	v_cvt_f32_i32_e32 v72, v72
	v_cvt_pk_bf16_f32 v94, v88, v89
	v_cvt_pk_bf16_f32 v95, v86, v87
	v_cvt_pk_bf16_f32 v96, v92, v93
	v_cvt_f32_i32_e32 v71, v71
	v_cvt_f32_i32_e32 v70, v70
	v_cvt_pk_bf16_f32 v97, v84, v85
	v_cvt_f32_i32_e32 v85, v69
	v_cvt_f32_i32_e32 v67, v67
	v_cvt_f32_i32_e32 v66, v66
	v_cvt_f32_i32_e32 v84, v68
	v_mul_f32_e32 v82, v196, v197
	v_pk_mul_f32 v[72:73], v[82:83], v[72:73] op_sel_hi:[0,1]
	v_pk_mul_f32 v[70:71], v[82:83], v[70:71] op_sel_hi:[0,1]
	v_pk_mul_f32 v[68:69], v[80:81], v[72:73]
	v_pk_mul_f32 v[66:67], v[82:83], v[66:67] op_sel_hi:[0,1]
	v_pk_mul_f32 v[72:73], v[82:83], v[84:85] op_sel_hi:[0,1]
	v_pk_mul_f32 v[70:71], v[78:79], v[70:71]
	v_pk_mul_f32 v[72:73], v[76:77], v[72:73]
	s_and_b64 vcc, exec, s[6:7]
	v_pk_mul_f32 v[84:85], v[74:75], v[66:67]
	global_store_dwordx4 v[90:91], v[94:97], off offset:256
	s_cbranch_vccnz .LBB0_512
	v_mul_f32_e32 v66, 0xbfb8aa3b, v70
	v_exp_f32_e32 v66, v66
	v_mul_f32_e32 v67, 0xbfb8aa3b, v71
	v_exp_f32_e32 v67, v67
	v_add_f32_e32 v66, 1.0, v66
	v_rcp_f32_e32 v70, v66
	v_mul_f32_e32 v66, 0xbfb8aa3b, v68
	v_add_f32_e32 v67, 1.0, v67
	v_exp_f32_e32 v66, v66
	v_mul_f32_e32 v68, 0xbfb8aa3b, v69
	v_exp_f32_e32 v69, v68
	v_rcp_f32_e32 v71, v67
	v_mul_f32_e32 v67, 0xbfb8aa3b, v84
	v_exp_f32_e32 v67, v67
	v_add_f32_e32 v66, 1.0, v66
	v_rcp_f32_e32 v68, v66
	v_add_f32_e32 v66, 1.0, v69
	v_mul_f32_e32 v69, 0xbfb8aa3b, v85
	v_exp_f32_e32 v83, v69
	v_rcp_f32_e32 v69, v66
	v_add_f32_e32 v66, 1.0, v67
	v_mul_f32_e32 v67, 0xbfb8aa3b, v72
	v_exp_f32_e32 v67, v67
	v_mul_f32_e32 v72, 0xbfb8aa3b, v73
	v_exp_f32_e32 v73, v72
	v_rcp_f32_e32 v84, v66
	v_add_f32_e32 v66, 1.0, v83
	v_rcp_f32_e32 v85, v66
	v_add_f32_e32 v66, 1.0, v67
	v_rcp_f32_e32 v72, v66
	v_add_f32_e32 v66, 1.0, v73
	v_rcp_f32_e32 v73, v66
.LBB0_512:
	v_add_u32_e32 v66, 0x80, v162
	v_cvt_f32_i32_e32 v55, v55
	v_cvt_f32_i32_e32 v57, v57
	v_cvt_f32_i32_e32 v56, v56
	v_cvt_f32_i32_e32 v54, v54
	v_cvt_f32_i32_e32 v51, v51
	v_cvt_f32_i32_e32 v53, v53
	v_cvt_f32_i32_e32 v52, v52
	v_cvt_f32_i32_e32 v50, v50
	v_ashrrev_i32_e32 v67, 31, v66
	v_mul_lo_u32 v86, s2, v67
	v_mul_lo_u32 v87, s3, v66
	v_mad_u64_u32 v[66:67], s[34:35], s2, v66, 0
	v_mov_b32_e32 v83, v82
	v_add3_u32 v67, v67, v86, v87
	v_cvt_pk_bf16_f32 v86, v70, v71
	v_cvt_pk_bf16_f32 v87, v68, v69
	v_mov_b32_e32 v68, v82
	v_mov_b32_e32 v69, v82
	v_pk_mul_f32 v[56:57], v[68:69], v[56:57]
	v_pk_mul_f32 v[70:71], v[82:83], v[54:55]
	v_pk_mul_f32 v[52:53], v[68:69], v[52:53]
	v_pk_mul_f32 v[50:51], v[82:83], v[50:51]
	v_lshl_add_u64 v[66:67], v[66:67], 1, v[138:139]
	v_pk_mul_f32 v[54:55], v[64:65], v[56:57]
	v_pk_mul_f32 v[56:57], v[62:63], v[70:71]
	v_pk_mul_f32 v[52:53], v[60:61], v[52:53]
	s_and_b64 vcc, exec, s[6:7]
	v_pk_mul_f32 v[68:69], v[58:59], v[50:51]
	v_cvt_pk_bf16_f32 v88, v84, v85
	v_cvt_pk_bf16_f32 v89, v72, v73
	global_store_dwordx4 v[66:67], v[86:89], off
	s_cbranch_vccnz .LBB0_514
	v_mul_f32_e32 v50, 0xbfb8aa3b, v56
	v_exp_f32_e32 v50, v50
	v_mul_f32_e32 v51, 0xbfb8aa3b, v57
	v_exp_f32_e32 v51, v51
	v_add_f32_e32 v50, 1.0, v50
	v_rcp_f32_e32 v56, v50
	v_mul_f32_e32 v50, 0xbfb8aa3b, v54
	v_add_f32_e32 v51, 1.0, v51
	v_exp_f32_e32 v50, v50
	v_mul_f32_e32 v54, 0xbfb8aa3b, v55
	v_exp_f32_e32 v55, v54
	v_rcp_f32_e32 v57, v51
	v_mul_f32_e32 v51, 0xbfb8aa3b, v68
	v_exp_f32_e32 v51, v51
	v_add_f32_e32 v50, 1.0, v50
	v_rcp_f32_e32 v54, v50
	v_add_f32_e32 v50, 1.0, v55
	v_mul_f32_e32 v55, 0xbfb8aa3b, v69
	v_exp_f32_e32 v69, v55
	v_rcp_f32_e32 v55, v50
	v_add_f32_e32 v50, 1.0, v51
	v_mul_f32_e32 v51, 0xbfb8aa3b, v52
	v_exp_f32_e32 v51, v51
	v_mul_f32_e32 v52, 0xbfb8aa3b, v53
	v_exp_f32_e32 v53, v52
	v_rcp_f32_e32 v68, v50
	v_add_f32_e32 v50, 1.0, v69
	v_rcp_f32_e32 v69, v50
	v_add_f32_e32 v50, 1.0, v51
	v_rcp_f32_e32 v52, v50
	v_add_f32_e32 v50, 1.0, v53
	v_rcp_f32_e32 v53, v50
; __device__ __forceinline__ unsigned cvt_pk_bf16(float lo, float hi) { unsigned r; asm volatile("s_nop 0\n\tv_cvt_pk_bf16_f32 %0, %1, %2" : "=v"(r) : "v"(lo), "v"(hi)); return r; }
; __device__ __forceinline__ float sigmoidf_(float x) { return __builtin_amdgcn_rcpf(1.0f + __builtin_amdgcn_exp2f(-1.4426950408889634f * x)); }
; __device__ __forceinline__ u32x4 pack8(const f32x4 v0, const f32x4 v1) { u32x4 w; w.x = cvt_pk_bf16(v0[0], v0[1]); w.y = cvt_pk_bf16(v0[2], v0[3]); w.z = cvt_pk_bf16(v1[0], v1[1]); w.w = cvt_pk_bf16(v1[2], v1[3]); return w; }
; __device__ __forceinline__ void unpack8(const u32x4 w, f32x4& v0, f32x4& v1) { v0 = (f32x4){bf_lo(w.x), bf_hi(w.x), bf_lo(w.y), bf_hi(w.y)}; v1 = (f32x4){bf_lo(w.z), bf_hi(w.z), bf_lo(w.w), bf_hi(w.w)}; }
; __device__ __forceinline__ f32x4 sig4(const f32x4 v) { return (f32x4){sigmoidf_(v[0]), sigmoidf_(v[1]), sigmoidf_(v[2]), sigmoidf_(v[3])}; }
;     __device__ __forceinline__ void operator()(const i32x4 (&acc)[2][2][4][2], const Unit& uu, int wr, int wc, int fr, int fq) const {
;     ...
; #pragma unroll
;         for (int ai = 0; ai < 2; ++ai)
; #pragma unroll
;             for (int m = 0; m < 4; ++m) { const int r = row0 + ai * HALF + m * 16; const float rs = rsv[ai][m]; bf16_t* rowp = base + (size_t)r * ldc + col0;
; #pragma unroll
;                 for (int bj = 0; bj < 2; ++bj) { f32x4 v0 = __builtin_convertvector(acc[ai][bj][m][0], f32x4) * rs * sv[bj][0], v1 = __builtin_convertvector(acc[ai][bj][m][1], f32x4) * rs * sv[bj][1];
;                     if (sg) { v0 = sig4(v0); v1 = sig4(v1); }
;                     *(u32x4*)(rowp + bj * HALF) = pack8(v0, v1); } }
.LBB0_514:
	v_cvt_f32_i32_e32 v49, v49
	v_cvt_f32_i32_e32 v48, v48
	v_cvt_pk_bf16_f32 v70, v56, v57
	v_cvt_pk_bf16_f32 v71, v54, v55
	v_cvt_pk_bf16_f32 v72, v68, v69
	v_cvt_f32_i32_e32 v47, v47
	v_cvt_f32_i32_e32 v46, v46
	v_cvt_pk_bf16_f32 v73, v52, v53
	v_cvt_f32_i32_e32 v53, v45
	v_cvt_f32_i32_e32 v43, v43
	v_cvt_f32_i32_e32 v42, v42
	v_cvt_f32_i32_e32 v52, v44
	v_mul_f32_e32 v50, v194, v195
	v_pk_mul_f32 v[48:49], v[50:51], v[48:49] op_sel_hi:[0,1]
	v_pk_mul_f32 v[46:47], v[50:51], v[46:47] op_sel_hi:[0,1]
	v_pk_mul_f32 v[44:45], v[80:81], v[48:49]
	v_pk_mul_f32 v[42:43], v[50:51], v[42:43] op_sel_hi:[0,1]
	v_pk_mul_f32 v[48:49], v[50:51], v[52:53] op_sel_hi:[0,1]
	v_pk_mul_f32 v[46:47], v[78:79], v[46:47]
	v_pk_mul_f32 v[48:49], v[76:77], v[48:49]
	s_and_b64 vcc, exec, s[6:7]
	v_pk_mul_f32 v[52:53], v[74:75], v[42:43]
	global_store_dwordx4 v[66:67], v[70:73], off offset:256
	s_cbranch_vccnz .LBB0_516
	v_mul_f32_e32 v42, 0xbfb8aa3b, v46
	v_exp_f32_e32 v42, v42
	v_mul_f32_e32 v43, 0xbfb8aa3b, v47
	v_exp_f32_e32 v43, v43
	v_add_f32_e32 v42, 1.0, v42
	v_rcp_f32_e32 v46, v42
	v_mul_f32_e32 v42, 0xbfb8aa3b, v44
	v_add_f32_e32 v43, 1.0, v43
	v_exp_f32_e32 v42, v42
	v_mul_f32_e32 v44, 0xbfb8aa3b, v45
	v_exp_f32_e32 v45, v44
	v_rcp_f32_e32 v47, v43
	v_mul_f32_e32 v43, 0xbfb8aa3b, v52
	v_exp_f32_e32 v43, v43
	v_add_f32_e32 v42, 1.0, v42
	v_rcp_f32_e32 v44, v42
	v_add_f32_e32 v42, 1.0, v45
	v_mul_f32_e32 v45, 0xbfb8aa3b, v53
	v_exp_f32_e32 v51, v45
	v_rcp_f32_e32 v45, v42
	v_add_f32_e32 v42, 1.0, v43
	v_mul_f32_e32 v43, 0xbfb8aa3b, v48
	v_exp_f32_e32 v43, v43
	v_mul_f32_e32 v48, 0xbfb8aa3b, v49
	v_exp_f32_e32 v49, v48
	v_rcp_f32_e32 v52, v42
	v_add_f32_e32 v42, 1.0, v51
	v_rcp_f32_e32 v53, v42
	v_add_f32_e32 v42, 1.0, v43
	v_rcp_f32_e32 v48, v42
	v_add_f32_e32 v42, 1.0, v49
	v_rcp_f32_e32 v49, v42
.LBB0_516:
	v_add_u32_e32 v42, 0x90, v162
	v_cvt_f32_i32_e32 v39, v39
	v_cvt_f32_i32_e32 v41, v41
	v_cvt_f32_i32_e32 v40, v40
	v_cvt_f32_i32_e32 v38, v38
	v_cvt_f32_i32_e32 v35, v35
	v_cvt_f32_i32_e32 v37, v37
	v_cvt_f32_i32_e32 v36, v36
	v_cvt_f32_i32_e32 v34, v34
	v_ashrrev_i32_e32 v43, 31, v42
	v_mul_lo_u32 v54, s2, v43
	v_mul_lo_u32 v55, s3, v42
	v_mad_u64_u32 v[42:43], s[34:35], s2, v42, 0
	v_mov_b32_e32 v51, v50
	v_add3_u32 v43, v43, v54, v55
	v_cvt_pk_bf16_f32 v54, v46, v47
	v_cvt_pk_bf16_f32 v55, v44, v45
	v_mov_b32_e32 v44, v50
	v_mov_b32_e32 v45, v50
	v_pk_mul_f32 v[40:41], v[44:45], v[40:41]
	v_pk_mul_f32 v[46:47], v[50:51], v[38:39]
	v_pk_mul_f32 v[36:37], v[44:45], v[36:37]
	v_pk_mul_f32 v[34:35], v[50:51], v[34:35]
	v_lshl_add_u64 v[42:43], v[42:43], 1, v[138:139]
	v_pk_mul_f32 v[38:39], v[64:65], v[40:41]
	v_pk_mul_f32 v[40:41], v[62:63], v[46:47]
	v_pk_mul_f32 v[36:37], v[60:61], v[36:37]
	s_and_b64 vcc, exec, s[6:7]
	v_pk_mul_f32 v[44:45], v[58:59], v[34:35]
	v_cvt_pk_bf16_f32 v56, v52, v53
	v_cvt_pk_bf16_f32 v57, v48, v49
	global_store_dwordx4 v[42:43], v[54:57], off
	s_cbranch_vccnz .LBB0_518
	v_mul_f32_e32 v34, 0xbfb8aa3b, v40
	v_exp_f32_e32 v34, v34
	v_mul_f32_e32 v35, 0xbfb8aa3b, v41
	v_exp_f32_e32 v35, v35
	v_add_f32_e32 v34, 1.0, v34
	v_rcp_f32_e32 v40, v34
	v_mul_f32_e32 v34, 0xbfb8aa3b, v38
	v_add_f32_e32 v35, 1.0, v35
	v_exp_f32_e32 v34, v34
	v_mul_f32_e32 v38, 0xbfb8aa3b, v39
	v_exp_f32_e32 v39, v38
	v_rcp_f32_e32 v41, v35
	v_mul_f32_e32 v35, 0xbfb8aa3b, v44
	v_exp_f32_e32 v35, v35
	v_add_f32_e32 v34, 1.0, v34
	v_rcp_f32_e32 v38, v34
	v_add_f32_e32 v34, 1.0, v39
	v_mul_f32_e32 v39, 0xbfb8aa3b, v45
	v_exp_f32_e32 v45, v39
	v_rcp_f32_e32 v39, v34
	v_add_f32_e32 v34, 1.0, v35
	v_mul_f32_e32 v35, 0xbfb8aa3b, v36
	v_exp_f32_e32 v35, v35
	v_mul_f32_e32 v36, 0xbfb8aa3b, v37
	v_exp_f32_e32 v37, v36
	v_rcp_f32_e32 v44, v34
	v_add_f32_e32 v34, 1.0, v45
	v_rcp_f32_e32 v45, v34
	v_add_f32_e32 v34, 1.0, v35
	v_rcp_f32_e32 v36, v34
	v_add_f32_e32 v34, 1.0, v37
	v_rcp_f32_e32 v37, v34
.LBB0_518:
	v_cvt_f32_i32_e32 v33, v33
	v_cvt_f32_i32_e32 v32, v32
	v_cvt_pk_bf16_f32 v46, v40, v41
	v_cvt_pk_bf16_f32 v47, v38, v39
	v_cvt_pk_bf16_f32 v48, v44, v45
	v_cvt_f32_i32_e32 v31, v31
	v_cvt_f32_i32_e32 v30, v30
	v_cvt_pk_bf16_f32 v49, v36, v37
	v_cvt_f32_i32_e32 v37, v29
	v_cvt_f32_i32_e32 v27, v27
	v_cvt_f32_i32_e32 v26, v26
	v_cvt_f32_i32_e32 v36, v28
	v_mul_f32_e32 v34, v192, v193
	v_pk_mul_f32 v[32:33], v[34:35], v[32:33] op_sel_hi:[0,1]
	v_pk_mul_f32 v[30:31], v[34:35], v[30:31] op_sel_hi:[0,1]
	v_pk_mul_f32 v[28:29], v[80:81], v[32:33]
	v_pk_mul_f32 v[26:27], v[34:35], v[26:27] op_sel_hi:[0,1]
	v_pk_mul_f32 v[32:33], v[34:35], v[36:37] op_sel_hi:[0,1]
	v_pk_mul_f32 v[30:31], v[78:79], v[30:31]
	v_pk_mul_f32 v[32:33], v[76:77], v[32:33]
	s_and_b64 vcc, exec, s[6:7]
	v_pk_mul_f32 v[36:37], v[74:75], v[26:27]
	global_store_dwordx4 v[42:43], v[46:49], off offset:256
	s_cbranch_vccnz .LBB0_520
	v_mul_f32_e32 v26, 0xbfb8aa3b, v30
	v_exp_f32_e32 v26, v26
	v_mul_f32_e32 v27, 0xbfb8aa3b, v31
	v_exp_f32_e32 v27, v27
	v_add_f32_e32 v26, 1.0, v26
	v_rcp_f32_e32 v30, v26
	v_mul_f32_e32 v26, 0xbfb8aa3b, v28
	v_add_f32_e32 v27, 1.0, v27
	v_exp_f32_e32 v26, v26
	v_mul_f32_e32 v28, 0xbfb8aa3b, v29
	v_exp_f32_e32 v29, v28
	v_rcp_f32_e32 v31, v27
	v_mul_f32_e32 v27, 0xbfb8aa3b, v36
	v_exp_f32_e32 v27, v27
	v_add_f32_e32 v26, 1.0, v26
	v_rcp_f32_e32 v28, v26
	v_add_f32_e32 v26, 1.0, v29
	v_mul_f32_e32 v29, 0xbfb8aa3b, v37
	v_exp_f32_e32 v35, v29
	v_rcp_f32_e32 v29, v26
	v_add_f32_e32 v26, 1.0, v27
	v_mul_f32_e32 v27, 0xbfb8aa3b, v32
	v_exp_f32_e32 v27, v27
	v_mul_f32_e32 v32, 0xbfb8aa3b, v33
	v_exp_f32_e32 v33, v32
	v_rcp_f32_e32 v36, v26
	v_add_f32_e32 v26, 1.0, v35
	v_rcp_f32_e32 v37, v26
	v_add_f32_e32 v26, 1.0, v27
	v_rcp_f32_e32 v32, v26
	v_add_f32_e32 v26, 1.0, v33
	v_rcp_f32_e32 v33, v26
; __device__ __forceinline__ unsigned cvt_pk_bf16(float lo, float hi) { unsigned r; asm volatile("s_nop 0\n\tv_cvt_pk_bf16_f32 %0, %1, %2" : "=v"(r) : "v"(lo), "v"(hi)); return r; }
; __device__ __forceinline__ float sigmoidf_(float x) { return __builtin_amdgcn_rcpf(1.0f + __builtin_amdgcn_exp2f(-1.4426950408889634f * x)); }
; #define PG8_BAR __builtin_amdgcn_s_barrier()
; template <class Epi, class Sched, bool ALIGN_EPI = false, bool SP2 = false, bool I8 = false>
; __device__ __forceinline__ void gemm_phase(PG8_LAS unsigned char* lds, const Gemm g, const Sched& S, const Epi& E) {
;     ...
;         if (!has_next) break;
; #pragma unroll
;         for (int a = 0; a < 2; ++a)
; #pragma unroll
;             for (int b = 0; b < 2; ++b)
; #pragma unroll
;                 for (int m = 0; m < 4; ++m)
; #pragma unroll
;                     for (int n = 0; n < 2; ++n) acc[a][b][m][n] = (typename AccT<I8>::type){0, 0, 0, 0};
;         cur = nxt; cA = nA; cB = nB; ++ui; nt = PG8_NT(cur);
;         if constexpr (ALIGN_EPI) { if (wr == 1) PG8_BAR; }
; __device__ __forceinline__ u32x4 pack8(const f32x4 v0, const f32x4 v1) { u32x4 w; w.x = cvt_pk_bf16(v0[0], v0[1]); w.y = cvt_pk_bf16(v0[2], v0[3]); w.z = cvt_pk_bf16(v1[0], v1[1]); w.w = cvt_pk_bf16(v1[2], v1[3]); return w; }
; __device__ __forceinline__ void unpack8(const u32x4 w, f32x4& v0, f32x4& v1) { v0 = (f32x4){bf_lo(w.x), bf_hi(w.x), bf_lo(w.y), bf_hi(w.y)}; v1 = (f32x4){bf_lo(w.z), bf_hi(w.z), bf_lo(w.w), bf_hi(w.w)}; }
; __device__ __forceinline__ f32x4 sig4(const f32x4 v) { return (f32x4){sigmoidf_(v[0]), sigmoidf_(v[1]), sigmoidf_(v[2]), sigmoidf_(v[3])}; }
;     __device__ __forceinline__ void operator()(const i32x4 (&acc)[2][2][4][2], const Unit& uu, int wr, int wc, int fr, int fq) const {
;     ...
; #pragma unroll
;         for (int ai = 0; ai < 2; ++ai)
; #pragma unroll
;             for (int m = 0; m < 4; ++m) { const int r = row0 + ai * HALF + m * 16; const float rs = rsv[ai][m]; bf16_t* rowp = base + (size_t)r * ldc + col0;
; #pragma unroll
;                 for (int bj = 0; bj < 2; ++bj) { f32x4 v0 = __builtin_convertvector(acc[ai][bj][m][0], f32x4) * rs * sv[bj][0], v1 = __builtin_convertvector(acc[ai][bj][m][1], f32x4) * rs * sv[bj][1];
;                     if (sg) { v0 = sig4(v0); v1 = sig4(v1); }
;                     *(u32x4*)(rowp + bj * HALF) = pack8(v0, v1); } }
.LBB0_520:
	v_add_u32_e32 v26, 0xa0, v162
	v_cvt_f32_i32_e32 v23, v23
	v_cvt_f32_i32_e32 v25, v25
	v_cvt_f32_i32_e32 v24, v24
	v_cvt_f32_i32_e32 v22, v22
	v_cvt_f32_i32_e32 v19, v19
	v_cvt_f32_i32_e32 v21, v21
	v_cvt_f32_i32_e32 v20, v20
	v_cvt_f32_i32_e32 v18, v18
	v_ashrrev_i32_e32 v27, 31, v26
	v_mul_lo_u32 v38, s2, v27
	v_mul_lo_u32 v39, s3, v26
	v_mad_u64_u32 v[26:27], s[34:35], s2, v26, 0
	v_mov_b32_e32 v35, v34
	v_add3_u32 v27, v27, v38, v39
	v_cvt_pk_bf16_f32 v38, v30, v31
	v_cvt_pk_bf16_f32 v39, v28, v29
	v_mov_b32_e32 v28, v34
	v_mov_b32_e32 v29, v34
	v_pk_mul_f32 v[24:25], v[28:29], v[24:25]
	v_pk_mul_f32 v[30:31], v[34:35], v[22:23]
	v_pk_mul_f32 v[20:21], v[28:29], v[20:21]
	v_pk_mul_f32 v[18:19], v[34:35], v[18:19]
	v_lshl_add_u64 v[26:27], v[26:27], 1, v[138:139]
	v_pk_mul_f32 v[22:23], v[64:65], v[24:25]
	v_pk_mul_f32 v[24:25], v[62:63], v[30:31]
	v_pk_mul_f32 v[20:21], v[60:61], v[20:21]
	s_and_b64 vcc, exec, s[6:7]
	v_pk_mul_f32 v[28:29], v[58:59], v[18:19]
	v_cvt_pk_bf16_f32 v40, v36, v37
	v_cvt_pk_bf16_f32 v41, v32, v33
	global_store_dwordx4 v[26:27], v[38:41], off
	s_cbranch_vccnz .LBB0_522
	v_mul_f32_e32 v18, 0xbfb8aa3b, v24
	v_exp_f32_e32 v18, v18
	v_mul_f32_e32 v19, 0xbfb8aa3b, v25
	v_exp_f32_e32 v19, v19
	v_add_f32_e32 v18, 1.0, v18
	v_rcp_f32_e32 v24, v18
	v_mul_f32_e32 v18, 0xbfb8aa3b, v22
	v_add_f32_e32 v19, 1.0, v19
	v_exp_f32_e32 v18, v18
	v_mul_f32_e32 v22, 0xbfb8aa3b, v23
	v_exp_f32_e32 v23, v22
	v_rcp_f32_e32 v25, v19
	v_mul_f32_e32 v19, 0xbfb8aa3b, v28
	v_exp_f32_e32 v19, v19
	v_add_f32_e32 v18, 1.0, v18
	v_rcp_f32_e32 v22, v18
	v_add_f32_e32 v18, 1.0, v23
	v_mul_f32_e32 v23, 0xbfb8aa3b, v29
	v_exp_f32_e32 v29, v23
	v_rcp_f32_e32 v23, v18
	v_add_f32_e32 v18, 1.0, v19
	v_mul_f32_e32 v19, 0xbfb8aa3b, v20
	v_exp_f32_e32 v19, v19
	v_mul_f32_e32 v20, 0xbfb8aa3b, v21
	v_exp_f32_e32 v21, v20
	v_rcp_f32_e32 v28, v18
	v_add_f32_e32 v18, 1.0, v29
	v_rcp_f32_e32 v29, v18
	v_add_f32_e32 v18, 1.0, v19
	v_rcp_f32_e32 v20, v18
	v_add_f32_e32 v18, 1.0, v21
	v_rcp_f32_e32 v21, v18
.LBB0_522:
	v_cvt_f32_i32_e32 v17, v17
	v_cvt_f32_i32_e32 v16, v16
	v_cvt_pk_bf16_f32 v30, v24, v25
	v_cvt_pk_bf16_f32 v31, v22, v23
	v_cvt_pk_bf16_f32 v32, v28, v29
	v_cvt_f32_i32_e32 v15, v15
	v_cvt_f32_i32_e32 v14, v14
	v_cvt_pk_bf16_f32 v33, v20, v21
	v_cvt_f32_i32_e32 v21, v13
	v_cvt_f32_i32_e32 v11, v11
	v_cvt_f32_i32_e32 v10, v10
	v_cvt_f32_i32_e32 v20, v12
	v_mul_f32_e32 v18, v190, v191
	v_pk_mul_f32 v[16:17], v[18:19], v[16:17] op_sel_hi:[0,1]
	v_pk_mul_f32 v[14:15], v[18:19], v[14:15] op_sel_hi:[0,1]
	v_pk_mul_f32 v[12:13], v[80:81], v[16:17]
	v_pk_mul_f32 v[10:11], v[18:19], v[10:11] op_sel_hi:[0,1]
	v_pk_mul_f32 v[16:17], v[18:19], v[20:21] op_sel_hi:[0,1]
	v_pk_mul_f32 v[14:15], v[78:79], v[14:15]
	v_pk_mul_f32 v[16:17], v[76:77], v[16:17]
	s_and_b64 vcc, exec, s[6:7]
	v_pk_mul_f32 v[20:21], v[74:75], v[10:11]
	global_store_dwordx4 v[26:27], v[30:33], off offset:256
	s_cbranch_vccnz .LBB0_524
	v_mul_f32_e32 v10, 0xbfb8aa3b, v14
	v_exp_f32_e32 v10, v10
	v_mul_f32_e32 v11, 0xbfb8aa3b, v15
	v_exp_f32_e32 v11, v11
	v_add_f32_e32 v10, 1.0, v10
	v_rcp_f32_e32 v14, v10
	v_mul_f32_e32 v10, 0xbfb8aa3b, v12
	v_add_f32_e32 v11, 1.0, v11
	v_exp_f32_e32 v10, v10
	v_mul_f32_e32 v12, 0xbfb8aa3b, v13
	v_exp_f32_e32 v13, v12
	v_rcp_f32_e32 v15, v11
	v_mul_f32_e32 v11, 0xbfb8aa3b, v20
	v_exp_f32_e32 v11, v11
	v_add_f32_e32 v10, 1.0, v10
	v_rcp_f32_e32 v12, v10
	v_add_f32_e32 v10, 1.0, v13
	v_mul_f32_e32 v13, 0xbfb8aa3b, v21
	v_exp_f32_e32 v19, v13
	v_rcp_f32_e32 v13, v10
	v_add_f32_e32 v10, 1.0, v11
	v_mul_f32_e32 v11, 0xbfb8aa3b, v16
	v_exp_f32_e32 v11, v11
	v_mul_f32_e32 v16, 0xbfb8aa3b, v17
	v_exp_f32_e32 v17, v16
	v_rcp_f32_e32 v20, v10
	v_add_f32_e32 v10, 1.0, v19
	v_rcp_f32_e32 v21, v10
	v_add_f32_e32 v10, 1.0, v11
	v_rcp_f32_e32 v16, v10
	v_add_f32_e32 v10, 1.0, v17
	v_rcp_f32_e32 v17, v10
.LBB0_524:
	v_add_u32_e32 v10, 0xb0, v162
	v_ashrrev_i32_e32 v11, 31, v10
	v_mul_lo_u32 v22, s2, v11
	v_mul_lo_u32 v23, s3, v10
	v_mad_u64_u32 v[10:11], s[2:3], s2, v10, 0
	v_cvt_f32_i32_e32 v7, v7
	v_cvt_f32_i32_e32 v9, v9
	v_cvt_f32_i32_e32 v8, v8
	v_cvt_f32_i32_e32 v6, v6
	v_add3_u32 v11, v11, v22, v23
	v_cvt_pk_bf16_f32 v22, v14, v15
	v_cvt_pk_bf16_f32 v23, v12, v13
	v_cvt_pk_bf16_f32 v24, v20, v21
	v_cvt_pk_bf16_f32 v25, v16, v17
	v_cvt_f32_i32_e32 v15, v3
	v_cvt_f32_i32_e32 v17, v5
	v_cvt_f32_i32_e32 v16, v4
	v_cvt_f32_i32_e32 v14, v2
	v_mov_b32_e32 v19, v18
	v_mov_b32_e32 v12, v18
	v_mov_b32_e32 v13, v18
	v_pk_mul_f32 v[8:9], v[12:13], v[8:9]
	v_pk_mul_f32 v[6:7], v[18:19], v[6:7]
	v_pk_mul_f32 v[2:3], v[64:65], v[8:9]
	v_pk_mul_f32 v[4:5], v[62:63], v[6:7]
	v_pk_mul_f32 v[6:7], v[12:13], v[16:17]
	v_pk_mul_f32 v[8:9], v[18:19], v[14:15]
	v_lshl_add_u64 v[10:11], v[10:11], 1, v[138:139]
	v_pk_mul_f32 v[6:7], v[60:61], v[6:7]
	s_and_b64 vcc, exec, s[6:7]
	v_pk_mul_f32 v[8:9], v[58:59], v[8:9]
	global_store_dwordx4 v[10:11], v[22:25], off
	s_cbranch_vccnz .LBB0_526
	v_mul_f32_e32 v4, 0xbfb8aa3b, v4
	v_mul_f32_e32 v5, 0xbfb8aa3b, v5
	v_mul_f32_e32 v2, 0xbfb8aa3b, v2
	v_mul_f32_e32 v3, 0xbfb8aa3b, v3
	v_mul_f32_e32 v8, 0xbfb8aa3b, v8
	v_mul_f32_e32 v9, 0xbfb8aa3b, v9
	v_mul_f32_e32 v6, 0xbfb8aa3b, v6
	v_mul_f32_e32 v7, 0xbfb8aa3b, v7
	v_exp_f32_e32 v4, v4
	v_exp_f32_e32 v5, v5
	v_exp_f32_e32 v2, v2
	v_exp_f32_e32 v3, v3
	v_exp_f32_e32 v8, v8
	v_exp_f32_e32 v9, v9
	v_exp_f32_e32 v6, v6
	v_exp_f32_e32 v7, v7
	v_add_f32_e32 v4, 1.0, v4
	v_add_f32_e32 v5, 1.0, v5
	v_add_f32_e32 v2, 1.0, v2
	v_add_f32_e32 v3, 1.0, v3
	v_add_f32_e32 v8, 1.0, v8
	v_add_f32_e32 v9, 1.0, v9
	v_add_f32_e32 v6, 1.0, v6
	v_add_f32_e32 v7, 1.0, v7
	v_rcp_f32_e32 v4, v4
	v_rcp_f32_e32 v5, v5
	v_rcp_f32_e32 v2, v2
	v_rcp_f32_e32 v3, v3
	v_rcp_f32_e32 v8, v8
	v_rcp_f32_e32 v9, v9
	v_rcp_f32_e32 v6, v6
	v_rcp_f32_e32 v7, v7
.LBB0_526:
	s_andn2_b64 vcc, exec, s[4:5]
	s_mov_b64 s[2:3], -1
	v_cvt_pk_bf16_f32 v12, v4, v5
	v_cvt_pk_bf16_f32 v13, v2, v3
	v_cvt_pk_bf16_f32 v14, v8, v9
	v_cvt_pk_bf16_f32 v15, v6, v7
	global_store_dwordx4 v[10:11], v[12:15], off offset:256
	s_cbranch_vccnz .LBB0_479
	s_andn2_b64 vcc, exec, s[16:17]
	s_cbranch_vccnz .LBB0_478
	s_barrier
	s_branch .LBB0_478

; #define PG8_STAGE(bufoff, gbase, voff) do { _Pragma("unroll") for (int _i = 0; _i < 2; ++_i) \
;         __builtin_amdgcn_global_load_lds((const unsigned*)((const char*)(gbase) + (voff)[_i]), (PG8_LAS unsigned*)(lds + (bufoff) + ldsw + _i * 8192), 16, 0, 0); } while (0)
; #define PG8_LDA(dst, b, h) do { _Pragma("unroll") for (int m = 0; m < 4; ++m) _Pragma("unroll") for (int k = 0; k < 2; ++k) dst[m][k] = *(const PG8_LAS bf16x8*)(lds + PG8_SA(b, h) + aoff + m * 2048 + k * 1024); } while (0)
; #define PG8_LDB(dst, b, h) do { _Pragma("unroll") for (int n = 0; n < 2; ++n) _Pragma("unroll") for (int k = 0; k < 2; ++k) dst[n][k] = *(const PG8_LAS bf16x8*)(lds + PG8_SB(b, h) + boff + n * 2048 + k * 1024); } while (0)
; #define PG8_MMA(ai, bj, At, Bt) do { __builtin_amdgcn_s_setprio(1); _Pragma("unroll") for (int m = 0; m < 4; ++m) _Pragma("unroll") for (int n = 0; n < 2; ++n) _Pragma("unroll") for (int k = 0; k < 2; ++k) \
;         acc[ai][bj][m][n] = mma_<I8>(Bt[n][k], At[m][k], acc[ai][bj][m][n]); __builtin_amdgcn_s_setprio(0); } while (0)
; #define PG8_WAIT_V(n) asm volatile("s_waitcnt vmcnt(" #n ")" ::: "memory")
; #define PG8_WAIT_L(n) asm volatile("s_waitcnt lgkmcnt(" #n ")" ::: "memory")
; #define PG8_BAR __builtin_amdgcn_s_barrier()
; #define PG8_SCHED __builtin_amdgcn_sched_barrier(0)
; template <class Epi, class Sched, bool ALIGN_EPI = false, bool SP2 = false, bool I8 = false>
; __device__ __forceinline__ void gemm_phase(PG8_LAS unsigned char* lds, const Gemm g, const Sched& S, const Epi& E) {
;     ...
;             PG8_LDB(B0, 0, 0); PG8_LDB(B1, 0, 1); PG8_SCHED; PG8_LDA(At, 0, 0); PG8_STAGE(PG8_SA(1, 1), a1 + hstepA, voffA);
;             PG8_WAIT_V(8); PG8_WAIT_L(0); PG8_BAR; PG8_MMA(0, 0, At, B0); PG8_MMA(0, 1, At, B1); PG8_BAR; PG8_SCHED;
;             PG8_LDA(At, 0, 1); PG8_STAGE(PG8_SB(0, 0), b2, voffB); PG8_STAGE(PG8_SB(0, 1), b2 + hstepB, voffB); PG8_STAGE(PG8_SA(0, 0), a2, voffA);
;             PG8_WAIT_V(8); PG8_WAIT_L(0); PG8_BAR; PG8_MMA(1, 0, At, B0); PG8_MMA(1, 1, At, B1); PG8_BAR; PG8_SCHED;
.LBB0_541:
	ds_read_b128 v[154:157], v149
	ds_read_b128 v[158:161], v149 offset:1024
	ds_read_b128 v[162:165], v149 offset:2048
	ds_read_b128 v[166:169], v149 offset:3072
	ds_read_b128 v[170:173], v151
	ds_read_b128 v[174:177], v151 offset:1024
	ds_read_b128 v[178:181], v151 offset:2048
	ds_read_b128 v[188:191], v151 offset:3072
	s_add_u32 s34, s30, 0xfff00080
	s_addc_u32 s35, s31, -1
	s_cmp_eq_u32 s94, 60
	s_cselect_b32 s37, s7, s35
	s_cselect_b32 s36, s25, s34
	s_cselect_b32 s35, s23, s93
	s_cselect_b32 s34, s29, s92
	s_add_i32 m0, s39, 0xc000
	ds_read_b128 v[192:195], v153
	ds_read_b128 v[196:199], v153 offset:1024
	ds_read_b128 v[200:203], v153 offset:2048
	ds_read_b128 v[204:207], v153 offset:3072
	ds_read_b128 v[208:211], v153 offset:4096
	ds_read_b128 v[212:215], v153 offset:5120
	ds_read_b128 v[216:219], v153 offset:6144
	ds_read_b128 v[220:223], v153 offset:7168
	global_load_lds_dwordx4 v138, s[30:31]
	s_add_i32 m0, s39, 0xe000
	s_nop 0
	global_load_lds_dwordx4 v140, s[30:31]
	s_waitcnt vmcnt(8) lgkmcnt(0)
	s_barrier
	v_mfma_f32_16x16x32_bf16 v[126:129], v[154:157], v[192:195], v[126:129]
	v_mfma_f32_16x16x32_bf16 v[122:125], v[162:165], v[192:195], v[122:125]
	v_mfma_f32_16x16x32_bf16 v[110:113], v[154:157], v[200:203], v[110:113]
	v_mfma_f32_16x16x32_bf16 v[106:109], v[162:165], v[200:203], v[106:109]
	v_mfma_f32_16x16x32_bf16 v[94:97], v[154:157], v[208:211], v[94:97]
	v_mfma_f32_16x16x32_bf16 v[90:93], v[162:165], v[208:211], v[90:93]
	v_mfma_f32_16x16x32_bf16 v[78:81], v[154:157], v[216:219], v[78:81]
	v_mfma_f32_16x16x32_bf16 v[74:77], v[162:165], v[216:219], v[74:77]
	v_mfma_f32_16x16x32_bf16 v[126:129], v[158:161], v[196:199], v[126:129]
	v_mfma_f32_16x16x32_bf16 v[122:125], v[166:169], v[196:199], v[122:125]
	v_mfma_f32_16x16x32_bf16 v[110:113], v[158:161], v[204:207], v[110:113]
	v_mfma_f32_16x16x32_bf16 v[106:109], v[166:169], v[204:207], v[106:109]
	v_mfma_f32_16x16x32_bf16 v[94:97], v[158:161], v[212:215], v[94:97]
	v_mfma_f32_16x16x32_bf16 v[90:93], v[166:169], v[212:215], v[90:93]
	v_mfma_f32_16x16x32_bf16 v[78:81], v[158:161], v[220:223], v[78:81]
	v_mfma_f32_16x16x32_bf16 v[74:77], v[166:169], v[220:223], v[74:77]
	v_mfma_f32_16x16x32_bf16 v[118:121], v[170:173], v[192:195], v[118:121]
	v_mfma_f32_16x16x32_bf16 v[114:117], v[178:181], v[192:195], v[114:117]
	v_mfma_f32_16x16x32_bf16 v[102:105], v[170:173], v[200:203], v[102:105]
	v_mfma_f32_16x16x32_bf16 v[98:101], v[178:181], v[200:203], v[98:101]
	v_mfma_f32_16x16x32_bf16 v[86:89], v[170:173], v[208:211], v[86:89]
	v_mfma_f32_16x16x32_bf16 v[82:85], v[178:181], v[208:211], v[82:85]
	v_mfma_f32_16x16x32_bf16 v[70:73], v[170:173], v[216:219], v[70:73]
	v_mfma_f32_16x16x32_bf16 v[66:69], v[178:181], v[216:219], v[66:69]
	v_mfma_f32_16x16x32_bf16 v[118:121], v[174:177], v[196:199], v[118:121]
	v_mfma_f32_16x16x32_bf16 v[114:117], v[188:191], v[196:199], v[114:117]
	v_mfma_f32_16x16x32_bf16 v[102:105], v[174:177], v[204:207], v[102:105]
	v_mfma_f32_16x16x32_bf16 v[98:101], v[188:191], v[204:207], v[98:101]
	v_mfma_f32_16x16x32_bf16 v[86:89], v[174:177], v[212:215], v[86:89]
	v_mfma_f32_16x16x32_bf16 v[82:85], v[188:191], v[212:215], v[82:85]
	v_mfma_f32_16x16x32_bf16 v[70:73], v[174:177], v[220:223], v[70:73]
	v_mfma_f32_16x16x32_bf16 v[66:69], v[188:191], v[220:223], v[66:69]
	s_barrier
	s_add_i32 s95, s88, s38
	s_mov_b64 s[98:99], s[34:35]
	s_mov_b32 m0, s95
	ds_read_b128 v[192:195], v153 offset:16384
	ds_read_b128 v[196:199], v153 offset:17408
	ds_read_b128 v[200:203], v153 offset:18432
	ds_read_b128 v[204:207], v153 offset:19456
	ds_read_b128 v[208:211], v153 offset:20480
	ds_read_b128 v[212:215], v153 offset:21504
	ds_read_b128 v[216:219], v153 offset:22528
	ds_read_b128 v[220:223], v153 offset:23552
	global_load_lds_dwordx4 v132, s[34:35]
	s_add_i32 m0, s95, 0x2000
	s_add_u32 vcc_lo, s34, 0x100000
	s_mov_b64 s[98:99], s[34:35]
	s_addc_u32 vcc_hi, s35, 0
	s_add_i32 s95, s89, s38
	global_load_lds_dwordx4 v136, s[34:35]
	s_mov_b32 m0, s95
	s_mov_b64 s[100:101], s[36:37]
	global_load_lds_dwordx4 v132, vcc
	s_add_i32 m0, s95, 0x2000
	s_nop 0
	global_load_lds_dwordx4 v136, vcc
	s_mov_b64 s[100:101], s[36:37]
	s_mov_b32 m0, s39
	s_nop 0
	global_load_lds_dwordx4 v130, s[36:37]
	s_mov_b32 m0, s40
	s_nop 0
	global_load_lds_dwordx4 v134, s[36:37]
	s_waitcnt vmcnt(8) lgkmcnt(0)
	s_barrier
	v_mfma_f32_16x16x32_bf16 v[62:65], v[154:157], v[192:195], v[62:65]
	v_mfma_f32_16x16x32_bf16 v[58:61], v[162:165], v[192:195], v[58:61]
	v_mfma_f32_16x16x32_bf16 v[46:49], v[154:157], v[200:203], v[46:49]
	v_mfma_f32_16x16x32_bf16 v[42:45], v[162:165], v[200:203], v[42:45]
	v_mfma_f32_16x16x32_bf16 v[30:33], v[154:157], v[208:211], v[30:33]
	v_mfma_f32_16x16x32_bf16 v[26:29], v[162:165], v[208:211], v[26:29]
	v_mfma_f32_16x16x32_bf16 v[14:17], v[154:157], v[216:219], v[14:17]
	v_mfma_f32_16x16x32_bf16 v[10:13], v[162:165], v[216:219], v[10:13]
	v_mfma_f32_16x16x32_bf16 v[62:65], v[158:161], v[196:199], v[62:65]
	v_mfma_f32_16x16x32_bf16 v[58:61], v[166:169], v[196:199], v[58:61]
	v_mfma_f32_16x16x32_bf16 v[46:49], v[158:161], v[204:207], v[46:49]
	v_mfma_f32_16x16x32_bf16 v[42:45], v[166:169], v[204:207], v[42:45]
	v_mfma_f32_16x16x32_bf16 v[30:33], v[158:161], v[212:215], v[30:33]
	v_mfma_f32_16x16x32_bf16 v[26:29], v[166:169], v[212:215], v[26:29]
	v_mfma_f32_16x16x32_bf16 v[14:17], v[158:161], v[220:223], v[14:17]
	v_mfma_f32_16x16x32_bf16 v[10:13], v[166:169], v[220:223], v[10:13]
	v_mfma_f32_16x16x32_bf16 v[54:57], v[170:173], v[192:195], v[54:57]
	v_mfma_f32_16x16x32_bf16 v[50:53], v[178:181], v[192:195], v[50:53]
	v_mfma_f32_16x16x32_bf16 v[38:41], v[170:173], v[200:203], v[38:41]
	v_mfma_f32_16x16x32_bf16 v[34:37], v[178:181], v[200:203], v[34:37]
	v_mfma_f32_16x16x32_bf16 v[22:25], v[170:173], v[208:211], v[22:25]
	v_mfma_f32_16x16x32_bf16 v[18:21], v[178:181], v[208:211], v[18:21]
	v_mfma_f32_16x16x32_bf16 v[6:9], v[170:173], v[216:219], v[6:9]
	v_mfma_f32_16x16x32_bf16 v[2:5], v[178:181], v[216:219], v[2:5]
	v_mfma_f32_16x16x32_bf16 v[54:57], v[174:177], v[196:199], v[54:57]
	v_mfma_f32_16x16x32_bf16 v[50:53], v[188:191], v[196:199], v[50:53]
	v_mfma_f32_16x16x32_bf16 v[38:41], v[174:177], v[204:207], v[38:41]
	v_mfma_f32_16x16x32_bf16 v[34:37], v[188:191], v[204:207], v[34:37]
	v_mfma_f32_16x16x32_bf16 v[22:25], v[174:177], v[212:215], v[22:25]
	v_mfma_f32_16x16x32_bf16 v[18:21], v[188:191], v[212:215], v[18:21]
	v_mfma_f32_16x16x32_bf16 v[6:9], v[174:177], v[220:223], v[6:9]
	v_mfma_f32_16x16x32_bf16 v[2:5], v[188:191], v[220:223], v[2:5]
	s_barrier
; #define PG8_STAGE(bufoff, gbase, voff) do { _Pragma("unroll") for (int _i = 0; _i < 2; ++_i) \
;         __builtin_amdgcn_global_load_lds((const unsigned*)((const char*)(gbase) + (voff)[_i]), (PG8_LAS unsigned*)(lds + (bufoff) + ldsw + _i * 8192), 16, 0, 0); } while (0)
; #define PG8_LDA(dst, b, h) do { _Pragma("unroll") for (int m = 0; m < 4; ++m) _Pragma("unroll") for (int k = 0; k < 2; ++k) dst[m][k] = *(const PG8_LAS bf16x8*)(lds + PG8_SA(b, h) + aoff + m * 2048 + k * 1024); } while (0)
; #define PG8_LDB(dst, b, h) do { _Pragma("unroll") for (int n = 0; n < 2; ++n) _Pragma("unroll") for (int k = 0; k < 2; ++k) dst[n][k] = *(const PG8_LAS bf16x8*)(lds + PG8_SB(b, h) + boff + n * 2048 + k * 1024); } while (0)
; #define PG8_MMA(ai, bj, At, Bt) do { __builtin_amdgcn_s_setprio(1); _Pragma("unroll") for (int m = 0; m < 4; ++m) _Pragma("unroll") for (int n = 0; n < 2; ++n) _Pragma("unroll") for (int k = 0; k < 2; ++k) \
;         acc[ai][bj][m][n] = mma_<I8>(Bt[n][k], At[m][k], acc[ai][bj][m][n]); __builtin_amdgcn_s_setprio(0); } while (0)
; #define PG8_WAIT_V(n) asm volatile("s_waitcnt vmcnt(" #n ")" ::: "memory")
; #define PG8_WAIT_L(n) asm volatile("s_waitcnt lgkmcnt(" #n ")" ::: "memory")
; #define PG8_BAR __builtin_amdgcn_s_barrier()
; #define PG8_SCHED __builtin_amdgcn_sched_barrier(0)
; template <class Epi, class Sched, bool ALIGN_EPI = false, bool SP2 = false, bool I8 = false>
; __device__ __forceinline__ void gemm_phase(PG8_LAS unsigned char* lds, const Gemm g, const Sched& S, const Epi& E) {
;     ...
;         for (int t = 0; t < nt; t += 2) {
;             const bool last = (t == nt - 2);
;             const char* a1 = cA + (size_t)(t + 1) * kstep;
;             const char* a2 = last ? nA : cA + (size_t)(t + 2) * kstep; const char* b2 = last ? nB : cB + (size_t)(t + 2) * kstep;
;             const char* a3 = a2 + kstep; const char* b3 = b2 + kstep;
;     ...
;             PG8_LDB(B0, 1, 0); PG8_LDB(B1, 1, 1); PG8_SCHED; PG8_LDA(At, 1, 0); PG8_STAGE(PG8_SA(0, 1), a2 + hstepA, voffA);
;             PG8_WAIT_V(8); PG8_WAIT_L(0); PG8_BAR; PG8_MMA(0, 0, At, B0); PG8_MMA(0, 1, At, B1); PG8_BAR; PG8_SCHED;
;             PG8_LDA(At, 1, 1); PG8_STAGE(PG8_SB(1, 0), b3, voffB); PG8_STAGE(PG8_SB(1, 1), b3 + hstepB, voffB); PG8_STAGE(PG8_SA(1, 0), a3, voffA);
;             PG8_WAIT_V(8); PG8_WAIT_L(0); PG8_BAR; PG8_MMA(1, 0, At, B0); PG8_MMA(1, 1, At, B1); PG8_BAR; PG8_SCHED;
	s_add_i32 s95, 0, 0x18000
	s_add_i32 vcc_lo, 0, 0x1c000
	ds_read_b128 v[154:157], v151 offset:16384
	ds_read_b128 v[158:161], v151 offset:17408
	ds_read_b128 v[162:165], v151 offset:18432
	ds_read_b128 v[166:169], v151 offset:19456
	ds_read_b128 v[170:173], v151 offset:32768
	ds_read_b128 v[174:177], v151 offset:33792
	ds_read_b128 v[178:181], v151 offset:34816
	ds_read_b128 v[188:191], v151 offset:35840
	s_add_u32 s36, s36, 0x100000
	s_addc_u32 s37, s37, 0
	s_mov_b32 m0, s41
	ds_read_b128 v[192:195], v153 offset:32768
	ds_read_b128 v[196:199], v153 offset:33792
	ds_read_b128 v[200:203], v153 offset:34816
	ds_read_b128 v[204:207], v153 offset:35840
	ds_read_b128 v[208:211], v153 offset:36864
	ds_read_b128 v[212:215], v153 offset:37888
	ds_read_b128 v[216:219], v153 offset:38912
	ds_read_b128 v[220:223], v153 offset:39936
	global_load_lds_dwordx4 v130, s[36:37]
	s_mov_b32 m0, s46
	s_nop 0
	global_load_lds_dwordx4 v134, s[36:37]
	s_waitcnt vmcnt(8) lgkmcnt(0)
	s_barrier
	v_mfma_f32_16x16x32_bf16 v[126:129], v[154:157], v[192:195], v[126:129]
	v_mfma_f32_16x16x32_bf16 v[122:125], v[162:165], v[192:195], v[122:125]
	v_mfma_f32_16x16x32_bf16 v[110:113], v[154:157], v[200:203], v[110:113]
	v_mfma_f32_16x16x32_bf16 v[106:109], v[162:165], v[200:203], v[106:109]
	v_mfma_f32_16x16x32_bf16 v[94:97], v[154:157], v[208:211], v[94:97]
	v_mfma_f32_16x16x32_bf16 v[90:93], v[162:165], v[208:211], v[90:93]
	v_mfma_f32_16x16x32_bf16 v[78:81], v[154:157], v[216:219], v[78:81]
	v_mfma_f32_16x16x32_bf16 v[74:77], v[162:165], v[216:219], v[74:77]
	v_mfma_f32_16x16x32_bf16 v[126:129], v[158:161], v[196:199], v[126:129]
	v_mfma_f32_16x16x32_bf16 v[122:125], v[166:169], v[196:199], v[122:125]
	v_mfma_f32_16x16x32_bf16 v[110:113], v[158:161], v[204:207], v[110:113]
	v_mfma_f32_16x16x32_bf16 v[106:109], v[166:169], v[204:207], v[106:109]
	v_mfma_f32_16x16x32_bf16 v[94:97], v[158:161], v[212:215], v[94:97]
	v_mfma_f32_16x16x32_bf16 v[90:93], v[166:169], v[212:215], v[90:93]
	v_mfma_f32_16x16x32_bf16 v[78:81], v[158:161], v[220:223], v[78:81]
	v_mfma_f32_16x16x32_bf16 v[74:77], v[166:169], v[220:223], v[74:77]
	v_mfma_f32_16x16x32_bf16 v[118:121], v[170:173], v[192:195], v[118:121]
	v_mfma_f32_16x16x32_bf16 v[114:117], v[178:181], v[192:195], v[114:117]
	v_mfma_f32_16x16x32_bf16 v[102:105], v[170:173], v[200:203], v[102:105]
	v_mfma_f32_16x16x32_bf16 v[98:101], v[178:181], v[200:203], v[98:101]
	v_mfma_f32_16x16x32_bf16 v[86:89], v[170:173], v[208:211], v[86:89]
	v_mfma_f32_16x16x32_bf16 v[82:85], v[178:181], v[208:211], v[82:85]
	v_mfma_f32_16x16x32_bf16 v[70:73], v[170:173], v[216:219], v[70:73]
	v_mfma_f32_16x16x32_bf16 v[66:69], v[178:181], v[216:219], v[66:69]
	v_mfma_f32_16x16x32_bf16 v[118:121], v[174:177], v[196:199], v[118:121]
	v_mfma_f32_16x16x32_bf16 v[114:117], v[188:191], v[196:199], v[114:117]
	v_mfma_f32_16x16x32_bf16 v[102:105], v[174:177], v[204:207], v[102:105]
	v_mfma_f32_16x16x32_bf16 v[98:101], v[188:191], v[204:207], v[98:101]
	v_mfma_f32_16x16x32_bf16 v[86:89], v[174:177], v[212:215], v[86:89]
	v_mfma_f32_16x16x32_bf16 v[82:85], v[188:191], v[212:215], v[82:85]
	v_mfma_f32_16x16x32_bf16 v[70:73], v[174:177], v[220:223], v[70:73]
	v_mfma_f32_16x16x32_bf16 v[66:69], v[188:191], v[220:223], v[66:69]
	s_barrier
	s_add_i32 s36, s95, s38
	s_add_i32 m0, s36, 0xffffff80
	ds_read_b128 v[192:195], v153 offset:49152
	ds_read_b128 v[196:199], v153 offset:50176
	ds_read_b128 v[200:203], v153 offset:51200
	ds_read_b128 v[204:207], v153 offset:52224
	ds_read_b128 v[208:211], v153 offset:53248
	ds_read_b128 v[212:215], v153 offset:54272
	ds_read_b128 v[216:219], v153 offset:55296
	ds_read_b128 v[220:223], v153 offset:56320
	global_load_lds_dwordx4 v132, s[98:99] offset:128
	s_add_i32 m0, s36, 0x1f80
	s_add_u32 s34, s34, 0x100080
	s_addc_u32 s35, s35, 0
	s_add_i32 s36, vcc_lo, s38
	global_load_lds_dwordx4 v136, s[98:99] offset:128
	s_mov_b32 m0, s36
	s_nop 0
	global_load_lds_dwordx4 v132, s[34:35]
	s_add_i32 m0, s36, 0x2000
	s_nop 0
	global_load_lds_dwordx4 v136, s[34:35]
	s_add_i32 m0, s68, 0xffffff80
	s_nop 0
	global_load_lds_dwordx4 v130, s[100:101] offset:128
	s_add_i32 m0, s69, 0xffffff80
	s_nop 0
	global_load_lds_dwordx4 v134, s[100:101] offset:128
	s_waitcnt vmcnt(8) lgkmcnt(0)
	s_barrier
	v_mfma_f32_16x16x32_bf16 v[62:65], v[154:157], v[192:195], v[62:65]
	v_mfma_f32_16x16x32_bf16 v[58:61], v[162:165], v[192:195], v[58:61]
	v_mfma_f32_16x16x32_bf16 v[46:49], v[154:157], v[200:203], v[46:49]
	v_mfma_f32_16x16x32_bf16 v[42:45], v[162:165], v[200:203], v[42:45]
	v_mfma_f32_16x16x32_bf16 v[30:33], v[154:157], v[208:211], v[30:33]
	v_mfma_f32_16x16x32_bf16 v[26:29], v[162:165], v[208:211], v[26:29]
	v_mfma_f32_16x16x32_bf16 v[14:17], v[154:157], v[216:219], v[14:17]
	v_mfma_f32_16x16x32_bf16 v[10:13], v[162:165], v[216:219], v[10:13]
	v_mfma_f32_16x16x32_bf16 v[62:65], v[158:161], v[196:199], v[62:65]
	v_mfma_f32_16x16x32_bf16 v[58:61], v[166:169], v[196:199], v[58:61]
	v_mfma_f32_16x16x32_bf16 v[46:49], v[158:161], v[204:207], v[46:49]
	v_mfma_f32_16x16x32_bf16 v[42:45], v[166:169], v[204:207], v[42:45]
	v_mfma_f32_16x16x32_bf16 v[30:33], v[158:161], v[212:215], v[30:33]
	v_mfma_f32_16x16x32_bf16 v[26:29], v[166:169], v[212:215], v[26:29]
	v_mfma_f32_16x16x32_bf16 v[14:17], v[158:161], v[220:223], v[14:17]
	v_mfma_f32_16x16x32_bf16 v[10:13], v[166:169], v[220:223], v[10:13]
	v_mfma_f32_16x16x32_bf16 v[54:57], v[170:173], v[192:195], v[54:57]
	v_mfma_f32_16x16x32_bf16 v[50:53], v[178:181], v[192:195], v[50:53]
	v_mfma_f32_16x16x32_bf16 v[38:41], v[170:173], v[200:203], v[38:41]
	v_mfma_f32_16x16x32_bf16 v[34:37], v[178:181], v[200:203], v[34:37]
	v_mfma_f32_16x16x32_bf16 v[22:25], v[170:173], v[208:211], v[22:25]
	v_mfma_f32_16x16x32_bf16 v[18:21], v[178:181], v[208:211], v[18:21]
	v_mfma_f32_16x16x32_bf16 v[6:9], v[170:173], v[216:219], v[6:9]
	v_mfma_f32_16x16x32_bf16 v[2:5], v[178:181], v[216:219], v[2:5]
	v_mfma_f32_16x16x32_bf16 v[54:57], v[174:177], v[196:199], v[54:57]
	v_mfma_f32_16x16x32_bf16 v[50:53], v[188:191], v[196:199], v[50:53]
	v_mfma_f32_16x16x32_bf16 v[38:41], v[174:177], v[204:207], v[38:41]
	v_mfma_f32_16x16x32_bf16 v[34:37], v[188:191], v[204:207], v[34:37]
	v_mfma_f32_16x16x32_bf16 v[22:25], v[174:177], v[212:215], v[22:25]
	v_mfma_f32_16x16x32_bf16 v[18:21], v[188:191], v[212:215], v[18:21]
	v_mfma_f32_16x16x32_bf16 v[6:9], v[174:177], v[220:223], v[6:9]
	v_mfma_f32_16x16x32_bf16 v[2:5], v[188:191], v[220:223], v[2:5]
	s_barrier
	s_add_i32 s94, s94, 2
	s_add_u32 s30, s30, 0x100
	s_addc_u32 s31, s31, 0
	s_add_u32 s92, s92, 0x100
	s_addc_u32 s93, s93, 0
	s_cmp_gt_u32 s94, 61
	s_cbranch_scc0 .LBB0_541
	s_and_b64 vcc, exec, s[20:21]
	s_cbranch_vccz .LBB0_544
	s_barrier

; __device__ __forceinline__ unsigned cvt_pk_bf16(float lo, float hi) { unsigned r; asm volatile("s_nop 0\n\tv_cvt_pk_bf16_f32 %0, %1, %2" : "=v"(r) : "v"(lo), "v"(hi)); return r; }
; __device__ __forceinline__ float sigmoidf_(float x) { return __builtin_amdgcn_rcpf(1.0f + __builtin_amdgcn_exp2f(-1.4426950408889634f * x)); }
; __device__ __forceinline__ u32x4 pack8(const f32x4 v0, const f32x4 v1) { u32x4 w; w.x = cvt_pk_bf16(v0[0], v0[1]); w.y = cvt_pk_bf16(v0[2], v0[3]); w.z = cvt_pk_bf16(v1[0], v1[1]); w.w = cvt_pk_bf16(v1[2], v1[3]); return w; }
; __device__ __forceinline__ void unpack8(const u32x4 w, f32x4& v0, f32x4& v1) { v0 = (f32x4){bf_lo(w.x), bf_hi(w.x), bf_lo(w.y), bf_hi(w.y)}; v1 = (f32x4){bf_lo(w.z), bf_hi(w.z), bf_lo(w.w), bf_hi(w.w)}; }
; __device__ __forceinline__ f32x4 sig4(const f32x4 v) { return (f32x4){sigmoidf_(v[0]), sigmoidf_(v[1]), sigmoidf_(v[2]), sigmoidf_(v[3])}; }
;     __device__ __forceinline__ void operator()(AccRef acc, const Unit& uu, int wr, int wc, int fr, int fq) const {
;     ...
; #pragma unroll
;         for (int ai = 0; ai < 2; ++ai)
; #pragma unroll
;             for (int m = 0; m < 4; ++m) { const int r = row0 + ai * HALF + m * 16; const float rs = rsv[ai][m]; bf16_t* rowp = base + (size_t)r * ldc + col0;
; #pragma unroll
;                 for (int bj = 0; bj < 2; ++bj) { f32x4 v0 = acc[ai][bj][m][0] * rs, v1 = acc[ai][bj][m][1] * rs;
;                     if (sg) { v0 = sig4(v0); v1 = sig4(v1); }
;                     *(u32x4*)(rowp + bj * HALF) = pack8(v0, v1); } }
.LBB0_554:
	v_lshrrev_b32_e32 v122, 1, v155
	v_and_b32_e32 v122, 0x78, v122
	v_add_u32_e32 v122, s23, v122
	v_ashrrev_i32_e32 v123, 31, v122
	v_lshl_add_u64 v[122:123], v[122:123], 1, s[30:31]
	v_mul_lo_u32 v155, s29, v156
	v_mul_lo_u32 v157, s28, v157
	v_mad_u64_u32 v[124:125], s[30:31], s28, v156, 0
	v_mov_b32_e32 v177, v176
	v_add3_u32 v125, v125, v157, v155
	v_cvt_pk_bf16_f32 v178, v178, v179
	v_cvt_pk_bf16_f32 v179, v128, v129
	v_cvt_pk_bf16_f32 v180, v180, v181
	v_cvt_pk_bf16_f32 v181, v126, v127
	v_mov_b32_e32 v126, v176
	v_mov_b32_e32 v127, v176
	v_lshl_add_u64 v[124:125], v[124:125], 1, v[122:123]
	v_pk_mul_f32 v[120:121], v[120:121], v[126:127]
	v_pk_mul_f32 v[118:119], v[118:119], v[176:177]
	v_pk_mul_f32 v[116:117], v[116:117], v[126:127]
	s_and_b64 vcc, exec, s[6:7]
	v_pk_mul_f32 v[114:115], v[114:115], v[176:177]
	global_store_dwordx4 v[124:125], v[178:181], off
	s_cbranch_vccnz .LBB0_556
	v_mul_f32_e32 v118, 0xbfb8aa3b, v118
	v_mul_f32_e32 v119, 0xbfb8aa3b, v119
	v_mul_f32_e32 v120, 0xbfb8aa3b, v120
	v_mul_f32_e32 v121, 0xbfb8aa3b, v121
	v_mul_f32_e32 v114, 0xbfb8aa3b, v114
	v_mul_f32_e32 v115, 0xbfb8aa3b, v115
	v_mul_f32_e32 v116, 0xbfb8aa3b, v116
	v_mul_f32_e32 v117, 0xbfb8aa3b, v117
	v_exp_f32_e32 v118, v118
	v_exp_f32_e32 v119, v119
	v_exp_f32_e32 v120, v120
	v_exp_f32_e32 v121, v121
	v_exp_f32_e32 v114, v114
	v_exp_f32_e32 v115, v115
	v_exp_f32_e32 v116, v116
	v_exp_f32_e32 v117, v117
	v_add_f32_e32 v118, 1.0, v118
	v_add_f32_e32 v119, 1.0, v119
	v_add_f32_e32 v120, 1.0, v120
	v_add_f32_e32 v121, 1.0, v121
	v_add_f32_e32 v114, 1.0, v114
	v_add_f32_e32 v115, 1.0, v115
	v_add_f32_e32 v116, 1.0, v116
	v_add_f32_e32 v117, 1.0, v117
	v_rcp_f32_e32 v118, v118
	v_rcp_f32_e32 v119, v119
	v_rcp_f32_e32 v120, v120
	v_rcp_f32_e32 v121, v121
	v_rcp_f32_e32 v114, v114
	v_rcp_f32_e32 v115, v115
	v_rcp_f32_e32 v116, v116
	v_rcp_f32_e32 v117, v117
.LBB0_556:
	v_cvt_pk_bf16_f32 v118, v118, v119
	v_cvt_pk_bf16_f32 v119, v120, v121
	v_cvt_pk_bf16_f32 v120, v114, v115
	v_pk_mul_f32 v[112:113], v[112:113], v[172:173] op_sel_hi:[1,0]
	v_pk_mul_f32 v[110:111], v[110:111], v[172:173] op_sel_hi:[1,0]
	v_pk_mul_f32 v[108:109], v[108:109], v[172:173] op_sel_hi:[1,0]
	s_and_b64 vcc, exec, s[6:7]
	v_pk_mul_f32 v[114:115], v[106:107], v[172:173] op_sel_hi:[1,0]
	v_cvt_pk_bf16_f32 v121, v116, v117
	global_store_dwordx4 v[124:125], v[118:121], off offset:256
	s_cbranch_vccnz .LBB0_558
	v_mul_f32_e32 v106, 0xbfb8aa3b, v110
	v_exp_f32_e32 v106, v106
	v_mul_f32_e32 v107, 0xbfb8aa3b, v111
	v_exp_f32_e32 v107, v107
	v_mul_f32_e32 v111, 0xbfb8aa3b, v113
	v_add_f32_e32 v106, 1.0, v106
	v_rcp_f32_e32 v110, v106
	v_mul_f32_e32 v106, 0xbfb8aa3b, v112
	v_add_f32_e32 v107, 1.0, v107
	v_exp_f32_e32 v106, v106
	v_exp_f32_e32 v113, v111
	v_rcp_f32_e32 v111, v107
	v_mul_f32_e32 v107, 0xbfb8aa3b, v114
	v_exp_f32_e32 v107, v107
	v_add_f32_e32 v106, 1.0, v106
	v_rcp_f32_e32 v112, v106
	v_add_f32_e32 v106, 1.0, v113
	v_mul_f32_e32 v113, 0xbfb8aa3b, v115
	v_exp_f32_e32 v115, v113
	v_rcp_f32_e32 v113, v106
	v_add_f32_e32 v106, 1.0, v107
	v_mul_f32_e32 v107, 0xbfb8aa3b, v108
	v_exp_f32_e32 v107, v107
	v_mul_f32_e32 v108, 0xbfb8aa3b, v109
	v_exp_f32_e32 v109, v108
	v_rcp_f32_e32 v114, v106
	v_add_f32_e32 v106, 1.0, v115
	v_rcp_f32_e32 v115, v106
	v_add_f32_e32 v106, 1.0, v107
	v_rcp_f32_e32 v108, v106
	v_add_f32_e32 v106, 1.0, v109
	v_rcp_f32_e32 v109, v106
.LBB0_558:
	v_mul_lo_u32 v116, s29, v174
	v_mul_lo_u32 v117, s28, v175
	v_mad_u64_u32 v[106:107], s[30:31], s28, v174, 0
	v_mov_b32_e32 v173, v172
	v_add3_u32 v107, v107, v117, v116
	v_cvt_pk_bf16_f32 v110, v110, v111
	v_cvt_pk_bf16_f32 v111, v112, v113
	v_cvt_pk_bf16_f32 v112, v114, v115
	v_cvt_pk_bf16_f32 v113, v108, v109
	v_mov_b32_e32 v108, v172
	v_mov_b32_e32 v109, v172
	v_lshl_add_u64 v[106:107], v[106:107], 1, v[122:123]
	v_pk_mul_f32 v[104:105], v[104:105], v[108:109]
	v_pk_mul_f32 v[102:103], v[102:103], v[172:173]
	v_pk_mul_f32 v[100:101], v[100:101], v[108:109]
	s_and_b64 vcc, exec, s[6:7]
	v_pk_mul_f32 v[98:99], v[98:99], v[172:173]
	global_store_dwordx4 v[106:107], v[110:113], off
	s_cbranch_vccnz .LBB0_560
	v_mul_f32_e32 v102, 0xbfb8aa3b, v102
	v_mul_f32_e32 v103, 0xbfb8aa3b, v103
	v_mul_f32_e32 v104, 0xbfb8aa3b, v104
	v_mul_f32_e32 v105, 0xbfb8aa3b, v105
	v_mul_f32_e32 v98, 0xbfb8aa3b, v98
	v_mul_f32_e32 v99, 0xbfb8aa3b, v99
	v_mul_f32_e32 v100, 0xbfb8aa3b, v100
	v_mul_f32_e32 v101, 0xbfb8aa3b, v101
	v_exp_f32_e32 v102, v102
	v_exp_f32_e32 v103, v103
	v_exp_f32_e32 v104, v104
	v_exp_f32_e32 v105, v105
	v_exp_f32_e32 v98, v98
	v_exp_f32_e32 v99, v99
	v_exp_f32_e32 v100, v100
	v_exp_f32_e32 v101, v101
	v_add_f32_e32 v102, 1.0, v102
	v_add_f32_e32 v103, 1.0, v103
	v_add_f32_e32 v104, 1.0, v104
	v_add_f32_e32 v105, 1.0, v105
	v_add_f32_e32 v98, 1.0, v98
	v_add_f32_e32 v99, 1.0, v99
	v_add_f32_e32 v100, 1.0, v100
	v_add_f32_e32 v101, 1.0, v101
	v_rcp_f32_e32 v102, v102
	v_rcp_f32_e32 v103, v103
	v_rcp_f32_e32 v104, v104
	v_rcp_f32_e32 v105, v105
	v_rcp_f32_e32 v98, v98
	v_rcp_f32_e32 v99, v99
	v_rcp_f32_e32 v100, v100
	v_rcp_f32_e32 v101, v101
; __device__ __forceinline__ unsigned cvt_pk_bf16(float lo, float hi) { unsigned r; asm volatile("s_nop 0\n\tv_cvt_pk_bf16_f32 %0, %1, %2" : "=v"(r) : "v"(lo), "v"(hi)); return r; }
; __device__ __forceinline__ float sigmoidf_(float x) { return __builtin_amdgcn_rcpf(1.0f + __builtin_amdgcn_exp2f(-1.4426950408889634f * x)); }
; __device__ __forceinline__ u32x4 pack8(const f32x4 v0, const f32x4 v1) { u32x4 w; w.x = cvt_pk_bf16(v0[0], v0[1]); w.y = cvt_pk_bf16(v0[2], v0[3]); w.z = cvt_pk_bf16(v1[0], v1[1]); w.w = cvt_pk_bf16(v1[2], v1[3]); return w; }
; __device__ __forceinline__ void unpack8(const u32x4 w, f32x4& v0, f32x4& v1) { v0 = (f32x4){bf_lo(w.x), bf_hi(w.x), bf_lo(w.y), bf_hi(w.y)}; v1 = (f32x4){bf_lo(w.z), bf_hi(w.z), bf_lo(w.w), bf_hi(w.w)}; }
; __device__ __forceinline__ f32x4 sig4(const f32x4 v) { return (f32x4){sigmoidf_(v[0]), sigmoidf_(v[1]), sigmoidf_(v[2]), sigmoidf_(v[3])}; }
;     __device__ __forceinline__ void operator()(AccRef acc, const Unit& uu, int wr, int wc, int fr, int fq) const {
;     ...
; #pragma unroll
;         for (int ai = 0; ai < 2; ++ai)
; #pragma unroll
;             for (int m = 0; m < 4; ++m) { const int r = row0 + ai * HALF + m * 16; const float rs = rsv[ai][m]; bf16_t* rowp = base + (size_t)r * ldc + col0;
; #pragma unroll
;                 for (int bj = 0; bj < 2; ++bj) { f32x4 v0 = acc[ai][bj][m][0] * rs, v1 = acc[ai][bj][m][1] * rs;
;                     if (sg) { v0 = sig4(v0); v1 = sig4(v1); }
;                     *(u32x4*)(rowp + bj * HALF) = pack8(v0, v1); } }
.LBB0_560:
	v_cvt_pk_bf16_f32 v102, v102, v103
	v_cvt_pk_bf16_f32 v103, v104, v105
	v_cvt_pk_bf16_f32 v104, v98, v99
	v_pk_mul_f32 v[96:97], v[96:97], v[168:169] op_sel_hi:[1,0]
	v_pk_mul_f32 v[94:95], v[94:95], v[168:169] op_sel_hi:[1,0]
	v_pk_mul_f32 v[92:93], v[92:93], v[168:169] op_sel_hi:[1,0]
	s_and_b64 vcc, exec, s[6:7]
	v_pk_mul_f32 v[98:99], v[90:91], v[168:169] op_sel_hi:[1,0]
	v_cvt_pk_bf16_f32 v105, v100, v101
	global_store_dwordx4 v[106:107], v[102:105], off offset:256
	s_cbranch_vccnz .LBB0_562
	v_mul_f32_e32 v90, 0xbfb8aa3b, v94
	v_exp_f32_e32 v90, v90
	v_mul_f32_e32 v91, 0xbfb8aa3b, v95
	v_exp_f32_e32 v91, v91
	v_mul_f32_e32 v95, 0xbfb8aa3b, v97
	v_add_f32_e32 v90, 1.0, v90
	v_rcp_f32_e32 v94, v90
	v_mul_f32_e32 v90, 0xbfb8aa3b, v96
	v_add_f32_e32 v91, 1.0, v91
	v_exp_f32_e32 v90, v90
	v_exp_f32_e32 v97, v95
	v_rcp_f32_e32 v95, v91
	v_mul_f32_e32 v91, 0xbfb8aa3b, v98
	v_exp_f32_e32 v91, v91
	v_add_f32_e32 v90, 1.0, v90
	v_rcp_f32_e32 v96, v90
	v_add_f32_e32 v90, 1.0, v97
	v_mul_f32_e32 v97, 0xbfb8aa3b, v99
	v_exp_f32_e32 v99, v97
	v_rcp_f32_e32 v97, v90
	v_add_f32_e32 v90, 1.0, v91
	v_mul_f32_e32 v91, 0xbfb8aa3b, v92
	v_exp_f32_e32 v91, v91
	v_mul_f32_e32 v92, 0xbfb8aa3b, v93
	v_exp_f32_e32 v93, v92
	v_rcp_f32_e32 v98, v90
	v_add_f32_e32 v90, 1.0, v99
	v_rcp_f32_e32 v99, v90
	v_add_f32_e32 v90, 1.0, v91
	v_rcp_f32_e32 v92, v90
	v_add_f32_e32 v90, 1.0, v93
	v_rcp_f32_e32 v93, v90
.LBB0_562:
	v_mul_lo_u32 v100, s29, v170
	v_mul_lo_u32 v101, s28, v171
	v_mad_u64_u32 v[90:91], s[30:31], s28, v170, 0
	v_mov_b32_e32 v169, v168
	v_add3_u32 v91, v91, v101, v100
	v_cvt_pk_bf16_f32 v94, v94, v95
	v_cvt_pk_bf16_f32 v95, v96, v97
	v_cvt_pk_bf16_f32 v96, v98, v99
	v_cvt_pk_bf16_f32 v97, v92, v93
	v_mov_b32_e32 v92, v168
	v_mov_b32_e32 v93, v168
	v_lshl_add_u64 v[90:91], v[90:91], 1, v[122:123]
	v_pk_mul_f32 v[88:89], v[88:89], v[92:93]
	v_pk_mul_f32 v[86:87], v[86:87], v[168:169]
	v_pk_mul_f32 v[84:85], v[84:85], v[92:93]
	s_and_b64 vcc, exec, s[6:7]
	v_pk_mul_f32 v[82:83], v[82:83], v[168:169]
	global_store_dwordx4 v[90:91], v[94:97], off
	s_cbranch_vccnz .LBB0_564
	v_mul_f32_e32 v86, 0xbfb8aa3b, v86
	v_mul_f32_e32 v87, 0xbfb8aa3b, v87
	v_mul_f32_e32 v88, 0xbfb8aa3b, v88
	v_mul_f32_e32 v89, 0xbfb8aa3b, v89
	v_mul_f32_e32 v82, 0xbfb8aa3b, v82
	v_mul_f32_e32 v83, 0xbfb8aa3b, v83
	v_mul_f32_e32 v84, 0xbfb8aa3b, v84
	v_mul_f32_e32 v85, 0xbfb8aa3b, v85
	v_exp_f32_e32 v86, v86
	v_exp_f32_e32 v87, v87
	v_exp_f32_e32 v88, v88
	v_exp_f32_e32 v89, v89
	v_exp_f32_e32 v82, v82
	v_exp_f32_e32 v83, v83
	v_exp_f32_e32 v84, v84
	v_exp_f32_e32 v85, v85
	v_add_f32_e32 v86, 1.0, v86
	v_add_f32_e32 v87, 1.0, v87
	v_add_f32_e32 v88, 1.0, v88
	v_add_f32_e32 v89, 1.0, v89
	v_add_f32_e32 v82, 1.0, v82
	v_add_f32_e32 v83, 1.0, v83
	v_add_f32_e32 v84, 1.0, v84
	v_add_f32_e32 v85, 1.0, v85
	v_rcp_f32_e32 v86, v86
	v_rcp_f32_e32 v87, v87
	v_rcp_f32_e32 v88, v88
	v_rcp_f32_e32 v89, v89
	v_rcp_f32_e32 v82, v82
	v_rcp_f32_e32 v83, v83
	v_rcp_f32_e32 v84, v84
	v_rcp_f32_e32 v85, v85
.LBB0_564:
	v_cvt_pk_bf16_f32 v86, v86, v87
	v_cvt_pk_bf16_f32 v87, v88, v89
	v_cvt_pk_bf16_f32 v88, v82, v83
	v_pk_mul_f32 v[80:81], v[80:81], v[164:165] op_sel_hi:[1,0]
	v_pk_mul_f32 v[78:79], v[78:79], v[164:165] op_sel_hi:[1,0]
	v_pk_mul_f32 v[76:77], v[76:77], v[164:165] op_sel_hi:[1,0]
	s_and_b64 vcc, exec, s[6:7]
	v_pk_mul_f32 v[82:83], v[74:75], v[164:165] op_sel_hi:[1,0]
	v_cvt_pk_bf16_f32 v89, v84, v85
	global_store_dwordx4 v[90:91], v[86:89], off offset:256
	s_cbranch_vccnz .LBB0_566
	v_mul_f32_e32 v74, 0xbfb8aa3b, v78
	v_exp_f32_e32 v74, v74
	v_mul_f32_e32 v75, 0xbfb8aa3b, v79
	v_exp_f32_e32 v75, v75
	v_mul_f32_e32 v79, 0xbfb8aa3b, v81
	v_add_f32_e32 v74, 1.0, v74
	v_rcp_f32_e32 v78, v74
	v_mul_f32_e32 v74, 0xbfb8aa3b, v80
	v_add_f32_e32 v75, 1.0, v75
	v_exp_f32_e32 v74, v74
	v_exp_f32_e32 v81, v79
	v_rcp_f32_e32 v79, v75
	v_mul_f32_e32 v75, 0xbfb8aa3b, v82
	v_exp_f32_e32 v75, v75
	v_add_f32_e32 v74, 1.0, v74
	v_rcp_f32_e32 v80, v74
	v_add_f32_e32 v74, 1.0, v81
	v_mul_f32_e32 v81, 0xbfb8aa3b, v83
	v_exp_f32_e32 v83, v81
	v_rcp_f32_e32 v81, v74
	v_add_f32_e32 v74, 1.0, v75
	v_mul_f32_e32 v75, 0xbfb8aa3b, v76
	v_exp_f32_e32 v75, v75
	v_mul_f32_e32 v76, 0xbfb8aa3b, v77
	v_exp_f32_e32 v77, v76
	v_rcp_f32_e32 v82, v74
	v_add_f32_e32 v74, 1.0, v83
	v_rcp_f32_e32 v83, v74
	v_add_f32_e32 v74, 1.0, v75
	v_rcp_f32_e32 v76, v74
	v_add_f32_e32 v74, 1.0, v77
	v_rcp_f32_e32 v77, v74
.LBB0_566:
	v_mul_lo_u32 v84, s29, v166
	v_mul_lo_u32 v85, s28, v167
	v_mad_u64_u32 v[74:75], s[30:31], s28, v166, 0
	v_mov_b32_e32 v165, v164
	v_add3_u32 v75, v75, v85, v84
	v_cvt_pk_bf16_f32 v78, v78, v79
	v_cvt_pk_bf16_f32 v79, v80, v81
	v_cvt_pk_bf16_f32 v80, v82, v83
	v_cvt_pk_bf16_f32 v81, v76, v77
	v_mov_b32_e32 v76, v164
	v_mov_b32_e32 v77, v164
	v_lshl_add_u64 v[74:75], v[74:75], 1, v[122:123]
	v_pk_mul_f32 v[72:73], v[72:73], v[76:77]
	v_pk_mul_f32 v[70:71], v[70:71], v[164:165]
	v_pk_mul_f32 v[68:69], v[68:69], v[76:77]
	s_and_b64 vcc, exec, s[6:7]
	v_pk_mul_f32 v[66:67], v[66:67], v[164:165]
	global_store_dwordx4 v[74:75], v[78:81], off
	s_cbranch_vccnz .LBB0_568
	v_mul_f32_e32 v70, 0xbfb8aa3b, v70
	v_mul_f32_e32 v71, 0xbfb8aa3b, v71
	v_mul_f32_e32 v72, 0xbfb8aa3b, v72
	v_mul_f32_e32 v73, 0xbfb8aa3b, v73
	v_mul_f32_e32 v66, 0xbfb8aa3b, v66
	v_mul_f32_e32 v67, 0xbfb8aa3b, v67
	v_mul_f32_e32 v68, 0xbfb8aa3b, v68
	v_mul_f32_e32 v69, 0xbfb8aa3b, v69
	v_exp_f32_e32 v70, v70
	v_exp_f32_e32 v71, v71
	v_exp_f32_e32 v72, v72
	v_exp_f32_e32 v73, v73
	v_exp_f32_e32 v66, v66
	v_exp_f32_e32 v67, v67
	v_exp_f32_e32 v68, v68
	v_exp_f32_e32 v69, v69
	v_add_f32_e32 v70, 1.0, v70
	v_add_f32_e32 v71, 1.0, v71
	v_add_f32_e32 v72, 1.0, v72
	v_add_f32_e32 v73, 1.0, v73
	v_add_f32_e32 v66, 1.0, v66
	v_add_f32_e32 v67, 1.0, v67
	v_add_f32_e32 v68, 1.0, v68
	v_add_f32_e32 v69, 1.0, v69
	v_rcp_f32_e32 v70, v70
	v_rcp_f32_e32 v71, v71
	v_rcp_f32_e32 v72, v72
	v_rcp_f32_e32 v73, v73
	v_rcp_f32_e32 v66, v66
	v_rcp_f32_e32 v67, v67
	v_rcp_f32_e32 v68, v68
	v_rcp_f32_e32 v69, v69
; __device__ __forceinline__ unsigned cvt_pk_bf16(float lo, float hi) { unsigned r; asm volatile("s_nop 0\n\tv_cvt_pk_bf16_f32 %0, %1, %2" : "=v"(r) : "v"(lo), "v"(hi)); return r; }
; __device__ __forceinline__ float sigmoidf_(float x) { return __builtin_amdgcn_rcpf(1.0f + __builtin_amdgcn_exp2f(-1.4426950408889634f * x)); }
; __device__ __forceinline__ u32x4 pack8(const f32x4 v0, const f32x4 v1) { u32x4 w; w.x = cvt_pk_bf16(v0[0], v0[1]); w.y = cvt_pk_bf16(v0[2], v0[3]); w.z = cvt_pk_bf16(v1[0], v1[1]); w.w = cvt_pk_bf16(v1[2], v1[3]); return w; }
; __device__ __forceinline__ void unpack8(const u32x4 w, f32x4& v0, f32x4& v1) { v0 = (f32x4){bf_lo(w.x), bf_hi(w.x), bf_lo(w.y), bf_hi(w.y)}; v1 = (f32x4){bf_lo(w.z), bf_hi(w.z), bf_lo(w.w), bf_hi(w.w)}; }
; __device__ __forceinline__ f32x4 sig4(const f32x4 v) { return (f32x4){sigmoidf_(v[0]), sigmoidf_(v[1]), sigmoidf_(v[2]), sigmoidf_(v[3])}; }
;     __device__ __forceinline__ void operator()(AccRef acc, const Unit& uu, int wr, int wc, int fr, int fq) const {
;     ...
; #pragma unroll
;         for (int ai = 0; ai < 2; ++ai)
; #pragma unroll
;             for (int m = 0; m < 4; ++m) { const int r = row0 + ai * HALF + m * 16; const float rs = rsv[ai][m]; bf16_t* rowp = base + (size_t)r * ldc + col0;
; #pragma unroll
;                 for (int bj = 0; bj < 2; ++bj) { f32x4 v0 = acc[ai][bj][m][0] * rs, v1 = acc[ai][bj][m][1] * rs;
;                     if (sg) { v0 = sig4(v0); v1 = sig4(v1); }
;                     *(u32x4*)(rowp + bj * HALF) = pack8(v0, v1); } }
.LBB0_568:
	v_cvt_pk_bf16_f32 v70, v70, v71
	v_cvt_pk_bf16_f32 v71, v72, v73
	v_cvt_pk_bf16_f32 v72, v66, v67
	v_pk_mul_f32 v[64:65], v[64:65], v[162:163] op_sel_hi:[1,0]
	v_pk_mul_f32 v[62:63], v[62:63], v[162:163] op_sel_hi:[1,0]
	v_pk_mul_f32 v[60:61], v[60:61], v[162:163] op_sel_hi:[1,0]
	s_and_b64 vcc, exec, s[6:7]
	v_pk_mul_f32 v[66:67], v[58:59], v[162:163] op_sel_hi:[1,0]
	v_cvt_pk_bf16_f32 v73, v68, v69
	global_store_dwordx4 v[74:75], v[70:73], off offset:256
	s_cbranch_vccnz .LBB0_570
	v_mul_f32_e32 v58, 0xbfb8aa3b, v62
	v_exp_f32_e32 v58, v58
	v_mul_f32_e32 v59, 0xbfb8aa3b, v63
	v_exp_f32_e32 v59, v59
	v_mul_f32_e32 v63, 0xbfb8aa3b, v65
	v_add_f32_e32 v58, 1.0, v58
	v_rcp_f32_e32 v62, v58
	v_mul_f32_e32 v58, 0xbfb8aa3b, v64
	v_add_f32_e32 v59, 1.0, v59
	v_exp_f32_e32 v58, v58
	v_exp_f32_e32 v65, v63
	v_rcp_f32_e32 v63, v59
	v_mul_f32_e32 v59, 0xbfb8aa3b, v66
	v_exp_f32_e32 v59, v59
	v_add_f32_e32 v58, 1.0, v58
	v_rcp_f32_e32 v64, v58
	v_add_f32_e32 v58, 1.0, v65
	v_mul_f32_e32 v65, 0xbfb8aa3b, v67
	v_exp_f32_e32 v67, v65
	v_rcp_f32_e32 v65, v58
	v_add_f32_e32 v58, 1.0, v59
	v_mul_f32_e32 v59, 0xbfb8aa3b, v60
	v_exp_f32_e32 v59, v59
	v_mul_f32_e32 v60, 0xbfb8aa3b, v61
	v_exp_f32_e32 v61, v60
	v_rcp_f32_e32 v66, v58
	v_add_f32_e32 v58, 1.0, v67
	v_rcp_f32_e32 v67, v58
	v_add_f32_e32 v58, 1.0, v59
	v_rcp_f32_e32 v60, v58
	v_add_f32_e32 v58, 1.0, v61
	v_rcp_f32_e32 v61, v58
.LBB0_570:
	v_add_u32_e32 v58, 0x80, v156
	v_ashrrev_i32_e32 v59, 31, v58
	v_mul_lo_u32 v68, s28, v59
	v_mul_lo_u32 v69, s29, v58
	v_mad_u64_u32 v[58:59], s[30:31], s28, v58, 0
	v_mov_b32_e32 v163, v162
	v_add3_u32 v59, v59, v68, v69
	v_cvt_pk_bf16_f32 v62, v62, v63
	v_cvt_pk_bf16_f32 v63, v64, v65
	v_cvt_pk_bf16_f32 v64, v66, v67
	v_cvt_pk_bf16_f32 v65, v60, v61
	v_mov_b32_e32 v60, v162
	v_mov_b32_e32 v61, v162
	v_lshl_add_u64 v[58:59], v[58:59], 1, v[122:123]
	v_pk_mul_f32 v[56:57], v[56:57], v[60:61]
	v_pk_mul_f32 v[54:55], v[54:55], v[162:163]
	v_pk_mul_f32 v[52:53], v[52:53], v[60:61]
	s_and_b64 vcc, exec, s[6:7]
	v_pk_mul_f32 v[50:51], v[50:51], v[162:163]
	global_store_dwordx4 v[58:59], v[62:65], off
	s_cbranch_vccnz .LBB0_572
	v_mul_f32_e32 v54, 0xbfb8aa3b, v54
	v_mul_f32_e32 v55, 0xbfb8aa3b, v55
	v_mul_f32_e32 v56, 0xbfb8aa3b, v56
	v_mul_f32_e32 v57, 0xbfb8aa3b, v57
	v_mul_f32_e32 v50, 0xbfb8aa3b, v50
	v_mul_f32_e32 v51, 0xbfb8aa3b, v51
	v_mul_f32_e32 v52, 0xbfb8aa3b, v52
	v_mul_f32_e32 v53, 0xbfb8aa3b, v53
	v_exp_f32_e32 v54, v54
	v_exp_f32_e32 v55, v55
	v_exp_f32_e32 v56, v56
	v_exp_f32_e32 v57, v57
	v_exp_f32_e32 v50, v50
	v_exp_f32_e32 v51, v51
	v_exp_f32_e32 v52, v52
	v_exp_f32_e32 v53, v53
	v_add_f32_e32 v54, 1.0, v54
	v_add_f32_e32 v55, 1.0, v55
	v_add_f32_e32 v56, 1.0, v56
	v_add_f32_e32 v57, 1.0, v57
	v_add_f32_e32 v50, 1.0, v50
	v_add_f32_e32 v51, 1.0, v51
	v_add_f32_e32 v52, 1.0, v52
	v_add_f32_e32 v53, 1.0, v53
	v_rcp_f32_e32 v54, v54
	v_rcp_f32_e32 v55, v55
	v_rcp_f32_e32 v56, v56
	v_rcp_f32_e32 v57, v57
	v_rcp_f32_e32 v50, v50
	v_rcp_f32_e32 v51, v51
	v_rcp_f32_e32 v52, v52
	v_rcp_f32_e32 v53, v53
.LBB0_572:
	v_cvt_pk_bf16_f32 v54, v54, v55
	v_cvt_pk_bf16_f32 v55, v56, v57
	v_cvt_pk_bf16_f32 v56, v50, v51
	v_pk_mul_f32 v[48:49], v[48:49], v[160:161] op_sel_hi:[1,0]
	v_pk_mul_f32 v[46:47], v[46:47], v[160:161] op_sel_hi:[1,0]
	v_pk_mul_f32 v[44:45], v[44:45], v[160:161] op_sel_hi:[1,0]
	s_and_b64 vcc, exec, s[6:7]
	v_pk_mul_f32 v[50:51], v[42:43], v[160:161] op_sel_hi:[1,0]
	v_cvt_pk_bf16_f32 v57, v52, v53
	global_store_dwordx4 v[58:59], v[54:57], off offset:256
	s_cbranch_vccnz .LBB0_574
	v_mul_f32_e32 v42, 0xbfb8aa3b, v46
	v_exp_f32_e32 v42, v42
	v_mul_f32_e32 v43, 0xbfb8aa3b, v47
	v_exp_f32_e32 v43, v43
	v_mul_f32_e32 v47, 0xbfb8aa3b, v49
	v_add_f32_e32 v42, 1.0, v42
	v_rcp_f32_e32 v46, v42
	v_mul_f32_e32 v42, 0xbfb8aa3b, v48
	v_add_f32_e32 v43, 1.0, v43
	v_exp_f32_e32 v42, v42
	v_exp_f32_e32 v49, v47
	v_rcp_f32_e32 v47, v43
	v_mul_f32_e32 v43, 0xbfb8aa3b, v50
	v_exp_f32_e32 v43, v43
	v_add_f32_e32 v42, 1.0, v42
	v_rcp_f32_e32 v48, v42
	v_add_f32_e32 v42, 1.0, v49
	v_mul_f32_e32 v49, 0xbfb8aa3b, v51
	v_exp_f32_e32 v51, v49
	v_rcp_f32_e32 v49, v42
	v_add_f32_e32 v42, 1.0, v43
	v_mul_f32_e32 v43, 0xbfb8aa3b, v44
	v_exp_f32_e32 v43, v43
	v_mul_f32_e32 v44, 0xbfb8aa3b, v45
	v_exp_f32_e32 v45, v44
	v_rcp_f32_e32 v50, v42
	v_add_f32_e32 v42, 1.0, v51
	v_rcp_f32_e32 v51, v42
	v_add_f32_e32 v42, 1.0, v43
	v_rcp_f32_e32 v44, v42
	v_add_f32_e32 v42, 1.0, v45
	v_rcp_f32_e32 v45, v42
.LBB0_574:
	v_add_u32_e32 v42, 0x90, v156
	v_ashrrev_i32_e32 v43, 31, v42
	v_mul_lo_u32 v52, s28, v43
	v_mul_lo_u32 v53, s29, v42
	v_mad_u64_u32 v[42:43], s[30:31], s28, v42, 0
	v_mov_b32_e32 v161, v160
	v_add3_u32 v43, v43, v52, v53
	v_cvt_pk_bf16_f32 v46, v46, v47
	v_cvt_pk_bf16_f32 v47, v48, v49
	v_cvt_pk_bf16_f32 v48, v50, v51
	v_cvt_pk_bf16_f32 v49, v44, v45
	v_mov_b32_e32 v44, v160
	v_mov_b32_e32 v45, v160
	v_lshl_add_u64 v[42:43], v[42:43], 1, v[122:123]
	v_pk_mul_f32 v[40:41], v[40:41], v[44:45]
	v_pk_mul_f32 v[38:39], v[38:39], v[160:161]
	v_pk_mul_f32 v[36:37], v[36:37], v[44:45]
	s_and_b64 vcc, exec, s[6:7]
	v_pk_mul_f32 v[34:35], v[34:35], v[160:161]
	global_store_dwordx4 v[42:43], v[46:49], off
	s_cbranch_vccnz .LBB0_576
	v_mul_f32_e32 v38, 0xbfb8aa3b, v38
	v_mul_f32_e32 v39, 0xbfb8aa3b, v39
	v_mul_f32_e32 v40, 0xbfb8aa3b, v40
	v_mul_f32_e32 v41, 0xbfb8aa3b, v41
	v_mul_f32_e32 v34, 0xbfb8aa3b, v34
	v_mul_f32_e32 v35, 0xbfb8aa3b, v35
	v_mul_f32_e32 v36, 0xbfb8aa3b, v36
	v_mul_f32_e32 v37, 0xbfb8aa3b, v37
	v_exp_f32_e32 v38, v38
	v_exp_f32_e32 v39, v39
	v_exp_f32_e32 v40, v40
	v_exp_f32_e32 v41, v41
	v_exp_f32_e32 v34, v34
	v_exp_f32_e32 v35, v35
	v_exp_f32_e32 v36, v36
	v_exp_f32_e32 v37, v37
	v_add_f32_e32 v38, 1.0, v38
	v_add_f32_e32 v39, 1.0, v39
	v_add_f32_e32 v40, 1.0, v40
	v_add_f32_e32 v41, 1.0, v41
	v_add_f32_e32 v34, 1.0, v34
	v_add_f32_e32 v35, 1.0, v35
	v_add_f32_e32 v36, 1.0, v36
	v_add_f32_e32 v37, 1.0, v37
	v_rcp_f32_e32 v38, v38
	v_rcp_f32_e32 v39, v39
	v_rcp_f32_e32 v40, v40
	v_rcp_f32_e32 v41, v41
	v_rcp_f32_e32 v34, v34
	v_rcp_f32_e32 v35, v35
	v_rcp_f32_e32 v36, v36
	v_rcp_f32_e32 v37, v37
; __device__ __forceinline__ unsigned cvt_pk_bf16(float lo, float hi) { unsigned r; asm volatile("s_nop 0\n\tv_cvt_pk_bf16_f32 %0, %1, %2" : "=v"(r) : "v"(lo), "v"(hi)); return r; }
; __device__ __forceinline__ float sigmoidf_(float x) { return __builtin_amdgcn_rcpf(1.0f + __builtin_amdgcn_exp2f(-1.4426950408889634f * x)); }
; #define PG8_BAR __builtin_amdgcn_s_barrier()
; template <class Epi, class Sched, bool ALIGN_EPI = false, bool SP2 = false, bool I8 = false>
; __device__ __forceinline__ void gemm_phase(PG8_LAS unsigned char* lds, const Gemm g, const Sched& S, const Epi& E) {
;     ...
;         if (!has_next) break;
; #pragma unroll
;         for (int a = 0; a < 2; ++a)
; #pragma unroll
;             for (int b = 0; b < 2; ++b)
; #pragma unroll
;                 for (int m = 0; m < 4; ++m)
; #pragma unroll
;                     for (int n = 0; n < 2; ++n) acc[a][b][m][n] = (typename AccT<I8>::type){0, 0, 0, 0};
;         cur = nxt; cA = nA; cB = nB; ++ui; nt = PG8_NT(cur);
;         if constexpr (ALIGN_EPI) { if (wr == 1) PG8_BAR; }
; __device__ __forceinline__ u32x4 pack8(const f32x4 v0, const f32x4 v1) { u32x4 w; w.x = cvt_pk_bf16(v0[0], v0[1]); w.y = cvt_pk_bf16(v0[2], v0[3]); w.z = cvt_pk_bf16(v1[0], v1[1]); w.w = cvt_pk_bf16(v1[2], v1[3]); return w; }
; __device__ __forceinline__ void unpack8(const u32x4 w, f32x4& v0, f32x4& v1) { v0 = (f32x4){bf_lo(w.x), bf_hi(w.x), bf_lo(w.y), bf_hi(w.y)}; v1 = (f32x4){bf_lo(w.z), bf_hi(w.z), bf_lo(w.w), bf_hi(w.w)}; }
; __device__ __forceinline__ f32x4 sig4(const f32x4 v) { return (f32x4){sigmoidf_(v[0]), sigmoidf_(v[1]), sigmoidf_(v[2]), sigmoidf_(v[3])}; }
;     __device__ __forceinline__ void operator()(AccRef acc, const Unit& uu, int wr, int wc, int fr, int fq) const {
;     ...
; #pragma unroll
;         for (int ai = 0; ai < 2; ++ai)
; #pragma unroll
;             for (int m = 0; m < 4; ++m) { const int r = row0 + ai * HALF + m * 16; const float rs = rsv[ai][m]; bf16_t* rowp = base + (size_t)r * ldc + col0;
; #pragma unroll
;                 for (int bj = 0; bj < 2; ++bj) { f32x4 v0 = acc[ai][bj][m][0] * rs, v1 = acc[ai][bj][m][1] * rs;
;                     if (sg) { v0 = sig4(v0); v1 = sig4(v1); }
;                     *(u32x4*)(rowp + bj * HALF) = pack8(v0, v1); } }
.LBB0_576:
	v_cvt_pk_bf16_f32 v38, v38, v39
	v_cvt_pk_bf16_f32 v39, v40, v41
	v_cvt_pk_bf16_f32 v40, v34, v35
	v_pk_mul_f32 v[32:33], v[32:33], v[158:159] op_sel_hi:[1,0]
	v_pk_mul_f32 v[30:31], v[30:31], v[158:159] op_sel_hi:[1,0]
	v_pk_mul_f32 v[28:29], v[28:29], v[158:159] op_sel_hi:[1,0]
	s_and_b64 vcc, exec, s[6:7]
	v_pk_mul_f32 v[34:35], v[26:27], v[158:159] op_sel_hi:[1,0]
	v_cvt_pk_bf16_f32 v41, v36, v37
	global_store_dwordx4 v[42:43], v[38:41], off offset:256
	s_cbranch_vccnz .LBB0_578
	v_mul_f32_e32 v26, 0xbfb8aa3b, v30
	v_exp_f32_e32 v26, v26
	v_mul_f32_e32 v27, 0xbfb8aa3b, v31
	v_exp_f32_e32 v27, v27
	v_mul_f32_e32 v31, 0xbfb8aa3b, v33
	v_add_f32_e32 v26, 1.0, v26
	v_rcp_f32_e32 v30, v26
	v_mul_f32_e32 v26, 0xbfb8aa3b, v32
	v_add_f32_e32 v27, 1.0, v27
	v_exp_f32_e32 v26, v26
	v_exp_f32_e32 v33, v31
	v_rcp_f32_e32 v31, v27
	v_mul_f32_e32 v27, 0xbfb8aa3b, v34
	v_exp_f32_e32 v27, v27
	v_add_f32_e32 v26, 1.0, v26
	v_rcp_f32_e32 v32, v26
	v_add_f32_e32 v26, 1.0, v33
	v_mul_f32_e32 v33, 0xbfb8aa3b, v35
	v_exp_f32_e32 v35, v33
	v_rcp_f32_e32 v33, v26
	v_add_f32_e32 v26, 1.0, v27
	v_mul_f32_e32 v27, 0xbfb8aa3b, v28
	v_exp_f32_e32 v27, v27
	v_mul_f32_e32 v28, 0xbfb8aa3b, v29
	v_exp_f32_e32 v29, v28
	v_rcp_f32_e32 v34, v26
	v_add_f32_e32 v26, 1.0, v35
	v_rcp_f32_e32 v35, v26
	v_add_f32_e32 v26, 1.0, v27
	v_rcp_f32_e32 v28, v26
	v_add_f32_e32 v26, 1.0, v29
	v_rcp_f32_e32 v29, v26
.LBB0_578:
	v_add_u32_e32 v26, 0xa0, v156
	v_ashrrev_i32_e32 v27, 31, v26
	v_mul_lo_u32 v36, s28, v27
	v_mul_lo_u32 v37, s29, v26
	v_mad_u64_u32 v[26:27], s[30:31], s28, v26, 0
	v_mov_b32_e32 v159, v158
	v_add3_u32 v27, v27, v36, v37
	v_cvt_pk_bf16_f32 v30, v30, v31
	v_cvt_pk_bf16_f32 v31, v32, v33
	v_cvt_pk_bf16_f32 v32, v34, v35
	v_cvt_pk_bf16_f32 v33, v28, v29
	v_mov_b32_e32 v28, v158
	v_mov_b32_e32 v29, v158
	v_lshl_add_u64 v[26:27], v[26:27], 1, v[122:123]
	v_pk_mul_f32 v[24:25], v[24:25], v[28:29]
	v_pk_mul_f32 v[22:23], v[22:23], v[158:159]
	v_pk_mul_f32 v[20:21], v[20:21], v[28:29]
	s_and_b64 vcc, exec, s[6:7]
	v_pk_mul_f32 v[18:19], v[18:19], v[158:159]
	global_store_dwordx4 v[26:27], v[30:33], off
	s_cbranch_vccnz .LBB0_580
	v_mul_f32_e32 v22, 0xbfb8aa3b, v22
	v_mul_f32_e32 v23, 0xbfb8aa3b, v23
	v_mul_f32_e32 v24, 0xbfb8aa3b, v24
	v_mul_f32_e32 v25, 0xbfb8aa3b, v25
	v_mul_f32_e32 v18, 0xbfb8aa3b, v18
	v_mul_f32_e32 v19, 0xbfb8aa3b, v19
	v_mul_f32_e32 v20, 0xbfb8aa3b, v20
	v_mul_f32_e32 v21, 0xbfb8aa3b, v21
	v_exp_f32_e32 v22, v22
	v_exp_f32_e32 v23, v23
	v_exp_f32_e32 v24, v24
	v_exp_f32_e32 v25, v25
	v_exp_f32_e32 v18, v18
	v_exp_f32_e32 v19, v19
	v_exp_f32_e32 v20, v20
	v_exp_f32_e32 v21, v21
	v_add_f32_e32 v22, 1.0, v22
	v_add_f32_e32 v23, 1.0, v23
	v_add_f32_e32 v24, 1.0, v24
	v_add_f32_e32 v25, 1.0, v25
	v_add_f32_e32 v18, 1.0, v18
	v_add_f32_e32 v19, 1.0, v19
	v_add_f32_e32 v20, 1.0, v20
	v_add_f32_e32 v21, 1.0, v21
	v_rcp_f32_e32 v22, v22
	v_rcp_f32_e32 v23, v23
	v_rcp_f32_e32 v24, v24
	v_rcp_f32_e32 v25, v25
	v_rcp_f32_e32 v18, v18
	v_rcp_f32_e32 v19, v19
	v_rcp_f32_e32 v20, v20
	v_rcp_f32_e32 v21, v21
.LBB0_580:
	v_cvt_pk_bf16_f32 v22, v22, v23
	v_cvt_pk_bf16_f32 v23, v24, v25
	v_cvt_pk_bf16_f32 v24, v18, v19
	v_pk_mul_f32 v[16:17], v[16:17], v[154:155] op_sel_hi:[1,0]
	v_pk_mul_f32 v[14:15], v[14:15], v[154:155] op_sel_hi:[1,0]
	v_pk_mul_f32 v[12:13], v[12:13], v[154:155] op_sel_hi:[1,0]
	s_and_b64 vcc, exec, s[6:7]
	v_pk_mul_f32 v[18:19], v[10:11], v[154:155] op_sel_hi:[1,0]
	v_cvt_pk_bf16_f32 v25, v20, v21
	global_store_dwordx4 v[26:27], v[22:25], off offset:256
	s_cbranch_vccnz .LBB0_582
	v_mul_f32_e32 v10, 0xbfb8aa3b, v14
	v_exp_f32_e32 v10, v10
	v_mul_f32_e32 v11, 0xbfb8aa3b, v15
	v_exp_f32_e32 v11, v11
	v_mul_f32_e32 v15, 0xbfb8aa3b, v17
	v_add_f32_e32 v10, 1.0, v10
	v_rcp_f32_e32 v14, v10
	v_mul_f32_e32 v10, 0xbfb8aa3b, v16
	v_add_f32_e32 v11, 1.0, v11
	v_exp_f32_e32 v10, v10
	v_exp_f32_e32 v17, v15
	v_rcp_f32_e32 v15, v11
	v_mul_f32_e32 v11, 0xbfb8aa3b, v18
	v_exp_f32_e32 v11, v11
	v_add_f32_e32 v10, 1.0, v10
	v_rcp_f32_e32 v16, v10
	v_add_f32_e32 v10, 1.0, v17
	v_mul_f32_e32 v17, 0xbfb8aa3b, v19
	v_exp_f32_e32 v19, v17
	v_rcp_f32_e32 v17, v10
	v_add_f32_e32 v10, 1.0, v11
	v_mul_f32_e32 v11, 0xbfb8aa3b, v12
	v_exp_f32_e32 v11, v11
	v_mul_f32_e32 v12, 0xbfb8aa3b, v13
	v_exp_f32_e32 v13, v12
	v_rcp_f32_e32 v18, v10
	v_add_f32_e32 v10, 1.0, v19
	v_rcp_f32_e32 v19, v10
	v_add_f32_e32 v10, 1.0, v11
	v_rcp_f32_e32 v12, v10
	v_add_f32_e32 v10, 1.0, v13
	v_rcp_f32_e32 v13, v10
.LBB0_582:
	v_add_u32_e32 v10, 0xb0, v156
	v_ashrrev_i32_e32 v11, 31, v10
	v_mul_lo_u32 v20, s28, v11
	v_mul_lo_u32 v21, s29, v10
	v_mad_u64_u32 v[10:11], s[28:29], s28, v10, 0
	v_mov_b32_e32 v155, v154
	v_add3_u32 v11, v11, v20, v21
	v_cvt_pk_bf16_f32 v14, v14, v15
	v_cvt_pk_bf16_f32 v15, v16, v17
	v_cvt_pk_bf16_f32 v16, v18, v19
	v_cvt_pk_bf16_f32 v17, v12, v13
	v_mov_b32_e32 v12, v154
	v_mov_b32_e32 v13, v154
	v_lshl_add_u64 v[10:11], v[10:11], 1, v[122:123]
	v_pk_mul_f32 v[8:9], v[8:9], v[12:13]
	v_pk_mul_f32 v[6:7], v[6:7], v[154:155]
	v_pk_mul_f32 v[4:5], v[4:5], v[12:13]
	s_and_b64 vcc, exec, s[6:7]
	v_pk_mul_f32 v[2:3], v[2:3], v[154:155]
	global_store_dwordx4 v[10:11], v[14:17], off
	s_cbranch_vccnz .LBB0_584
	v_mul_f32_e32 v6, 0xbfb8aa3b, v6
	v_mul_f32_e32 v7, 0xbfb8aa3b, v7
	v_mul_f32_e32 v8, 0xbfb8aa3b, v8
	v_mul_f32_e32 v9, 0xbfb8aa3b, v9
	v_mul_f32_e32 v2, 0xbfb8aa3b, v2
	v_mul_f32_e32 v3, 0xbfb8aa3b, v3
	v_mul_f32_e32 v4, 0xbfb8aa3b, v4
	v_mul_f32_e32 v5, 0xbfb8aa3b, v5
	v_exp_f32_e32 v6, v6
	v_exp_f32_e32 v7, v7
	v_exp_f32_e32 v8, v8
	v_exp_f32_e32 v9, v9
	v_exp_f32_e32 v2, v2
	v_exp_f32_e32 v3, v3
	v_exp_f32_e32 v4, v4
	v_exp_f32_e32 v5, v5
	v_add_f32_e32 v6, 1.0, v6
	v_add_f32_e32 v7, 1.0, v7
	v_add_f32_e32 v8, 1.0, v8
	v_add_f32_e32 v9, 1.0, v9
	v_add_f32_e32 v2, 1.0, v2
	v_add_f32_e32 v3, 1.0, v3
	v_add_f32_e32 v4, 1.0, v4
	v_add_f32_e32 v5, 1.0, v5
	v_rcp_f32_e32 v6, v6
	v_rcp_f32_e32 v7, v7
	v_rcp_f32_e32 v8, v8
	v_rcp_f32_e32 v9, v9
	v_rcp_f32_e32 v2, v2
	v_rcp_f32_e32 v3, v3
	v_rcp_f32_e32 v4, v4
	v_rcp_f32_e32 v5, v5
.LBB0_584:
	s_andn2_b64 vcc, exec, s[4:5]
	s_mov_b64 s[4:5], -1
	v_cvt_pk_bf16_f32 v6, v6, v7
	v_cvt_pk_bf16_f32 v7, v8, v9
	v_cvt_pk_bf16_f32 v8, v2, v3
	v_cvt_pk_bf16_f32 v9, v4, v5
	global_store_dwordx4 v[10:11], v[6:9], off offset:256
	s_cbranch_vccnz .LBB0_537
	s_andn2_b64 vcc, exec, s[16:17]
	s_cbranch_vccnz .LBB0_536
	s_barrier
	s_branch .LBB0_536

; #define PG8_STAGE(bufoff, gbase, voff) do { _Pragma("unroll") for (int _i = 0; _i < 2; ++_i) \
;         __builtin_amdgcn_global_load_lds((const unsigned*)((const char*)(gbase) + (voff)[_i]), (PG8_LAS unsigned*)(lds + (bufoff) + ldsw + _i * 8192), 16, 0, 0); } while (0)
; #define PG8_LDA(dst, b, h) do { _Pragma("unroll") for (int m = 0; m < 4; ++m) _Pragma("unroll") for (int k = 0; k < 2; ++k) dst[m][k] = *(const PG8_LAS bf16x8*)(lds + PG8_SA(b, h) + aoff + m * 2048 + k * 1024); } while (0)
; #define PG8_LDB(dst, b, h) do { _Pragma("unroll") for (int n = 0; n < 2; ++n) _Pragma("unroll") for (int k = 0; k < 2; ++k) dst[n][k] = *(const PG8_LAS bf16x8*)(lds + PG8_SB(b, h) + boff + n * 2048 + k * 1024); } while (0)
; #define PG8_MMA(ai, bj, At, Bt) do { __builtin_amdgcn_s_setprio(1); _Pragma("unroll") for (int m = 0; m < 4; ++m) _Pragma("unroll") for (int n = 0; n < 2; ++n) _Pragma("unroll") for (int k = 0; k < 2; ++k) \
;         acc[ai][bj][m][n] = mma_<I8>(Bt[n][k], At[m][k], acc[ai][bj][m][n]); __builtin_amdgcn_s_setprio(0); } while (0)
; #define PG8_WAIT_V(n) asm volatile("s_waitcnt vmcnt(" #n ")" ::: "memory")
; #define PG8_WAIT_L(n) asm volatile("s_waitcnt lgkmcnt(" #n ")" ::: "memory")
; #define PG8_BAR __builtin_amdgcn_s_barrier()
; #define PG8_SCHED __builtin_amdgcn_sched_barrier(0)
; template <class Epi, class Sched, bool ALIGN_EPI = false, bool SP2 = false, bool I8 = false>
; __device__ __forceinline__ void gemm_phase(PG8_LAS unsigned char* lds, const Gemm g, const Sched& S, const Epi& E) {
;     ...
;             PG8_LDB(B0, 0, 0); PG8_LDB(B1, 0, 1); PG8_SCHED; PG8_LDA(At, 0, 0); PG8_STAGE(PG8_SA(1, 1), a1 + hstepA, voffA);
;             PG8_WAIT_V(8); PG8_WAIT_L(0); PG8_BAR; PG8_MMA(0, 0, At, B0); PG8_MMA(0, 1, At, B1); PG8_BAR; PG8_SCHED;
;             PG8_LDA(At, 0, 1); PG8_STAGE(PG8_SB(0, 0), b2, voffB); PG8_STAGE(PG8_SB(0, 1), b2 + hstepB, voffB); PG8_STAGE(PG8_SA(0, 0), a2, voffA);
;             PG8_WAIT_V(8); PG8_WAIT_L(0); PG8_BAR; PG8_MMA(1, 0, At, B0); PG8_MMA(1, 1, At, B1); PG8_BAR; PG8_SCHED;
.LBB0_607:
	ds_read_b128 v[58:61], v177
	ds_read_b128 v[62:65], v177 offset:1024
	ds_read_b128 v[74:77], v177 offset:2048
	ds_read_b128 v[78:81], v177 offset:3072
	ds_read_b128 v[162:165], v178
	ds_read_b128 v[166:169], v178 offset:1024
	ds_read_b128 v[170:173], v178 offset:2048
	ds_read_b128 v[180:183], v178 offset:3072
	s_add_u32 s34, s2, 0xfff80080
	s_addc_u32 s35, s3, -1
	s_cmp_eq_u32 s39, 28
	s_cselect_b32 s37, s7, s35
	s_cselect_b32 s36, s9, s34
	s_cselect_b32 s35, s23, s38
	s_cselect_b32 s34, s25, s31
	s_add_i32 m0, s69, 0xc000
	ds_read_b128 v[184:187], v179
	ds_read_b128 v[188:191], v179 offset:1024
	ds_read_b128 v[192:195], v179 offset:2048
	ds_read_b128 v[196:199], v179 offset:3072
	ds_read_b128 v[200:203], v179 offset:4096
	ds_read_b128 v[204:207], v179 offset:5120
	ds_read_b128 v[208:211], v179 offset:6144
	ds_read_b128 v[212:215], v179 offset:7168
	global_load_lds_dwordx4 v154, s[2:3]
	s_add_i32 m0, s69, 0xe000
	s_nop 0
	global_load_lds_dwordx4 v156, s[2:3]
	s_waitcnt vmcnt(8) lgkmcnt(0)
	s_barrier
	v_mfma_i32_16x16x64_i8 v[142:145], v[58:61], v[184:187], v[142:145]
	v_mfma_i32_16x16x64_i8 v[138:141], v[74:77], v[184:187], v[138:141]
	v_mfma_i32_16x16x64_i8 v[126:129], v[58:61], v[192:195], v[126:129]
	v_mfma_i32_16x16x64_i8 v[122:125], v[74:77], v[192:195], v[122:125]
	v_mfma_i32_16x16x64_i8 v[110:113], v[58:61], v[200:203], v[110:113]
	v_mfma_i32_16x16x64_i8 v[106:109], v[74:77], v[200:203], v[106:109]
	v_mfma_i32_16x16x64_i8 v[94:97], v[58:61], v[208:211], v[94:97]
	v_mfma_i32_16x16x64_i8 v[90:93], v[74:77], v[208:211], v[90:93]
	v_mfma_i32_16x16x64_i8 v[142:145], v[62:65], v[188:191], v[142:145]
	v_mfma_i32_16x16x64_i8 v[138:141], v[78:81], v[188:191], v[138:141]
	v_mfma_i32_16x16x64_i8 v[126:129], v[62:65], v[196:199], v[126:129]
	v_mfma_i32_16x16x64_i8 v[122:125], v[78:81], v[196:199], v[122:125]
	v_mfma_i32_16x16x64_i8 v[110:113], v[62:65], v[204:207], v[110:113]
	v_mfma_i32_16x16x64_i8 v[106:109], v[78:81], v[204:207], v[106:109]
	v_mfma_i32_16x16x64_i8 v[94:97], v[62:65], v[212:215], v[94:97]
	v_mfma_i32_16x16x64_i8 v[90:93], v[78:81], v[212:215], v[90:93]
	v_mfma_i32_16x16x64_i8 v[134:137], v[162:165], v[184:187], v[134:137]
	v_mfma_i32_16x16x64_i8 v[130:133], v[170:173], v[184:187], v[130:133]
	v_mfma_i32_16x16x64_i8 v[118:121], v[162:165], v[192:195], v[118:121]
	v_mfma_i32_16x16x64_i8 v[114:117], v[170:173], v[192:195], v[114:117]
	v_mfma_i32_16x16x64_i8 v[102:105], v[162:165], v[200:203], v[102:105]
	v_mfma_i32_16x16x64_i8 v[98:101], v[170:173], v[200:203], v[98:101]
	v_mfma_i32_16x16x64_i8 v[86:89], v[162:165], v[208:211], v[86:89]
	v_mfma_i32_16x16x64_i8 v[82:85], v[170:173], v[208:211], v[82:85]
	v_mfma_i32_16x16x64_i8 v[134:137], v[166:169], v[188:191], v[134:137]
	v_mfma_i32_16x16x64_i8 v[130:133], v[180:183], v[188:191], v[130:133]
	v_mfma_i32_16x16x64_i8 v[118:121], v[166:169], v[196:199], v[118:121]
	v_mfma_i32_16x16x64_i8 v[114:117], v[180:183], v[196:199], v[114:117]
	v_mfma_i32_16x16x64_i8 v[102:105], v[166:169], v[204:207], v[102:105]
	v_mfma_i32_16x16x64_i8 v[98:101], v[180:183], v[204:207], v[98:101]
	v_mfma_i32_16x16x64_i8 v[86:89], v[166:169], v[212:215], v[86:89]
	v_mfma_i32_16x16x64_i8 v[82:85], v[180:183], v[212:215], v[82:85]
	s_barrier
	s_add_i32 s40, s33, s68
	s_mov_b64 s[98:99], s[34:35]
	s_mov_b32 m0, s40
	ds_read_b128 v[184:187], v179 offset:16384
	ds_read_b128 v[188:191], v179 offset:17408
	ds_read_b128 v[192:195], v179 offset:18432
	ds_read_b128 v[196:199], v179 offset:19456
	ds_read_b128 v[200:203], v179 offset:20480
	ds_read_b128 v[204:207], v179 offset:21504
	ds_read_b128 v[208:211], v179 offset:22528
	ds_read_b128 v[212:215], v179 offset:23552
	global_load_lds_dwordx4 v148, s[34:35]
	s_add_i32 m0, s40, 0x2000
	s_add_u32 s40, s34, 0x80000
	s_mov_b64 s[98:99], s[34:35]
	s_addc_u32 s41, s35, 0
	s_add_i32 vcc_lo, s8, s68
	global_load_lds_dwordx4 v152, s[34:35]
	s_mov_b32 m0, vcc_lo
	s_mov_b64 s[100:101], s[36:37]
	global_load_lds_dwordx4 v148, s[40:41]
	s_add_i32 m0, vcc_lo, 0x2000
	s_nop 0
	global_load_lds_dwordx4 v152, s[40:41]
	s_mov_b64 s[100:101], s[36:37]
	s_mov_b32 m0, s69
	s_nop 0
	global_load_lds_dwordx4 v146, s[36:37]
	s_mov_b32 m0, s70
	s_nop 0
	global_load_lds_dwordx4 v150, s[36:37]
	s_waitcnt vmcnt(8) lgkmcnt(0)
	s_barrier
	v_mfma_i32_16x16x64_i8 v[70:73], v[58:61], v[184:187], v[70:73]
	v_mfma_i32_16x16x64_i8 v[66:69], v[74:77], v[184:187], v[66:69]
	v_mfma_i32_16x16x64_i8 v[46:49], v[58:61], v[192:195], v[46:49]
	v_mfma_i32_16x16x64_i8 v[42:45], v[74:77], v[192:195], v[42:45]
	v_mfma_i32_16x16x64_i8 v[30:33], v[58:61], v[200:203], v[30:33]
	v_mfma_i32_16x16x64_i8 v[26:29], v[74:77], v[200:203], v[26:29]
	v_mfma_i32_16x16x64_i8 v[14:17], v[58:61], v[208:211], v[14:17]
	v_mfma_i32_16x16x64_i8 v[10:13], v[74:77], v[208:211], v[10:13]
	v_mfma_i32_16x16x64_i8 v[70:73], v[62:65], v[188:191], v[70:73]
	v_mfma_i32_16x16x64_i8 v[66:69], v[78:81], v[188:191], v[66:69]
	v_mfma_i32_16x16x64_i8 v[46:49], v[62:65], v[196:199], v[46:49]
	v_mfma_i32_16x16x64_i8 v[42:45], v[78:81], v[196:199], v[42:45]
	v_mfma_i32_16x16x64_i8 v[30:33], v[62:65], v[204:207], v[30:33]
	v_mfma_i32_16x16x64_i8 v[26:29], v[78:81], v[204:207], v[26:29]
	v_mfma_i32_16x16x64_i8 v[14:17], v[62:65], v[212:215], v[14:17]
	v_mfma_i32_16x16x64_i8 v[10:13], v[78:81], v[212:215], v[10:13]
	v_mfma_i32_16x16x64_i8 v[54:57], v[162:165], v[184:187], v[54:57]
	v_mfma_i32_16x16x64_i8 v[50:53], v[170:173], v[184:187], v[50:53]
	v_mfma_i32_16x16x64_i8 v[38:41], v[162:165], v[192:195], v[38:41]
	v_mfma_i32_16x16x64_i8 v[34:37], v[170:173], v[192:195], v[34:37]
	v_mfma_i32_16x16x64_i8 v[22:25], v[162:165], v[200:203], v[22:25]
	v_mfma_i32_16x16x64_i8 v[18:21], v[170:173], v[200:203], v[18:21]
	v_mfma_i32_16x16x64_i8 v[6:9], v[162:165], v[208:211], v[6:9]
	v_mfma_i32_16x16x64_i8 v[2:5], v[170:173], v[208:211], v[2:5]
	v_mfma_i32_16x16x64_i8 v[54:57], v[166:169], v[188:191], v[54:57]
	v_mfma_i32_16x16x64_i8 v[50:53], v[180:183], v[188:191], v[50:53]
	v_mfma_i32_16x16x64_i8 v[38:41], v[166:169], v[196:199], v[38:41]
	v_mfma_i32_16x16x64_i8 v[34:37], v[180:183], v[196:199], v[34:37]
	v_mfma_i32_16x16x64_i8 v[22:25], v[166:169], v[204:207], v[22:25]
	v_mfma_i32_16x16x64_i8 v[18:21], v[180:183], v[204:207], v[18:21]
	v_mfma_i32_16x16x64_i8 v[6:9], v[166:169], v[212:215], v[6:9]
	v_mfma_i32_16x16x64_i8 v[2:5], v[180:183], v[212:215], v[2:5]
	s_barrier
; #define PG8_STAGE(bufoff, gbase, voff) do { _Pragma("unroll") for (int _i = 0; _i < 2; ++_i) \
;         __builtin_amdgcn_global_load_lds((const unsigned*)((const char*)(gbase) + (voff)[_i]), (PG8_LAS unsigned*)(lds + (bufoff) + ldsw + _i * 8192), 16, 0, 0); } while (0)
; #define PG8_LDA(dst, b, h) do { _Pragma("unroll") for (int m = 0; m < 4; ++m) _Pragma("unroll") for (int k = 0; k < 2; ++k) dst[m][k] = *(const PG8_LAS bf16x8*)(lds + PG8_SA(b, h) + aoff + m * 2048 + k * 1024); } while (0)
; #define PG8_LDB(dst, b, h) do { _Pragma("unroll") for (int n = 0; n < 2; ++n) _Pragma("unroll") for (int k = 0; k < 2; ++k) dst[n][k] = *(const PG8_LAS bf16x8*)(lds + PG8_SB(b, h) + boff + n * 2048 + k * 1024); } while (0)
; #define PG8_MMA(ai, bj, At, Bt) do { __builtin_amdgcn_s_setprio(1); _Pragma("unroll") for (int m = 0; m < 4; ++m) _Pragma("unroll") for (int n = 0; n < 2; ++n) _Pragma("unroll") for (int k = 0; k < 2; ++k) \
;         acc[ai][bj][m][n] = mma_<I8>(Bt[n][k], At[m][k], acc[ai][bj][m][n]); __builtin_amdgcn_s_setprio(0); } while (0)
; #define PG8_WAIT_V(n) asm volatile("s_waitcnt vmcnt(" #n ")" ::: "memory")
; #define PG8_WAIT_L(n) asm volatile("s_waitcnt lgkmcnt(" #n ")" ::: "memory")
; #define PG8_BAR __builtin_amdgcn_s_barrier()
; #define PG8_SCHED __builtin_amdgcn_sched_barrier(0)
; template <class Epi, class Sched, bool ALIGN_EPI = false, bool SP2 = false, bool I8 = false>
; __device__ __forceinline__ void gemm_phase(PG8_LAS unsigned char* lds, const Gemm g, const Sched& S, const Epi& E) {
;     ...
;         for (int t = 0; t < nt; t += 2) {
;             const bool last = (t == nt - 2);
;             const char* a1 = cA + (size_t)(t + 1) * kstep;
;             const char* a2 = last ? nA : cA + (size_t)(t + 2) * kstep; const char* b2 = last ? nB : cB + (size_t)(t + 2) * kstep;
;             const char* a3 = a2 + kstep; const char* b3 = b2 + kstep;
;     ...
;             PG8_LDB(B0, 1, 0); PG8_LDB(B1, 1, 1); PG8_SCHED; PG8_LDA(At, 1, 0); PG8_STAGE(PG8_SA(0, 1), a2 + hstepA, voffA);
;             PG8_WAIT_V(8); PG8_WAIT_L(0); PG8_BAR; PG8_MMA(0, 0, At, B0); PG8_MMA(0, 1, At, B1); PG8_BAR; PG8_SCHED;
;             PG8_LDA(At, 1, 1); PG8_STAGE(PG8_SB(1, 0), b3, voffB); PG8_STAGE(PG8_SB(1, 1), b3 + hstepB, voffB); PG8_STAGE(PG8_SA(1, 0), a3, voffA);
;             PG8_WAIT_V(8); PG8_WAIT_L(0); PG8_BAR; PG8_MMA(1, 0, At, B0); PG8_MMA(1, 1, At, B1); PG8_BAR; PG8_SCHED;
	s_add_i32 s40, 0, 0x18000
	s_add_i32 s41, 0, 0x1c000
	ds_read_b128 v[58:61], v178 offset:16384
	ds_read_b128 v[62:65], v178 offset:17408
	ds_read_b128 v[74:77], v178 offset:18432
	ds_read_b128 v[78:81], v178 offset:19456
	ds_read_b128 v[162:165], v178 offset:32768
	ds_read_b128 v[166:169], v178 offset:33792
	ds_read_b128 v[170:173], v178 offset:34816
	ds_read_b128 v[180:183], v178 offset:35840
	s_add_u32 s36, s36, 0x80000
	s_addc_u32 s37, s37, 0
	s_mov_b32 m0, s71
	ds_read_b128 v[184:187], v179 offset:32768
	ds_read_b128 v[188:191], v179 offset:33792
	ds_read_b128 v[192:195], v179 offset:34816
	ds_read_b128 v[196:199], v179 offset:35840
	ds_read_b128 v[200:203], v179 offset:36864
	ds_read_b128 v[204:207], v179 offset:37888
	ds_read_b128 v[208:211], v179 offset:38912
	ds_read_b128 v[212:215], v179 offset:39936
	global_load_lds_dwordx4 v146, s[36:37]
	s_mov_b32 m0, s88
	s_nop 0
	global_load_lds_dwordx4 v150, s[36:37]
	s_waitcnt vmcnt(8) lgkmcnt(0)
	s_barrier
	v_mfma_i32_16x16x64_i8 v[142:145], v[58:61], v[184:187], v[142:145]
	v_mfma_i32_16x16x64_i8 v[138:141], v[74:77], v[184:187], v[138:141]
	v_mfma_i32_16x16x64_i8 v[126:129], v[58:61], v[192:195], v[126:129]
	v_mfma_i32_16x16x64_i8 v[122:125], v[74:77], v[192:195], v[122:125]
	v_mfma_i32_16x16x64_i8 v[110:113], v[58:61], v[200:203], v[110:113]
	v_mfma_i32_16x16x64_i8 v[106:109], v[74:77], v[200:203], v[106:109]
	v_mfma_i32_16x16x64_i8 v[94:97], v[58:61], v[208:211], v[94:97]
	v_mfma_i32_16x16x64_i8 v[90:93], v[74:77], v[208:211], v[90:93]
	v_mfma_i32_16x16x64_i8 v[142:145], v[62:65], v[188:191], v[142:145]
	v_mfma_i32_16x16x64_i8 v[138:141], v[78:81], v[188:191], v[138:141]
	v_mfma_i32_16x16x64_i8 v[126:129], v[62:65], v[196:199], v[126:129]
	v_mfma_i32_16x16x64_i8 v[122:125], v[78:81], v[196:199], v[122:125]
	v_mfma_i32_16x16x64_i8 v[110:113], v[62:65], v[204:207], v[110:113]
	v_mfma_i32_16x16x64_i8 v[106:109], v[78:81], v[204:207], v[106:109]
	v_mfma_i32_16x16x64_i8 v[94:97], v[62:65], v[212:215], v[94:97]
	v_mfma_i32_16x16x64_i8 v[90:93], v[78:81], v[212:215], v[90:93]
	v_mfma_i32_16x16x64_i8 v[134:137], v[162:165], v[184:187], v[134:137]
	v_mfma_i32_16x16x64_i8 v[130:133], v[170:173], v[184:187], v[130:133]
	v_mfma_i32_16x16x64_i8 v[118:121], v[162:165], v[192:195], v[118:121]
	v_mfma_i32_16x16x64_i8 v[114:117], v[170:173], v[192:195], v[114:117]
	v_mfma_i32_16x16x64_i8 v[102:105], v[162:165], v[200:203], v[102:105]
	v_mfma_i32_16x16x64_i8 v[98:101], v[170:173], v[200:203], v[98:101]
	v_mfma_i32_16x16x64_i8 v[86:89], v[162:165], v[208:211], v[86:89]
	v_mfma_i32_16x16x64_i8 v[82:85], v[170:173], v[208:211], v[82:85]
	v_mfma_i32_16x16x64_i8 v[134:137], v[166:169], v[188:191], v[134:137]
	v_mfma_i32_16x16x64_i8 v[130:133], v[180:183], v[188:191], v[130:133]
	v_mfma_i32_16x16x64_i8 v[118:121], v[166:169], v[196:199], v[118:121]
	v_mfma_i32_16x16x64_i8 v[114:117], v[180:183], v[196:199], v[114:117]
	v_mfma_i32_16x16x64_i8 v[102:105], v[166:169], v[204:207], v[102:105]
	v_mfma_i32_16x16x64_i8 v[98:101], v[180:183], v[204:207], v[98:101]
	v_mfma_i32_16x16x64_i8 v[86:89], v[166:169], v[212:215], v[86:89]
	v_mfma_i32_16x16x64_i8 v[82:85], v[180:183], v[212:215], v[82:85]
	s_barrier
	s_add_i32 s36, s40, s68
	s_add_i32 m0, s36, 0xffffff80
	ds_read_b128 v[184:187], v179 offset:49152
	ds_read_b128 v[188:191], v179 offset:50176
	ds_read_b128 v[192:195], v179 offset:51200
	ds_read_b128 v[196:199], v179 offset:52224
	ds_read_b128 v[200:203], v179 offset:53248
	ds_read_b128 v[204:207], v179 offset:54272
	ds_read_b128 v[208:211], v179 offset:55296
	ds_read_b128 v[212:215], v179 offset:56320
	global_load_lds_dwordx4 v148, s[98:99] offset:128
	s_add_i32 m0, s36, 0x1f80
	s_add_u32 s34, s34, 0x80080
	s_addc_u32 s35, s35, 0
	s_add_i32 s36, s41, s68
	global_load_lds_dwordx4 v152, s[98:99] offset:128
	s_mov_b32 m0, s36
	s_nop 0
	global_load_lds_dwordx4 v148, s[34:35]
	s_add_i32 m0, s36, 0x2000
	s_nop 0
	global_load_lds_dwordx4 v152, s[34:35]
	s_add_i32 m0, s92, 0xffffff80
	s_nop 0
	global_load_lds_dwordx4 v146, s[100:101] offset:128
	s_add_i32 m0, s93, 0xffffff80
	s_nop 0
	global_load_lds_dwordx4 v150, s[100:101] offset:128
	s_waitcnt vmcnt(8) lgkmcnt(0)
	s_barrier
	v_mfma_i32_16x16x64_i8 v[70:73], v[58:61], v[184:187], v[70:73]
	v_mfma_i32_16x16x64_i8 v[66:69], v[74:77], v[184:187], v[66:69]
	v_mfma_i32_16x16x64_i8 v[46:49], v[58:61], v[192:195], v[46:49]
	v_mfma_i32_16x16x64_i8 v[42:45], v[74:77], v[192:195], v[42:45]
	v_mfma_i32_16x16x64_i8 v[30:33], v[58:61], v[200:203], v[30:33]
	v_mfma_i32_16x16x64_i8 v[26:29], v[74:77], v[200:203], v[26:29]
	v_mfma_i32_16x16x64_i8 v[14:17], v[58:61], v[208:211], v[14:17]
	v_mfma_i32_16x16x64_i8 v[10:13], v[74:77], v[208:211], v[10:13]
	v_mfma_i32_16x16x64_i8 v[70:73], v[62:65], v[188:191], v[70:73]
	v_mfma_i32_16x16x64_i8 v[66:69], v[78:81], v[188:191], v[66:69]
	v_mfma_i32_16x16x64_i8 v[46:49], v[62:65], v[196:199], v[46:49]
	v_mfma_i32_16x16x64_i8 v[42:45], v[78:81], v[196:199], v[42:45]
	v_mfma_i32_16x16x64_i8 v[30:33], v[62:65], v[204:207], v[30:33]
	v_mfma_i32_16x16x64_i8 v[26:29], v[78:81], v[204:207], v[26:29]
	v_mfma_i32_16x16x64_i8 v[14:17], v[62:65], v[212:215], v[14:17]
	v_mfma_i32_16x16x64_i8 v[10:13], v[78:81], v[212:215], v[10:13]
	v_mfma_i32_16x16x64_i8 v[54:57], v[162:165], v[184:187], v[54:57]
	v_mfma_i32_16x16x64_i8 v[50:53], v[170:173], v[184:187], v[50:53]
	v_mfma_i32_16x16x64_i8 v[38:41], v[162:165], v[192:195], v[38:41]
	v_mfma_i32_16x16x64_i8 v[34:37], v[170:173], v[192:195], v[34:37]
	v_mfma_i32_16x16x64_i8 v[22:25], v[162:165], v[200:203], v[22:25]
	v_mfma_i32_16x16x64_i8 v[18:21], v[170:173], v[200:203], v[18:21]
	v_mfma_i32_16x16x64_i8 v[6:9], v[162:165], v[208:211], v[6:9]
	v_mfma_i32_16x16x64_i8 v[2:5], v[170:173], v[208:211], v[2:5]
	v_mfma_i32_16x16x64_i8 v[54:57], v[166:169], v[188:191], v[54:57]
	v_mfma_i32_16x16x64_i8 v[50:53], v[180:183], v[188:191], v[50:53]
	v_mfma_i32_16x16x64_i8 v[38:41], v[166:169], v[196:199], v[38:41]
	v_mfma_i32_16x16x64_i8 v[34:37], v[180:183], v[196:199], v[34:37]
	v_mfma_i32_16x16x64_i8 v[22:25], v[166:169], v[204:207], v[22:25]
	v_mfma_i32_16x16x64_i8 v[18:21], v[180:183], v[204:207], v[18:21]
	v_mfma_i32_16x16x64_i8 v[6:9], v[166:169], v[212:215], v[6:9]
	v_mfma_i32_16x16x64_i8 v[2:5], v[180:183], v[212:215], v[2:5]
	s_barrier
	s_add_i32 s39, s39, 2
	s_add_u32 s2, s2, 0x100
	s_addc_u32 s3, s3, 0
	s_add_u32 s31, s31, 0x100
	s_addc_u32 s38, s38, 0
	s_cmp_gt_u32 s39, 29
	s_cbranch_scc0 .LBB0_607
	s_and_b64 vcc, exec, s[20:21]
	s_cbranch_vccz .LBB0_610
	s_barrier

; __device__ __forceinline__ unsigned cvt_pk_bf16(float lo, float hi) { unsigned r; asm volatile("s_nop 0\n\tv_cvt_pk_bf16_f32 %0, %1, %2" : "=v"(r) : "v"(lo), "v"(hi)); return r; }
; __device__ __forceinline__ float sigmoidf_(float x) { return __builtin_amdgcn_rcpf(1.0f + __builtin_amdgcn_exp2f(-1.4426950408889634f * x)); }
; __device__ __forceinline__ u32x4 pack8(const f32x4 v0, const f32x4 v1) { u32x4 w; w.x = cvt_pk_bf16(v0[0], v0[1]); w.y = cvt_pk_bf16(v0[2], v0[3]); w.z = cvt_pk_bf16(v1[0], v1[1]); w.w = cvt_pk_bf16(v1[2], v1[3]); return w; }
; __device__ __forceinline__ void unpack8(const u32x4 w, f32x4& v0, f32x4& v1) { v0 = (f32x4){bf_lo(w.x), bf_hi(w.x), bf_lo(w.y), bf_hi(w.y)}; v1 = (f32x4){bf_lo(w.z), bf_hi(w.z), bf_lo(w.w), bf_hi(w.w)}; }
; __device__ __forceinline__ f32x4 sig4(const f32x4 v) { return (f32x4){sigmoidf_(v[0]), sigmoidf_(v[1]), sigmoidf_(v[2]), sigmoidf_(v[3])}; }
;     __device__ __forceinline__ void operator()(const i32x4 (&acc)[2][2][4][2], const Unit& uu, int wr, int wc, int fr, int fq) const {
;     ...
; #pragma unroll
;         for (int ai = 0; ai < 2; ++ai)
; #pragma unroll
;             for (int m = 0; m < 4; ++m) { const int r = row0 + ai * HALF + m * 16; const float rs = rsv[ai][m]; bf16_t* rowp = base + (size_t)r * ldc + col0;
; #pragma unroll
;                 for (int bj = 0; bj < 2; ++bj) { f32x4 v0 = __builtin_convertvector(acc[ai][bj][m][0], f32x4) * rs * sv[bj][0], v1 = __builtin_convertvector(acc[ai][bj][m][1], f32x4) * rs * sv[bj][1];
;                     if (sg) { v0 = sig4(v0); v1 = sig4(v1); }
;                     *(u32x4*)(rowp + bj * HALF) = pack8(v0, v1); } }
.LBB0_620:
	v_cvt_f32_i32_e32 v135, v135
	v_cvt_f32_i32_e32 v137, v137
	v_cvt_f32_i32_e32 v136, v136
	v_cvt_f32_i32_e32 v134, v134
	v_cvt_f32_i32_e32 v131, v131
	v_cvt_f32_i32_e32 v133, v133
	v_cvt_f32_i32_e32 v132, v132
	v_cvt_f32_i32_e32 v130, v130
	v_add_u32_e32 v138, s9, v194
	v_mov_b32_e32 v143, v142
	v_ashrrev_i32_e32 v139, 31, v138
	v_mul_lo_u32 v194, s3, v162
	v_mul_lo_u32 v163, s2, v163
	v_mad_u64_u32 v[140:141], s[30:31], s2, v162, 0
	v_cvt_pk_bf16_f32 v172, v172, v173
	v_cvt_pk_bf16_f32 v173, v170, v171
	v_cvt_pk_bf16_f32 v174, v174, v175
	v_cvt_pk_bf16_f32 v175, v144, v145
	v_mov_b32_e32 v144, v142
	v_mov_b32_e32 v145, v142
	v_lshl_add_u64 v[138:139], v[138:139], 1, s[34:35]
	v_add3_u32 v141, v141, v163, v194
	v_pk_mul_f32 v[136:137], v[144:145], v[136:137]
	v_pk_mul_f32 v[170:171], v[142:143], v[134:135]
	v_pk_mul_f32 v[132:133], v[144:145], v[132:133]
	v_pk_mul_f32 v[130:131], v[142:143], v[130:131]
	s_mov_b64 s[98:99], 0x0
	v_lshl_add_u64 v[140:141], v[248:249], 0, s[98:99]
	v_pk_mul_f32 v[134:135], v[64:65], v[136:137]
	v_pk_mul_f32 v[136:137], v[62:63], v[170:171]
	v_pk_mul_f32 v[132:133], v[60:61], v[132:133]
	s_and_b64 vcc, exec, s[6:7]
	v_pk_mul_f32 v[142:143], v[58:59], v[130:131]
	global_store_dwordx4 v[140:141], v[172:175], off
	s_cbranch_vccnz .LBB0_622
	v_mul_f32_e32 v130, 0xbfb8aa3b, v136
	v_exp_f32_e32 v130, v130
	v_mul_f32_e32 v131, 0xbfb8aa3b, v137
	v_exp_f32_e32 v131, v131
	v_add_f32_e32 v130, 1.0, v130
	v_rcp_f32_e32 v136, v130
	v_mul_f32_e32 v130, 0xbfb8aa3b, v134
	v_add_f32_e32 v131, 1.0, v131
	v_exp_f32_e32 v130, v130
	v_mul_f32_e32 v134, 0xbfb8aa3b, v135
	v_exp_f32_e32 v135, v134
	v_rcp_f32_e32 v137, v131
	v_mul_f32_e32 v131, 0xbfb8aa3b, v142
	v_exp_f32_e32 v131, v131
	v_add_f32_e32 v130, 1.0, v130
	v_rcp_f32_e32 v134, v130
	v_add_f32_e32 v130, 1.0, v135
	v_mul_f32_e32 v135, 0xbfb8aa3b, v143
	v_exp_f32_e32 v143, v135
	v_rcp_f32_e32 v135, v130
	v_add_f32_e32 v130, 1.0, v131
	v_mul_f32_e32 v131, 0xbfb8aa3b, v132
	v_exp_f32_e32 v131, v131
	v_mul_f32_e32 v132, 0xbfb8aa3b, v133
	v_exp_f32_e32 v133, v132
	v_rcp_f32_e32 v142, v130
	v_add_f32_e32 v130, 1.0, v143
	v_rcp_f32_e32 v143, v130
	v_add_f32_e32 v130, 1.0, v131
	v_rcp_f32_e32 v132, v130
	v_add_f32_e32 v130, 1.0, v133
	v_rcp_f32_e32 v133, v130
.LBB0_622:
	v_cvt_f32_i32_e32 v129, v129
	v_cvt_f32_i32_e32 v128, v128
	v_cvt_pk_bf16_f32 v170, v136, v137
	v_cvt_pk_bf16_f32 v171, v134, v135
	v_cvt_pk_bf16_f32 v172, v142, v143
	v_cvt_f32_i32_e32 v127, v127
	v_cvt_f32_i32_e32 v126, v126
	v_cvt_pk_bf16_f32 v173, v132, v133
	v_cvt_f32_i32_e32 v133, v125
	v_cvt_f32_i32_e32 v123, v123
	v_cvt_f32_i32_e32 v122, v122
	v_cvt_f32_i32_e32 v132, v124
	v_mul_f32_e32 v130, v192, v193
	v_pk_mul_f32 v[128:129], v[130:131], v[128:129] op_sel_hi:[0,1]
	v_pk_mul_f32 v[126:127], v[130:131], v[126:127] op_sel_hi:[0,1]
	v_pk_mul_f32 v[124:125], v[80:81], v[128:129]
	v_pk_mul_f32 v[122:123], v[130:131], v[122:123] op_sel_hi:[0,1]
	v_pk_mul_f32 v[128:129], v[130:131], v[132:133] op_sel_hi:[0,1]
	v_pk_mul_f32 v[126:127], v[78:79], v[126:127]
	v_pk_mul_f32 v[128:129], v[76:77], v[128:129]
	s_and_b64 vcc, exec, s[6:7]
	v_pk_mul_f32 v[132:133], v[74:75], v[122:123]
	global_store_dwordx4 v[140:141], v[170:173], off offset:1024
	s_cbranch_vccnz .LBB0_624
	v_mul_f32_e32 v122, 0xbfb8aa3b, v126
	v_exp_f32_e32 v122, v122
	v_mul_f32_e32 v123, 0xbfb8aa3b, v127
	v_exp_f32_e32 v123, v123
	v_add_f32_e32 v122, 1.0, v122
	v_rcp_f32_e32 v126, v122
	v_mul_f32_e32 v122, 0xbfb8aa3b, v124
	v_add_f32_e32 v123, 1.0, v123
	v_exp_f32_e32 v122, v122
	v_mul_f32_e32 v124, 0xbfb8aa3b, v125
	v_exp_f32_e32 v125, v124
	v_rcp_f32_e32 v127, v123
	v_mul_f32_e32 v123, 0xbfb8aa3b, v132
	v_exp_f32_e32 v123, v123
	v_add_f32_e32 v122, 1.0, v122
	v_rcp_f32_e32 v124, v122
	v_add_f32_e32 v122, 1.0, v125
	v_mul_f32_e32 v125, 0xbfb8aa3b, v133
	v_exp_f32_e32 v131, v125
	v_rcp_f32_e32 v125, v122
	v_add_f32_e32 v122, 1.0, v123
	v_mul_f32_e32 v123, 0xbfb8aa3b, v128
	v_exp_f32_e32 v123, v123
	v_mul_f32_e32 v128, 0xbfb8aa3b, v129
	v_exp_f32_e32 v129, v128
	v_rcp_f32_e32 v132, v122
	v_add_f32_e32 v122, 1.0, v131
	v_rcp_f32_e32 v133, v122
	v_add_f32_e32 v122, 1.0, v123
	v_rcp_f32_e32 v128, v122
	v_add_f32_e32 v122, 1.0, v129
	v_rcp_f32_e32 v129, v122
.LBB0_624:
	v_cvt_f32_i32_e32 v119, v119
	v_cvt_f32_i32_e32 v121, v121
	v_cvt_f32_i32_e32 v120, v120
	v_cvt_f32_i32_e32 v118, v118
	v_cvt_f32_i32_e32 v115, v115
	v_cvt_f32_i32_e32 v117, v117
	v_cvt_f32_i32_e32 v116, v116
	v_cvt_f32_i32_e32 v114, v114
	v_mul_lo_u32 v134, s3, v168
	v_mul_lo_u32 v135, s2, v169
	v_mad_u64_u32 v[122:123], s[30:31], s2, v168, 0
	v_mov_b32_e32 v131, v130
	v_add3_u32 v123, v123, v135, v134
	v_cvt_pk_bf16_f32 v134, v126, v127
	v_cvt_pk_bf16_f32 v135, v124, v125
	v_mov_b32_e32 v124, v130
	v_mov_b32_e32 v125, v130
	v_pk_mul_f32 v[120:121], v[124:125], v[120:121]
	v_pk_mul_f32 v[126:127], v[130:131], v[118:119]
	v_pk_mul_f32 v[116:117], v[124:125], v[116:117]
	v_pk_mul_f32 v[114:115], v[130:131], v[114:115]
	s_mov_b64 s[98:99], 0x800
	v_lshl_add_u64 v[122:123], v[248:249], 0, s[98:99]
	v_pk_mul_f32 v[118:119], v[64:65], v[120:121]
	v_pk_mul_f32 v[120:121], v[62:63], v[126:127]
	v_pk_mul_f32 v[116:117], v[60:61], v[116:117]
	s_and_b64 vcc, exec, s[6:7]
	v_pk_mul_f32 v[124:125], v[58:59], v[114:115]
	v_cvt_pk_bf16_f32 v136, v132, v133
	v_cvt_pk_bf16_f32 v137, v128, v129
	global_store_dwordx4 v[122:123], v[134:137], off
	s_cbranch_vccnz .LBB0_626
	v_mul_f32_e32 v114, 0xbfb8aa3b, v120
	v_exp_f32_e32 v114, v114
	v_mul_f32_e32 v115, 0xbfb8aa3b, v121
	v_exp_f32_e32 v115, v115
	v_add_f32_e32 v114, 1.0, v114
	v_rcp_f32_e32 v120, v114
	v_mul_f32_e32 v114, 0xbfb8aa3b, v118
	v_add_f32_e32 v115, 1.0, v115
	v_exp_f32_e32 v114, v114
	v_mul_f32_e32 v118, 0xbfb8aa3b, v119
	v_exp_f32_e32 v119, v118
	v_rcp_f32_e32 v121, v115
	v_mul_f32_e32 v115, 0xbfb8aa3b, v124
	v_exp_f32_e32 v115, v115
	v_add_f32_e32 v114, 1.0, v114
	v_rcp_f32_e32 v118, v114
	v_add_f32_e32 v114, 1.0, v119
	v_mul_f32_e32 v119, 0xbfb8aa3b, v125
	v_exp_f32_e32 v125, v119
	v_rcp_f32_e32 v119, v114
	v_add_f32_e32 v114, 1.0, v115
	v_mul_f32_e32 v115, 0xbfb8aa3b, v116
	v_exp_f32_e32 v115, v115
	v_mul_f32_e32 v116, 0xbfb8aa3b, v117
	v_exp_f32_e32 v117, v116
	v_rcp_f32_e32 v124, v114
	v_add_f32_e32 v114, 1.0, v125
	v_rcp_f32_e32 v125, v114
	v_add_f32_e32 v114, 1.0, v115
	v_rcp_f32_e32 v116, v114
	v_add_f32_e32 v114, 1.0, v117
	v_rcp_f32_e32 v117, v114
; __device__ __forceinline__ unsigned cvt_pk_bf16(float lo, float hi) { unsigned r; asm volatile("s_nop 0\n\tv_cvt_pk_bf16_f32 %0, %1, %2" : "=v"(r) : "v"(lo), "v"(hi)); return r; }
; __device__ __forceinline__ float sigmoidf_(float x) { return __builtin_amdgcn_rcpf(1.0f + __builtin_amdgcn_exp2f(-1.4426950408889634f * x)); }
; __device__ __forceinline__ u32x4 pack8(const f32x4 v0, const f32x4 v1) { u32x4 w; w.x = cvt_pk_bf16(v0[0], v0[1]); w.y = cvt_pk_bf16(v0[2], v0[3]); w.z = cvt_pk_bf16(v1[0], v1[1]); w.w = cvt_pk_bf16(v1[2], v1[3]); return w; }
; __device__ __forceinline__ void unpack8(const u32x4 w, f32x4& v0, f32x4& v1) { v0 = (f32x4){bf_lo(w.x), bf_hi(w.x), bf_lo(w.y), bf_hi(w.y)}; v1 = (f32x4){bf_lo(w.z), bf_hi(w.z), bf_lo(w.w), bf_hi(w.w)}; }
; __device__ __forceinline__ f32x4 sig4(const f32x4 v) { return (f32x4){sigmoidf_(v[0]), sigmoidf_(v[1]), sigmoidf_(v[2]), sigmoidf_(v[3])}; }
;     __device__ __forceinline__ void operator()(const i32x4 (&acc)[2][2][4][2], const Unit& uu, int wr, int wc, int fr, int fq) const {
;     ...
; #pragma unroll
;         for (int ai = 0; ai < 2; ++ai)
; #pragma unroll
;             for (int m = 0; m < 4; ++m) { const int r = row0 + ai * HALF + m * 16; const float rs = rsv[ai][m]; bf16_t* rowp = base + (size_t)r * ldc + col0;
; #pragma unroll
;                 for (int bj = 0; bj < 2; ++bj) { f32x4 v0 = __builtin_convertvector(acc[ai][bj][m][0], f32x4) * rs * sv[bj][0], v1 = __builtin_convertvector(acc[ai][bj][m][1], f32x4) * rs * sv[bj][1];
;                     if (sg) { v0 = sig4(v0); v1 = sig4(v1); }
;                     *(u32x4*)(rowp + bj * HALF) = pack8(v0, v1); } }
.LBB0_626:
	v_cvt_f32_i32_e32 v113, v113
	v_cvt_f32_i32_e32 v112, v112
	v_cvt_pk_bf16_f32 v126, v120, v121
	v_cvt_pk_bf16_f32 v127, v118, v119
	v_cvt_pk_bf16_f32 v128, v124, v125
	v_cvt_f32_i32_e32 v111, v111
	v_cvt_f32_i32_e32 v110, v110
	v_cvt_pk_bf16_f32 v129, v116, v117
	v_cvt_f32_i32_e32 v117, v109
	v_cvt_f32_i32_e32 v107, v107
	v_cvt_f32_i32_e32 v106, v106
	v_cvt_f32_i32_e32 v116, v108
	v_mul_f32_e32 v114, v190, v191
	v_pk_mul_f32 v[112:113], v[114:115], v[112:113] op_sel_hi:[0,1]
	v_pk_mul_f32 v[110:111], v[114:115], v[110:111] op_sel_hi:[0,1]
	v_pk_mul_f32 v[108:109], v[80:81], v[112:113]
	v_pk_mul_f32 v[106:107], v[114:115], v[106:107] op_sel_hi:[0,1]
	v_pk_mul_f32 v[112:113], v[114:115], v[116:117] op_sel_hi:[0,1]
	v_pk_mul_f32 v[110:111], v[78:79], v[110:111]
	v_pk_mul_f32 v[112:113], v[76:77], v[112:113]
	s_and_b64 vcc, exec, s[6:7]
	v_pk_mul_f32 v[116:117], v[74:75], v[106:107]
	global_store_dwordx4 v[122:123], v[126:129], off offset:1024
	s_cbranch_vccnz .LBB0_628
	v_mul_f32_e32 v106, 0xbfb8aa3b, v110
	v_exp_f32_e32 v106, v106
	v_mul_f32_e32 v107, 0xbfb8aa3b, v111
	v_exp_f32_e32 v107, v107
	v_add_f32_e32 v106, 1.0, v106
	v_rcp_f32_e32 v110, v106
	v_mul_f32_e32 v106, 0xbfb8aa3b, v108
	v_add_f32_e32 v107, 1.0, v107
	v_exp_f32_e32 v106, v106
	v_mul_f32_e32 v108, 0xbfb8aa3b, v109
	v_exp_f32_e32 v109, v108
	v_rcp_f32_e32 v111, v107
	v_mul_f32_e32 v107, 0xbfb8aa3b, v116
	v_exp_f32_e32 v107, v107
	v_add_f32_e32 v106, 1.0, v106
	v_rcp_f32_e32 v108, v106
	v_add_f32_e32 v106, 1.0, v109
	v_mul_f32_e32 v109, 0xbfb8aa3b, v117
	v_exp_f32_e32 v115, v109
	v_rcp_f32_e32 v109, v106
	v_add_f32_e32 v106, 1.0, v107
	v_mul_f32_e32 v107, 0xbfb8aa3b, v112
	v_exp_f32_e32 v107, v107
	v_mul_f32_e32 v112, 0xbfb8aa3b, v113
	v_exp_f32_e32 v113, v112
	v_rcp_f32_e32 v116, v106
	v_add_f32_e32 v106, 1.0, v115
	v_rcp_f32_e32 v117, v106
	v_add_f32_e32 v106, 1.0, v107
	v_rcp_f32_e32 v112, v106
	v_add_f32_e32 v106, 1.0, v113
	v_rcp_f32_e32 v113, v106
.LBB0_628:
	v_cvt_f32_i32_e32 v103, v103
	v_cvt_f32_i32_e32 v105, v105
	v_cvt_f32_i32_e32 v104, v104
	v_cvt_f32_i32_e32 v102, v102
	v_cvt_f32_i32_e32 v99, v99
	v_cvt_f32_i32_e32 v101, v101
	v_cvt_f32_i32_e32 v100, v100
	v_cvt_f32_i32_e32 v98, v98
	v_mul_lo_u32 v118, s3, v166
	v_mul_lo_u32 v119, s2, v167
	v_mad_u64_u32 v[106:107], s[30:31], s2, v166, 0
	v_mov_b32_e32 v115, v114
	v_add3_u32 v107, v107, v119, v118
	v_cvt_pk_bf16_f32 v118, v110, v111
	v_cvt_pk_bf16_f32 v119, v108, v109
	v_mov_b32_e32 v108, v114
	v_mov_b32_e32 v109, v114
	v_pk_mul_f32 v[104:105], v[108:109], v[104:105]
	v_pk_mul_f32 v[110:111], v[114:115], v[102:103]
	v_pk_mul_f32 v[100:101], v[108:109], v[100:101]
	v_pk_mul_f32 v[98:99], v[114:115], v[98:99]
	s_mov_b64 s[98:99], 0x1000
	v_lshl_add_u64 v[106:107], v[248:249], 0, s[98:99]
	v_pk_mul_f32 v[102:103], v[64:65], v[104:105]
	v_pk_mul_f32 v[104:105], v[62:63], v[110:111]
	v_pk_mul_f32 v[100:101], v[60:61], v[100:101]
	s_and_b64 vcc, exec, s[6:7]
	v_pk_mul_f32 v[108:109], v[58:59], v[98:99]
	v_cvt_pk_bf16_f32 v120, v116, v117
	v_cvt_pk_bf16_f32 v121, v112, v113
	global_store_dwordx4 v[106:107], v[118:121], off
	s_cbranch_vccnz .LBB0_630
	v_mul_f32_e32 v98, 0xbfb8aa3b, v104
	v_exp_f32_e32 v98, v98
	v_mul_f32_e32 v99, 0xbfb8aa3b, v105
	v_exp_f32_e32 v99, v99
	v_add_f32_e32 v98, 1.0, v98
	v_rcp_f32_e32 v104, v98
	v_mul_f32_e32 v98, 0xbfb8aa3b, v102
	v_add_f32_e32 v99, 1.0, v99
	v_exp_f32_e32 v98, v98
	v_mul_f32_e32 v102, 0xbfb8aa3b, v103
	v_exp_f32_e32 v103, v102
	v_rcp_f32_e32 v105, v99
	v_mul_f32_e32 v99, 0xbfb8aa3b, v108
	v_exp_f32_e32 v99, v99
	v_add_f32_e32 v98, 1.0, v98
	v_rcp_f32_e32 v102, v98
	v_add_f32_e32 v98, 1.0, v103
	v_mul_f32_e32 v103, 0xbfb8aa3b, v109
	v_exp_f32_e32 v109, v103
	v_rcp_f32_e32 v103, v98
	v_add_f32_e32 v98, 1.0, v99
	v_mul_f32_e32 v99, 0xbfb8aa3b, v100
	v_exp_f32_e32 v99, v99
	v_mul_f32_e32 v100, 0xbfb8aa3b, v101
	v_exp_f32_e32 v101, v100
	v_rcp_f32_e32 v108, v98
	v_add_f32_e32 v98, 1.0, v109
	v_rcp_f32_e32 v109, v98
	v_add_f32_e32 v98, 1.0, v99
	v_rcp_f32_e32 v100, v98
	v_add_f32_e32 v98, 1.0, v101
	v_rcp_f32_e32 v101, v98
.LBB0_630:
	v_cvt_f32_i32_e32 v97, v97
	v_cvt_f32_i32_e32 v96, v96
	v_cvt_pk_bf16_f32 v110, v104, v105
	v_cvt_pk_bf16_f32 v111, v102, v103
	v_cvt_pk_bf16_f32 v112, v108, v109
	v_cvt_f32_i32_e32 v95, v95
	v_cvt_f32_i32_e32 v94, v94
	v_cvt_pk_bf16_f32 v113, v100, v101
	v_cvt_f32_i32_e32 v101, v93
	v_cvt_f32_i32_e32 v91, v91
	v_cvt_f32_i32_e32 v90, v90
	v_cvt_f32_i32_e32 v100, v92
	v_mul_f32_e32 v98, v188, v189
	v_pk_mul_f32 v[96:97], v[98:99], v[96:97] op_sel_hi:[0,1]
	v_pk_mul_f32 v[94:95], v[98:99], v[94:95] op_sel_hi:[0,1]
	v_pk_mul_f32 v[92:93], v[80:81], v[96:97]
	v_pk_mul_f32 v[90:91], v[98:99], v[90:91] op_sel_hi:[0,1]
	v_pk_mul_f32 v[96:97], v[98:99], v[100:101] op_sel_hi:[0,1]
	v_pk_mul_f32 v[94:95], v[78:79], v[94:95]
	v_pk_mul_f32 v[96:97], v[76:77], v[96:97]
	s_and_b64 vcc, exec, s[6:7]
	v_pk_mul_f32 v[100:101], v[74:75], v[90:91]
	global_store_dwordx4 v[106:107], v[110:113], off offset:1024
	s_cbranch_vccnz .LBB0_632
	v_mul_f32_e32 v90, 0xbfb8aa3b, v94
	v_exp_f32_e32 v90, v90
	v_mul_f32_e32 v91, 0xbfb8aa3b, v95
	v_exp_f32_e32 v91, v91
	v_add_f32_e32 v90, 1.0, v90
	v_rcp_f32_e32 v94, v90
	v_mul_f32_e32 v90, 0xbfb8aa3b, v92
	v_add_f32_e32 v91, 1.0, v91
	v_exp_f32_e32 v90, v90
	v_mul_f32_e32 v92, 0xbfb8aa3b, v93
	v_exp_f32_e32 v93, v92
	v_rcp_f32_e32 v95, v91
	v_mul_f32_e32 v91, 0xbfb8aa3b, v100
	v_exp_f32_e32 v91, v91
	v_add_f32_e32 v90, 1.0, v90
	v_rcp_f32_e32 v92, v90
	v_add_f32_e32 v90, 1.0, v93
	v_mul_f32_e32 v93, 0xbfb8aa3b, v101
	v_exp_f32_e32 v99, v93
	v_rcp_f32_e32 v93, v90
	v_add_f32_e32 v90, 1.0, v91
	v_mul_f32_e32 v91, 0xbfb8aa3b, v96
	v_exp_f32_e32 v91, v91
	v_mul_f32_e32 v96, 0xbfb8aa3b, v97
	v_exp_f32_e32 v97, v96
	v_rcp_f32_e32 v100, v90
	v_add_f32_e32 v90, 1.0, v99
	v_rcp_f32_e32 v101, v90
	v_add_f32_e32 v90, 1.0, v91
	v_rcp_f32_e32 v96, v90
	v_add_f32_e32 v90, 1.0, v97
	v_rcp_f32_e32 v97, v90
; __device__ __forceinline__ u32x4 pack8(const f32x4 v0, const f32x4 v1) { u32x4 w; w.x = cvt_pk_bf16(v0[0], v0[1]); w.y = cvt_pk_bf16(v0[2], v0[3]); w.z = cvt_pk_bf16(v1[0], v1[1]); w.w = cvt_pk_bf16(v1[2], v1[3]); return w; }
; __device__ __forceinline__ f32x4 sig4(const f32x4 v) { return (f32x4){sigmoidf_(v[0]), sigmoidf_(v[1]), sigmoidf_(v[2]), sigmoidf_(v[3])}; }
;     __device__ __forceinline__ void operator()(const i32x4 (&acc)[2][2][4][2], const Unit& uu, int wr, int wc, int fr, int fq) const {
;     ...
;         for (int ai = 0; ai < 2; ++ai)
; #pragma unroll
;             for (int m = 0; m < 4; ++m) { const int r = row0 + ai * HALF + m * 16; const float rs = rsv[ai][m]; bf16_t* rowp = base + (size_t)r * ldc + col0;
; #pragma unroll
;                 for (int bj = 0; bj < 2; ++bj) { f32x4 v0 = __builtin_convertvector(acc[ai][bj][m][0], f32x4) * rs * sv[bj][0], v1 = __builtin_convertvector(acc[ai][bj][m][1], f32x4) * rs * sv[bj][1];
;                     if (sg) { v0 = sig4(v0); v1 = sig4(v1); }
;                     *(u32x4*)(rowp + bj * HALF) = pack8(v0, v1); } }
.LBB0_632:
	v_cvt_f32_i32_e32 v87, v87
	v_cvt_f32_i32_e32 v89, v89
	v_cvt_f32_i32_e32 v88, v88
	v_cvt_f32_i32_e32 v86, v86
	v_cvt_f32_i32_e32 v83, v83
	v_cvt_f32_i32_e32 v85, v85
	v_cvt_f32_i32_e32 v84, v84
	v_cvt_f32_i32_e32 v82, v82
	v_mul_lo_u32 v102, s3, v164
	v_mul_lo_u32 v103, s2, v165
	v_mad_u64_u32 v[90:91], s[30:31], s2, v164, 0
	v_mov_b32_e32 v99, v98
	v_add3_u32 v91, v91, v103, v102
	v_cvt_pk_bf16_f32 v102, v94, v95
	v_cvt_pk_bf16_f32 v103, v92, v93
	v_mov_b32_e32 v92, v98
	v_mov_b32_e32 v93, v98
	v_pk_mul_f32 v[88:89], v[92:93], v[88:89]
	v_pk_mul_f32 v[94:95], v[98:99], v[86:87]
	v_pk_mul_f32 v[84:85], v[92:93], v[84:85]
	v_pk_mul_f32 v[82:83], v[98:99], v[82:83]
	s_mov_b64 s[98:99], 0x1800
	v_lshl_add_u64 v[90:91], v[248:249], 0, s[98:99]
	v_pk_mul_f32 v[86:87], v[64:65], v[88:89]
	v_pk_mul_f32 v[88:89], v[62:63], v[94:95]
	v_pk_mul_f32 v[84:85], v[60:61], v[84:85]
	s_and_b64 vcc, exec, s[6:7]
	v_pk_mul_f32 v[92:93], v[58:59], v[82:83]
	v_cvt_pk_bf16_f32 v104, v100, v101
	v_cvt_pk_bf16_f32 v105, v96, v97
	global_store_dwordx4 v[90:91], v[102:105], off
	s_cbranch_vccnz .LBB0_634
	v_mul_f32_e32 v82, 0xbfb8aa3b, v88
	v_exp_f32_e32 v82, v82
	v_mul_f32_e32 v83, 0xbfb8aa3b, v89
	v_exp_f32_e32 v83, v83
	v_add_f32_e32 v82, 1.0, v82
	v_rcp_f32_e32 v88, v82
	v_mul_f32_e32 v82, 0xbfb8aa3b, v86
	v_add_f32_e32 v83, 1.0, v83
	v_exp_f32_e32 v82, v82
	v_mul_f32_e32 v86, 0xbfb8aa3b, v87
	v_exp_f32_e32 v87, v86
	v_rcp_f32_e32 v89, v83
	v_mul_f32_e32 v83, 0xbfb8aa3b, v92
	v_exp_f32_e32 v83, v83
	v_add_f32_e32 v82, 1.0, v82
	v_rcp_f32_e32 v86, v82
	v_add_f32_e32 v82, 1.0, v87
	v_mul_f32_e32 v87, 0xbfb8aa3b, v93
	v_exp_f32_e32 v93, v87
	v_rcp_f32_e32 v87, v82
	v_add_f32_e32 v82, 1.0, v83
	v_mul_f32_e32 v83, 0xbfb8aa3b, v84
	v_exp_f32_e32 v83, v83
	v_mul_f32_e32 v84, 0xbfb8aa3b, v85
	v_exp_f32_e32 v85, v84
	v_rcp_f32_e32 v92, v82
	v_add_f32_e32 v82, 1.0, v93
	v_rcp_f32_e32 v93, v82
	v_add_f32_e32 v82, 1.0, v83
	v_rcp_f32_e32 v84, v82
	v_add_f32_e32 v82, 1.0, v85
	v_rcp_f32_e32 v85, v82
.LBB0_634:
	v_cvt_f32_i32_e32 v73, v73
	v_cvt_f32_i32_e32 v72, v72
	v_cvt_pk_bf16_f32 v94, v88, v89
	v_cvt_pk_bf16_f32 v95, v86, v87
	v_cvt_pk_bf16_f32 v96, v92, v93
	v_cvt_f32_i32_e32 v71, v71
	v_cvt_f32_i32_e32 v70, v70
	v_cvt_pk_bf16_f32 v97, v84, v85
	v_cvt_f32_i32_e32 v85, v69
	v_cvt_f32_i32_e32 v67, v67
	v_cvt_f32_i32_e32 v66, v66
	v_cvt_f32_i32_e32 v84, v68
	v_mul_f32_e32 v82, v186, v187
	v_pk_mul_f32 v[72:73], v[82:83], v[72:73] op_sel_hi:[0,1]
	v_pk_mul_f32 v[70:71], v[82:83], v[70:71] op_sel_hi:[0,1]
	v_pk_mul_f32 v[68:69], v[80:81], v[72:73]
	v_pk_mul_f32 v[66:67], v[82:83], v[66:67] op_sel_hi:[0,1]
	v_pk_mul_f32 v[72:73], v[82:83], v[84:85] op_sel_hi:[0,1]
	v_pk_mul_f32 v[70:71], v[78:79], v[70:71]
	v_pk_mul_f32 v[72:73], v[76:77], v[72:73]
	s_and_b64 vcc, exec, s[6:7]
	v_pk_mul_f32 v[84:85], v[74:75], v[66:67]
	global_store_dwordx4 v[90:91], v[94:97], off offset:1024
	s_cbranch_vccnz .LBB0_636
	v_mul_f32_e32 v66, 0xbfb8aa3b, v70
	v_exp_f32_e32 v66, v66
	v_mul_f32_e32 v67, 0xbfb8aa3b, v71
	v_exp_f32_e32 v67, v67
	v_add_f32_e32 v66, 1.0, v66
	v_rcp_f32_e32 v70, v66
	v_mul_f32_e32 v66, 0xbfb8aa3b, v68
	v_add_f32_e32 v67, 1.0, v67
	v_exp_f32_e32 v66, v66
	v_mul_f32_e32 v68, 0xbfb8aa3b, v69
	v_exp_f32_e32 v69, v68
	v_rcp_f32_e32 v71, v67
	v_mul_f32_e32 v67, 0xbfb8aa3b, v84
	v_exp_f32_e32 v67, v67
	v_add_f32_e32 v66, 1.0, v66
	v_rcp_f32_e32 v68, v66
	v_add_f32_e32 v66, 1.0, v69
	v_mul_f32_e32 v69, 0xbfb8aa3b, v85
	v_exp_f32_e32 v83, v69
	v_rcp_f32_e32 v69, v66
	v_add_f32_e32 v66, 1.0, v67
	v_mul_f32_e32 v67, 0xbfb8aa3b, v72
	v_exp_f32_e32 v67, v67
	v_mul_f32_e32 v72, 0xbfb8aa3b, v73
	v_exp_f32_e32 v73, v72
	v_rcp_f32_e32 v84, v66
	v_add_f32_e32 v66, 1.0, v83
	v_rcp_f32_e32 v85, v66
	v_add_f32_e32 v66, 1.0, v67
	v_rcp_f32_e32 v72, v66
	v_add_f32_e32 v66, 1.0, v73
	v_rcp_f32_e32 v73, v66
.LBB0_636:
	v_add_u32_e32 v66, 0x80, v162
	v_cvt_f32_i32_e32 v55, v55
	v_cvt_f32_i32_e32 v57, v57
	v_cvt_f32_i32_e32 v56, v56
	v_cvt_f32_i32_e32 v54, v54
	v_cvt_f32_i32_e32 v51, v51
	v_cvt_f32_i32_e32 v53, v53
	v_cvt_f32_i32_e32 v52, v52
	v_cvt_f32_i32_e32 v50, v50
	v_ashrrev_i32_e32 v67, 31, v66
	v_mul_lo_u32 v86, s2, v67
	v_mul_lo_u32 v87, s3, v66
	v_mad_u64_u32 v[66:67], s[30:31], s2, v66, 0
	v_mov_b32_e32 v83, v82
	v_add3_u32 v67, v67, v86, v87
	v_cvt_pk_bf16_f32 v86, v70, v71
	v_cvt_pk_bf16_f32 v87, v68, v69
	v_mov_b32_e32 v68, v82
	v_mov_b32_e32 v69, v82
	v_pk_mul_f32 v[56:57], v[68:69], v[56:57]
	v_pk_mul_f32 v[70:71], v[82:83], v[54:55]
	v_pk_mul_f32 v[52:53], v[68:69], v[52:53]
	v_pk_mul_f32 v[50:51], v[82:83], v[50:51]
	s_mov_b64 s[98:99], 0x2000
	v_lshl_add_u64 v[66:67], v[248:249], 0, s[98:99]
	v_pk_mul_f32 v[54:55], v[64:65], v[56:57]
	v_pk_mul_f32 v[56:57], v[62:63], v[70:71]
	v_pk_mul_f32 v[52:53], v[60:61], v[52:53]
	s_and_b64 vcc, exec, s[6:7]
	v_pk_mul_f32 v[68:69], v[58:59], v[50:51]
	v_cvt_pk_bf16_f32 v88, v84, v85
	v_cvt_pk_bf16_f32 v89, v72, v73
	global_store_dwordx4 v[66:67], v[86:89], off
	s_cbranch_vccnz .LBB0_638
	v_mul_f32_e32 v50, 0xbfb8aa3b, v56
	v_exp_f32_e32 v50, v50
	v_mul_f32_e32 v51, 0xbfb8aa3b, v57
	v_exp_f32_e32 v51, v51
	v_add_f32_e32 v50, 1.0, v50
	v_rcp_f32_e32 v56, v50
	v_mul_f32_e32 v50, 0xbfb8aa3b, v54
	v_add_f32_e32 v51, 1.0, v51
	v_exp_f32_e32 v50, v50
	v_mul_f32_e32 v54, 0xbfb8aa3b, v55
	v_exp_f32_e32 v55, v54
	v_rcp_f32_e32 v57, v51
	v_mul_f32_e32 v51, 0xbfb8aa3b, v68
	v_exp_f32_e32 v51, v51
	v_add_f32_e32 v50, 1.0, v50
	v_rcp_f32_e32 v54, v50
	v_add_f32_e32 v50, 1.0, v55
	v_mul_f32_e32 v55, 0xbfb8aa3b, v69
	v_exp_f32_e32 v69, v55
	v_rcp_f32_e32 v55, v50
	v_add_f32_e32 v50, 1.0, v51
	v_mul_f32_e32 v51, 0xbfb8aa3b, v52
	v_exp_f32_e32 v51, v51
	v_mul_f32_e32 v52, 0xbfb8aa3b, v53
	v_exp_f32_e32 v53, v52
	v_rcp_f32_e32 v68, v50
	v_add_f32_e32 v50, 1.0, v69
	v_rcp_f32_e32 v69, v50
	v_add_f32_e32 v50, 1.0, v51
	v_rcp_f32_e32 v52, v50
	v_add_f32_e32 v50, 1.0, v53
	v_rcp_f32_e32 v53, v50
; __device__ __forceinline__ u32x4 pack8(const f32x4 v0, const f32x4 v1) { u32x4 w; w.x = cvt_pk_bf16(v0[0], v0[1]); w.y = cvt_pk_bf16(v0[2], v0[3]); w.z = cvt_pk_bf16(v1[0], v1[1]); w.w = cvt_pk_bf16(v1[2], v1[3]); return w; }
; __device__ __forceinline__ f32x4 sig4(const f32x4 v) { return (f32x4){sigmoidf_(v[0]), sigmoidf_(v[1]), sigmoidf_(v[2]), sigmoidf_(v[3])}; }
;     __device__ __forceinline__ void operator()(const i32x4 (&acc)[2][2][4][2], const Unit& uu, int wr, int wc, int fr, int fq) const {
;     ...
;         for (int ai = 0; ai < 2; ++ai)
; #pragma unroll
;             for (int m = 0; m < 4; ++m) { const int r = row0 + ai * HALF + m * 16; const float rs = rsv[ai][m]; bf16_t* rowp = base + (size_t)r * ldc + col0;
; #pragma unroll
;                 for (int bj = 0; bj < 2; ++bj) { f32x4 v0 = __builtin_convertvector(acc[ai][bj][m][0], f32x4) * rs * sv[bj][0], v1 = __builtin_convertvector(acc[ai][bj][m][1], f32x4) * rs * sv[bj][1];
;                     if (sg) { v0 = sig4(v0); v1 = sig4(v1); }
;                     *(u32x4*)(rowp + bj * HALF) = pack8(v0, v1); } }
.LBB0_638:
	v_cvt_f32_i32_e32 v49, v49
	v_cvt_f32_i32_e32 v48, v48
	v_cvt_pk_bf16_f32 v70, v56, v57
	v_cvt_pk_bf16_f32 v71, v54, v55
	v_cvt_pk_bf16_f32 v72, v68, v69
	v_cvt_f32_i32_e32 v47, v47
	v_cvt_f32_i32_e32 v46, v46
	v_cvt_pk_bf16_f32 v73, v52, v53
	v_cvt_f32_i32_e32 v53, v45
	v_cvt_f32_i32_e32 v43, v43
	v_cvt_f32_i32_e32 v42, v42
	v_cvt_f32_i32_e32 v52, v44
	v_mul_f32_e32 v50, v184, v185
	v_pk_mul_f32 v[48:49], v[50:51], v[48:49] op_sel_hi:[0,1]
	v_pk_mul_f32 v[46:47], v[50:51], v[46:47] op_sel_hi:[0,1]
	v_pk_mul_f32 v[44:45], v[80:81], v[48:49]
	v_pk_mul_f32 v[42:43], v[50:51], v[42:43] op_sel_hi:[0,1]
	v_pk_mul_f32 v[48:49], v[50:51], v[52:53] op_sel_hi:[0,1]
	v_pk_mul_f32 v[46:47], v[78:79], v[46:47]
	v_pk_mul_f32 v[48:49], v[76:77], v[48:49]
	s_and_b64 vcc, exec, s[6:7]
	v_pk_mul_f32 v[52:53], v[74:75], v[42:43]
	global_store_dwordx4 v[66:67], v[70:73], off offset:1024
	s_cbranch_vccnz .LBB0_640
	v_mul_f32_e32 v42, 0xbfb8aa3b, v46
	v_exp_f32_e32 v42, v42
	v_mul_f32_e32 v43, 0xbfb8aa3b, v47
	v_exp_f32_e32 v43, v43
	v_add_f32_e32 v42, 1.0, v42
	v_rcp_f32_e32 v46, v42
	v_mul_f32_e32 v42, 0xbfb8aa3b, v44
	v_add_f32_e32 v43, 1.0, v43
	v_exp_f32_e32 v42, v42
	v_mul_f32_e32 v44, 0xbfb8aa3b, v45
	v_exp_f32_e32 v45, v44
	v_rcp_f32_e32 v47, v43
	v_mul_f32_e32 v43, 0xbfb8aa3b, v52
	v_exp_f32_e32 v43, v43
	v_add_f32_e32 v42, 1.0, v42
	v_rcp_f32_e32 v44, v42
	v_add_f32_e32 v42, 1.0, v45
	v_mul_f32_e32 v45, 0xbfb8aa3b, v53
	v_exp_f32_e32 v51, v45
	v_rcp_f32_e32 v45, v42
	v_add_f32_e32 v42, 1.0, v43
	v_mul_f32_e32 v43, 0xbfb8aa3b, v48
	v_exp_f32_e32 v43, v43
	v_mul_f32_e32 v48, 0xbfb8aa3b, v49
	v_exp_f32_e32 v49, v48
	v_rcp_f32_e32 v52, v42
	v_add_f32_e32 v42, 1.0, v51
	v_rcp_f32_e32 v53, v42
	v_add_f32_e32 v42, 1.0, v43
	v_rcp_f32_e32 v48, v42
	v_add_f32_e32 v42, 1.0, v49
	v_rcp_f32_e32 v49, v42
.LBB0_640:
	v_add_u32_e32 v42, 0x90, v162
	v_cvt_f32_i32_e32 v39, v39
	v_cvt_f32_i32_e32 v41, v41
	v_cvt_f32_i32_e32 v40, v40
	v_cvt_f32_i32_e32 v38, v38
	v_cvt_f32_i32_e32 v35, v35
	v_cvt_f32_i32_e32 v37, v37
	v_cvt_f32_i32_e32 v36, v36
	v_cvt_f32_i32_e32 v34, v34
	v_ashrrev_i32_e32 v43, 31, v42
	v_mul_lo_u32 v54, s2, v43
	v_mul_lo_u32 v55, s3, v42
	v_mad_u64_u32 v[42:43], s[30:31], s2, v42, 0
	v_mov_b32_e32 v51, v50
	v_add3_u32 v43, v43, v54, v55
	v_cvt_pk_bf16_f32 v54, v46, v47
	v_cvt_pk_bf16_f32 v55, v44, v45
	v_mov_b32_e32 v44, v50
	v_mov_b32_e32 v45, v50
	v_pk_mul_f32 v[40:41], v[44:45], v[40:41]
	v_pk_mul_f32 v[46:47], v[50:51], v[38:39]
	v_pk_mul_f32 v[36:37], v[44:45], v[36:37]
	v_pk_mul_f32 v[34:35], v[50:51], v[34:35]
	s_mov_b64 s[98:99], 0x2800
	v_lshl_add_u64 v[42:43], v[248:249], 0, s[98:99]
	v_pk_mul_f32 v[38:39], v[64:65], v[40:41]
	v_pk_mul_f32 v[40:41], v[62:63], v[46:47]
	v_pk_mul_f32 v[36:37], v[60:61], v[36:37]
	s_and_b64 vcc, exec, s[6:7]
	v_pk_mul_f32 v[44:45], v[58:59], v[34:35]
	v_cvt_pk_bf16_f32 v56, v52, v53
	v_cvt_pk_bf16_f32 v57, v48, v49
	global_store_dwordx4 v[42:43], v[54:57], off
	s_cbranch_vccnz .LBB0_642
	v_mul_f32_e32 v34, 0xbfb8aa3b, v40
	v_exp_f32_e32 v34, v34
	v_mul_f32_e32 v35, 0xbfb8aa3b, v41
	v_exp_f32_e32 v35, v35
	v_add_f32_e32 v34, 1.0, v34
	v_rcp_f32_e32 v40, v34
	v_mul_f32_e32 v34, 0xbfb8aa3b, v38
	v_add_f32_e32 v35, 1.0, v35
	v_exp_f32_e32 v34, v34
	v_mul_f32_e32 v38, 0xbfb8aa3b, v39
	v_exp_f32_e32 v39, v38
	v_rcp_f32_e32 v41, v35
	v_mul_f32_e32 v35, 0xbfb8aa3b, v44
	v_exp_f32_e32 v35, v35
	v_add_f32_e32 v34, 1.0, v34
	v_rcp_f32_e32 v38, v34
	v_add_f32_e32 v34, 1.0, v39
	v_mul_f32_e32 v39, 0xbfb8aa3b, v45
	v_exp_f32_e32 v45, v39
	v_rcp_f32_e32 v39, v34
	v_add_f32_e32 v34, 1.0, v35
	v_mul_f32_e32 v35, 0xbfb8aa3b, v36
	v_exp_f32_e32 v35, v35
	v_mul_f32_e32 v36, 0xbfb8aa3b, v37
	v_exp_f32_e32 v37, v36
	v_rcp_f32_e32 v44, v34
	v_add_f32_e32 v34, 1.0, v45
	v_rcp_f32_e32 v45, v34
	v_add_f32_e32 v34, 1.0, v35
	v_rcp_f32_e32 v36, v34
	v_add_f32_e32 v34, 1.0, v37
	v_rcp_f32_e32 v37, v34
.LBB0_642:
	v_cvt_f32_i32_e32 v33, v33
	v_cvt_f32_i32_e32 v32, v32
	v_cvt_pk_bf16_f32 v46, v40, v41
	v_cvt_pk_bf16_f32 v47, v38, v39
	v_cvt_pk_bf16_f32 v48, v44, v45
	v_cvt_f32_i32_e32 v31, v31
	v_cvt_f32_i32_e32 v30, v30
	v_cvt_pk_bf16_f32 v49, v36, v37
	v_cvt_f32_i32_e32 v37, v29
	v_cvt_f32_i32_e32 v27, v27
	v_cvt_f32_i32_e32 v26, v26
	v_cvt_f32_i32_e32 v36, v28
	v_mul_f32_e32 v34, v182, v183
	v_pk_mul_f32 v[32:33], v[34:35], v[32:33] op_sel_hi:[0,1]
	v_pk_mul_f32 v[30:31], v[34:35], v[30:31] op_sel_hi:[0,1]
	v_pk_mul_f32 v[28:29], v[80:81], v[32:33]
	v_pk_mul_f32 v[26:27], v[34:35], v[26:27] op_sel_hi:[0,1]
	v_pk_mul_f32 v[32:33], v[34:35], v[36:37] op_sel_hi:[0,1]
	v_pk_mul_f32 v[30:31], v[78:79], v[30:31]
	v_pk_mul_f32 v[32:33], v[76:77], v[32:33]
	s_and_b64 vcc, exec, s[6:7]
	v_pk_mul_f32 v[36:37], v[74:75], v[26:27]
	global_store_dwordx4 v[42:43], v[46:49], off offset:1024
	s_cbranch_vccnz .LBB0_644
	v_mul_f32_e32 v26, 0xbfb8aa3b, v30
	v_exp_f32_e32 v26, v26
	v_mul_f32_e32 v27, 0xbfb8aa3b, v31
	v_exp_f32_e32 v27, v27
	v_add_f32_e32 v26, 1.0, v26
	v_rcp_f32_e32 v30, v26
	v_mul_f32_e32 v26, 0xbfb8aa3b, v28
	v_add_f32_e32 v27, 1.0, v27
	v_exp_f32_e32 v26, v26
	v_mul_f32_e32 v28, 0xbfb8aa3b, v29
	v_exp_f32_e32 v29, v28
	v_rcp_f32_e32 v31, v27
	v_mul_f32_e32 v27, 0xbfb8aa3b, v36
	v_exp_f32_e32 v27, v27
	v_add_f32_e32 v26, 1.0, v26
	v_rcp_f32_e32 v28, v26
	v_add_f32_e32 v26, 1.0, v29
	v_mul_f32_e32 v29, 0xbfb8aa3b, v37
	v_exp_f32_e32 v35, v29
	v_rcp_f32_e32 v29, v26
	v_add_f32_e32 v26, 1.0, v27
	v_mul_f32_e32 v27, 0xbfb8aa3b, v32
	v_exp_f32_e32 v27, v27
	v_mul_f32_e32 v32, 0xbfb8aa3b, v33
	v_exp_f32_e32 v33, v32
	v_rcp_f32_e32 v36, v26
	v_add_f32_e32 v26, 1.0, v35
	v_rcp_f32_e32 v37, v26
	v_add_f32_e32 v26, 1.0, v27
	v_rcp_f32_e32 v32, v26
	v_add_f32_e32 v26, 1.0, v33
	v_rcp_f32_e32 v33, v26
; #define PG8_BAR __builtin_amdgcn_s_barrier()
; __device__ __forceinline__ u32x4 pack8(const f32x4 v0, const f32x4 v1) { u32x4 w; w.x = cvt_pk_bf16(v0[0], v0[1]); w.y = cvt_pk_bf16(v0[2], v0[3]); w.z = cvt_pk_bf16(v1[0], v1[1]); w.w = cvt_pk_bf16(v1[2], v1[3]); return w; }
; __device__ __forceinline__ f32x4 sig4(const f32x4 v) { return (f32x4){sigmoidf_(v[0]), sigmoidf_(v[1]), sigmoidf_(v[2]), sigmoidf_(v[3])}; }
; template <class Epi, class Sched, bool ALIGN_EPI = false, bool SP2 = false, bool I8 = false>
; __device__ __forceinline__ void gemm_phase(PG8_LAS unsigned char* lds, const Gemm g, const Sched& S, const Epi& E) {
;     ...
;         if (!has_next) break;
; #pragma unroll
;         for (int a = 0; a < 2; ++a)
; #pragma unroll
;             for (int b = 0; b < 2; ++b)
; #pragma unroll
;                 for (int m = 0; m < 4; ++m)
; #pragma unroll
;                     for (int n = 0; n < 2; ++n) acc[a][b][m][n] = (typename AccT<I8>::type){0, 0, 0, 0};
;         cur = nxt; cA = nA; cB = nB; ++ui; nt = PG8_NT(cur);
;         if constexpr (ALIGN_EPI) { if (wr == 1) PG8_BAR; }
;     __device__ __forceinline__ void operator()(const i32x4 (&acc)[2][2][4][2], const Unit& uu, int wr, int wc, int fr, int fq) const {
;     ...
;         for (int ai = 0; ai < 2; ++ai)
; #pragma unroll
;             for (int m = 0; m < 4; ++m) { const int r = row0 + ai * HALF + m * 16; const float rs = rsv[ai][m]; bf16_t* rowp = base + (size_t)r * ldc + col0;
; #pragma unroll
;                 for (int bj = 0; bj < 2; ++bj) { f32x4 v0 = __builtin_convertvector(acc[ai][bj][m][0], f32x4) * rs * sv[bj][0], v1 = __builtin_convertvector(acc[ai][bj][m][1], f32x4) * rs * sv[bj][1];
;                     if (sg) { v0 = sig4(v0); v1 = sig4(v1); }
;                     *(u32x4*)(rowp + bj * HALF) = pack8(v0, v1); } }
.LBB0_644:
	v_add_u32_e32 v26, 0xa0, v162
	v_cvt_f32_i32_e32 v23, v23
	v_cvt_f32_i32_e32 v25, v25
	v_cvt_f32_i32_e32 v24, v24
	v_cvt_f32_i32_e32 v22, v22
	v_cvt_f32_i32_e32 v19, v19
	v_cvt_f32_i32_e32 v21, v21
	v_cvt_f32_i32_e32 v20, v20
	v_cvt_f32_i32_e32 v18, v18
	v_ashrrev_i32_e32 v27, 31, v26
	v_mul_lo_u32 v38, s2, v27
	v_mul_lo_u32 v39, s3, v26
	v_mad_u64_u32 v[26:27], s[30:31], s2, v26, 0
	v_mov_b32_e32 v35, v34
	v_add3_u32 v27, v27, v38, v39
	v_cvt_pk_bf16_f32 v38, v30, v31
	v_cvt_pk_bf16_f32 v39, v28, v29
	v_mov_b32_e32 v28, v34
	v_mov_b32_e32 v29, v34
	v_pk_mul_f32 v[24:25], v[28:29], v[24:25]
	v_pk_mul_f32 v[30:31], v[34:35], v[22:23]
	v_pk_mul_f32 v[20:21], v[28:29], v[20:21]
	v_pk_mul_f32 v[18:19], v[34:35], v[18:19]
	s_mov_b64 s[98:99], 0x3000
	v_lshl_add_u64 v[26:27], v[248:249], 0, s[98:99]
	v_pk_mul_f32 v[22:23], v[64:65], v[24:25]
	v_pk_mul_f32 v[24:25], v[62:63], v[30:31]
	v_pk_mul_f32 v[20:21], v[60:61], v[20:21]
	s_and_b64 vcc, exec, s[6:7]
	v_pk_mul_f32 v[28:29], v[58:59], v[18:19]
	v_cvt_pk_bf16_f32 v40, v36, v37
	v_cvt_pk_bf16_f32 v41, v32, v33
	global_store_dwordx4 v[26:27], v[38:41], off
	s_cbranch_vccnz .LBB0_646
	v_mul_f32_e32 v18, 0xbfb8aa3b, v24
	v_exp_f32_e32 v18, v18
	v_mul_f32_e32 v19, 0xbfb8aa3b, v25
	v_exp_f32_e32 v19, v19
	v_add_f32_e32 v18, 1.0, v18
	v_rcp_f32_e32 v24, v18
	v_mul_f32_e32 v18, 0xbfb8aa3b, v22
	v_add_f32_e32 v19, 1.0, v19
	v_exp_f32_e32 v18, v18
	v_mul_f32_e32 v22, 0xbfb8aa3b, v23
	v_exp_f32_e32 v23, v22
	v_rcp_f32_e32 v25, v19
	v_mul_f32_e32 v19, 0xbfb8aa3b, v28
	v_exp_f32_e32 v19, v19
	v_add_f32_e32 v18, 1.0, v18
	v_rcp_f32_e32 v22, v18
	v_add_f32_e32 v18, 1.0, v23
	v_mul_f32_e32 v23, 0xbfb8aa3b, v29
	v_exp_f32_e32 v29, v23
	v_rcp_f32_e32 v23, v18
	v_add_f32_e32 v18, 1.0, v19
	v_mul_f32_e32 v19, 0xbfb8aa3b, v20
	v_exp_f32_e32 v19, v19
	v_mul_f32_e32 v20, 0xbfb8aa3b, v21
	v_exp_f32_e32 v21, v20
	v_rcp_f32_e32 v28, v18
	v_add_f32_e32 v18, 1.0, v29
	v_rcp_f32_e32 v29, v18
	v_add_f32_e32 v18, 1.0, v19
	v_rcp_f32_e32 v20, v18
	v_add_f32_e32 v18, 1.0, v21
	v_rcp_f32_e32 v21, v18
.LBB0_646:
	v_cvt_f32_i32_e32 v17, v17
	v_cvt_f32_i32_e32 v16, v16
	v_cvt_pk_bf16_f32 v30, v24, v25
	v_cvt_pk_bf16_f32 v31, v22, v23
	v_cvt_pk_bf16_f32 v32, v28, v29
	v_cvt_f32_i32_e32 v15, v15
	v_cvt_f32_i32_e32 v14, v14
	v_cvt_pk_bf16_f32 v33, v20, v21
	v_cvt_f32_i32_e32 v21, v13
	v_cvt_f32_i32_e32 v11, v11
	v_cvt_f32_i32_e32 v10, v10
	v_cvt_f32_i32_e32 v20, v12
	v_mul_f32_e32 v18, v180, v181
	v_pk_mul_f32 v[16:17], v[18:19], v[16:17] op_sel_hi:[0,1]
	v_pk_mul_f32 v[14:15], v[18:19], v[14:15] op_sel_hi:[0,1]
	v_pk_mul_f32 v[12:13], v[80:81], v[16:17]
	v_pk_mul_f32 v[10:11], v[18:19], v[10:11] op_sel_hi:[0,1]
	v_pk_mul_f32 v[16:17], v[18:19], v[20:21] op_sel_hi:[0,1]
	v_pk_mul_f32 v[14:15], v[78:79], v[14:15]
	v_pk_mul_f32 v[16:17], v[76:77], v[16:17]
	s_and_b64 vcc, exec, s[6:7]
	v_pk_mul_f32 v[20:21], v[74:75], v[10:11]
	global_store_dwordx4 v[26:27], v[30:33], off offset:1024
	s_cbranch_vccnz .LBB0_648
	v_mul_f32_e32 v10, 0xbfb8aa3b, v14
	v_exp_f32_e32 v10, v10
	v_mul_f32_e32 v11, 0xbfb8aa3b, v15
	v_exp_f32_e32 v11, v11
	v_add_f32_e32 v10, 1.0, v10
	v_rcp_f32_e32 v14, v10
	v_mul_f32_e32 v10, 0xbfb8aa3b, v12
	v_add_f32_e32 v11, 1.0, v11
	v_exp_f32_e32 v10, v10
	v_mul_f32_e32 v12, 0xbfb8aa3b, v13
	v_exp_f32_e32 v13, v12
	v_rcp_f32_e32 v15, v11
	v_mul_f32_e32 v11, 0xbfb8aa3b, v20
	v_exp_f32_e32 v11, v11
	v_add_f32_e32 v10, 1.0, v10
	v_rcp_f32_e32 v12, v10
	v_add_f32_e32 v10, 1.0, v13
	v_mul_f32_e32 v13, 0xbfb8aa3b, v21
	v_exp_f32_e32 v19, v13
	v_rcp_f32_e32 v13, v10
	v_add_f32_e32 v10, 1.0, v11
	v_mul_f32_e32 v11, 0xbfb8aa3b, v16
	v_exp_f32_e32 v11, v11
	v_mul_f32_e32 v16, 0xbfb8aa3b, v17
	v_exp_f32_e32 v17, v16
	v_rcp_f32_e32 v20, v10
	v_add_f32_e32 v10, 1.0, v19
	v_rcp_f32_e32 v21, v10
	v_add_f32_e32 v10, 1.0, v11
	v_rcp_f32_e32 v16, v10
	v_add_f32_e32 v10, 1.0, v17
	v_rcp_f32_e32 v17, v10
.LBB0_648:
	v_add_u32_e32 v10, 0xb0, v162
	v_ashrrev_i32_e32 v11, 31, v10
	v_mul_lo_u32 v22, s2, v11
	v_mul_lo_u32 v23, s3, v10
	v_mad_u64_u32 v[10:11], s[2:3], s2, v10, 0
	v_cvt_f32_i32_e32 v7, v7
	v_cvt_f32_i32_e32 v9, v9
	v_cvt_f32_i32_e32 v8, v8
	v_cvt_f32_i32_e32 v6, v6
	v_add3_u32 v11, v11, v22, v23
	v_cvt_pk_bf16_f32 v22, v14, v15
	v_cvt_pk_bf16_f32 v23, v12, v13
	v_cvt_pk_bf16_f32 v24, v20, v21
	v_cvt_pk_bf16_f32 v25, v16, v17
	v_cvt_f32_i32_e32 v15, v3
	v_cvt_f32_i32_e32 v17, v5
	v_cvt_f32_i32_e32 v16, v4
	v_cvt_f32_i32_e32 v14, v2
	v_mov_b32_e32 v19, v18
	v_mov_b32_e32 v12, v18
	v_mov_b32_e32 v13, v18
	v_pk_mul_f32 v[8:9], v[12:13], v[8:9]
	v_pk_mul_f32 v[6:7], v[18:19], v[6:7]
	v_pk_mul_f32 v[2:3], v[64:65], v[8:9]
	v_pk_mul_f32 v[4:5], v[62:63], v[6:7]
	v_pk_mul_f32 v[6:7], v[12:13], v[16:17]
	v_pk_mul_f32 v[8:9], v[18:19], v[14:15]
	s_mov_b64 s[98:99], 0x3800
	v_lshl_add_u64 v[10:11], v[248:249], 0, s[98:99]
	v_pk_mul_f32 v[6:7], v[60:61], v[6:7]
	s_and_b64 vcc, exec, s[6:7]
	v_pk_mul_f32 v[8:9], v[58:59], v[8:9]
	global_store_dwordx4 v[10:11], v[22:25], off
	s_cbranch_vccnz .LBB0_650
	v_mul_f32_e32 v4, 0xbfb8aa3b, v4
	v_mul_f32_e32 v5, 0xbfb8aa3b, v5
	v_mul_f32_e32 v2, 0xbfb8aa3b, v2
	v_mul_f32_e32 v3, 0xbfb8aa3b, v3
	v_mul_f32_e32 v8, 0xbfb8aa3b, v8
	v_mul_f32_e32 v9, 0xbfb8aa3b, v9
	v_mul_f32_e32 v6, 0xbfb8aa3b, v6
	v_mul_f32_e32 v7, 0xbfb8aa3b, v7
	v_exp_f32_e32 v4, v4
	v_exp_f32_e32 v5, v5
	v_exp_f32_e32 v2, v2
	v_exp_f32_e32 v3, v3
	v_exp_f32_e32 v8, v8
	v_exp_f32_e32 v9, v9
	v_exp_f32_e32 v6, v6
	v_exp_f32_e32 v7, v7
	v_add_f32_e32 v4, 1.0, v4
	v_add_f32_e32 v5, 1.0, v5
	v_add_f32_e32 v2, 1.0, v2
	v_add_f32_e32 v3, 1.0, v3
	v_add_f32_e32 v8, 1.0, v8
	v_add_f32_e32 v9, 1.0, v9
	v_add_f32_e32 v6, 1.0, v6
	v_add_f32_e32 v7, 1.0, v7
	v_rcp_f32_e32 v4, v4
	v_rcp_f32_e32 v5, v5
	v_rcp_f32_e32 v2, v2
	v_rcp_f32_e32 v3, v3
	v_rcp_f32_e32 v8, v8
	v_rcp_f32_e32 v9, v9
	v_rcp_f32_e32 v6, v6
	v_rcp_f32_e32 v7, v7
.LBB0_650:
	s_andn2_b64 vcc, exec, s[4:5]
	s_mov_b64 s[2:3], -1
	v_cvt_pk_bf16_f32 v12, v4, v5
	v_cvt_pk_bf16_f32 v13, v2, v3
	v_cvt_pk_bf16_f32 v14, v8, v9
	v_cvt_pk_bf16_f32 v15, v6, v7
	global_store_dwordx4 v[10:11], v[12:15], off offset:1024
	s_cbranch_vccnz .LBB0_599
	s_andn2_b64 vcc, exec, s[16:17]
	s_cbranch_vccnz .LBB0_598
	s_barrier
	s_branch .LBB0_598

; __device__ __forceinline__ unsigned cvt_pk_bf16(float lo, float hi) { unsigned r; asm volatile("s_nop 0\n\tv_cvt_pk_bf16_f32 %0, %1, %2" : "=v"(r) : "v"(lo), "v"(hi)); return r; }
; #define LAS __attribute__((address_space(3)))
; __device__ __forceinline__ void t_attn(Frame& F) {
;     ...
;         mx = fmaxf(mx, __shfl_xor(mx, 16)); mx = fmaxf(mx, __shfl_xor(mx, 32));
;         float l = 0.f;
; #pragma unroll
;         for (int u = 0; u < 9; ++u)
; #pragma unroll
;             for (int i = 0; i < 4; ++i) { const float p = __expf(sacc[u][i] - mx); sacc[u][i] = p; l += p; }
;         l += __shfl_xor(l, 16); l += __shfl_xor(l, 32);
;         f32x4 oacc[8];
; #pragma unroll
;         for (int dt = 0; dt < 8; ++dt) oacc[dt] = (f32x4){0.f, 0.f, 0.f, 0.f};
; #pragma unroll
;         for (int blk = 0; blk < 5; ++blk) { const int u0 = 2 * blk, u1 = (2 * blk + 1 < 9) ? 2 * blk + 1 : u0;
;             u32x4_t pw; pw.x = pg8::cvt_pk_bf16(sacc[u0][0], sacc[u0][1]); pw.y = pg8::cvt_pk_bf16(sacc[u0][2], sacc[u0][3]);
;             if (2 * blk + 1 < 9) { pw.z = pg8::cvt_pk_bf16(sacc[u1][0], sacc[u1][1]); pw.w = pg8::cvt_pk_bf16(sacc[u1][2], sacc[u1][3]); } else { pw.z = 0u; pw.w = 0u; }
;             const bf16x8 pf = __builtin_bit_cast(bf16x8, pw);
; #pragma unroll
;             for (int dt = 0; dt < 8; ++dt) { const LAS unsigned char* vr = VT + (16 * dt + n) * VT_STRIDE + 8 * g;
;                 const v2u lo = *(const LAS v2u*)(vr + 32 * (w + u0)), hi = *(const LAS v2u*)(vr + 32 * (w + u1));
;                 u32x4_t aw; aw.x = lo.x; aw.y = lo.y; aw.z = hi.x; aw.w = hi.y;
;                 oacc[dt] = __builtin_amdgcn_mfma_f32_16x16x32_bf16(__builtin_bit_cast(bf16x8, aw), pf, oacc[dt], 0, 0, 0); } }
.LBB0_823:
	s_or_b64 exec, exec, s[0:1]
	s_mov_b32 s0, 0xf149f2ca
	v_max3_f32 v1, v135, s0, v133
	v_max3_f32 v1, v1, v127, v126
	v_max3_f32 v1, v1, v129, v128
	v_max3_f32 v1, v1, v123, v122
	v_max3_f32 v1, v1, v125, v124
	v_max3_f32 v1, v1, v119, v118
	v_max3_f32 v1, v1, v121, v120
	v_max3_f32 v1, v1, v115, v114
	v_max3_f32 v1, v1, v117, v116
	v_max3_f32 v1, v1, v137, v136
	v_max3_f32 v1, v1, v113, v111
	v_max3_f32 v1, v1, v112, v110
	v_max3_f32 v1, v1, v109, v107
	v_max3_f32 v1, v1, v108, v106
	v_max3_f32 v1, v1, v104, v102
	v_max3_f32 v1, v1, v103, v99
	v_max3_f32 v1, v1, v100, v42
	v_max3_f32 v1, v1, v98, v43
	ds_bpermute_b32 v44, v216, v1
	s_sub_i32 s0, 5, s21
	v_lshl_add_u32 v94, s47, 7, v172
	s_ashr_i32 s73, s72, 31
	s_lshr_b32 s6, s45, s0
	s_waitcnt lgkmcnt(0)
	v_max_f32_e32 v44, v44, v44
	v_max_f32_e32 v1, v1, v44
	ds_bpermute_b32 v96, v154, v1
	v_lshlrev_b32_e32 v44, s21, v94
	s_lshl_b64 s[0:1], s[72:73], 12
	v_add_u32_e32 v44, s6, v44
	v_lshl_add_u64 v[94:95], s[0:1], 0, v[44:45]
	s_waitcnt lgkmcnt(0)
	v_max_f32_e32 v44, v96, v96
	v_max_f32_e32 v1, v1, v44
	v_sub_f32_e32 v44, v135, v1
	v_mul_f32_e32 v44, 0x3fb8aa3b, v44
	v_sub_f32_e32 v96, v133, v1
	v_exp_f32_e32 v44, v44
	v_mul_f32_e32 v96, 0x3fb8aa3b, v96
	v_sub_f32_e32 v97, v127, v1
	v_exp_f32_e32 v96, v96
	v_mul_f32_e32 v97, 0x3fb8aa3b, v97
	v_sub_f32_e32 v101, v126, v1
	v_exp_f32_e32 v97, v97
	v_mul_f32_e32 v101, 0x3fb8aa3b, v101
	v_sub_f32_e32 v126, v129, v1
	v_exp_f32_e32 v101, v101
	v_mul_f32_e32 v126, 0x3fb8aa3b, v126
	v_sub_f32_e32 v127, v128, v1
	v_add_f32_e32 v105, 0, v44
	v_exp_f32_e32 v126, v126
	v_mul_f32_e32 v127, 0x3fb8aa3b, v127
	v_sub_f32_e32 v123, v123, v1
	v_add_f32_e32 v105, v96, v105
	v_exp_f32_e32 v127, v127
	v_mul_f32_e32 v123, 0x3fb8aa3b, v123
	v_sub_f32_e32 v122, v122, v1
	v_add_f32_e32 v105, v97, v105
	v_exp_f32_e32 v123, v123
	v_mul_f32_e32 v122, 0x3fb8aa3b, v122
	v_sub_f32_e32 v125, v125, v1
	v_add_f32_e32 v105, v101, v105
	v_exp_f32_e32 v122, v122
	v_mul_f32_e32 v125, 0x3fb8aa3b, v125
	v_sub_f32_e32 v124, v124, v1
	v_sub_f32_e32 v118, v118, v1
	v_add_f32_e32 v105, v126, v105
	v_exp_f32_e32 v133, v125
	v_mul_f32_e32 v124, 0x3fb8aa3b, v124
	v_sub_f32_e32 v119, v119, v1
	v_mul_f32_e32 v118, 0x3fb8aa3b, v118
	v_add_f32_e32 v105, v127, v105
	v_exp_f32_e32 v135, v124
	v_mul_f32_e32 v119, 0x3fb8aa3b, v119
	v_exp_f32_e32 v153, v118
	v_sub_f32_e32 v118, v121, v1
	v_sub_f32_e32 v114, v114, v1
	v_add_f32_e32 v105, v123, v105
	v_exp_f32_e32 v152, v119
	v_mul_f32_e32 v118, 0x3fb8aa3b, v118
	v_mul_f32_e32 v114, 0x3fb8aa3b, v114
	v_add_f32_e32 v105, v122, v105
	v_exp_f32_e32 v155, v118
	v_sub_f32_e32 v118, v120, v1
	v_exp_f32_e32 v160, v114
	v_sub_f32_e32 v114, v117, v1
	v_add_f32_e32 v105, v133, v105
	v_mul_f32_e32 v118, 0x3fb8aa3b, v118
	v_sub_f32_e32 v115, v115, v1
	v_mul_f32_e32 v114, 0x3fb8aa3b, v114
	v_add_f32_e32 v105, v135, v105
	v_exp_f32_e32 v158, v118
	v_mul_f32_e32 v115, 0x3fb8aa3b, v115
	v_exp_f32_e32 v164, v114
	v_sub_f32_e32 v114, v116, v1
	v_add_f32_e32 v105, v152, v105
	v_exp_f32_e32 v159, v115
	v_mul_f32_e32 v114, 0x3fb8aa3b, v114
	v_add_f32_e32 v105, v153, v105
	v_exp_f32_e32 v165, v114
	v_sub_f32_e32 v114, v137, v1
	v_add_f32_e32 v105, v155, v105
	v_mul_f32_e32 v114, 0x3fb8aa3b, v114
	v_add_f32_e32 v105, v158, v105
	v_exp_f32_e32 v167, v114
	v_sub_f32_e32 v114, v136, v1
	v_add_f32_e32 v105, v159, v105
	v_mul_f32_e32 v114, 0x3fb8aa3b, v114
	v_sub_f32_e32 v113, v113, v1
	v_add_f32_e32 v105, v160, v105
	v_exp_f32_e32 v173, v114
	v_mul_f32_e32 v113, 0x3fb8aa3b, v113
	v_cvt_pk_bf16_f32 v114, v44, v96
	v_add_u32_e32 v44, s33, v188
	v_add_u32_e32 v96, s10, v188
	v_add_f32_e32 v105, v164, v105
	v_exp_f32_e32 v217, v113
	s_nop 0
	v_cvt_pk_bf16_f32 v115, v97, v101
	v_cvt_pk_bf16_f32 v116, v126, v127
	v_cvt_pk_bf16_f32 v117, v123, v122
	ds_read_b64 v[118:119], v44
	ds_read_b64 v[120:121], v96
	ds_read_b64 v[124:125], v96 offset:8320
	ds_read_b64 v[122:123], v44 offset:8320
	ds_read_b64 v[126:127], v44 offset:16640
	ds_read_b64 v[136:137], v44 offset:24960
	ds_read_b64 v[128:129], v96 offset:16640
	ds_read_b64 v[138:139], v96 offset:24960
	v_add_f32_e32 v105, v165, v105
	v_add_f32_e32 v105, v167, v105
	v_sub_f32_e32 v140, v110, v1
	v_add_f32_e32 v105, v173, v105
	v_sub_f32_e32 v101, v111, v1
	v_mul_f32_e32 v156, 0x3fb8aa3b, v140
	v_add_f32_e32 v97, v217, v105
	v_mul_f32_e32 v101, 0x3fb8aa3b, v101
	v_sub_f32_e32 v105, v112, v1
	s_waitcnt lgkmcnt(1)
	v_mfma_f32_16x16x32_bf16 v[110:113], v[126:129], v[114:117], 0
	ds_read_b64 v[126:127], v44 offset:33280
	ds_read_b64 v[128:129], v96 offset:33280
	ds_read_b64 v[142:143], v96 offset:41600
	ds_read_b64 v[140:141], v44 offset:41600
	ds_read_b64 v[144:145], v44 offset:49920
	ds_read_b64 v[148:149], v44 offset:58240
	ds_read_b64 v[146:147], v96 offset:49920
	ds_read_b64 v[150:151], v96 offset:58240
	v_exp_f32_e32 v44, v156
	s_nop 0
	v_cvt_pk_bf16_f32 v156, v133, v135
	v_add_u32_e32 v133, s11, v188
	v_add_u32_e32 v135, s12, v188
	v_exp_f32_e32 v101, v101
	s_nop 0
	v_cvt_pk_bf16_f32 v157, v152, v153
	v_cvt_pk_bf16_f32 v158, v155, v158
	v_cvt_pk_bf16_f32 v159, v159, v160
	ds_read_b64 v[160:161], v133
	ds_read_b64 v[162:163], v135
	v_mul_f32_e32 v105, 0x3fb8aa3b, v105
	v_mfma_f32_16x16x32_bf16 v[118:121], v[118:121], v[114:117], 0
	v_exp_f32_e32 v105, v105
	v_add_f32_e32 v96, v101, v97
	v_sub_f32_e32 v97, v109, v1
	v_mfma_f32_16x16x32_bf16 v[122:125], v[122:125], v[114:117], 0
	v_sub_f32_e32 v107, v107, v1
	v_mul_f32_e32 v97, 0x3fb8aa3b, v97
	v_mul_f32_e32 v107, 0x3fb8aa3b, v107
	s_waitcnt lgkmcnt(10)
	v_mfma_f32_16x16x32_bf16 v[136:139], v[136:139], v[114:117], 0
	v_exp_f32_e32 v97, v97
	v_exp_f32_e32 v152, v107
	v_sub_f32_e32 v107, v108, v1
	s_waitcnt lgkmcnt(8)
; __device__ __forceinline__ unsigned cvt_pk_bf16(float lo, float hi) { unsigned r; asm volatile("s_nop 0\n\tv_cvt_pk_bf16_f32 %0, %1, %2" : "=v"(r) : "v"(lo), "v"(hi)); return r; }
; #define LAS __attribute__((address_space(3)))
; __device__ __forceinline__ void t_attn(Frame& F) {
;     ...
;             for (int i = 0; i < 4; ++i) { const float p = __expf(sacc[u][i] - mx); sacc[u][i] = p; l += p; }
;         l += __shfl_xor(l, 16); l += __shfl_xor(l, 32);
;         f32x4 oacc[8];
; #pragma unroll
;         for (int dt = 0; dt < 8; ++dt) oacc[dt] = (f32x4){0.f, 0.f, 0.f, 0.f};
; #pragma unroll
;         for (int blk = 0; blk < 5; ++blk) { const int u0 = 2 * blk, u1 = (2 * blk + 1 < 9) ? 2 * blk + 1 : u0;
;             u32x4_t pw; pw.x = pg8::cvt_pk_bf16(sacc[u0][0], sacc[u0][1]); pw.y = pg8::cvt_pk_bf16(sacc[u0][2], sacc[u0][3]);
;             if (2 * blk + 1 < 9) { pw.z = pg8::cvt_pk_bf16(sacc[u1][0], sacc[u1][1]); pw.w = pg8::cvt_pk_bf16(sacc[u1][2], sacc[u1][3]); } else { pw.z = 0u; pw.w = 0u; }
;             const bf16x8 pf = __builtin_bit_cast(bf16x8, pw);
; #pragma unroll
;             for (int dt = 0; dt < 8; ++dt) { const LAS unsigned char* vr = VT + (16 * dt + n) * VT_STRIDE + 8 * g;
;                 const v2u lo = *(const LAS v2u*)(vr + 32 * (w + u0)), hi = *(const LAS v2u*)(vr + 32 * (w + u1));
;                 u32x4_t aw; aw.x = lo.x; aw.y = lo.y; aw.z = hi.x; aw.w = hi.y;
;                 oacc[dt] = __builtin_amdgcn_mfma_f32_16x16x32_bf16(__builtin_bit_cast(bf16x8, aw), pf, oacc[dt], 0, 0, 0); } }
	v_mfma_f32_16x16x32_bf16 v[126:129], v[126:129], v[114:117], 0
	v_mul_f32_e32 v107, 0x3fb8aa3b, v107
	v_sub_f32_e32 v106, v106, v1
	v_add_f32_e32 v96, v105, v96
	s_waitcnt lgkmcnt(6)
	v_mfma_f32_16x16x32_bf16 v[140:143], v[140:143], v[114:117], 0
	v_exp_f32_e32 v153, v107
	v_mul_f32_e32 v106, 0x3fb8aa3b, v106
	v_add_f32_e32 v96, v44, v96
	s_waitcnt lgkmcnt(3)
	v_mfma_f32_16x16x32_bf16 v[144:147], v[144:147], v[114:117], 0
	v_add_f32_e32 v96, v97, v96
	v_add_f32_e32 v96, v152, v96
	v_add_f32_e32 v96, v153, v96
	s_waitcnt lgkmcnt(2)
	v_mfma_f32_16x16x32_bf16 v[114:117], v[148:151], v[114:117], 0
	ds_read_b64 v[150:151], v135 offset:8320
	ds_read_b64 v[148:149], v133 offset:8320
	ds_read_b64 v[168:169], v133 offset:16640
	ds_read_b64 v[218:219], v133 offset:24960
	ds_read_b64 v[170:171], v135 offset:16640
	ds_read_b64 v[220:221], v135 offset:24960
	v_sub_f32_e32 v42, v42, v1
	v_mul_f32_e32 v42, 0x3fb8aa3b, v42
	s_waitcnt lgkmcnt(4)
	v_mfma_f32_16x16x32_bf16 v[122:125], v[148:151], v[156:159], v[122:125]
	ds_read_b64 v[148:149], v133 offset:33280
	ds_read_b64 v[150:151], v135 offset:33280
	v_mfma_f32_16x16x32_bf16 v[118:121], v[160:163], v[156:159], v[118:121]
	s_waitcnt lgkmcnt(3)
	v_mfma_f32_16x16x32_bf16 v[108:111], v[168:171], v[156:159], v[110:113]
	s_waitcnt lgkmcnt(2)
	v_mfma_f32_16x16x32_bf16 v[136:139], v[218:221], v[156:159], v[136:139]
	ds_read_b64 v[162:163], v135 offset:41600
	ds_read_b64 v[160:161], v133 offset:41600
	ds_read_b64 v[168:169], v133 offset:49920
	ds_read_b64 v[218:219], v133 offset:58240
	ds_read_b64 v[170:171], v135 offset:49920
	ds_read_b64 v[220:221], v135 offset:58240
	v_exp_f32_e32 v133, v106
	s_waitcnt lgkmcnt(6)
	v_mfma_f32_16x16x32_bf16 v[126:129], v[148:151], v[156:159], v[126:129]
	v_cvt_pk_bf16_f32 v148, v164, v165
	v_add_f32_e32 v135, v133, v96
	v_cvt_pk_bf16_f32 v149, v167, v173
	v_cvt_pk_bf16_f32 v150, v217, v101
	v_cvt_pk_bf16_f32 v151, v105, v44
	v_add_u32_e32 v44, s13, v188
	v_add_u32_e32 v96, s14, v188
	s_waitcnt lgkmcnt(4)
	v_mfma_f32_16x16x32_bf16 v[140:143], v[160:163], v[156:159], v[140:143]
	ds_read_b64 v[160:161], v44
	ds_read_b64 v[162:163], v96
	v_sub_f32_e32 v101, v104, v1
	s_waitcnt lgkmcnt(3)
	v_mfma_f32_16x16x32_bf16 v[144:147], v[168:171], v[156:159], v[144:147]
	v_mul_f32_e32 v101, 0x3fb8aa3b, v101
	v_exp_f32_e32 v155, v101
	v_sub_f32_e32 v101, v102, v1
	s_waitcnt lgkmcnt(2)
	v_mfma_f32_16x16x32_bf16 v[104:107], v[218:221], v[156:159], v[114:117]
	s_nop 2
	ds_read_b64 v[114:115], v96 offset:8320
	ds_read_b64 v[112:113], v44 offset:8320
	ds_read_b64 v[156:157], v44 offset:16640
	ds_read_b64 v[168:169], v44 offset:24960
	ds_read_b64 v[158:159], v96 offset:16640
	ds_read_b64 v[170:171], v96 offset:24960
	v_mul_f32_e32 v101, 0x3fb8aa3b, v101
	v_exp_f32_e32 v164, v101
	s_waitcnt lgkmcnt(6)
	v_mfma_f32_16x16x32_bf16 v[116:119], v[160:163], v[148:151], v[118:121]
	v_sub_f32_e32 v101, v103, v1
	v_mul_f32_e32 v101, 0x3fb8aa3b, v101
	v_exp_f32_e32 v165, v42
	s_waitcnt lgkmcnt(4)
	v_mfma_f32_16x16x32_bf16 v[112:115], v[112:115], v[148:151], v[122:125]
	ds_read_b64 v[120:121], v44 offset:33280
	s_nop 1
	ds_read_b64 v[122:123], v96 offset:33280
	v_sub_f32_e32 v42, v98, v1
	v_mul_f32_e32 v42, 0x3fb8aa3b, v42
	s_waitcnt lgkmcnt(3)
	v_mfma_f32_16x16x32_bf16 v[108:111], v[156:159], v[148:151], v[108:111]
	v_exp_f32_e32 v167, v42
	v_sub_f32_e32 v42, v43, v1
	v_mul_f32_e32 v42, 0x3fb8aa3b, v42
	s_waitcnt lgkmcnt(2)
	v_mfma_f32_16x16x32_bf16 v[136:139], v[168:171], v[148:151], v[136:139]
	ds_read_b64 v[158:159], v96 offset:41600
	ds_read_b64 v[156:157], v44 offset:41600
	ds_read_b64 v[160:161], v44 offset:49920
	ds_read_b64 v[168:169], v44 offset:58240
	ds_read_b64 v[162:163], v96 offset:49920
	ds_read_b64 v[170:171], v96 offset:58240
	v_sub_f32_e32 v44, v99, v1
	v_mul_f32_e32 v44, 0x3fb8aa3b, v44
	s_waitcnt lgkmcnt(6)
	v_mfma_f32_16x16x32_bf16 v[120:123], v[120:123], v[148:151], v[126:129]
	v_add_f32_e32 v135, v155, v135
	s_waitcnt lgkmcnt(4)
	v_mfma_f32_16x16x32_bf16 v[124:127], v[156:159], v[148:151], v[140:143]
	v_cvt_pk_bf16_f32 v140, v97, v152
	v_cvt_pk_bf16_f32 v141, v153, v133
	v_add_u32_e32 v133, s15, v188
	v_add_u32_e32 v152, s16, v188
	v_exp_f32_e32 v128, v101
	v_exp_f32_e32 v129, v44
	v_sub_f32_e32 v44, v100, v1
	s_waitcnt lgkmcnt(1)
	v_mfma_f32_16x16x32_bf16 v[100:103], v[160:163], v[148:151], v[144:147]
	v_cvt_pk_bf16_f32 v142, v155, v164
	v_cvt_pk_bf16_f32 v143, v128, v129
	v_mul_f32_e32 v44, 0x3fb8aa3b, v44
	s_waitcnt lgkmcnt(0)
	v_mfma_f32_16x16x32_bf16 v[104:107], v[168:171], v[148:151], v[104:107]
	v_exp_f32_e32 v153, v44
	ds_read_b64 v[144:145], v133
	ds_read_b64 v[146:147], v152
	ds_read_b64 v[150:151], v152 offset:8320
	ds_read_b64 v[148:149], v133 offset:8320
	ds_read_b64 v[156:157], v133 offset:16640
	ds_read_b64 v[160:161], v133 offset:24960
	ds_read_b64 v[158:159], v152 offset:16640
	ds_read_b64 v[162:163], v152 offset:24960
	s_waitcnt lgkmcnt(1)
	v_mfma_f32_16x16x32_bf16 v[96:99], v[156:159], v[140:143], v[108:111]
	s_nop 2
	ds_read_b64 v[108:109], v133 offset:33280
	ds_read_b64 v[110:111], v152 offset:33280
	v_mov_b32_e32 v44, v45
	v_mfma_f32_16x16x32_bf16 v[116:119], v[144:147], v[140:143], v[116:119]
	v_mfma_f32_16x16x32_bf16 v[112:115], v[148:151], v[140:143], v[112:115]
	ds_read_b64 v[146:147], v152 offset:41600
	ds_read_b64 v[144:145], v133 offset:41600
	ds_read_b64 v[148:149], v133 offset:49920
	ds_read_b64 v[156:157], v133 offset:58240
	ds_read_b64 v[150:151], v152 offset:49920
	ds_read_b64 v[158:159], v152 offset:58240
	v_add_u32_e32 v152, s17, v188
	v_exp_f32_e32 v133, v42
	s_waitcnt lgkmcnt(6)
; __device__ __forceinline__ unsigned cvt_pk_bf16(float lo, float hi) { unsigned r; asm volatile("s_nop 0\n\tv_cvt_pk_bf16_f32 %0, %1, %2" : "=v"(r) : "v"(lo), "v"(hi)); return r; }
; #define LAS __attribute__((address_space(3)))
; __device__ __forceinline__ unsigned pk2(float lo, float hi) { return pg8::cvt_pk_bf16_n(lo, hi); }
; __device__ __forceinline__ void t_attn(Frame& F) {
;     ...
;         for (int blk = 0; blk < 5; ++blk) { const int u0 = 2 * blk, u1 = (2 * blk + 1 < 9) ? 2 * blk + 1 : u0;
;             u32x4_t pw; pw.x = pg8::cvt_pk_bf16(sacc[u0][0], sacc[u0][1]); pw.y = pg8::cvt_pk_bf16(sacc[u0][2], sacc[u0][3]);
;             if (2 * blk + 1 < 9) { pw.z = pg8::cvt_pk_bf16(sacc[u1][0], sacc[u1][1]); pw.w = pg8::cvt_pk_bf16(sacc[u1][2], sacc[u1][3]); } else { pw.z = 0u; pw.w = 0u; }
;             const bf16x8 pf = __builtin_bit_cast(bf16x8, pw);
; #pragma unroll
;             for (int dt = 0; dt < 8; ++dt) { const LAS unsigned char* vr = VT + (16 * dt + n) * VT_STRIDE + 8 * g;
;                 const v2u lo = *(const LAS v2u*)(vr + 32 * (w + u0)), hi = *(const LAS v2u*)(vr + 32 * (w + u1));
;                 u32x4_t aw; aw.x = lo.x; aw.y = lo.y; aw.z = hi.x; aw.w = hi.y;
;                 oacc[dt] = __builtin_amdgcn_mfma_f32_16x16x32_bf16(__builtin_bit_cast(bf16x8, aw), pf, oacc[dt], 0, 0, 0); } }
;         const float inv = 1.0f / l; bf16* op = OG + rowq * 1536 + h * 128 + 4 * g;
; #pragma unroll
;         for (int dt = 0; dt < 8; ++dt) { v2u o; o.x = pk2(oacc[dt][0] * inv, oacc[dt][1] * inv); o.y = pk2(oacc[dt][2] * inv, oacc[dt][3] * inv); *(v2u*)(op + 16 * dt) = o; }
;         if (g == 0) LSE[rowq * 12 + h] = mx + __logf(l);
	v_mfma_f32_16x16x32_bf16 v[108:111], v[108:111], v[140:143], v[120:123]
	v_cvt_pk_bf16_f32 v42, v153, v165
	v_cvt_pk_bf16_f32 v43, v167, v133
	s_waitcnt lgkmcnt(4)
	v_mfma_f32_16x16x32_bf16 v[120:123], v[144:147], v[140:143], v[124:127]
	s_nop 2
	ds_read_b64 v[124:125], v152
	v_mfma_f32_16x16x32_bf16 v[136:139], v[160:163], v[140:143], v[136:139]
	s_waitcnt lgkmcnt(0)
	v_mov_b32_e32 v126, v124
	v_mfma_f32_16x16x32_bf16 v[100:103], v[148:151], v[140:143], v[100:103]
	ds_read_b64 v[144:145], v152 offset:8320
	ds_read_b64 v[148:149], v152 offset:16640
	ds_read_b64 v[160:161], v152 offset:24960
	v_mov_b32_e32 v127, v125
	s_waitcnt lgkmcnt(2)
	v_mov_b32_e32 v146, v144
	s_waitcnt lgkmcnt(1)
	v_mov_b32_e32 v150, v148
	v_mov_b32_e32 v151, v149
	v_mfma_f32_16x16x32_bf16 v[116:119], v[124:127], v[42:45], v[116:119]
	v_add_f32_e32 v124, v164, v135
	v_add_f32_e32 v124, v128, v124
	v_add_f32_e32 v124, v129, v124
	v_add_f32_e32 v128, v153, v124
	v_mfma_f32_16x16x32_bf16 v[124:127], v[148:151], v[42:45], v[96:99]
	v_add_f32_e32 v128, v165, v128
	v_add_f32_e32 v128, v167, v128
	v_add_f32_e32 v128, v133, v128
	ds_read_b64 v[96:97], v152 offset:33280
	v_mov_b32_e32 v147, v145
	v_mfma_f32_16x16x32_bf16 v[104:107], v[156:159], v[140:143], v[104:107]
	s_waitcnt lgkmcnt(1)
	v_mov_b32_e32 v162, v160
	v_mov_b32_e32 v163, v161
	s_waitcnt lgkmcnt(0)
	v_mov_b32_e32 v98, v96
	v_mov_b32_e32 v99, v97
	v_mfma_f32_16x16x32_bf16 v[112:115], v[144:147], v[42:45], v[112:115]
	ds_read_b64 v[140:141], v152 offset:41600
	ds_read_b64 v[144:145], v152 offset:49920
	ds_read_b64 v[148:149], v152 offset:58240
	v_mov_b32_e32 v135, v45
	s_waitcnt lgkmcnt(2)
	v_mov_b32_e32 v142, v140
	v_mfma_f32_16x16x32_bf16 v[108:111], v[96:99], v[42:45], v[108:111]
	ds_bpermute_b32 v96, v216, v128
	v_mov_b32_e32 v143, v141
	s_waitcnt lgkmcnt(2)
	v_mov_b32_e32 v146, v144
	v_mov_b32_e32 v147, v145
	s_waitcnt lgkmcnt(1)
	v_mov_b32_e32 v150, v148
	s_waitcnt lgkmcnt(0)
	v_add_f32_e32 v96, v128, v96
	ds_bpermute_b32 v97, v154, v96
	v_mov_b32_e32 v151, v149
	v_mfma_f32_16x16x32_bf16 v[136:139], v[160:163], v[42:45], v[136:139]
	s_waitcnt lgkmcnt(0)
	v_add_f32_e32 v96, v96, v97
	v_div_scale_f32 v97, s[0:1], v96, v96, 1.0
	v_rcp_f32_e32 v128, v97
	v_mfma_f32_16x16x32_bf16 v[120:123], v[140:143], v[42:45], v[120:123]
	v_mfma_f32_16x16x32_bf16 v[98:101], v[144:147], v[42:45], v[100:103]
	v_mfma_f32_16x16x32_bf16 v[102:105], v[148:151], v[42:45], v[104:107]
	v_fma_f32 v42, -v97, v128, 1.0
	v_fmac_f32_e32 v128, v42, v128
	v_div_scale_f32 v42, vcc, 1.0, v96, 1.0
	v_mul_f32_e32 v43, v42, v128
	v_fma_f32 v44, -v97, v43, v42
	v_fmac_f32_e32 v43, v44, v128
	v_mov_b64_e32 v[106:107], s[70:71]
	v_fma_f32 v42, -v97, v43, v42
	v_mad_u64_u32 v[106:107], s[0:1], v94, s46, v[106:107]
	v_div_fmas_f32 v42, v42, v128, v43
	s_lshl_b32 s0, s44, 7
	v_div_fixup_f32 v42, v42, v96, 1.0
	v_mad_i32_i24 v107, v95, s46, v107
	s_ashr_i32 s1, s0, 31
	v_lshl_add_u64 v[106:107], s[0:1], 1, v[106:107]
	v_pk_mul_f32 v[112:113], v[42:43], v[112:113] op_sel_hi:[0,1]
	v_pk_mul_f32 v[114:115], v[42:43], v[114:115] op_sel_hi:[0,1]
	v_lshl_add_u64 v[106:107], v[106:107], 0, v[134:135]
	v_cvt_pk_bf16_f32 v112, v112, v113
	v_cvt_pk_bf16_f32 v113, v114, v115
	global_store_dwordx2 v[106:107], v[112:113], off offset:32
	v_pk_mul_f32 v[112:113], v[42:43], v[124:125] op_sel_hi:[0,1]
	v_pk_mul_f32 v[114:115], v[42:43], v[126:127] op_sel_hi:[0,1]
	v_pk_mul_f32 v[108:109], v[42:43], v[108:109] op_sel_hi:[0,1]
	v_pk_mul_f32 v[110:111], v[42:43], v[110:111] op_sel_hi:[0,1]
	v_pk_mul_f32 v[98:99], v[42:43], v[98:99] op_sel_hi:[0,1]
	v_pk_mul_f32 v[100:101], v[42:43], v[100:101] op_sel_hi:[0,1]
	v_cvt_pk_bf16_f32 v112, v112, v113
	v_cvt_pk_bf16_f32 v113, v114, v115
	v_cvt_pk_bf16_f32 v108, v108, v109
	v_cvt_pk_bf16_f32 v109, v110, v111
	v_cvt_pk_bf16_f32 v98, v98, v99
	v_cvt_pk_bf16_f32 v99, v100, v101
	v_pk_mul_f32 v[116:117], v[42:43], v[116:117] op_sel_hi:[0,1]
	v_pk_mul_f32 v[118:119], v[42:43], v[118:119] op_sel_hi:[0,1]
	global_store_dwordx2 v[106:107], v[112:113], off offset:64
	v_pk_mul_f32 v[112:113], v[42:43], v[136:137] op_sel_hi:[0,1]
	v_pk_mul_f32 v[114:115], v[42:43], v[138:139] op_sel_hi:[0,1]
	global_store_dwordx2 v[106:107], v[108:109], off offset:128
	v_pk_mul_f32 v[108:109], v[42:43], v[120:121] op_sel_hi:[0,1]
	v_pk_mul_f32 v[110:111], v[42:43], v[122:123] op_sel_hi:[0,1]
	global_store_dwordx2 v[106:107], v[98:99], off offset:192
	v_pk_mul_f32 v[98:99], v[42:43], v[102:103] op_sel_hi:[0,1]
	v_pk_mul_f32 v[42:43], v[42:43], v[104:105] op_sel_hi:[0,1]
	v_cvt_pk_bf16_f32 v116, v116, v117
	v_cvt_pk_bf16_f32 v117, v118, v119
	v_cvt_pk_bf16_f32 v112, v112, v113
	v_cvt_pk_bf16_f32 v113, v114, v115
	v_cvt_pk_bf16_f32 v108, v108, v109
	v_cvt_pk_bf16_f32 v109, v110, v111
	v_cvt_pk_bf16_f32 v98, v98, v99
	v_cvt_pk_bf16_f32 v99, v42, v43
	global_store_dwordx2 v[106:107], v[116:117], off
	global_store_dwordx2 v[106:107], v[112:113], off offset:96
	global_store_dwordx2 v[106:107], v[108:109], off offset:160
	global_store_dwordx2 v[106:107], v[98:99], off offset:224
	s_and_saveexec_b64 s[0:1], s[42:43]
	s_cbranch_execz .LBB0_734
	s_mov_b32 s6, 0x800000
	v_cmp_gt_f32_e32 vcc, s6, v96
	s_mov_b32 s6, 0x3f317217
	s_ashr_i32 s45, s44, 31
	v_cndmask_b32_e64 v42, 0, 32, vcc
	v_ldexp_f32 v42, v96, v42
	v_log_f32_e32 v42, v42
	v_cndmask_b32_e32 v43, 0, v215, vcc
	v_mul_f32_e32 v44, 0x3f317217, v42
	v_fma_f32 v44, v42, s6, -v44
	v_fmac_f32_e32 v44, 0x3377d1cf, v42
	s_mov_b32 s6, 0x7f800000
	v_fmac_f32_e32 v44, 0x3f317217, v42
	v_cmp_lt_f32_e64 vcc, |v42|, s6
	v_readlane_b32 s6, v254, 42
	v_readlane_b32 s7, v254, 43
	v_cndmask_b32_e32 v42, v42, v44, vcc
	v_sub_f32_e32 v42, v42, v43
	v_add_f32_e32 v1, v1, v42
	v_mad_u64_u32 v[42:43], s[6:7], v94, 48, s[6:7]
	v_mad_i32_i24 v43, v95, 48, v43
	v_lshl_add_u64 v[42:43], s[44:45], 2, v[42:43]
	global_store_dword v[42:43], v1, off
	s_branch .LBB0_734

; #define PG8_STAGE(bufoff, gbase, voff) do { _Pragma("unroll") for (int _i = 0; _i < 2; ++_i) \
;         __builtin_amdgcn_global_load_lds((const unsigned*)((const char*)(gbase) + (voff)[_i]), (PG8_LAS unsigned*)(lds + (bufoff) + ldsw + _i * 8192), 16, 0, 0); } while (0)
; #define PG8_LDA(dst, b, h) do { _Pragma("unroll") for (int m = 0; m < 4; ++m) _Pragma("unroll") for (int k = 0; k < 2; ++k) dst[m][k] = *(const PG8_LAS bf16x8*)(lds + PG8_SA(b, h) + aoff + m * 2048 + k * 1024); } while (0)
; #define PG8_WAIT_V(n) asm volatile("s_waitcnt vmcnt(" #n ")" ::: "memory")
; #define PG8_WAIT_L(n) asm volatile("s_waitcnt lgkmcnt(" #n ")" ::: "memory")
; #define PG8_BAR __builtin_amdgcn_s_barrier()
; template <class Epi, class Sched, bool ALIGN_EPI = false, bool SP2 = false, bool I8 = false>
; __device__ __forceinline__ void gemm_phase(PG8_LAS unsigned char* lds, const Gemm g, const Sched& S, const Epi& E) {
;     ...
;         for (int t = 0; t < nt; t += 2) {
;             const bool last = (t == nt - 2);
;             const char* a1 = cA + (size_t)(t + 1) * kstep;
;             const char* a2 = last ? nA : cA + (size_t)(t + 2) * kstep; const char* b2 = last ? nB : cB + (size_t)(t + 2) * kstep;
;             const char* a3 = a2 + kstep; const char* b3 = b2 + kstep;
;             if (last && has_next) S.a_ready(nxt);
;             if constexpr (SP2) {
;             PG8_LDB(B0, 0, 0); PG8_LDB(B1, 0, 1); PG8_SCHED; PG8_LDA(At, 0, 0); PG8_STAGE(PG8_SA(1, 1), a1 + hstepA, voffA);
;             PG8_WAIT_V(8); PG8_WAIT_L(0); PG8_BAR; PG8_MMA(0, 0, At, B0); PG8_MMA(0, 1, At, B1); PG8_BAR; PG8_SCHED;
;             PG8_LDA(At, 0, 1); PG8_STAGE(PG8_SB(0, 0), b2, voffB); PG8_STAGE(PG8_SB(0, 1), b2 + hstepB, voffB); PG8_STAGE(PG8_SA(0, 0), a2, voffA);
;             PG8_WAIT_V(8); PG8_WAIT_L(0); PG8_BAR; PG8_MMA(1, 0, At, B0); PG8_MMA(1, 1, At, B1); PG8_BAR; PG8_SCHED;
;             PG8_LDB(B0, 1, 0); PG8_LDB(B1, 1, 1); PG8_SCHED; PG8_LDA(At, 1, 0); PG8_STAGE(PG8_SA(0, 1), a2 + hstepA, voffA);
;             PG8_WAIT_V(8); PG8_WAIT_L(0); PG8_BAR; PG8_MMA(0, 0, At, B0); PG8_MMA(0, 1, At, B1); PG8_BAR; PG8_SCHED;
;             PG8_LDA(At, 1, 1); PG8_STAGE(PG8_SB(1, 0), b3, voffB); PG8_STAGE(PG8_SB(1, 1), b3 + hstepB, voffB); PG8_STAGE(PG8_SA(1, 0), a3, voffA);
;             PG8_WAIT_V(8); PG8_WAIT_L(0); PG8_BAR; PG8_MMA(1, 0, At, B0); PG8_MMA(1, 1, At, B1); PG8_BAR; PG8_SCHED;
.LBB0_1092:
	ds_read_b128 v[58:61], v172
	ds_read_b128 v[62:65], v172 offset:1024
	ds_read_b128 v[74:77], v172 offset:2048
	ds_read_b128 v[78:81], v172 offset:3072
	ds_read_b128 v[164:167], v173
	ds_read_b128 v[168:171], v173 offset:1024
	ds_read_b128 v[176:179], v173 offset:2048
	ds_read_b128 v[180:183], v173 offset:3072
	s_add_i32 s47, s22, 2
	s_add_u32 s23, s8, 0xfffe0080
	s_addc_u32 s24, s9, -1
	s_cmp_eq_u32 s3, s22
	s_cselect_b32 s22, s20, s17
	s_cselect_b32 s25, s1, s24
	s_cselect_b32 s24, s0, s23
	s_cselect_b32 s23, s21, s19
	s_add_i32 m0, s33, 0xc000
	ds_read_b128 v[184:187], v174
	ds_read_b128 v[188:191], v174 offset:1024
	ds_read_b128 v[192:195], v174 offset:2048
	ds_read_b128 v[196:199], v174 offset:3072
	ds_read_b128 v[200:203], v174 offset:4096
	ds_read_b128 v[204:207], v174 offset:5120
	ds_read_b128 v[208:211], v174 offset:6144
	ds_read_b128 v[212:215], v174 offset:7168
	global_load_lds_dwordx4 v156, s[8:9]
	s_add_i32 m0, s33, 0xe000
	s_nop 0
	global_load_lds_dwordx4 v158, s[8:9]
	s_waitcnt vmcnt(8) lgkmcnt(0)
	s_barrier
	v_mfma_f32_16x16x32_bf16 v[142:145], v[58:61], v[184:187], v[142:145]
	v_mfma_f32_16x16x32_bf16 v[138:141], v[74:77], v[184:187], v[138:141]
	v_mfma_f32_16x16x32_bf16 v[126:129], v[58:61], v[192:195], v[126:129]
	v_mfma_f32_16x16x32_bf16 v[122:125], v[74:77], v[192:195], v[122:125]
	v_mfma_f32_16x16x32_bf16 v[110:113], v[58:61], v[200:203], v[110:113]
	v_mfma_f32_16x16x32_bf16 v[106:109], v[74:77], v[200:203], v[106:109]
	v_mfma_f32_16x16x32_bf16 v[94:97], v[58:61], v[208:211], v[94:97]
	v_mfma_f32_16x16x32_bf16 v[90:93], v[74:77], v[208:211], v[90:93]
	v_mfma_f32_16x16x32_bf16 v[142:145], v[62:65], v[188:191], v[142:145]
	v_mfma_f32_16x16x32_bf16 v[138:141], v[78:81], v[188:191], v[138:141]
	v_mfma_f32_16x16x32_bf16 v[126:129], v[62:65], v[196:199], v[126:129]
	v_mfma_f32_16x16x32_bf16 v[122:125], v[78:81], v[196:199], v[122:125]
	v_mfma_f32_16x16x32_bf16 v[110:113], v[62:65], v[204:207], v[110:113]
	v_mfma_f32_16x16x32_bf16 v[106:109], v[78:81], v[204:207], v[106:109]
	v_mfma_f32_16x16x32_bf16 v[94:97], v[62:65], v[212:215], v[94:97]
	v_mfma_f32_16x16x32_bf16 v[90:93], v[78:81], v[212:215], v[90:93]
	v_mfma_f32_16x16x32_bf16 v[134:137], v[164:167], v[184:187], v[134:137]
	v_mfma_f32_16x16x32_bf16 v[130:133], v[176:179], v[184:187], v[130:133]
	v_mfma_f32_16x16x32_bf16 v[118:121], v[164:167], v[192:195], v[118:121]
	v_mfma_f32_16x16x32_bf16 v[114:117], v[176:179], v[192:195], v[114:117]
	v_mfma_f32_16x16x32_bf16 v[102:105], v[164:167], v[200:203], v[102:105]
	v_mfma_f32_16x16x32_bf16 v[98:101], v[176:179], v[200:203], v[98:101]
	v_mfma_f32_16x16x32_bf16 v[86:89], v[164:167], v[208:211], v[86:89]
	v_mfma_f32_16x16x32_bf16 v[82:85], v[176:179], v[208:211], v[82:85]
	v_mfma_f32_16x16x32_bf16 v[134:137], v[168:171], v[188:191], v[134:137]
	v_mfma_f32_16x16x32_bf16 v[130:133], v[180:183], v[188:191], v[130:133]
	v_mfma_f32_16x16x32_bf16 v[118:121], v[168:171], v[196:199], v[118:121]
	v_mfma_f32_16x16x32_bf16 v[114:117], v[180:183], v[196:199], v[114:117]
	v_mfma_f32_16x16x32_bf16 v[102:105], v[168:171], v[204:207], v[102:105]
	v_mfma_f32_16x16x32_bf16 v[98:101], v[180:183], v[204:207], v[98:101]
	v_mfma_f32_16x16x32_bf16 v[86:89], v[168:171], v[212:215], v[86:89]
	v_mfma_f32_16x16x32_bf16 v[82:85], v[180:183], v[212:215], v[82:85]
	s_barrier
	s_add_i32 s56, s44, s30
	s_mov_b64 s[98:99], s[22:23]
	s_mov_b32 m0, s56
	ds_read_b128 v[184:187], v174 offset:16384
	ds_read_b128 v[188:191], v174 offset:17408
	ds_read_b128 v[192:195], v174 offset:18432
	ds_read_b128 v[196:199], v174 offset:19456
	ds_read_b128 v[200:203], v174 offset:20480
	ds_read_b128 v[204:207], v174 offset:21504
	ds_read_b128 v[208:211], v174 offset:22528
	ds_read_b128 v[212:215], v174 offset:23552
	global_load_lds_dwordx4 v148, s[22:23]
	s_add_i32 m0, s56, 0x2000
	s_add_u32 s56, s22, 0x20000
	s_mov_b64 s[98:99], s[22:23]
	s_addc_u32 s57, s23, 0
	s_add_i32 s58, s45, s30
	global_load_lds_dwordx4 v152, s[22:23]
	s_mov_b32 m0, s58
	s_mov_b64 s[100:101], s[24:25]
	global_load_lds_dwordx4 v148, s[56:57]
	s_add_i32 m0, s58, 0x2000
	s_nop 0
	global_load_lds_dwordx4 v152, s[56:57]
	s_mov_b64 s[100:101], s[24:25]
	s_mov_b32 m0, s33
	s_nop 0
	global_load_lds_dwordx4 v146, s[24:25]
	s_mov_b32 m0, s34
	s_nop 0
	global_load_lds_dwordx4 v150, s[24:25]
	s_waitcnt vmcnt(8) lgkmcnt(0)
	s_barrier
	v_mfma_f32_16x16x32_bf16 v[70:73], v[58:61], v[184:187], v[70:73]
	v_mfma_f32_16x16x32_bf16 v[66:69], v[74:77], v[184:187], v[66:69]
	v_mfma_f32_16x16x32_bf16 v[46:49], v[58:61], v[192:195], v[46:49]
	v_mfma_f32_16x16x32_bf16 v[42:45], v[74:77], v[192:195], v[42:45]
	v_mfma_f32_16x16x32_bf16 v[30:33], v[58:61], v[200:203], v[30:33]
	v_mfma_f32_16x16x32_bf16 v[26:29], v[74:77], v[200:203], v[26:29]
	v_mfma_f32_16x16x32_bf16 v[14:17], v[58:61], v[208:211], v[14:17]
	v_mfma_f32_16x16x32_bf16 v[10:13], v[74:77], v[208:211], v[10:13]
	v_mfma_f32_16x16x32_bf16 v[70:73], v[62:65], v[188:191], v[70:73]
	v_mfma_f32_16x16x32_bf16 v[66:69], v[78:81], v[188:191], v[66:69]
	v_mfma_f32_16x16x32_bf16 v[46:49], v[62:65], v[196:199], v[46:49]
	v_mfma_f32_16x16x32_bf16 v[42:45], v[78:81], v[196:199], v[42:45]
	v_mfma_f32_16x16x32_bf16 v[30:33], v[62:65], v[204:207], v[30:33]
	v_mfma_f32_16x16x32_bf16 v[26:29], v[78:81], v[204:207], v[26:29]
	v_mfma_f32_16x16x32_bf16 v[14:17], v[62:65], v[212:215], v[14:17]
	v_mfma_f32_16x16x32_bf16 v[10:13], v[78:81], v[212:215], v[10:13]
	v_mfma_f32_16x16x32_bf16 v[54:57], v[164:167], v[184:187], v[54:57]
	v_mfma_f32_16x16x32_bf16 v[50:53], v[176:179], v[184:187], v[50:53]
	v_mfma_f32_16x16x32_bf16 v[38:41], v[164:167], v[192:195], v[38:41]
	v_mfma_f32_16x16x32_bf16 v[34:37], v[176:179], v[192:195], v[34:37]
	v_mfma_f32_16x16x32_bf16 v[22:25], v[164:167], v[200:203], v[22:25]
	v_mfma_f32_16x16x32_bf16 v[18:21], v[176:179], v[200:203], v[18:21]
	v_mfma_f32_16x16x32_bf16 v[6:9], v[164:167], v[208:211], v[6:9]
	v_mfma_f32_16x16x32_bf16 v[2:5], v[176:179], v[208:211], v[2:5]
	v_mfma_f32_16x16x32_bf16 v[54:57], v[168:171], v[188:191], v[54:57]
	v_mfma_f32_16x16x32_bf16 v[50:53], v[180:183], v[188:191], v[50:53]
	v_mfma_f32_16x16x32_bf16 v[38:41], v[168:171], v[196:199], v[38:41]
	v_mfma_f32_16x16x32_bf16 v[34:37], v[180:183], v[196:199], v[34:37]
	v_mfma_f32_16x16x32_bf16 v[22:25], v[168:171], v[204:207], v[22:25]
	v_mfma_f32_16x16x32_bf16 v[18:21], v[180:183], v[204:207], v[18:21]
	v_mfma_f32_16x16x32_bf16 v[6:9], v[168:171], v[212:215], v[6:9]
	v_mfma_f32_16x16x32_bf16 v[2:5], v[180:183], v[212:215], v[2:5]
	s_barrier
; #define PG8_STAGE(bufoff, gbase, voff) do { _Pragma("unroll") for (int _i = 0; _i < 2; ++_i) \
;         __builtin_amdgcn_global_load_lds((const unsigned*)((const char*)(gbase) + (voff)[_i]), (PG8_LAS unsigned*)(lds + (bufoff) + ldsw + _i * 8192), 16, 0, 0); } while (0)
; #define PG8_LDA(dst, b, h) do { _Pragma("unroll") for (int m = 0; m < 4; ++m) _Pragma("unroll") for (int k = 0; k < 2; ++k) dst[m][k] = *(const PG8_LAS bf16x8*)(lds + PG8_SA(b, h) + aoff + m * 2048 + k * 1024); } while (0)
; #define PG8_WAIT_V(n) asm volatile("s_waitcnt vmcnt(" #n ")" ::: "memory")
; #define PG8_WAIT_L(n) asm volatile("s_waitcnt lgkmcnt(" #n ")" ::: "memory")
; #define PG8_BAR __builtin_amdgcn_s_barrier()
; template <class Epi, class Sched, bool ALIGN_EPI = false, bool SP2 = false, bool I8 = false>
; __device__ __forceinline__ void gemm_phase(PG8_LAS unsigned char* lds, const Gemm g, const Sched& S, const Epi& E) {
;     ...
;         for (int t = 0; t < nt; t += 2) {
;             const bool last = (t == nt - 2);
;             const char* a1 = cA + (size_t)(t + 1) * kstep;
;             const char* a2 = last ? nA : cA + (size_t)(t + 2) * kstep; const char* b2 = last ? nB : cB + (size_t)(t + 2) * kstep;
;             const char* a3 = a2 + kstep; const char* b3 = b2 + kstep;
;             if (last && has_next) S.a_ready(nxt);
;             if constexpr (SP2) {
;             PG8_LDB(B0, 0, 0); PG8_LDB(B1, 0, 1); PG8_SCHED; PG8_LDA(At, 0, 0); PG8_STAGE(PG8_SA(1, 1), a1 + hstepA, voffA);
;             PG8_WAIT_V(8); PG8_WAIT_L(0); PG8_BAR; PG8_MMA(0, 0, At, B0); PG8_MMA(0, 1, At, B1); PG8_BAR; PG8_SCHED;
;             PG8_LDA(At, 0, 1); PG8_STAGE(PG8_SB(0, 0), b2, voffB); PG8_STAGE(PG8_SB(0, 1), b2 + hstepB, voffB); PG8_STAGE(PG8_SA(0, 0), a2, voffA);
;             PG8_WAIT_V(8); PG8_WAIT_L(0); PG8_BAR; PG8_MMA(1, 0, At, B0); PG8_MMA(1, 1, At, B1); PG8_BAR; PG8_SCHED;
;             PG8_LDB(B0, 1, 0); PG8_LDB(B1, 1, 1); PG8_SCHED; PG8_LDA(At, 1, 0); PG8_STAGE(PG8_SA(0, 1), a2 + hstepA, voffA);
;             PG8_WAIT_V(8); PG8_WAIT_L(0); PG8_BAR; PG8_MMA(0, 0, At, B0); PG8_MMA(0, 1, At, B1); PG8_BAR; PG8_SCHED;
;             PG8_LDA(At, 1, 1); PG8_STAGE(PG8_SB(1, 0), b3, voffB); PG8_STAGE(PG8_SB(1, 1), b3 + hstepB, voffB); PG8_STAGE(PG8_SA(1, 0), a3, voffA);
;             PG8_WAIT_V(8); PG8_WAIT_L(0); PG8_BAR; PG8_MMA(1, 0, At, B0); PG8_MMA(1, 1, At, B1); PG8_BAR; PG8_SCHED;
	s_add_i32 s56, 0, 0x18000
	s_add_i32 s57, 0, 0x1c000
	ds_read_b128 v[58:61], v173 offset:16384
	ds_read_b128 v[62:65], v173 offset:17408
	ds_read_b128 v[74:77], v173 offset:18432
	ds_read_b128 v[78:81], v173 offset:19456
	ds_read_b128 v[164:167], v173 offset:32768
	ds_read_b128 v[168:171], v173 offset:33792
	ds_read_b128 v[176:179], v173 offset:34816
	ds_read_b128 v[180:183], v173 offset:35840
	s_add_u32 s24, s24, 0x20000
	s_addc_u32 s25, s25, 0
	s_mov_b32 m0, s35
	ds_read_b128 v[184:187], v174 offset:32768
	ds_read_b128 v[188:191], v174 offset:33792
	ds_read_b128 v[192:195], v174 offset:34816
	ds_read_b128 v[196:199], v174 offset:35840
	ds_read_b128 v[200:203], v174 offset:36864
	ds_read_b128 v[204:207], v174 offset:37888
	ds_read_b128 v[208:211], v174 offset:38912
	ds_read_b128 v[212:215], v174 offset:39936
	global_load_lds_dwordx4 v146, s[24:25]
	s_mov_b32 m0, s36
	s_nop 0
	global_load_lds_dwordx4 v150, s[24:25]
	s_waitcnt vmcnt(8) lgkmcnt(0)
	s_barrier
	v_mfma_f32_16x16x32_bf16 v[142:145], v[58:61], v[184:187], v[142:145]
	v_mfma_f32_16x16x32_bf16 v[138:141], v[74:77], v[184:187], v[138:141]
	v_mfma_f32_16x16x32_bf16 v[126:129], v[58:61], v[192:195], v[126:129]
	v_mfma_f32_16x16x32_bf16 v[122:125], v[74:77], v[192:195], v[122:125]
	v_mfma_f32_16x16x32_bf16 v[110:113], v[58:61], v[200:203], v[110:113]
	v_mfma_f32_16x16x32_bf16 v[106:109], v[74:77], v[200:203], v[106:109]
	v_mfma_f32_16x16x32_bf16 v[94:97], v[58:61], v[208:211], v[94:97]
	v_mfma_f32_16x16x32_bf16 v[90:93], v[74:77], v[208:211], v[90:93]
	v_mfma_f32_16x16x32_bf16 v[142:145], v[62:65], v[188:191], v[142:145]
	v_mfma_f32_16x16x32_bf16 v[138:141], v[78:81], v[188:191], v[138:141]
	v_mfma_f32_16x16x32_bf16 v[126:129], v[62:65], v[196:199], v[126:129]
	v_mfma_f32_16x16x32_bf16 v[122:125], v[78:81], v[196:199], v[122:125]
	v_mfma_f32_16x16x32_bf16 v[110:113], v[62:65], v[204:207], v[110:113]
	v_mfma_f32_16x16x32_bf16 v[106:109], v[78:81], v[204:207], v[106:109]
	v_mfma_f32_16x16x32_bf16 v[94:97], v[62:65], v[212:215], v[94:97]
	v_mfma_f32_16x16x32_bf16 v[90:93], v[78:81], v[212:215], v[90:93]
	v_mfma_f32_16x16x32_bf16 v[134:137], v[164:167], v[184:187], v[134:137]
	v_mfma_f32_16x16x32_bf16 v[130:133], v[176:179], v[184:187], v[130:133]
	v_mfma_f32_16x16x32_bf16 v[118:121], v[164:167], v[192:195], v[118:121]
	v_mfma_f32_16x16x32_bf16 v[114:117], v[176:179], v[192:195], v[114:117]
	v_mfma_f32_16x16x32_bf16 v[102:105], v[164:167], v[200:203], v[102:105]
	v_mfma_f32_16x16x32_bf16 v[98:101], v[176:179], v[200:203], v[98:101]
	v_mfma_f32_16x16x32_bf16 v[86:89], v[164:167], v[208:211], v[86:89]
	v_mfma_f32_16x16x32_bf16 v[82:85], v[176:179], v[208:211], v[82:85]
	v_mfma_f32_16x16x32_bf16 v[134:137], v[168:171], v[188:191], v[134:137]
	v_mfma_f32_16x16x32_bf16 v[130:133], v[180:183], v[188:191], v[130:133]
	v_mfma_f32_16x16x32_bf16 v[118:121], v[168:171], v[196:199], v[118:121]
	v_mfma_f32_16x16x32_bf16 v[114:117], v[180:183], v[196:199], v[114:117]
	v_mfma_f32_16x16x32_bf16 v[102:105], v[168:171], v[204:207], v[102:105]
	v_mfma_f32_16x16x32_bf16 v[98:101], v[180:183], v[204:207], v[98:101]
	v_mfma_f32_16x16x32_bf16 v[86:89], v[168:171], v[212:215], v[86:89]
	v_mfma_f32_16x16x32_bf16 v[82:85], v[180:183], v[212:215], v[82:85]
	s_barrier
	s_add_i32 s24, s56, s30
	s_add_i32 m0, s24, 0xffffff80
	ds_read_b128 v[184:187], v174 offset:49152
	ds_read_b128 v[188:191], v174 offset:50176
	ds_read_b128 v[192:195], v174 offset:51200
	ds_read_b128 v[196:199], v174 offset:52224
	ds_read_b128 v[200:203], v174 offset:53248
	ds_read_b128 v[204:207], v174 offset:54272
	ds_read_b128 v[208:211], v174 offset:55296
	ds_read_b128 v[212:215], v174 offset:56320
	global_load_lds_dwordx4 v148, s[98:99] offset:128
	s_add_i32 m0, s24, 0x1f80
	s_add_u32 s22, s22, 0x20080
	s_addc_u32 s23, s23, 0
	s_add_i32 s24, s57, s30
	global_load_lds_dwordx4 v152, s[98:99] offset:128
	s_mov_b32 m0, s24
	s_nop 0
	global_load_lds_dwordx4 v148, s[22:23]
	s_add_i32 m0, s24, 0x2000
	s_nop 0
	global_load_lds_dwordx4 v152, s[22:23]
	s_add_i32 m0, s40, 0xffffff80
	s_nop 0
	global_load_lds_dwordx4 v146, s[100:101] offset:128
	s_add_i32 m0, s41, 0xffffff80
	s_nop 0
	global_load_lds_dwordx4 v150, s[100:101] offset:128
	s_waitcnt vmcnt(8) lgkmcnt(0)
	s_barrier
	v_mfma_f32_16x16x32_bf16 v[70:73], v[58:61], v[184:187], v[70:73]
	v_mfma_f32_16x16x32_bf16 v[66:69], v[74:77], v[184:187], v[66:69]
	v_mfma_f32_16x16x32_bf16 v[46:49], v[58:61], v[192:195], v[46:49]
	v_mfma_f32_16x16x32_bf16 v[42:45], v[74:77], v[192:195], v[42:45]
	v_mfma_f32_16x16x32_bf16 v[30:33], v[58:61], v[200:203], v[30:33]
	v_mfma_f32_16x16x32_bf16 v[26:29], v[74:77], v[200:203], v[26:29]
	v_mfma_f32_16x16x32_bf16 v[14:17], v[58:61], v[208:211], v[14:17]
	v_mfma_f32_16x16x32_bf16 v[10:13], v[74:77], v[208:211], v[10:13]
	v_mfma_f32_16x16x32_bf16 v[70:73], v[62:65], v[188:191], v[70:73]
	v_mfma_f32_16x16x32_bf16 v[66:69], v[78:81], v[188:191], v[66:69]
	v_mfma_f32_16x16x32_bf16 v[46:49], v[62:65], v[196:199], v[46:49]
	v_mfma_f32_16x16x32_bf16 v[42:45], v[78:81], v[196:199], v[42:45]
	v_mfma_f32_16x16x32_bf16 v[30:33], v[62:65], v[204:207], v[30:33]
	v_mfma_f32_16x16x32_bf16 v[26:29], v[78:81], v[204:207], v[26:29]
	v_mfma_f32_16x16x32_bf16 v[14:17], v[62:65], v[212:215], v[14:17]
	v_mfma_f32_16x16x32_bf16 v[10:13], v[78:81], v[212:215], v[10:13]
	v_mfma_f32_16x16x32_bf16 v[54:57], v[164:167], v[184:187], v[54:57]
	v_mfma_f32_16x16x32_bf16 v[50:53], v[176:179], v[184:187], v[50:53]
	v_mfma_f32_16x16x32_bf16 v[38:41], v[164:167], v[192:195], v[38:41]
	v_mfma_f32_16x16x32_bf16 v[34:37], v[176:179], v[192:195], v[34:37]
	v_mfma_f32_16x16x32_bf16 v[22:25], v[164:167], v[200:203], v[22:25]
	v_mfma_f32_16x16x32_bf16 v[18:21], v[176:179], v[200:203], v[18:21]
	v_mfma_f32_16x16x32_bf16 v[6:9], v[164:167], v[208:211], v[6:9]
	v_mfma_f32_16x16x32_bf16 v[2:5], v[176:179], v[208:211], v[2:5]
	v_mfma_f32_16x16x32_bf16 v[54:57], v[168:171], v[188:191], v[54:57]
	v_mfma_f32_16x16x32_bf16 v[50:53], v[180:183], v[188:191], v[50:53]
	v_mfma_f32_16x16x32_bf16 v[38:41], v[168:171], v[196:199], v[38:41]
	v_mfma_f32_16x16x32_bf16 v[34:37], v[180:183], v[196:199], v[34:37]
	v_mfma_f32_16x16x32_bf16 v[22:25], v[168:171], v[204:207], v[22:25]
	v_mfma_f32_16x16x32_bf16 v[18:21], v[180:183], v[204:207], v[18:21]
	v_mfma_f32_16x16x32_bf16 v[6:9], v[168:171], v[212:215], v[6:9]
	v_mfma_f32_16x16x32_bf16 v[2:5], v[180:183], v[212:215], v[2:5]
	s_barrier
	s_add_u32 s8, s8, 0x100
	s_addc_u32 s9, s9, 0
	s_add_u32 s17, s17, 0x100
	s_addc_u32 s19, s19, 0
	s_cmp_ge_u32 s47, s7
	s_mov_b32 s22, s47
	s_cbranch_scc0 .LBB0_1092
	s_and_b64 vcc, exec, s[14:15]
	s_cbranch_vccz .LBB0_1095
	s_barrier

; __device__ __forceinline__ u32x4 pack8(const f32x4 v0, const f32x4 v1) { u32x4 w; w.x = cvt_pk_bf16(v0[0], v0[1]); w.y = cvt_pk_bf16(v0[2], v0[3]); w.z = cvt_pk_bf16(v1[0], v1[1]); w.w = cvt_pk_bf16(v1[2], v1[3]); return w; }
; __device__ __forceinline__ f32x4 sig4(const f32x4 v) { return (f32x4){sigmoidf_(v[0]), sigmoidf_(v[1]), sigmoidf_(v[2]), sigmoidf_(v[3])}; }
;     __device__ __forceinline__ void operator()(AccRef acc, const Unit& u, int wr, int wc, int fr, int fq) const {
;     ...
; #pragma unroll
;         for (int ai = 0; ai < 2; ++ai)
; #pragma unroll
;             for (int m = 0; m < 4; ++m) { const int r = row0 + ai * HALF + m * 16; bf16_t* rowp = base + (size_t)r * 2048 + col0;
; #pragma unroll
;                 for (int bj = 0; bj < 2; ++bj) { f32x4 v0 = acc[ai][bj][m][0] + bv[bj][0], v1 = acc[ai][bj][m][1] + bv[bj][1];
;                     if (third < 2) { v0 = sig4(v0) * mul; v1 = sig4(v1) * mul; }
;                     *(u32x4*)(rowp + bj * HALF) = pack8(v0, v1); } }
.LBB0_1105:
	v_ashrrev_i32_e32 v138, 2, v176
	v_and_b32_e32 v138, 0xffffffc0, v138
	s_ashr_i32 s23, s22, 31
	v_lshl_add_u32 v138, s2, 8, v138
	s_lshl_b64 s[2:3], s[22:23], 26
	v_and_or_b32 v138, v176, 15, v138
	s_add_u32 s2, s38, s2
	s_addc_u32 s3, s39, s3
	v_lshlrev_b32_e32 v154, 1, v177
	v_ashrrev_i32_e32 v139, 31, v138
	v_lshl_add_u64 v[140:141], s[2:3], 0, v[154:155]
	v_lshlrev_b64 v[142:143], 12, v[138:139]
	v_lshl_add_u64 v[142:143], v[140:141], 0, v[142:143]
	v_pk_add_f32 v[136:137], v[136:137], v[64:65]
	v_pk_add_f32 v[134:135], v[134:135], v[62:63]
	v_pk_add_f32 v[132:133], v[132:133], v[60:61]
	s_and_b64 vcc, exec, s[6:7]
	v_pk_add_f32 v[130:131], v[130:131], v[58:59]
	v_cvt_pk_bf16_f32 v176, v170, v171
	v_cvt_pk_bf16_f32 v177, v168, v169
	v_cvt_pk_bf16_f32 v178, v166, v167
	v_cvt_pk_bf16_f32 v179, v144, v145
	global_store_dwordx4 v[142:143], v[176:179], off
	s_cbranch_vccnz .LBB0_1107
	v_mul_f32_e32 v134, 0xbfb8aa3b, v134
	v_mul_f32_e32 v135, 0xbfb8aa3b, v135
	v_mul_f32_e32 v136, 0xbfb8aa3b, v136
	v_mul_f32_e32 v137, 0xbfb8aa3b, v137
	v_mul_f32_e32 v130, 0xbfb8aa3b, v130
	v_mul_f32_e32 v131, 0xbfb8aa3b, v131
	v_mul_f32_e32 v132, 0xbfb8aa3b, v132
	v_mul_f32_e32 v133, 0xbfb8aa3b, v133
	v_exp_f32_e32 v134, v134
	v_exp_f32_e32 v135, v135
	v_exp_f32_e32 v136, v136
	v_exp_f32_e32 v137, v137
	v_exp_f32_e32 v130, v130
	v_exp_f32_e32 v131, v131
	v_exp_f32_e32 v132, v132
	v_exp_f32_e32 v133, v133
	v_add_f32_e32 v134, 1.0, v134
	v_add_f32_e32 v135, 1.0, v135
	v_add_f32_e32 v136, 1.0, v136
	v_add_f32_e32 v137, 1.0, v137
	v_add_f32_e32 v130, 1.0, v130
	v_add_f32_e32 v131, 1.0, v131
	v_add_f32_e32 v132, 1.0, v132
	v_add_f32_e32 v133, 1.0, v133
	v_rcp_f32_e32 v134, v134
	v_rcp_f32_e32 v135, v135
	v_rcp_f32_e32 v136, v136
	v_rcp_f32_e32 v137, v137
	v_rcp_f32_e32 v130, v130
	v_rcp_f32_e32 v132, v132
	v_rcp_f32_e32 v133, v133
	v_rcp_f32_e32 v131, v131
	v_mov_b32_e32 v144, v164
	v_mov_b32_e32 v145, v164
	v_pk_mul_f32 v[136:137], v[144:145], v[136:137]
	v_pk_mul_f32 v[134:135], v[164:165], v[134:135]
	v_pk_mul_f32 v[132:133], v[144:145], v[132:133]
	v_pk_mul_f32 v[130:131], v[164:165], v[130:131]
.LBB0_1107:
	v_cvt_pk_bf16_f32 v134, v134, v135
	v_cvt_pk_bf16_f32 v135, v136, v137
	s_nop 0
	v_cvt_pk_bf16_f32 v136, v130, v131
	v_pk_add_f32 v[128:129], v[128:129], v[80:81]
	v_pk_add_f32 v[130:131], v[126:127], v[78:79]
	v_pk_add_f32 v[124:125], v[124:125], v[76:77]
	s_and_b64 vcc, exec, s[6:7]
	v_pk_add_f32 v[126:127], v[122:123], v[74:75]
	v_cvt_pk_bf16_f32 v137, v132, v133
	global_store_dwordx4 v[142:143], v[134:137], off offset:256
	s_cbranch_vccnz .LBB0_1109
	v_mul_f32_e32 v122, 0xbfb8aa3b, v130
	v_mul_f32_e32 v123, 0xbfb8aa3b, v131
	v_mul_f32_e32 v128, 0xbfb8aa3b, v128
	v_mul_f32_e32 v129, 0xbfb8aa3b, v129
	v_mul_f32_e32 v126, 0xbfb8aa3b, v126
	v_mul_f32_e32 v127, 0xbfb8aa3b, v127
	v_mul_f32_e32 v124, 0xbfb8aa3b, v124
	v_mul_f32_e32 v125, 0xbfb8aa3b, v125
	v_exp_f32_e32 v122, v122
	v_exp_f32_e32 v123, v123
	v_exp_f32_e32 v128, v128
	v_exp_f32_e32 v129, v129
	v_exp_f32_e32 v126, v126
	v_exp_f32_e32 v127, v127
	v_exp_f32_e32 v124, v124
	v_exp_f32_e32 v125, v125
	v_add_f32_e32 v122, 1.0, v122
	v_add_f32_e32 v123, 1.0, v123
	v_add_f32_e32 v128, 1.0, v128
	v_add_f32_e32 v129, 1.0, v129
	v_add_f32_e32 v126, 1.0, v126
	v_add_f32_e32 v127, 1.0, v127
	v_add_f32_e32 v124, 1.0, v124
	v_add_f32_e32 v125, 1.0, v125
	v_rcp_f32_e32 v122, v122
	v_rcp_f32_e32 v123, v123
	v_rcp_f32_e32 v128, v128
	v_rcp_f32_e32 v129, v129
	v_rcp_f32_e32 v126, v126
	v_rcp_f32_e32 v124, v124
	v_rcp_f32_e32 v125, v125
	v_rcp_f32_e32 v127, v127
	v_mov_b32_e32 v132, v164
	v_mov_b32_e32 v133, v164
	v_pk_mul_f32 v[128:129], v[132:133], v[128:129]
	v_pk_mul_f32 v[130:131], v[164:165], v[122:123]
	v_pk_mul_f32 v[124:125], v[132:133], v[124:125]
	v_pk_mul_f32 v[126:127], v[164:165], v[126:127]
.LBB0_1109:
	v_or_b32_e32 v122, 16, v138
	v_ashrrev_i32_e32 v123, 31, v122
	v_lshlrev_b64 v[122:123], 12, v[122:123]
	v_lshl_add_u64 v[122:123], v[140:141], 0, v[122:123]
	v_pk_add_f32 v[120:121], v[120:121], v[64:65]
	v_pk_add_f32 v[118:119], v[118:119], v[62:63]
	v_pk_add_f32 v[116:117], v[116:117], v[60:61]
	s_and_b64 vcc, exec, s[6:7]
	v_pk_add_f32 v[114:115], v[114:115], v[58:59]
	v_cvt_pk_bf16_f32 v130, v130, v131
	v_cvt_pk_bf16_f32 v131, v128, v129
	v_cvt_pk_bf16_f32 v132, v126, v127
	v_cvt_pk_bf16_f32 v133, v124, v125
	global_store_dwordx4 v[122:123], v[130:133], off
	s_cbranch_vccnz .LBB0_1111
	v_mul_f32_e32 v118, 0xbfb8aa3b, v118
	v_mul_f32_e32 v119, 0xbfb8aa3b, v119
	v_mul_f32_e32 v120, 0xbfb8aa3b, v120
	v_mul_f32_e32 v121, 0xbfb8aa3b, v121
	v_mul_f32_e32 v114, 0xbfb8aa3b, v114
	v_mul_f32_e32 v115, 0xbfb8aa3b, v115
	v_mul_f32_e32 v116, 0xbfb8aa3b, v116
	v_mul_f32_e32 v117, 0xbfb8aa3b, v117
	v_exp_f32_e32 v118, v118
	v_exp_f32_e32 v119, v119
	v_exp_f32_e32 v120, v120
	v_exp_f32_e32 v121, v121
	v_exp_f32_e32 v114, v114
	v_exp_f32_e32 v115, v115
	v_exp_f32_e32 v116, v116
	v_exp_f32_e32 v117, v117
	v_add_f32_e32 v118, 1.0, v118
	v_add_f32_e32 v119, 1.0, v119
	v_add_f32_e32 v120, 1.0, v120
	v_add_f32_e32 v121, 1.0, v121
	v_add_f32_e32 v114, 1.0, v114
	v_add_f32_e32 v115, 1.0, v115
	v_add_f32_e32 v116, 1.0, v116
	v_add_f32_e32 v117, 1.0, v117
	v_rcp_f32_e32 v118, v118
	v_rcp_f32_e32 v119, v119
	v_rcp_f32_e32 v120, v120
	v_rcp_f32_e32 v121, v121
	v_rcp_f32_e32 v114, v114
	v_rcp_f32_e32 v116, v116
	v_rcp_f32_e32 v117, v117
	v_rcp_f32_e32 v115, v115
	v_mov_b32_e32 v124, v164
	v_mov_b32_e32 v125, v164
	v_pk_mul_f32 v[120:121], v[124:125], v[120:121]
	v_pk_mul_f32 v[118:119], v[164:165], v[118:119]
	v_pk_mul_f32 v[116:117], v[124:125], v[116:117]
	v_pk_mul_f32 v[114:115], v[164:165], v[114:115]
; __device__ __forceinline__ u32x4 pack8(const f32x4 v0, const f32x4 v1) { u32x4 w; w.x = cvt_pk_bf16(v0[0], v0[1]); w.y = cvt_pk_bf16(v0[2], v0[3]); w.z = cvt_pk_bf16(v1[0], v1[1]); w.w = cvt_pk_bf16(v1[2], v1[3]); return w; }
; __device__ __forceinline__ f32x4 sig4(const f32x4 v) { return (f32x4){sigmoidf_(v[0]), sigmoidf_(v[1]), sigmoidf_(v[2]), sigmoidf_(v[3])}; }
;     __device__ __forceinline__ void operator()(AccRef acc, const Unit& u, int wr, int wc, int fr, int fq) const {
;     ...
; #pragma unroll
;         for (int ai = 0; ai < 2; ++ai)
; #pragma unroll
;             for (int m = 0; m < 4; ++m) { const int r = row0 + ai * HALF + m * 16; bf16_t* rowp = base + (size_t)r * 2048 + col0;
; #pragma unroll
;                 for (int bj = 0; bj < 2; ++bj) { f32x4 v0 = acc[ai][bj][m][0] + bv[bj][0], v1 = acc[ai][bj][m][1] + bv[bj][1];
;                     if (third < 2) { v0 = sig4(v0) * mul; v1 = sig4(v1) * mul; }
;                     *(u32x4*)(rowp + bj * HALF) = pack8(v0, v1); } }
.LBB0_1111:
	v_cvt_pk_bf16_f32 v118, v118, v119
	v_cvt_pk_bf16_f32 v119, v120, v121
	s_nop 0
	v_cvt_pk_bf16_f32 v120, v114, v115
	v_pk_add_f32 v[112:113], v[112:113], v[80:81]
	v_pk_add_f32 v[114:115], v[110:111], v[78:79]
	v_pk_add_f32 v[108:109], v[108:109], v[76:77]
	s_and_b64 vcc, exec, s[6:7]
	v_pk_add_f32 v[110:111], v[106:107], v[74:75]
	v_cvt_pk_bf16_f32 v121, v116, v117
	global_store_dwordx4 v[122:123], v[118:121], off offset:256
	s_cbranch_vccnz .LBB0_1113
	v_mul_f32_e32 v106, 0xbfb8aa3b, v114
	v_mul_f32_e32 v107, 0xbfb8aa3b, v115
	v_mul_f32_e32 v112, 0xbfb8aa3b, v112
	v_mul_f32_e32 v113, 0xbfb8aa3b, v113
	v_mul_f32_e32 v110, 0xbfb8aa3b, v110
	v_mul_f32_e32 v111, 0xbfb8aa3b, v111
	v_mul_f32_e32 v108, 0xbfb8aa3b, v108
	v_mul_f32_e32 v109, 0xbfb8aa3b, v109
	v_exp_f32_e32 v106, v106
	v_exp_f32_e32 v107, v107
	v_exp_f32_e32 v112, v112
	v_exp_f32_e32 v113, v113
	v_exp_f32_e32 v110, v110
	v_exp_f32_e32 v111, v111
	v_exp_f32_e32 v108, v108
	v_exp_f32_e32 v109, v109
	v_add_f32_e32 v106, 1.0, v106
	v_add_f32_e32 v107, 1.0, v107
	v_add_f32_e32 v112, 1.0, v112
	v_add_f32_e32 v113, 1.0, v113
	v_add_f32_e32 v110, 1.0, v110
	v_add_f32_e32 v111, 1.0, v111
	v_add_f32_e32 v108, 1.0, v108
	v_add_f32_e32 v109, 1.0, v109
	v_rcp_f32_e32 v106, v106
	v_rcp_f32_e32 v107, v107
	v_rcp_f32_e32 v112, v112
	v_rcp_f32_e32 v113, v113
	v_rcp_f32_e32 v110, v110
	v_rcp_f32_e32 v108, v108
	v_rcp_f32_e32 v109, v109
	v_rcp_f32_e32 v111, v111
	v_mov_b32_e32 v116, v164
	v_mov_b32_e32 v117, v164
	v_pk_mul_f32 v[112:113], v[116:117], v[112:113]
	v_pk_mul_f32 v[114:115], v[164:165], v[106:107]
	v_pk_mul_f32 v[108:109], v[116:117], v[108:109]
	v_pk_mul_f32 v[110:111], v[164:165], v[110:111]
.LBB0_1113:
	v_or_b32_e32 v106, 32, v138
	v_ashrrev_i32_e32 v107, 31, v106
	v_lshlrev_b64 v[106:107], 12, v[106:107]
	v_lshl_add_u64 v[106:107], v[140:141], 0, v[106:107]
	v_pk_add_f32 v[104:105], v[104:105], v[64:65]
	v_pk_add_f32 v[102:103], v[102:103], v[62:63]
	v_pk_add_f32 v[100:101], v[100:101], v[60:61]
	s_and_b64 vcc, exec, s[6:7]
	v_pk_add_f32 v[98:99], v[98:99], v[58:59]
	v_cvt_pk_bf16_f32 v114, v114, v115
	v_cvt_pk_bf16_f32 v115, v112, v113
	v_cvt_pk_bf16_f32 v116, v110, v111
	v_cvt_pk_bf16_f32 v117, v108, v109
	global_store_dwordx4 v[106:107], v[114:117], off
	s_cbranch_vccnz .LBB0_1115
	v_mul_f32_e32 v102, 0xbfb8aa3b, v102
	v_mul_f32_e32 v103, 0xbfb8aa3b, v103
	v_mul_f32_e32 v104, 0xbfb8aa3b, v104
	v_mul_f32_e32 v105, 0xbfb8aa3b, v105
	v_mul_f32_e32 v98, 0xbfb8aa3b, v98
	v_mul_f32_e32 v99, 0xbfb8aa3b, v99
	v_mul_f32_e32 v100, 0xbfb8aa3b, v100
	v_mul_f32_e32 v101, 0xbfb8aa3b, v101
	v_exp_f32_e32 v102, v102
	v_exp_f32_e32 v103, v103
	v_exp_f32_e32 v104, v104
	v_exp_f32_e32 v105, v105
	v_exp_f32_e32 v98, v98
	v_exp_f32_e32 v99, v99
	v_exp_f32_e32 v100, v100
	v_exp_f32_e32 v101, v101
	v_add_f32_e32 v102, 1.0, v102
	v_add_f32_e32 v103, 1.0, v103
	v_add_f32_e32 v104, 1.0, v104
	v_add_f32_e32 v105, 1.0, v105
	v_add_f32_e32 v98, 1.0, v98
	v_add_f32_e32 v99, 1.0, v99
	v_add_f32_e32 v100, 1.0, v100
	v_add_f32_e32 v101, 1.0, v101
	v_rcp_f32_e32 v102, v102
	v_rcp_f32_e32 v103, v103
	v_rcp_f32_e32 v104, v104
	v_rcp_f32_e32 v105, v105
	v_rcp_f32_e32 v98, v98
	v_rcp_f32_e32 v100, v100
	v_rcp_f32_e32 v101, v101
	v_rcp_f32_e32 v99, v99
	v_mov_b32_e32 v108, v164
	v_mov_b32_e32 v109, v164
	v_pk_mul_f32 v[104:105], v[108:109], v[104:105]
	v_pk_mul_f32 v[102:103], v[164:165], v[102:103]
	v_pk_mul_f32 v[100:101], v[108:109], v[100:101]
	v_pk_mul_f32 v[98:99], v[164:165], v[98:99]
.LBB0_1115:
	v_cvt_pk_bf16_f32 v102, v102, v103
	v_cvt_pk_bf16_f32 v103, v104, v105
	s_nop 0
	v_cvt_pk_bf16_f32 v104, v98, v99
	v_pk_add_f32 v[96:97], v[96:97], v[80:81]
	v_pk_add_f32 v[98:99], v[94:95], v[78:79]
	v_pk_add_f32 v[92:93], v[92:93], v[76:77]
	s_and_b64 vcc, exec, s[6:7]
	v_pk_add_f32 v[94:95], v[90:91], v[74:75]
	v_cvt_pk_bf16_f32 v105, v100, v101
	global_store_dwordx4 v[106:107], v[102:105], off offset:256
	s_cbranch_vccnz .LBB0_1117
	v_mul_f32_e32 v90, 0xbfb8aa3b, v98
	v_mul_f32_e32 v91, 0xbfb8aa3b, v99
	v_mul_f32_e32 v96, 0xbfb8aa3b, v96
	v_mul_f32_e32 v97, 0xbfb8aa3b, v97
	v_mul_f32_e32 v94, 0xbfb8aa3b, v94
	v_mul_f32_e32 v95, 0xbfb8aa3b, v95
	v_mul_f32_e32 v92, 0xbfb8aa3b, v92
	v_mul_f32_e32 v93, 0xbfb8aa3b, v93
	v_exp_f32_e32 v90, v90
	v_exp_f32_e32 v91, v91
	v_exp_f32_e32 v96, v96
	v_exp_f32_e32 v97, v97
	v_exp_f32_e32 v94, v94
	v_exp_f32_e32 v95, v95
	v_exp_f32_e32 v92, v92
	v_exp_f32_e32 v93, v93
	v_add_f32_e32 v90, 1.0, v90
	v_add_f32_e32 v91, 1.0, v91
	v_add_f32_e32 v96, 1.0, v96
	v_add_f32_e32 v97, 1.0, v97
	v_add_f32_e32 v94, 1.0, v94
	v_add_f32_e32 v95, 1.0, v95
	v_add_f32_e32 v92, 1.0, v92
	v_add_f32_e32 v93, 1.0, v93
	v_rcp_f32_e32 v90, v90
	v_rcp_f32_e32 v91, v91
	v_rcp_f32_e32 v96, v96
	v_rcp_f32_e32 v97, v97
	v_rcp_f32_e32 v94, v94
	v_rcp_f32_e32 v92, v92
	v_rcp_f32_e32 v93, v93
	v_rcp_f32_e32 v95, v95
	v_mov_b32_e32 v100, v164
	v_mov_b32_e32 v101, v164
	v_pk_mul_f32 v[96:97], v[100:101], v[96:97]
	v_pk_mul_f32 v[98:99], v[164:165], v[90:91]
	v_pk_mul_f32 v[92:93], v[100:101], v[92:93]
	v_pk_mul_f32 v[94:95], v[164:165], v[94:95]
; __device__ __forceinline__ u32x4 pack8(const f32x4 v0, const f32x4 v1) { u32x4 w; w.x = cvt_pk_bf16(v0[0], v0[1]); w.y = cvt_pk_bf16(v0[2], v0[3]); w.z = cvt_pk_bf16(v1[0], v1[1]); w.w = cvt_pk_bf16(v1[2], v1[3]); return w; }
; __device__ __forceinline__ f32x4 sig4(const f32x4 v) { return (f32x4){sigmoidf_(v[0]), sigmoidf_(v[1]), sigmoidf_(v[2]), sigmoidf_(v[3])}; }
;     __device__ __forceinline__ void operator()(AccRef acc, const Unit& u, int wr, int wc, int fr, int fq) const {
;     ...
; #pragma unroll
;         for (int ai = 0; ai < 2; ++ai)
; #pragma unroll
;             for (int m = 0; m < 4; ++m) { const int r = row0 + ai * HALF + m * 16; bf16_t* rowp = base + (size_t)r * 2048 + col0;
; #pragma unroll
;                 for (int bj = 0; bj < 2; ++bj) { f32x4 v0 = acc[ai][bj][m][0] + bv[bj][0], v1 = acc[ai][bj][m][1] + bv[bj][1];
;                     if (third < 2) { v0 = sig4(v0) * mul; v1 = sig4(v1) * mul; }
;                     *(u32x4*)(rowp + bj * HALF) = pack8(v0, v1); } }
.LBB0_1117:
	v_or_b32_e32 v90, 48, v138
	v_ashrrev_i32_e32 v91, 31, v90
	v_lshlrev_b64 v[90:91], 12, v[90:91]
	v_lshl_add_u64 v[90:91], v[140:141], 0, v[90:91]
	v_pk_add_f32 v[88:89], v[88:89], v[64:65]
	v_pk_add_f32 v[86:87], v[86:87], v[62:63]
	v_pk_add_f32 v[84:85], v[84:85], v[60:61]
	s_and_b64 vcc, exec, s[6:7]
	v_pk_add_f32 v[82:83], v[82:83], v[58:59]
	v_cvt_pk_bf16_f32 v98, v98, v99
	v_cvt_pk_bf16_f32 v99, v96, v97
	v_cvt_pk_bf16_f32 v100, v94, v95
	v_cvt_pk_bf16_f32 v101, v92, v93
	global_store_dwordx4 v[90:91], v[98:101], off
	s_cbranch_vccnz .LBB0_1119
	v_mul_f32_e32 v86, 0xbfb8aa3b, v86
	v_mul_f32_e32 v87, 0xbfb8aa3b, v87
	v_mul_f32_e32 v88, 0xbfb8aa3b, v88
	v_mul_f32_e32 v89, 0xbfb8aa3b, v89
	v_mul_f32_e32 v82, 0xbfb8aa3b, v82
	v_mul_f32_e32 v83, 0xbfb8aa3b, v83
	v_mul_f32_e32 v84, 0xbfb8aa3b, v84
	v_mul_f32_e32 v85, 0xbfb8aa3b, v85
	v_exp_f32_e32 v86, v86
	v_exp_f32_e32 v87, v87
	v_exp_f32_e32 v88, v88
	v_exp_f32_e32 v89, v89
	v_exp_f32_e32 v82, v82
	v_exp_f32_e32 v83, v83
	v_exp_f32_e32 v84, v84
	v_exp_f32_e32 v85, v85
	v_add_f32_e32 v86, 1.0, v86
	v_add_f32_e32 v87, 1.0, v87
	v_add_f32_e32 v88, 1.0, v88
	v_add_f32_e32 v89, 1.0, v89
	v_add_f32_e32 v82, 1.0, v82
	v_add_f32_e32 v83, 1.0, v83
	v_add_f32_e32 v84, 1.0, v84
	v_add_f32_e32 v85, 1.0, v85
	v_rcp_f32_e32 v86, v86
	v_rcp_f32_e32 v87, v87
	v_rcp_f32_e32 v88, v88
	v_rcp_f32_e32 v89, v89
	v_rcp_f32_e32 v82, v82
	v_rcp_f32_e32 v84, v84
	v_rcp_f32_e32 v85, v85
	v_rcp_f32_e32 v83, v83
	v_mov_b32_e32 v92, v164
	v_mov_b32_e32 v93, v164
	v_pk_mul_f32 v[88:89], v[92:93], v[88:89]
	v_pk_mul_f32 v[86:87], v[164:165], v[86:87]
	v_pk_mul_f32 v[84:85], v[92:93], v[84:85]
	v_pk_mul_f32 v[82:83], v[164:165], v[82:83]
.LBB0_1119:
	v_cvt_pk_bf16_f32 v86, v86, v87
	v_cvt_pk_bf16_f32 v87, v88, v89
	s_nop 0
	v_cvt_pk_bf16_f32 v88, v82, v83
	v_pk_add_f32 v[72:73], v[72:73], v[80:81]
	v_pk_add_f32 v[82:83], v[70:71], v[78:79]
	v_pk_add_f32 v[68:69], v[68:69], v[76:77]
	s_and_b64 vcc, exec, s[6:7]
	v_pk_add_f32 v[70:71], v[66:67], v[74:75]
	v_cvt_pk_bf16_f32 v89, v84, v85
	global_store_dwordx4 v[90:91], v[86:89], off offset:256
	s_cbranch_vccnz .LBB0_1121
	v_mul_f32_e32 v66, 0xbfb8aa3b, v82
	v_mul_f32_e32 v67, 0xbfb8aa3b, v83
	v_mul_f32_e32 v72, 0xbfb8aa3b, v72
	v_mul_f32_e32 v73, 0xbfb8aa3b, v73
	v_mul_f32_e32 v70, 0xbfb8aa3b, v70
	v_mul_f32_e32 v71, 0xbfb8aa3b, v71
	v_mul_f32_e32 v68, 0xbfb8aa3b, v68
	v_mul_f32_e32 v69, 0xbfb8aa3b, v69
	v_exp_f32_e32 v66, v66
	v_exp_f32_e32 v67, v67
	v_exp_f32_e32 v72, v72
	v_exp_f32_e32 v73, v73
	v_exp_f32_e32 v70, v70
	v_exp_f32_e32 v71, v71
	v_exp_f32_e32 v68, v68
	v_exp_f32_e32 v69, v69
	v_add_f32_e32 v66, 1.0, v66
	v_add_f32_e32 v67, 1.0, v67
	v_add_f32_e32 v72, 1.0, v72
	v_add_f32_e32 v73, 1.0, v73
	v_add_f32_e32 v70, 1.0, v70
	v_add_f32_e32 v71, 1.0, v71
	v_add_f32_e32 v68, 1.0, v68
	v_add_f32_e32 v69, 1.0, v69
	v_rcp_f32_e32 v66, v66
	v_rcp_f32_e32 v67, v67
	v_rcp_f32_e32 v72, v72
	v_rcp_f32_e32 v73, v73
	v_rcp_f32_e32 v70, v70
	v_rcp_f32_e32 v68, v68
	v_rcp_f32_e32 v69, v69
	v_rcp_f32_e32 v71, v71
	v_mov_b32_e32 v84, v164
	v_mov_b32_e32 v85, v164
	v_pk_mul_f32 v[72:73], v[84:85], v[72:73]
	v_pk_mul_f32 v[82:83], v[164:165], v[66:67]
	v_pk_mul_f32 v[68:69], v[84:85], v[68:69]
	v_pk_mul_f32 v[70:71], v[164:165], v[70:71]
.LBB0_1121:
	v_lshlrev_b64 v[66:67], 12, v[138:139]
	v_lshl_add_u64 v[66:67], v[140:141], 0, v[66:67]
	s_mov_b32 s2, 0x80000
	v_cvt_pk_bf16_f32 v82, v82, v83
	v_cvt_pk_bf16_f32 v83, v72, v73
	v_cvt_pk_bf16_f32 v84, v70, v71
	v_cvt_pk_bf16_f32 v85, v68, v69
	v_add_co_u32_e32 v68, vcc, s2, v66
	v_pk_add_f32 v[56:57], v[56:57], v[64:65]
	s_nop 0
	v_addc_co_u32_e32 v69, vcc, 0, v67, vcc
	v_pk_add_f32 v[54:55], v[54:55], v[62:63]
	v_pk_add_f32 v[52:53], v[52:53], v[60:61]
	s_and_b64 vcc, exec, s[6:7]
	v_pk_add_f32 v[50:51], v[50:51], v[58:59]
	global_store_dwordx4 v[68:69], v[82:85], off
	s_cbranch_vccnz .LBB0_1123
	v_mul_f32_e32 v54, 0xbfb8aa3b, v54
	v_mul_f32_e32 v55, 0xbfb8aa3b, v55
	v_mul_f32_e32 v56, 0xbfb8aa3b, v56
	v_mul_f32_e32 v57, 0xbfb8aa3b, v57
	v_mul_f32_e32 v50, 0xbfb8aa3b, v50
	v_mul_f32_e32 v51, 0xbfb8aa3b, v51
	v_mul_f32_e32 v52, 0xbfb8aa3b, v52
	v_mul_f32_e32 v53, 0xbfb8aa3b, v53
	v_exp_f32_e32 v54, v54
	v_exp_f32_e32 v55, v55
	v_exp_f32_e32 v56, v56
	v_exp_f32_e32 v57, v57
	v_exp_f32_e32 v50, v50
	v_exp_f32_e32 v51, v51
	v_exp_f32_e32 v52, v52
	v_exp_f32_e32 v53, v53
	v_add_f32_e32 v54, 1.0, v54
	v_add_f32_e32 v55, 1.0, v55
	v_add_f32_e32 v56, 1.0, v56
	v_add_f32_e32 v57, 1.0, v57
	v_add_f32_e32 v50, 1.0, v50
	v_add_f32_e32 v51, 1.0, v51
	v_add_f32_e32 v52, 1.0, v52
	v_add_f32_e32 v53, 1.0, v53
	v_rcp_f32_e32 v54, v54
	v_rcp_f32_e32 v55, v55
	v_rcp_f32_e32 v56, v56
	v_rcp_f32_e32 v57, v57
	v_rcp_f32_e32 v50, v50
	v_rcp_f32_e32 v52, v52
	v_rcp_f32_e32 v53, v53
	v_rcp_f32_e32 v51, v51
	v_mov_b32_e32 v68, v164
	v_mov_b32_e32 v69, v164
	v_pk_mul_f32 v[56:57], v[68:69], v[56:57]
	v_pk_mul_f32 v[54:55], v[164:165], v[54:55]
	v_pk_mul_f32 v[52:53], v[68:69], v[52:53]
	v_pk_mul_f32 v[50:51], v[164:165], v[50:51]
; __device__ __forceinline__ u32x4 pack8(const f32x4 v0, const f32x4 v1) { u32x4 w; w.x = cvt_pk_bf16(v0[0], v0[1]); w.y = cvt_pk_bf16(v0[2], v0[3]); w.z = cvt_pk_bf16(v1[0], v1[1]); w.w = cvt_pk_bf16(v1[2], v1[3]); return w; }
; __device__ __forceinline__ f32x4 sig4(const f32x4 v) { return (f32x4){sigmoidf_(v[0]), sigmoidf_(v[1]), sigmoidf_(v[2]), sigmoidf_(v[3])}; }
;     __device__ __forceinline__ void operator()(AccRef acc, const Unit& u, int wr, int wc, int fr, int fq) const {
;     ...
; #pragma unroll
;         for (int ai = 0; ai < 2; ++ai)
; #pragma unroll
;             for (int m = 0; m < 4; ++m) { const int r = row0 + ai * HALF + m * 16; bf16_t* rowp = base + (size_t)r * 2048 + col0;
; #pragma unroll
;                 for (int bj = 0; bj < 2; ++bj) { f32x4 v0 = acc[ai][bj][m][0] + bv[bj][0], v1 = acc[ai][bj][m][1] + bv[bj][1];
;                     if (third < 2) { v0 = sig4(v0) * mul; v1 = sig4(v1) * mul; }
;                     *(u32x4*)(rowp + bj * HALF) = pack8(v0, v1); } }
.LBB0_1123:
	s_mov_b64 s[2:3], 0x80000
	v_lshl_add_u64 v[66:67], v[66:67], 0, s[2:3]
	v_cvt_pk_bf16_f32 v54, v54, v55
	v_cvt_pk_bf16_f32 v55, v56, v57
	v_cvt_pk_bf16_f32 v56, v50, v51
	v_pk_add_f32 v[48:49], v[48:49], v[80:81]
	v_pk_add_f32 v[50:51], v[46:47], v[78:79]
	v_pk_add_f32 v[44:45], v[44:45], v[76:77]
	s_and_b64 vcc, exec, s[6:7]
	v_pk_add_f32 v[46:47], v[42:43], v[74:75]
	v_cvt_pk_bf16_f32 v57, v52, v53
	global_store_dwordx4 v[66:67], v[54:57], off offset:256
	s_cbranch_vccnz .LBB0_1125
	v_mul_f32_e32 v42, 0xbfb8aa3b, v50
	v_mul_f32_e32 v43, 0xbfb8aa3b, v51
	v_mul_f32_e32 v48, 0xbfb8aa3b, v48
	v_mul_f32_e32 v49, 0xbfb8aa3b, v49
	v_mul_f32_e32 v46, 0xbfb8aa3b, v46
	v_mul_f32_e32 v47, 0xbfb8aa3b, v47
	v_mul_f32_e32 v44, 0xbfb8aa3b, v44
	v_mul_f32_e32 v45, 0xbfb8aa3b, v45
	v_exp_f32_e32 v42, v42
	v_exp_f32_e32 v43, v43
	v_exp_f32_e32 v48, v48
	v_exp_f32_e32 v49, v49
	v_exp_f32_e32 v46, v46
	v_exp_f32_e32 v47, v47
	v_exp_f32_e32 v44, v44
	v_exp_f32_e32 v45, v45
	v_add_f32_e32 v42, 1.0, v42
	v_add_f32_e32 v43, 1.0, v43
	v_add_f32_e32 v48, 1.0, v48
	v_add_f32_e32 v49, 1.0, v49
	v_add_f32_e32 v46, 1.0, v46
	v_add_f32_e32 v47, 1.0, v47
	v_add_f32_e32 v44, 1.0, v44
	v_add_f32_e32 v45, 1.0, v45
	v_rcp_f32_e32 v42, v42
	v_rcp_f32_e32 v43, v43
	v_rcp_f32_e32 v48, v48
	v_rcp_f32_e32 v49, v49
	v_rcp_f32_e32 v46, v46
	v_rcp_f32_e32 v44, v44
	v_rcp_f32_e32 v45, v45
	v_rcp_f32_e32 v47, v47
	v_mov_b32_e32 v52, v164
	v_mov_b32_e32 v53, v164
	v_pk_mul_f32 v[48:49], v[52:53], v[48:49]
	v_pk_mul_f32 v[50:51], v[164:165], v[42:43]
	v_pk_mul_f32 v[44:45], v[52:53], v[44:45]
	v_pk_mul_f32 v[46:47], v[164:165], v[46:47]
.LBB0_1125:
	v_lshlrev_b64 v[42:43], 12, v[138:139]
	v_lshl_add_u64 v[42:43], v[140:141], 0, v[42:43]
	s_mov_b32 s2, 0x90000
	v_cvt_pk_bf16_f32 v50, v50, v51
	v_cvt_pk_bf16_f32 v51, v48, v49
	v_cvt_pk_bf16_f32 v52, v46, v47
	v_cvt_pk_bf16_f32 v53, v44, v45
	v_add_co_u32_e32 v44, vcc, s2, v42
	v_pk_add_f32 v[40:41], v[40:41], v[64:65]
	s_nop 0
	v_addc_co_u32_e32 v45, vcc, 0, v43, vcc
	v_pk_add_f32 v[38:39], v[38:39], v[62:63]
	v_pk_add_f32 v[36:37], v[36:37], v[60:61]
	s_and_b64 vcc, exec, s[6:7]
	v_pk_add_f32 v[34:35], v[34:35], v[58:59]
	global_store_dwordx4 v[44:45], v[50:53], off
	s_cbranch_vccnz .LBB0_1127
	v_mul_f32_e32 v38, 0xbfb8aa3b, v38
	v_mul_f32_e32 v39, 0xbfb8aa3b, v39
	v_mul_f32_e32 v40, 0xbfb8aa3b, v40
	v_mul_f32_e32 v41, 0xbfb8aa3b, v41
	v_mul_f32_e32 v34, 0xbfb8aa3b, v34
	v_mul_f32_e32 v35, 0xbfb8aa3b, v35
	v_mul_f32_e32 v36, 0xbfb8aa3b, v36
	v_mul_f32_e32 v37, 0xbfb8aa3b, v37
	v_exp_f32_e32 v38, v38
	v_exp_f32_e32 v39, v39
	v_exp_f32_e32 v40, v40
	v_exp_f32_e32 v41, v41
	v_exp_f32_e32 v34, v34
	v_exp_f32_e32 v35, v35
	v_exp_f32_e32 v36, v36
	v_exp_f32_e32 v37, v37
	v_add_f32_e32 v38, 1.0, v38
	v_add_f32_e32 v39, 1.0, v39
	v_add_f32_e32 v40, 1.0, v40
	v_add_f32_e32 v41, 1.0, v41
	v_add_f32_e32 v34, 1.0, v34
	v_add_f32_e32 v35, 1.0, v35
	v_add_f32_e32 v36, 1.0, v36
	v_add_f32_e32 v37, 1.0, v37
	v_rcp_f32_e32 v38, v38
	v_rcp_f32_e32 v39, v39
	v_rcp_f32_e32 v40, v40
	v_rcp_f32_e32 v41, v41
	v_rcp_f32_e32 v34, v34
	v_rcp_f32_e32 v36, v36
	v_rcp_f32_e32 v37, v37
	v_rcp_f32_e32 v35, v35
	v_mov_b32_e32 v44, v164
	v_mov_b32_e32 v45, v164
	v_pk_mul_f32 v[40:41], v[44:45], v[40:41]
	v_pk_mul_f32 v[38:39], v[164:165], v[38:39]
	v_pk_mul_f32 v[36:37], v[44:45], v[36:37]
	v_pk_mul_f32 v[34:35], v[164:165], v[34:35]
.LBB0_1127:
	s_mov_b64 s[2:3], 0x90000
	v_lshl_add_u64 v[42:43], v[42:43], 0, s[2:3]
	v_cvt_pk_bf16_f32 v38, v38, v39
	v_cvt_pk_bf16_f32 v39, v40, v41
	v_cvt_pk_bf16_f32 v40, v34, v35
	v_pk_add_f32 v[32:33], v[32:33], v[80:81]
	v_pk_add_f32 v[34:35], v[30:31], v[78:79]
	v_pk_add_f32 v[28:29], v[28:29], v[76:77]
	s_and_b64 vcc, exec, s[6:7]
	v_pk_add_f32 v[30:31], v[26:27], v[74:75]
	v_cvt_pk_bf16_f32 v41, v36, v37
	global_store_dwordx4 v[42:43], v[38:41], off offset:256
	s_cbranch_vccnz .LBB0_1129
	v_mul_f32_e32 v26, 0xbfb8aa3b, v34
	v_mul_f32_e32 v27, 0xbfb8aa3b, v35
	v_mul_f32_e32 v32, 0xbfb8aa3b, v32
	v_mul_f32_e32 v33, 0xbfb8aa3b, v33
	v_mul_f32_e32 v30, 0xbfb8aa3b, v30
	v_mul_f32_e32 v31, 0xbfb8aa3b, v31
	v_mul_f32_e32 v28, 0xbfb8aa3b, v28
	v_mul_f32_e32 v29, 0xbfb8aa3b, v29
	v_exp_f32_e32 v26, v26
	v_exp_f32_e32 v27, v27
	v_exp_f32_e32 v32, v32
	v_exp_f32_e32 v33, v33
	v_exp_f32_e32 v30, v30
	v_exp_f32_e32 v31, v31
	v_exp_f32_e32 v28, v28
	v_exp_f32_e32 v29, v29
	v_add_f32_e32 v26, 1.0, v26
	v_add_f32_e32 v27, 1.0, v27
	v_add_f32_e32 v32, 1.0, v32
	v_add_f32_e32 v33, 1.0, v33
	v_add_f32_e32 v30, 1.0, v30
	v_add_f32_e32 v31, 1.0, v31
	v_add_f32_e32 v28, 1.0, v28
	v_add_f32_e32 v29, 1.0, v29
	v_rcp_f32_e32 v26, v26
	v_rcp_f32_e32 v27, v27
	v_rcp_f32_e32 v32, v32
	v_rcp_f32_e32 v33, v33
	v_rcp_f32_e32 v30, v30
	v_rcp_f32_e32 v28, v28
	v_rcp_f32_e32 v29, v29
	v_rcp_f32_e32 v31, v31
	v_mov_b32_e32 v36, v164
	v_mov_b32_e32 v37, v164
	v_pk_mul_f32 v[32:33], v[36:37], v[32:33]
	v_pk_mul_f32 v[34:35], v[164:165], v[26:27]
	v_pk_mul_f32 v[28:29], v[36:37], v[28:29]
	v_pk_mul_f32 v[30:31], v[164:165], v[30:31]
; #define PG8_BAR __builtin_amdgcn_s_barrier()
; __device__ __forceinline__ u32x4 pack8(const f32x4 v0, const f32x4 v1) { u32x4 w; w.x = cvt_pk_bf16(v0[0], v0[1]); w.y = cvt_pk_bf16(v0[2], v0[3]); w.z = cvt_pk_bf16(v1[0], v1[1]); w.w = cvt_pk_bf16(v1[2], v1[3]); return w; }
; __device__ __forceinline__ f32x4 sig4(const f32x4 v) { return (f32x4){sigmoidf_(v[0]), sigmoidf_(v[1]), sigmoidf_(v[2]), sigmoidf_(v[3])}; }
; template <class Epi, class Sched, bool ALIGN_EPI = false, bool SP2 = false, bool I8 = false>
; __device__ __forceinline__ void gemm_phase(PG8_LAS unsigned char* lds, const Gemm g, const Sched& S, const Epi& E) {
;     ...
;         if (!has_next) break;
; #pragma unroll
;         for (int a = 0; a < 2; ++a)
; #pragma unroll
;             for (int b = 0; b < 2; ++b)
; #pragma unroll
;                 for (int m = 0; m < 4; ++m)
; #pragma unroll
;                     for (int n = 0; n < 2; ++n) acc[a][b][m][n] = (typename AccT<I8>::type){0, 0, 0, 0};
;         cur = nxt; cA = nA; cB = nB; ++ui; nt = PG8_NT(cur);
;         if constexpr (ALIGN_EPI) { if (wr == 1) PG8_BAR; }
;     __device__ __forceinline__ void operator()(AccRef acc, const Unit& u, int wr, int wc, int fr, int fq) const {
;     ...
;             for (int m = 0; m < 4; ++m) { const int r = row0 + ai * HALF + m * 16; bf16_t* rowp = base + (size_t)r * 2048 + col0;
; #pragma unroll
;                 for (int bj = 0; bj < 2; ++bj) { f32x4 v0 = acc[ai][bj][m][0] + bv[bj][0], v1 = acc[ai][bj][m][1] + bv[bj][1];
;                     if (third < 2) { v0 = sig4(v0) * mul; v1 = sig4(v1) * mul; }
;                     *(u32x4*)(rowp + bj * HALF) = pack8(v0, v1); } }
.LBB0_1129:
	v_lshlrev_b64 v[26:27], 12, v[138:139]
	v_lshl_add_u64 v[26:27], v[140:141], 0, v[26:27]
	s_mov_b32 s2, 0xa0000
	v_cvt_pk_bf16_f32 v34, v34, v35
	v_cvt_pk_bf16_f32 v35, v32, v33
	v_cvt_pk_bf16_f32 v36, v30, v31
	v_cvt_pk_bf16_f32 v37, v28, v29
	v_add_co_u32_e32 v28, vcc, s2, v26
	v_pk_add_f32 v[24:25], v[24:25], v[64:65]
	s_nop 0
	v_addc_co_u32_e32 v29, vcc, 0, v27, vcc
	v_pk_add_f32 v[22:23], v[22:23], v[62:63]
	v_pk_add_f32 v[20:21], v[20:21], v[60:61]
	s_and_b64 vcc, exec, s[6:7]
	v_pk_add_f32 v[18:19], v[18:19], v[58:59]
	global_store_dwordx4 v[28:29], v[34:37], off
	s_cbranch_vccnz .LBB0_1131
	v_mul_f32_e32 v22, 0xbfb8aa3b, v22
	v_mul_f32_e32 v23, 0xbfb8aa3b, v23
	v_mul_f32_e32 v24, 0xbfb8aa3b, v24
	v_mul_f32_e32 v25, 0xbfb8aa3b, v25
	v_mul_f32_e32 v18, 0xbfb8aa3b, v18
	v_mul_f32_e32 v19, 0xbfb8aa3b, v19
	v_mul_f32_e32 v20, 0xbfb8aa3b, v20
	v_mul_f32_e32 v21, 0xbfb8aa3b, v21
	v_exp_f32_e32 v22, v22
	v_exp_f32_e32 v23, v23
	v_exp_f32_e32 v24, v24
	v_exp_f32_e32 v25, v25
	v_exp_f32_e32 v18, v18
	v_exp_f32_e32 v19, v19
	v_exp_f32_e32 v20, v20
	v_exp_f32_e32 v21, v21
	v_add_f32_e32 v22, 1.0, v22
	v_add_f32_e32 v23, 1.0, v23
	v_add_f32_e32 v24, 1.0, v24
	v_add_f32_e32 v25, 1.0, v25
	v_add_f32_e32 v18, 1.0, v18
	v_add_f32_e32 v19, 1.0, v19
	v_add_f32_e32 v20, 1.0, v20
	v_add_f32_e32 v21, 1.0, v21
	v_rcp_f32_e32 v22, v22
	v_rcp_f32_e32 v23, v23
	v_rcp_f32_e32 v24, v24
	v_rcp_f32_e32 v25, v25
	v_rcp_f32_e32 v18, v18
	v_rcp_f32_e32 v20, v20
	v_rcp_f32_e32 v21, v21
	v_rcp_f32_e32 v19, v19
	v_mov_b32_e32 v28, v164
	v_mov_b32_e32 v29, v164
	v_pk_mul_f32 v[24:25], v[28:29], v[24:25]
	v_pk_mul_f32 v[22:23], v[164:165], v[22:23]
	v_pk_mul_f32 v[20:21], v[28:29], v[20:21]
	v_pk_mul_f32 v[18:19], v[164:165], v[18:19]
.LBB0_1131:
	s_mov_b64 s[2:3], 0xa0000
	v_lshl_add_u64 v[26:27], v[26:27], 0, s[2:3]
	v_cvt_pk_bf16_f32 v22, v22, v23
	v_cvt_pk_bf16_f32 v23, v24, v25
	v_cvt_pk_bf16_f32 v24, v18, v19
	v_pk_add_f32 v[16:17], v[16:17], v[80:81]
	v_pk_add_f32 v[18:19], v[14:15], v[78:79]
	v_pk_add_f32 v[12:13], v[12:13], v[76:77]
	s_and_b64 vcc, exec, s[6:7]
	v_pk_add_f32 v[14:15], v[10:11], v[74:75]
	v_cvt_pk_bf16_f32 v25, v20, v21
	global_store_dwordx4 v[26:27], v[22:25], off offset:256
	s_cbranch_vccnz .LBB0_1133
	v_mul_f32_e32 v10, 0xbfb8aa3b, v18
	v_mul_f32_e32 v11, 0xbfb8aa3b, v19
	v_mul_f32_e32 v16, 0xbfb8aa3b, v16
	v_mul_f32_e32 v17, 0xbfb8aa3b, v17
	v_mul_f32_e32 v14, 0xbfb8aa3b, v14
	v_mul_f32_e32 v15, 0xbfb8aa3b, v15
	v_mul_f32_e32 v12, 0xbfb8aa3b, v12
	v_mul_f32_e32 v13, 0xbfb8aa3b, v13
	v_exp_f32_e32 v10, v10
	v_exp_f32_e32 v11, v11
	v_exp_f32_e32 v16, v16
	v_exp_f32_e32 v17, v17
	v_exp_f32_e32 v14, v14
	v_exp_f32_e32 v15, v15
	v_exp_f32_e32 v12, v12
	v_exp_f32_e32 v13, v13
	v_add_f32_e32 v10, 1.0, v10
	v_add_f32_e32 v11, 1.0, v11
	v_add_f32_e32 v16, 1.0, v16
	v_add_f32_e32 v17, 1.0, v17
	v_add_f32_e32 v14, 1.0, v14
	v_add_f32_e32 v15, 1.0, v15
	v_add_f32_e32 v12, 1.0, v12
	v_add_f32_e32 v13, 1.0, v13
	v_rcp_f32_e32 v10, v10
	v_rcp_f32_e32 v11, v11
	v_rcp_f32_e32 v16, v16
	v_rcp_f32_e32 v17, v17
	v_rcp_f32_e32 v14, v14
	v_rcp_f32_e32 v12, v12
	v_rcp_f32_e32 v13, v13
	v_rcp_f32_e32 v15, v15
	v_mov_b32_e32 v20, v164
	v_mov_b32_e32 v21, v164
	v_pk_mul_f32 v[16:17], v[20:21], v[16:17]
	v_pk_mul_f32 v[18:19], v[164:165], v[10:11]
	v_pk_mul_f32 v[12:13], v[20:21], v[12:13]
	v_pk_mul_f32 v[14:15], v[164:165], v[14:15]
.LBB0_1133:
	v_lshlrev_b64 v[10:11], 12, v[138:139]
	v_lshl_add_u64 v[10:11], v[140:141], 0, v[10:11]
	v_cvt_pk_bf16_f32 v18, v18, v19
	v_cvt_pk_bf16_f32 v19, v16, v17
	v_cvt_pk_bf16_f32 v20, v14, v15
	v_cvt_pk_bf16_f32 v21, v12, v13
	v_add_co_u32_e32 v12, vcc, s46, v10
	v_pk_add_f32 v[8:9], v[8:9], v[64:65]
	s_nop 0
	v_addc_co_u32_e32 v13, vcc, 0, v11, vcc
	v_pk_add_f32 v[6:7], v[6:7], v[62:63]
	v_pk_add_f32 v[4:5], v[4:5], v[60:61]
	s_and_b64 vcc, exec, s[6:7]
	v_pk_add_f32 v[2:3], v[2:3], v[58:59]
	global_store_dwordx4 v[12:13], v[18:21], off
	s_cbranch_vccnz .LBB0_1135
	v_mul_f32_e32 v6, 0xbfb8aa3b, v6
	v_mul_f32_e32 v7, 0xbfb8aa3b, v7
	v_mul_f32_e32 v8, 0xbfb8aa3b, v8
	v_mul_f32_e32 v9, 0xbfb8aa3b, v9
	v_mul_f32_e32 v2, 0xbfb8aa3b, v2
	v_mul_f32_e32 v3, 0xbfb8aa3b, v3
	v_mul_f32_e32 v4, 0xbfb8aa3b, v4
	v_mul_f32_e32 v5, 0xbfb8aa3b, v5
	v_exp_f32_e32 v6, v6
	v_exp_f32_e32 v7, v7
	v_exp_f32_e32 v8, v8
	v_exp_f32_e32 v9, v9
	v_exp_f32_e32 v2, v2
	v_exp_f32_e32 v3, v3
	v_exp_f32_e32 v4, v4
	v_exp_f32_e32 v5, v5
	v_add_f32_e32 v6, 1.0, v6
	v_add_f32_e32 v7, 1.0, v7
	v_add_f32_e32 v8, 1.0, v8
	v_add_f32_e32 v9, 1.0, v9
	v_add_f32_e32 v2, 1.0, v2
	v_add_f32_e32 v3, 1.0, v3
	v_add_f32_e32 v4, 1.0, v4
	v_add_f32_e32 v5, 1.0, v5
	v_rcp_f32_e32 v6, v6
	v_rcp_f32_e32 v7, v7
	v_rcp_f32_e32 v8, v8
	v_rcp_f32_e32 v9, v9
	v_rcp_f32_e32 v2, v2
	v_rcp_f32_e32 v4, v4
	v_rcp_f32_e32 v5, v5
	v_rcp_f32_e32 v3, v3
	v_mov_b32_e32 v12, v164
	v_mov_b32_e32 v13, v164
	v_pk_mul_f32 v[8:9], v[12:13], v[8:9]
	v_pk_mul_f32 v[6:7], v[164:165], v[6:7]
	v_pk_mul_f32 v[4:5], v[12:13], v[4:5]
	v_pk_mul_f32 v[2:3], v[164:165], v[2:3]
.LBB0_1135:
	s_mov_b64 s[2:3], 0xb0000
	v_lshl_add_u64 v[10:11], v[10:11], 0, s[2:3]
	s_and_b64 vcc, exec, s[4:5]
	s_mov_b64 s[2:3], -1
	v_cvt_pk_bf16_f32 v6, v6, v7
	v_cvt_pk_bf16_f32 v7, v8, v9
	v_cvt_pk_bf16_f32 v8, v2, v3
	v_cvt_pk_bf16_f32 v9, v4, v5
	global_store_dwordx4 v[10:11], v[6:9], off offset:256
	s_cbranch_vccnz .LBB0_1084
	s_and_b32 s2, s16, -8
	s_cmp_eq_u32 s2, 16
	s_cselect_b32 s7, 4, 2
	s_andn2_b64 vcc, exec, s[10:11]
	s_cbranch_vccnz .LBB0_1083
	s_barrier
	s_branch .LBB0_1083

; #define PG8_STAGE(bufoff, gbase, voff) do { _Pragma("unroll") for (int _i = 0; _i < 2; ++_i) \
;         __builtin_amdgcn_global_load_lds((const unsigned*)((const char*)(gbase) + (voff)[_i]), (PG8_LAS unsigned*)(lds + (bufoff) + ldsw + _i * 8192), 16, 0, 0); } while (0)
; #define PG8_LDA(dst, b, h) do { _Pragma("unroll") for (int m = 0; m < 4; ++m) _Pragma("unroll") for (int k = 0; k < 2; ++k) dst[m][k] = *(const PG8_LAS bf16x8*)(lds + PG8_SA(b, h) + aoff + m * 2048 + k * 1024); } while (0)
; #define PG8_WAIT_V(n) asm volatile("s_waitcnt vmcnt(" #n ")" ::: "memory")
; #define PG8_WAIT_L(n) asm volatile("s_waitcnt lgkmcnt(" #n ")" ::: "memory")
; #define PG8_BAR __builtin_amdgcn_s_barrier()
; template <class Epi, class Sched, bool ALIGN_EPI = false, bool SP2 = false, bool I8 = false>
; __device__ __forceinline__ void gemm_phase(PG8_LAS unsigned char* lds, const Gemm g, const Sched& S, const Epi& E) {
;     ...
;         for (int t = 0; t < nt; t += 2) {
;             const bool last = (t == nt - 2);
;             const char* a1 = cA + (size_t)(t + 1) * kstep;
;             const char* a2 = last ? nA : cA + (size_t)(t + 2) * kstep; const char* b2 = last ? nB : cB + (size_t)(t + 2) * kstep;
;             const char* a3 = a2 + kstep; const char* b3 = b2 + kstep;
;             if (last && has_next) S.a_ready(nxt);
;             if constexpr (SP2) {
;             PG8_LDB(B0, 0, 0); PG8_LDB(B1, 0, 1); PG8_SCHED; PG8_LDA(At, 0, 0); PG8_STAGE(PG8_SA(1, 1), a1 + hstepA, voffA);
;             PG8_WAIT_V(8); PG8_WAIT_L(0); PG8_BAR; PG8_MMA(0, 0, At, B0); PG8_MMA(0, 1, At, B1); PG8_BAR; PG8_SCHED;
;             PG8_LDA(At, 0, 1); PG8_STAGE(PG8_SB(0, 0), b2, voffB); PG8_STAGE(PG8_SB(0, 1), b2 + hstepB, voffB); PG8_STAGE(PG8_SA(0, 0), a2, voffA);
;             PG8_WAIT_V(8); PG8_WAIT_L(0); PG8_BAR; PG8_MMA(1, 0, At, B0); PG8_MMA(1, 1, At, B1); PG8_BAR; PG8_SCHED;
;             PG8_LDB(B0, 1, 0); PG8_LDB(B1, 1, 1); PG8_SCHED; PG8_LDA(At, 1, 0); PG8_STAGE(PG8_SA(0, 1), a2 + hstepA, voffA);
;             PG8_WAIT_V(8); PG8_WAIT_L(0); PG8_BAR; PG8_MMA(0, 0, At, B0); PG8_MMA(0, 1, At, B1); PG8_BAR; PG8_SCHED;
;             PG8_LDA(At, 1, 1); PG8_STAGE(PG8_SB(1, 0), b3, voffB); PG8_STAGE(PG8_SB(1, 1), b3 + hstepB, voffB); PG8_STAGE(PG8_SA(1, 0), a3, voffA);
;             PG8_WAIT_V(8); PG8_WAIT_L(0); PG8_BAR; PG8_MMA(1, 0, At, B0); PG8_MMA(1, 1, At, B1); PG8_BAR; PG8_SCHED;
.LBB0_1538:
	ds_read_b128 v[146:149], v154
	ds_read_b128 v[150:153], v154 offset:1024
	ds_read_b128 v[158:161], v154 offset:2048
	ds_read_b128 v[162:165], v154 offset:3072
	ds_read_b128 v[166:169], v155
	ds_read_b128 v[170:173], v155 offset:1024
	ds_read_b128 v[174:177], v155 offset:2048
	ds_read_b128 v[178:181], v155 offset:3072
	s_add_u32 s24, s22, 0xfffe0080
	s_addc_u32 s25, s23, -1
	s_cmp_eq_u32 s49, 4
	s_cselect_b32 s27, s15, s25
	s_cselect_b32 s26, s45, s24
	s_cselect_b32 s25, s13, s48
	s_cselect_b32 s24, s46, s47
	s_add_i32 m0, s21, 0xc000
	ds_read_b128 v[182:185], v156
	ds_read_b128 v[186:189], v156 offset:1024
	ds_read_b128 v[190:193], v156 offset:2048
	ds_read_b128 v[194:197], v156 offset:3072
	ds_read_b128 v[198:201], v156 offset:4096
	ds_read_b128 v[202:205], v156 offset:5120
	ds_read_b128 v[206:209], v156 offset:6144
	ds_read_b128 v[210:213], v156 offset:7168
	global_load_lds_dwordx4 v138, s[22:23]
	s_add_i32 m0, s21, 0xe000
	s_nop 0
	global_load_lds_dwordx4 v140, s[22:23]
	s_waitcnt vmcnt(8) lgkmcnt(0)
	s_barrier
	v_mfma_f32_16x16x32_bf16 v[126:129], v[146:149], v[182:185], v[126:129]
	v_mfma_f32_16x16x32_bf16 v[122:125], v[158:161], v[182:185], v[122:125]
	v_mfma_f32_16x16x32_bf16 v[114:117], v[146:149], v[190:193], v[114:117]
	v_mfma_f32_16x16x32_bf16 v[106:109], v[158:161], v[190:193], v[106:109]
	v_mfma_f32_16x16x32_bf16 v[94:97], v[146:149], v[198:201], v[94:97]
	v_mfma_f32_16x16x32_bf16 v[90:93], v[158:161], v[198:201], v[90:93]
	v_mfma_f32_16x16x32_bf16 v[86:89], v[146:149], v[206:209], v[86:89]
	v_mfma_f32_16x16x32_bf16 v[82:85], v[158:161], v[206:209], v[82:85]
	v_mfma_f32_16x16x32_bf16 v[126:129], v[150:153], v[186:189], v[126:129]
	v_mfma_f32_16x16x32_bf16 v[122:125], v[162:165], v[186:189], v[122:125]
	v_mfma_f32_16x16x32_bf16 v[114:117], v[150:153], v[194:197], v[114:117]
	v_mfma_f32_16x16x32_bf16 v[106:109], v[162:165], v[194:197], v[106:109]
	v_mfma_f32_16x16x32_bf16 v[94:97], v[150:153], v[202:205], v[94:97]
	v_mfma_f32_16x16x32_bf16 v[90:93], v[162:165], v[202:205], v[90:93]
	v_mfma_f32_16x16x32_bf16 v[86:89], v[150:153], v[210:213], v[86:89]
	v_mfma_f32_16x16x32_bf16 v[82:85], v[162:165], v[210:213], v[82:85]
	v_mfma_f32_16x16x32_bf16 v[118:121], v[166:169], v[182:185], v[118:121]
	v_mfma_f32_16x16x32_bf16 v[110:113], v[174:177], v[182:185], v[110:113]
	v_mfma_f32_16x16x32_bf16 v[102:105], v[166:169], v[190:193], v[102:105]
	v_mfma_f32_16x16x32_bf16 v[98:101], v[174:177], v[190:193], v[98:101]
	v_mfma_f32_16x16x32_bf16 v[78:81], v[166:169], v[198:201], v[78:81]
	v_mfma_f32_16x16x32_bf16 v[74:77], v[174:177], v[198:201], v[74:77]
	v_mfma_f32_16x16x32_bf16 v[70:73], v[166:169], v[206:209], v[70:73]
	v_mfma_f32_16x16x32_bf16 v[66:69], v[174:177], v[206:209], v[66:69]
	v_mfma_f32_16x16x32_bf16 v[118:121], v[170:173], v[186:189], v[118:121]
	v_mfma_f32_16x16x32_bf16 v[110:113], v[178:181], v[186:189], v[110:113]
	v_mfma_f32_16x16x32_bf16 v[102:105], v[170:173], v[194:197], v[102:105]
	v_mfma_f32_16x16x32_bf16 v[98:101], v[178:181], v[194:197], v[98:101]
	v_mfma_f32_16x16x32_bf16 v[78:81], v[170:173], v[202:205], v[78:81]
	v_mfma_f32_16x16x32_bf16 v[74:77], v[178:181], v[202:205], v[74:77]
	v_mfma_f32_16x16x32_bf16 v[70:73], v[170:173], v[210:213], v[70:73]
	v_mfma_f32_16x16x32_bf16 v[66:69], v[178:181], v[210:213], v[66:69]
	s_barrier
	s_add_i32 s50, s42, s34
	s_mov_b64 s[98:99], s[24:25]
	s_mov_b32 m0, s50
	ds_read_b128 v[182:185], v156 offset:16384
	ds_read_b128 v[186:189], v156 offset:17408
	ds_read_b128 v[190:193], v156 offset:18432
	ds_read_b128 v[194:197], v156 offset:19456
	ds_read_b128 v[198:201], v156 offset:20480
	ds_read_b128 v[202:205], v156 offset:21504
	ds_read_b128 v[206:209], v156 offset:22528
	ds_read_b128 v[210:213], v156 offset:23552
	global_load_lds_dwordx4 v132, s[24:25]
	s_add_i32 m0, s50, 0x2000
	s_add_u32 s50, s24, 0x20000
	s_mov_b64 s[98:99], s[24:25]
	s_addc_u32 s51, s25, 0
	s_add_i32 s52, s43, s34
	global_load_lds_dwordx4 v136, s[24:25]
	s_mov_b32 m0, s52
	s_mov_b64 s[100:101], s[26:27]
	global_load_lds_dwordx4 v132, s[50:51]
	s_add_i32 m0, s52, 0x2000
	s_nop 0
	global_load_lds_dwordx4 v136, s[50:51]
	s_mov_b64 s[100:101], s[26:27]
	s_mov_b32 m0, s21
	s_nop 0
	global_load_lds_dwordx4 v130, s[26:27]
	s_mov_b32 m0, s35
	s_nop 0
	global_load_lds_dwordx4 v134, s[26:27]
	s_waitcnt vmcnt(8) lgkmcnt(0)
	s_barrier
	v_mfma_f32_16x16x32_bf16 v[62:65], v[146:149], v[182:185], v[62:65]
	v_mfma_f32_16x16x32_bf16 v[58:61], v[158:161], v[182:185], v[58:61]
	v_mfma_f32_16x16x32_bf16 v[54:57], v[146:149], v[190:193], v[54:57]
	v_mfma_f32_16x16x32_bf16 v[50:53], v[158:161], v[190:193], v[50:53]
	v_mfma_f32_16x16x32_bf16 v[30:33], v[146:149], v[198:201], v[30:33]
	v_mfma_f32_16x16x32_bf16 v[26:29], v[158:161], v[198:201], v[26:29]
	v_mfma_f32_16x16x32_bf16 v[22:25], v[146:149], v[206:209], v[22:25]
	v_mfma_f32_16x16x32_bf16 v[10:13], v[158:161], v[206:209], v[10:13]
	v_mfma_f32_16x16x32_bf16 v[62:65], v[150:153], v[186:189], v[62:65]
	v_mfma_f32_16x16x32_bf16 v[58:61], v[162:165], v[186:189], v[58:61]
	v_mfma_f32_16x16x32_bf16 v[54:57], v[150:153], v[194:197], v[54:57]
	v_mfma_f32_16x16x32_bf16 v[50:53], v[162:165], v[194:197], v[50:53]
	v_mfma_f32_16x16x32_bf16 v[30:33], v[150:153], v[202:205], v[30:33]
	v_mfma_f32_16x16x32_bf16 v[26:29], v[162:165], v[202:205], v[26:29]
	v_mfma_f32_16x16x32_bf16 v[22:25], v[150:153], v[210:213], v[22:25]
	v_mfma_f32_16x16x32_bf16 v[10:13], v[162:165], v[210:213], v[10:13]
	v_mfma_f32_16x16x32_bf16 v[46:49], v[166:169], v[182:185], v[46:49]
	v_mfma_f32_16x16x32_bf16 v[42:45], v[174:177], v[182:185], v[42:45]
	v_mfma_f32_16x16x32_bf16 v[38:41], v[166:169], v[190:193], v[38:41]
	v_mfma_f32_16x16x32_bf16 v[34:37], v[174:177], v[190:193], v[34:37]
	v_mfma_f32_16x16x32_bf16 v[18:21], v[166:169], v[198:201], v[18:21]
	v_mfma_f32_16x16x32_bf16 v[14:17], v[174:177], v[198:201], v[14:17]
	v_mfma_f32_16x16x32_bf16 v[6:9], v[166:169], v[206:209], v[6:9]
	v_mfma_f32_16x16x32_bf16 v[2:5], v[174:177], v[206:209], v[2:5]
	v_mfma_f32_16x16x32_bf16 v[46:49], v[170:173], v[186:189], v[46:49]
	v_mfma_f32_16x16x32_bf16 v[42:45], v[178:181], v[186:189], v[42:45]
	v_mfma_f32_16x16x32_bf16 v[38:41], v[170:173], v[194:197], v[38:41]
	v_mfma_f32_16x16x32_bf16 v[34:37], v[178:181], v[194:197], v[34:37]
	v_mfma_f32_16x16x32_bf16 v[18:21], v[170:173], v[202:205], v[18:21]
	v_mfma_f32_16x16x32_bf16 v[14:17], v[178:181], v[202:205], v[14:17]
	v_mfma_f32_16x16x32_bf16 v[6:9], v[170:173], v[210:213], v[6:9]
	v_mfma_f32_16x16x32_bf16 v[2:5], v[178:181], v[210:213], v[2:5]
	s_barrier
; #define PG8_STAGE(bufoff, gbase, voff) do { _Pragma("unroll") for (int _i = 0; _i < 2; ++_i) \
;         __builtin_amdgcn_global_load_lds((const unsigned*)((const char*)(gbase) + (voff)[_i]), (PG8_LAS unsigned*)(lds + (bufoff) + ldsw + _i * 8192), 16, 0, 0); } while (0)
; #define PG8_LDA(dst, b, h) do { _Pragma("unroll") for (int m = 0; m < 4; ++m) _Pragma("unroll") for (int k = 0; k < 2; ++k) dst[m][k] = *(const PG8_LAS bf16x8*)(lds + PG8_SA(b, h) + aoff + m * 2048 + k * 1024); } while (0)
; #define PG8_WAIT_V(n) asm volatile("s_waitcnt vmcnt(" #n ")" ::: "memory")
; #define PG8_WAIT_L(n) asm volatile("s_waitcnt lgkmcnt(" #n ")" ::: "memory")
; #define PG8_BAR __builtin_amdgcn_s_barrier()
; template <class Epi, class Sched, bool ALIGN_EPI = false, bool SP2 = false, bool I8 = false>
; __device__ __forceinline__ void gemm_phase(PG8_LAS unsigned char* lds, const Gemm g, const Sched& S, const Epi& E) {
;     ...
;         for (int t = 0; t < nt; t += 2) {
;             const bool last = (t == nt - 2);
;             const char* a1 = cA + (size_t)(t + 1) * kstep;
;             const char* a2 = last ? nA : cA + (size_t)(t + 2) * kstep; const char* b2 = last ? nB : cB + (size_t)(t + 2) * kstep;
;             const char* a3 = a2 + kstep; const char* b3 = b2 + kstep;
;             if (last && has_next) S.a_ready(nxt);
;             if constexpr (SP2) {
;             PG8_LDB(B0, 0, 0); PG8_LDB(B1, 0, 1); PG8_SCHED; PG8_LDA(At, 0, 0); PG8_STAGE(PG8_SA(1, 1), a1 + hstepA, voffA);
;             PG8_WAIT_V(8); PG8_WAIT_L(0); PG8_BAR; PG8_MMA(0, 0, At, B0); PG8_MMA(0, 1, At, B1); PG8_BAR; PG8_SCHED;
;             PG8_LDA(At, 0, 1); PG8_STAGE(PG8_SB(0, 0), b2, voffB); PG8_STAGE(PG8_SB(0, 1), b2 + hstepB, voffB); PG8_STAGE(PG8_SA(0, 0), a2, voffA);
;             PG8_WAIT_V(8); PG8_WAIT_L(0); PG8_BAR; PG8_MMA(1, 0, At, B0); PG8_MMA(1, 1, At, B1); PG8_BAR; PG8_SCHED;
;             PG8_LDB(B0, 1, 0); PG8_LDB(B1, 1, 1); PG8_SCHED; PG8_LDA(At, 1, 0); PG8_STAGE(PG8_SA(0, 1), a2 + hstepA, voffA);
;             PG8_WAIT_V(8); PG8_WAIT_L(0); PG8_BAR; PG8_MMA(0, 0, At, B0); PG8_MMA(0, 1, At, B1); PG8_BAR; PG8_SCHED;
;             PG8_LDA(At, 1, 1); PG8_STAGE(PG8_SB(1, 0), b3, voffB); PG8_STAGE(PG8_SB(1, 1), b3 + hstepB, voffB); PG8_STAGE(PG8_SA(1, 0), a3, voffA);
;             PG8_WAIT_V(8); PG8_WAIT_L(0); PG8_BAR; PG8_MMA(1, 0, At, B0); PG8_MMA(1, 1, At, B1); PG8_BAR; PG8_SCHED;
	s_add_i32 s50, 0, 0x18000
	s_add_i32 s51, 0, 0x1c000
	ds_read_b128 v[146:149], v155 offset:16384
	ds_read_b128 v[150:153], v155 offset:17408
	ds_read_b128 v[158:161], v155 offset:18432
	ds_read_b128 v[162:165], v155 offset:19456
	ds_read_b128 v[166:169], v155 offset:32768
	ds_read_b128 v[170:173], v155 offset:33792
	ds_read_b128 v[174:177], v155 offset:34816
	ds_read_b128 v[178:181], v155 offset:35840
	s_add_u32 s26, s26, 0x20000
	s_addc_u32 s27, s27, 0
	s_mov_b32 m0, s36
	ds_read_b128 v[182:185], v156 offset:32768
	ds_read_b128 v[186:189], v156 offset:33792
	ds_read_b128 v[190:193], v156 offset:34816
	ds_read_b128 v[194:197], v156 offset:35840
	ds_read_b128 v[198:201], v156 offset:36864
	ds_read_b128 v[202:205], v156 offset:37888
	ds_read_b128 v[206:209], v156 offset:38912
	ds_read_b128 v[210:213], v156 offset:39936
	global_load_lds_dwordx4 v130, s[26:27]
	s_mov_b32 m0, s37
	s_nop 0
	global_load_lds_dwordx4 v134, s[26:27]
	s_waitcnt vmcnt(8) lgkmcnt(0)
	s_barrier
	v_mfma_f32_16x16x32_bf16 v[126:129], v[146:149], v[182:185], v[126:129]
	v_mfma_f32_16x16x32_bf16 v[122:125], v[158:161], v[182:185], v[122:125]
	v_mfma_f32_16x16x32_bf16 v[114:117], v[146:149], v[190:193], v[114:117]
	v_mfma_f32_16x16x32_bf16 v[106:109], v[158:161], v[190:193], v[106:109]
	v_mfma_f32_16x16x32_bf16 v[94:97], v[146:149], v[198:201], v[94:97]
	v_mfma_f32_16x16x32_bf16 v[90:93], v[158:161], v[198:201], v[90:93]
	v_mfma_f32_16x16x32_bf16 v[86:89], v[146:149], v[206:209], v[86:89]
	v_mfma_f32_16x16x32_bf16 v[82:85], v[158:161], v[206:209], v[82:85]
	v_mfma_f32_16x16x32_bf16 v[126:129], v[150:153], v[186:189], v[126:129]
	v_mfma_f32_16x16x32_bf16 v[122:125], v[162:165], v[186:189], v[122:125]
	v_mfma_f32_16x16x32_bf16 v[114:117], v[150:153], v[194:197], v[114:117]
	v_mfma_f32_16x16x32_bf16 v[106:109], v[162:165], v[194:197], v[106:109]
	v_mfma_f32_16x16x32_bf16 v[94:97], v[150:153], v[202:205], v[94:97]
	v_mfma_f32_16x16x32_bf16 v[90:93], v[162:165], v[202:205], v[90:93]
	v_mfma_f32_16x16x32_bf16 v[86:89], v[150:153], v[210:213], v[86:89]
	v_mfma_f32_16x16x32_bf16 v[82:85], v[162:165], v[210:213], v[82:85]
	v_mfma_f32_16x16x32_bf16 v[118:121], v[166:169], v[182:185], v[118:121]
	v_mfma_f32_16x16x32_bf16 v[110:113], v[174:177], v[182:185], v[110:113]
	v_mfma_f32_16x16x32_bf16 v[102:105], v[166:169], v[190:193], v[102:105]
	v_mfma_f32_16x16x32_bf16 v[98:101], v[174:177], v[190:193], v[98:101]
	v_mfma_f32_16x16x32_bf16 v[78:81], v[166:169], v[198:201], v[78:81]
	v_mfma_f32_16x16x32_bf16 v[74:77], v[174:177], v[198:201], v[74:77]
	v_mfma_f32_16x16x32_bf16 v[70:73], v[166:169], v[206:209], v[70:73]
	v_mfma_f32_16x16x32_bf16 v[66:69], v[174:177], v[206:209], v[66:69]
	v_mfma_f32_16x16x32_bf16 v[118:121], v[170:173], v[186:189], v[118:121]
	v_mfma_f32_16x16x32_bf16 v[110:113], v[178:181], v[186:189], v[110:113]
	v_mfma_f32_16x16x32_bf16 v[102:105], v[170:173], v[194:197], v[102:105]
	v_mfma_f32_16x16x32_bf16 v[98:101], v[178:181], v[194:197], v[98:101]
	v_mfma_f32_16x16x32_bf16 v[78:81], v[170:173], v[202:205], v[78:81]
	v_mfma_f32_16x16x32_bf16 v[74:77], v[178:181], v[202:205], v[74:77]
	v_mfma_f32_16x16x32_bf16 v[70:73], v[170:173], v[210:213], v[70:73]
	v_mfma_f32_16x16x32_bf16 v[66:69], v[178:181], v[210:213], v[66:69]
	s_barrier
	s_add_i32 s26, s50, s34
	s_add_i32 m0, s26, 0xffffff80
	ds_read_b128 v[182:185], v156 offset:49152
	ds_read_b128 v[186:189], v156 offset:50176
	ds_read_b128 v[190:193], v156 offset:51200
	ds_read_b128 v[194:197], v156 offset:52224
	ds_read_b128 v[198:201], v156 offset:53248
	ds_read_b128 v[202:205], v156 offset:54272
	ds_read_b128 v[206:209], v156 offset:55296
	ds_read_b128 v[210:213], v156 offset:56320
	global_load_lds_dwordx4 v132, s[98:99] offset:128
	s_add_i32 m0, s26, 0x1f80
	s_add_u32 s24, s24, 0x20080
	s_addc_u32 s25, s25, 0
	s_add_i32 s26, s51, s34
	global_load_lds_dwordx4 v136, s[98:99] offset:128
	s_mov_b32 m0, s26
	s_nop 0
	global_load_lds_dwordx4 v132, s[24:25]
	s_add_i32 m0, s26, 0x2000
	s_nop 0
	global_load_lds_dwordx4 v136, s[24:25]
	s_add_i32 m0, s39, 0xffffff80
	s_nop 0
	global_load_lds_dwordx4 v130, s[100:101] offset:128
	s_add_i32 m0, s40, 0xffffff80
	s_nop 0
	global_load_lds_dwordx4 v134, s[100:101] offset:128
	s_waitcnt vmcnt(8) lgkmcnt(0)
	s_barrier
	v_mfma_f32_16x16x32_bf16 v[62:65], v[146:149], v[182:185], v[62:65]
	v_mfma_f32_16x16x32_bf16 v[58:61], v[158:161], v[182:185], v[58:61]
	v_mfma_f32_16x16x32_bf16 v[54:57], v[146:149], v[190:193], v[54:57]
	v_mfma_f32_16x16x32_bf16 v[50:53], v[158:161], v[190:193], v[50:53]
	v_mfma_f32_16x16x32_bf16 v[30:33], v[146:149], v[198:201], v[30:33]
	v_mfma_f32_16x16x32_bf16 v[26:29], v[158:161], v[198:201], v[26:29]
	v_mfma_f32_16x16x32_bf16 v[22:25], v[146:149], v[206:209], v[22:25]
	v_mfma_f32_16x16x32_bf16 v[10:13], v[158:161], v[206:209], v[10:13]
	v_mfma_f32_16x16x32_bf16 v[62:65], v[150:153], v[186:189], v[62:65]
	v_mfma_f32_16x16x32_bf16 v[58:61], v[162:165], v[186:189], v[58:61]
	v_mfma_f32_16x16x32_bf16 v[54:57], v[150:153], v[194:197], v[54:57]
	v_mfma_f32_16x16x32_bf16 v[50:53], v[162:165], v[194:197], v[50:53]
	v_mfma_f32_16x16x32_bf16 v[30:33], v[150:153], v[202:205], v[30:33]
	v_mfma_f32_16x16x32_bf16 v[26:29], v[162:165], v[202:205], v[26:29]
	v_mfma_f32_16x16x32_bf16 v[22:25], v[150:153], v[210:213], v[22:25]
	v_mfma_f32_16x16x32_bf16 v[10:13], v[162:165], v[210:213], v[10:13]
	v_mfma_f32_16x16x32_bf16 v[46:49], v[166:169], v[182:185], v[46:49]
	v_mfma_f32_16x16x32_bf16 v[42:45], v[174:177], v[182:185], v[42:45]
	v_mfma_f32_16x16x32_bf16 v[38:41], v[166:169], v[190:193], v[38:41]
	v_mfma_f32_16x16x32_bf16 v[34:37], v[174:177], v[190:193], v[34:37]
	v_mfma_f32_16x16x32_bf16 v[18:21], v[166:169], v[198:201], v[18:21]
	v_mfma_f32_16x16x32_bf16 v[14:17], v[174:177], v[198:201], v[14:17]
	v_mfma_f32_16x16x32_bf16 v[6:9], v[166:169], v[206:209], v[6:9]
	v_mfma_f32_16x16x32_bf16 v[2:5], v[174:177], v[206:209], v[2:5]
	v_mfma_f32_16x16x32_bf16 v[46:49], v[170:173], v[186:189], v[46:49]
	v_mfma_f32_16x16x32_bf16 v[42:45], v[178:181], v[186:189], v[42:45]
	v_mfma_f32_16x16x32_bf16 v[38:41], v[170:173], v[194:197], v[38:41]
	v_mfma_f32_16x16x32_bf16 v[34:37], v[178:181], v[194:197], v[34:37]
	v_mfma_f32_16x16x32_bf16 v[18:21], v[170:173], v[202:205], v[18:21]
	v_mfma_f32_16x16x32_bf16 v[14:17], v[178:181], v[202:205], v[14:17]
	v_mfma_f32_16x16x32_bf16 v[6:9], v[170:173], v[210:213], v[6:9]
	v_mfma_f32_16x16x32_bf16 v[2:5], v[178:181], v[210:213], v[2:5]
	s_barrier
	s_add_i32 s49, s49, 2
	s_add_u32 s22, s22, 0x100
	s_addc_u32 s23, s23, 0
	s_add_u32 s47, s47, 0x100
	s_addc_u32 s48, s48, 0
	s_cmp_gt_u32 s49, 5
	s_cbranch_scc0 .LBB0_1538
	s_and_b64 vcc, exec, s[10:11]
	s_cbranch_vccz .LBB0_1541
	s_barrier
; __device__ __forceinline__ u32x4 pack8(const f32x4 v0, const f32x4 v1) { u32x4 w; w.x = cvt_pk_bf16(v0[0], v0[1]); w.y = cvt_pk_bf16(v0[2], v0[3]); w.z = cvt_pk_bf16(v1[0], v1[1]); w.w = cvt_pk_bf16(v1[2], v1[3]); return w; }
; __device__ __forceinline__ void unpack8(const u32x4 w, f32x4& v0, f32x4& v1) { v0 = (f32x4){bf_lo(w.x), bf_hi(w.x), bf_lo(w.y), bf_hi(w.y)}; v1 = (f32x4){bf_lo(w.z), bf_hi(w.z), bf_lo(w.w), bf_hi(w.w)}; }
;     __device__ __forceinline__ void load_row(RowIn& R, int r, int col0) const {
;     ...
;             if (MODE == 2) R.g[bj] = *(const u32x4*)(GT + (size_t)r * 8192 + col0 + bj * HALF);
;             if (MODE == 3) { R.g[bj] = *(const u32x4*)(GT + (size_t)r * 8192 + 4096 + col0 + bj * HALF); R.a[bj] = *(const u32x4*)(AD + (size_t)r * 4096 + col0 + bj * HALF); } }
;     }
;     __device__ __forceinline__ void operator()(AccRef acc, const Unit& u, int wr, int wc, int fr, int fq) const {
;         const int row0 = u.pm * BM + wr * 64 + fr, col0 = u.pn * BM + wc * 32 + 8 * fq;
;         RowIn cur, nxt;
;         if (MODE >= 2) load_row(cur, row0, col0);
; #pragma unroll
;         for (int s = 0; s < 8; ++s) { const int ai = s >> 2, m = s & 3; const int r = row0 + ai * HALF + m * 16; bf16_t* rowp = O + (size_t)r * ldc + col0;
;                 if (MODE >= 2 && s + 1 < 8) load_row(nxt, row0 + ((s + 1) >> 2) * HALF + ((s + 1) & 3) * 16, col0);
;                 float rs = 1.f; if (MODE == 1) rs = __builtin_amdgcn_rsqf(rstd[r] * (1.0f / 4096.0f) + 1e-6f);
;                 float mx = 0.f;
; #pragma unroll
;                 for (int bj = 0; bj < 2; ++bj) { f32x4 v0 = acc[ai][bj][m][0], v1 = acc[ai][bj][m][1];
;                     if (MODE == 1) { v0 = v0 * rs; v1 = v1 * rs;
; #pragma unroll
;                         for (int j = 0; j < 4; ++j) { const float a = v0[j] > 0.f ? v0[j] : 0.f, b = v1[j] > 0.f ? v1[j] : 0.f; v0[j] = a * a; v1[j] = b * b; } }
;                     if (MODE == 2) { f32x4 g0, g1; unpack8(cur.g[bj], g0, g1); v0 = v0 * g0; v1 = v1 * g1; }
;                     if (MODE == 3) { f32x4 g0, g1, a0, a1; unpack8(cur.g[bj], g0, g1); unpack8(cur.a[bj], a0, a1);
;                         v0 = a0 + v0 * g0; v1 = a1 + v1 * g1;
; #pragma unroll
;                         for (int j = 0; j < 4; ++j) mx = fmaxf(mx, fmaxf(fabsf(v0[j]), fabsf(v1[j]))); }
;                     *(u32x4*)(rowp + bj * HALF) = pack8(v0, v1); }
.LBB0_1541:
	s_lshl_b32 s98, s20, 5
	s_add_i32 s98, s98, s44
	s_lshl_b32 s98, s98, 17
	v_and_b32_e32 v248, 63, v0
	v_lshlrev_b32_e32 v248, 4, v248
	v_lshrrev_b32_e32 v249, 6, v0
	v_lshl_add_u32 v248, v249, 14, v248
	v_add_u32_e32 v248, s98, v248
	v_mov_b32_e32 v249, 0
	v_lshl_add_u64 v[248:249], s[6:7], 0, v[248:249]
	s_lshl_b32 s98, s20, 4
	s_add_i32 s98, s98, s44
	s_lshl_b32 s98, s98, 17
	v_and_b32_e32 v250, 63, v0
	v_lshlrev_b32_e32 v250, 4, v250
	v_lshrrev_b32_e32 v251, 6, v0
	v_lshl_add_u32 v250, v251, 14, v250
	v_add_u32_e32 v250, s98, v250
	v_mov_b32_e32 v251, 0
	v_lshl_add_u64 v[250:251], s[2:3], 0, v[250:251]
	v_mov_b32_e32 v146, v0
	s_andn2_b64 vcc, exec, s[4:5]
	v_ashrrev_i32_e32 v147, 2, v146
	v_and_b32_e32 v147, 0xffffffc0, v147
	v_lshl_add_u32 v147, s20, 8, v147
	v_and_or_b32 v148, v146, 15, v147
	v_lshrrev_b32_e32 v146, 1, v146
	v_and_b32_e32 v146, 0x78, v146
	v_lshl_or_b32 v146, s44, 8, v146
	v_ashrrev_i32_e32 v149, 31, v148
	v_lshlrev_b64 v[150:151], 14, v[148:149]
	v_ashrrev_i32_e32 v147, 31, v146
	v_lshl_add_u64 v[150:151], s[6:7], 0, v[150:151]
	v_lshlrev_b64 v[146:147], 1, v[146:147]
	v_or_b32_e32 v174, 16, v148
	s_mov_b64 s[98:99], 0x0
	v_lshl_add_u64 v[150:151], v[248:249], 0, s[98:99]
	v_ashrrev_i32_e32 v175, 31, v174
	global_load_dwordx4 v[158:161], v[150:151], off
	global_load_dwordx4 v[162:165], v[150:151], off offset:1024
	v_lshlrev_b64 v[150:151], 14, v[174:175]
	v_lshl_add_u64 v[150:151], s[6:7], 0, v[150:151]
	s_mov_b64 s[98:99], 0x800
	v_lshl_add_u64 v[150:151], v[248:249], 0, s[98:99]
	global_load_dwordx4 v[166:169], v[150:151], off
	global_load_dwordx4 v[170:173], v[150:151], off offset:1024
	v_or_b32_e32 v150, 32, v148
	v_ashrrev_i32_e32 v151, 31, v150
	v_lshlrev_b64 v[176:177], 13, v[148:149]
	v_lshlrev_b64 v[178:179], 14, v[150:151]
	v_lshl_add_u64 v[176:177], s[2:3], 0, v[176:177]
	v_lshl_add_u64 v[178:179], s[6:7], 0, v[178:179]
	s_mov_b64 s[98:99], 0x0
	v_lshl_add_u64 v[176:177], v[250:251], 0, s[98:99]
	s_mov_b64 s[98:99], 0x1000
	v_lshl_add_u64 v[178:179], v[248:249], 0, s[98:99]
	v_or_b32_e32 v152, 48, v148
	v_ashrrev_i32_e32 v153, 31, v152
	v_lshlrev_b64 v[174:175], 13, v[174:175]
	v_lshlrev_b64 v[180:181], 14, v[152:153]
	v_lshl_add_u64 v[174:175], s[2:3], 0, v[174:175]
	v_lshl_add_u64 v[180:181], s[6:7], 0, v[180:181]
	s_mov_b64 s[98:99], 0x800
	v_lshl_add_u64 v[174:175], v[250:251], 0, s[98:99]
	s_mov_b64 s[98:99], 0x1800
	v_lshl_add_u64 v[180:181], v[248:249], 0, s[98:99]
	s_mov_b64 s[4:5], -1
	s_waitcnt vmcnt(0)
	v_lshlrev_b32_e32 v182, 16, v158
	v_and_b32_e32 v183, 0xffff0000, v158
	v_lshlrev_b32_e32 v158, 16, v159
	v_and_b32_e32 v159, 0xffff0000, v159
	v_lshlrev_b32_e32 v184, 16, v160
	v_and_b32_e32 v185, 0xffff0000, v160
	v_lshlrev_b32_e32 v160, 16, v161
	v_and_b32_e32 v161, 0xffff0000, v161
	v_lshlrev_b32_e32 v186, 16, v162
	v_and_b32_e32 v187, 0xffff0000, v162
	v_lshlrev_b32_e32 v162, 16, v163
	v_and_b32_e32 v163, 0xffff0000, v163
	v_lshlrev_b32_e32 v188, 16, v164
	v_and_b32_e32 v189, 0xffff0000, v164
	v_lshlrev_b32_e32 v164, 16, v165
	v_and_b32_e32 v165, 0xffff0000, v165
	v_pk_mul_f32 v[128:129], v[128:129], v[158:159]
	v_pk_mul_f32 v[126:127], v[126:127], v[182:183]
	v_pk_mul_f32 v[124:125], v[124:125], v[160:161]
	v_pk_mul_f32 v[122:123], v[122:123], v[184:185]
	v_pk_mul_f32 v[120:121], v[120:121], v[162:163]
	v_pk_mul_f32 v[118:119], v[118:119], v[186:187]
	v_pk_mul_f32 v[158:159], v[112:113], v[164:165]
	v_pk_mul_f32 v[160:161], v[110:111], v[188:189]
	v_cvt_pk_bf16_f32 v110, v126, v127
	v_cvt_pk_bf16_f32 v111, v128, v129
	v_cvt_pk_bf16_f32 v112, v122, v123
	v_cvt_pk_bf16_f32 v113, v124, v125
	global_store_dwordx4 v[176:177], v[110:113], off
	v_lshlrev_b32_e32 v162, 16, v166
	v_and_b32_e32 v163, 0xffff0000, v166
	v_cvt_pk_bf16_f32 v110, v118, v119
	v_cvt_pk_bf16_f32 v111, v120, v121
	v_cvt_pk_bf16_f32 v112, v160, v161
	v_cvt_pk_bf16_f32 v113, v158, v159
	global_load_dwordx4 v[118:121], v[178:179], off
	v_lshlrev_b32_e32 v164, 16, v167
	v_and_b32_e32 v165, 0xffff0000, v167
	v_lshlrev_b32_e32 v166, 16, v168
	v_and_b32_e32 v167, 0xffff0000, v168
	v_lshlrev_b32_e32 v124, 16, v171
	v_and_b32_e32 v125, 0xffff0000, v171
	global_store_dwordx4 v[176:177], v[110:113], off offset:1024
	v_pk_mul_f32 v[158:159], v[106:107], v[166:167]
	v_pk_mul_f32 v[124:125], v[104:105], v[124:125]
	global_load_dwordx4 v[104:107], v[178:179], off offset:1024
	v_lshlrev_b32_e32 v168, 16, v169
	v_and_b32_e32 v169, 0xffff0000, v169
	v_lshlrev_b32_e32 v126, 16, v172
	v_and_b32_e32 v127, 0xffff0000, v172
	v_lshlrev_b32_e32 v128, 16, v173
	v_and_b32_e32 v129, 0xffff0000, v173
	v_lshlrev_b32_e32 v122, 16, v170
	v_and_b32_e32 v123, 0xffff0000, v170
	v_pk_mul_f32 v[116:117], v[116:117], v[164:165]
	v_pk_mul_f32 v[114:115], v[114:115], v[162:163]
	v_pk_mul_f32 v[108:109], v[108:109], v[168:169]
	v_pk_mul_f32 v[110:111], v[100:101], v[128:129]
	v_pk_mul_f32 v[112:113], v[98:99], v[126:127]
	v_cvt_pk_bf16_f32 v98, v114, v115
	v_cvt_pk_bf16_f32 v99, v116, v117
	v_cvt_pk_bf16_f32 v100, v158, v159
	v_cvt_pk_bf16_f32 v101, v108, v109
	v_pk_mul_f32 v[102:103], v[102:103], v[122:123]
	global_store_dwordx4 v[174:175], v[98:101], off
	v_lshlrev_b64 v[116:117], 13, v[152:153]
	v_lshl_add_u64 v[116:117], s[2:3], 0, v[116:117]
	v_cvt_pk_bf16_f32 v98, v102, v103
	v_cvt_pk_bf16_f32 v99, v124, v125
	v_cvt_pk_bf16_f32 v100, v112, v113
	v_cvt_pk_bf16_f32 v101, v110, v111
	global_load_dwordx4 v[108:111], v[180:181], off
	v_lshlrev_b64 v[102:103], 13, v[150:151]
	global_store_dwordx4 v[174:175], v[98:101], off offset:1024
	global_load_dwordx4 v[112:115], v[180:181], off offset:1024
	v_lshl_add_u64 v[102:103], s[2:3], 0, v[102:103]
	v_add_u32_e32 v98, 0x80, v148
	v_ashrrev_i32_e32 v99, 31, v98
	v_lshlrev_b64 v[122:123], 14, v[98:99]
	v_lshl_add_u64 v[122:123], s[6:7], 0, v[122:123]
	s_mov_b64 s[98:99], 0x1000
	v_lshl_add_u64 v[102:103], v[250:251], 0, s[98:99]
	v_add_u32_e32 v100, 0x90, v148
	s_mov_b64 s[98:99], 0x2000
	v_lshl_add_u64 v[122:123], v[248:249], 0, s[98:99]
	v_ashrrev_i32_e32 v101, 31, v100
	v_lshlrev_b64 v[124:125], 14, v[100:101]
	v_lshl_add_u64 v[124:125], s[6:7], 0, v[124:125]
	s_mov_b64 s[98:99], 0x1800
	v_lshl_add_u64 v[116:117], v[250:251], 0, s[98:99]
	s_mov_b64 s[98:99], 0x2800
	v_lshl_add_u64 v[124:125], v[248:249], 0, s[98:99]
	s_waitcnt vmcnt(6)
; __device__ __forceinline__ u32x4 pack8(const f32x4 v0, const f32x4 v1) { u32x4 w; w.x = cvt_pk_bf16(v0[0], v0[1]); w.y = cvt_pk_bf16(v0[2], v0[3]); w.z = cvt_pk_bf16(v1[0], v1[1]); w.w = cvt_pk_bf16(v1[2], v1[3]); return w; }
; __device__ __forceinline__ void unpack8(const u32x4 w, f32x4& v0, f32x4& v1) { v0 = (f32x4){bf_lo(w.x), bf_hi(w.x), bf_lo(w.y), bf_hi(w.y)}; v1 = (f32x4){bf_lo(w.z), bf_hi(w.z), bf_lo(w.w), bf_hi(w.w)}; }
;     __device__ __forceinline__ void operator()(AccRef acc, const Unit& u, int wr, int wc, int fr, int fq) const {
;     ...
;         for (int s = 0; s < 8; ++s) { const int ai = s >> 2, m = s & 3; const int r = row0 + ai * HALF + m * 16; bf16_t* rowp = O + (size_t)r * ldc + col0;
;                 if (MODE >= 2 && s + 1 < 8) load_row(nxt, row0 + ((s + 1) >> 2) * HALF + ((s + 1) & 3) * 16, col0);
;                 float rs = 1.f; if (MODE == 1) rs = __builtin_amdgcn_rsqf(rstd[r] * (1.0f / 4096.0f) + 1e-6f);
;                 float mx = 0.f;
; #pragma unroll
;                 for (int bj = 0; bj < 2; ++bj) { f32x4 v0 = acc[ai][bj][m][0], v1 = acc[ai][bj][m][1];
;                     if (MODE == 1) { v0 = v0 * rs; v1 = v1 * rs;
; #pragma unroll
;                         for (int j = 0; j < 4; ++j) { const float a = v0[j] > 0.f ? v0[j] : 0.f, b = v1[j] > 0.f ? v1[j] : 0.f; v0[j] = a * a; v1[j] = b * b; } }
;                     if (MODE == 2) { f32x4 g0, g1; unpack8(cur.g[bj], g0, g1); v0 = v0 * g0; v1 = v1 * g1; }
;                     if (MODE == 3) { f32x4 g0, g1, a0, a1; unpack8(cur.g[bj], g0, g1); unpack8(cur.a[bj], a0, a1);
;                         v0 = a0 + v0 * g0; v1 = a1 + v1 * g1;
; #pragma unroll
;                         for (int j = 0; j < 4; ++j) mx = fmaxf(mx, fmaxf(fabsf(v0[j]), fabsf(v1[j]))); }
;                     *(u32x4*)(rowp + bj * HALF) = pack8(v0, v1); }
	v_lshlrev_b32_e32 v126, 16, v118
	v_and_b32_e32 v127, 0xffff0000, v118
	v_lshlrev_b32_e32 v118, 16, v119
	v_and_b32_e32 v119, 0xffff0000, v119
	v_lshlrev_b32_e32 v128, 16, v120
	v_and_b32_e32 v129, 0xffff0000, v120
	v_lshlrev_b32_e32 v120, 16, v121
	v_and_b32_e32 v121, 0xffff0000, v121
	v_pk_mul_f32 v[96:97], v[96:97], v[118:119]
	v_pk_mul_f32 v[94:95], v[94:95], v[126:127]
	v_pk_mul_f32 v[118:119], v[92:93], v[120:121]
	v_pk_mul_f32 v[92:93], v[90:91], v[128:129]
	v_cvt_pk_bf16_f32 v90, v94, v95
	v_cvt_pk_bf16_f32 v91, v96, v97
	s_waitcnt vmcnt(4)
	v_lshlrev_b32_e32 v94, 16, v104
	v_and_b32_e32 v95, 0xffff0000, v104
	v_lshlrev_b32_e32 v96, 16, v105
	v_and_b32_e32 v97, 0xffff0000, v105
	v_lshlrev_b32_e32 v104, 16, v106
	v_and_b32_e32 v105, 0xffff0000, v106
	v_lshlrev_b32_e32 v106, 16, v107
	v_and_b32_e32 v107, 0xffff0000, v107
	v_cvt_pk_bf16_f32 v92, v92, v93
	v_cvt_pk_bf16_f32 v93, v118, v119
	global_store_dwordx4 v[102:103], v[90:93], off
	v_pk_mul_f32 v[80:81], v[80:81], v[96:97]
	v_pk_mul_f32 v[78:79], v[78:79], v[94:95]
	v_pk_mul_f32 v[90:91], v[76:77], v[106:107]
	v_pk_mul_f32 v[76:77], v[74:75], v[104:105]
	v_cvt_pk_bf16_f32 v74, v78, v79
	v_cvt_pk_bf16_f32 v75, v80, v81
	s_waitcnt vmcnt(3)
	v_lshlrev_b32_e32 v92, 16, v108
	v_cvt_pk_bf16_f32 v76, v76, v77
	v_cvt_pk_bf16_f32 v77, v90, v91
	global_load_dwordx4 v[78:81], v[122:123], off
	v_and_b32_e32 v93, 0xffff0000, v108
	v_lshlrev_b32_e32 v94, 16, v109
	v_and_b32_e32 v95, 0xffff0000, v109
	v_lshlrev_b32_e32 v96, 16, v110
	v_and_b32_e32 v97, 0xffff0000, v110
	v_lshlrev_b32_e32 v104, 16, v111
	v_and_b32_e32 v105, 0xffff0000, v111
	global_store_dwordx4 v[102:103], v[74:77], off offset:1024
	v_pk_mul_f32 v[88:89], v[88:89], v[94:95]
	v_pk_mul_f32 v[86:87], v[86:87], v[92:93]
	v_pk_mul_f32 v[90:91], v[84:85], v[104:105]
	v_pk_mul_f32 v[84:85], v[82:83], v[96:97]
	s_waitcnt vmcnt(3)
	v_lshlrev_b32_e32 v92, 16, v112
	v_and_b32_e32 v93, 0xffff0000, v112
	v_lshlrev_b32_e32 v94, 16, v113
	v_and_b32_e32 v95, 0xffff0000, v113
	v_lshlrev_b32_e32 v96, 16, v114
	v_and_b32_e32 v97, 0xffff0000, v114
	v_lshlrev_b32_e32 v102, 16, v115
	v_and_b32_e32 v103, 0xffff0000, v115
	global_load_dwordx4 v[74:77], v[122:123], off offset:1024
	v_cvt_pk_bf16_f32 v82, v86, v87
	v_pk_mul_f32 v[72:73], v[72:73], v[94:95]
	v_pk_mul_f32 v[70:71], v[70:71], v[92:93]
	v_pk_mul_f32 v[86:87], v[68:69], v[102:103]
	v_pk_mul_f32 v[68:69], v[66:67], v[96:97]
	v_cvt_pk_bf16_f32 v83, v88, v89
	v_cvt_pk_bf16_f32 v84, v84, v85
	v_cvt_pk_bf16_f32 v85, v90, v91
	global_store_dwordx4 v[116:117], v[82:85], off
	v_cvt_pk_bf16_f32 v66, v70, v71
	v_cvt_pk_bf16_f32 v67, v72, v73
	v_cvt_pk_bf16_f32 v68, v68, v69
	v_cvt_pk_bf16_f32 v69, v86, v87
	global_load_dwordx4 v[70:73], v[124:125], off
	s_nop 0
	v_add_u32_e32 v82, 0xa0, v148
	global_store_dwordx4 v[116:117], v[66:69], off offset:1024
	global_load_dwordx4 v[66:69], v[124:125], off offset:1024
	v_ashrrev_i32_e32 v83, 31, v82
	v_lshlrev_b64 v[86:87], 13, v[98:99]
	v_lshlrev_b64 v[90:91], 14, v[82:83]
	v_lshl_add_u64 v[86:87], s[2:3], 0, v[86:87]
	v_add_u32_e32 v84, 0xb0, v148
	v_lshl_add_u64 v[90:91], s[6:7], 0, v[90:91]
	s_mov_b64 s[98:99], 0x2000
	v_lshl_add_u64 v[86:87], v[250:251], 0, s[98:99]
	v_ashrrev_i32_e32 v85, 31, v84
	s_mov_b64 s[98:99], 0x3000
	v_lshl_add_u64 v[90:91], v[248:249], 0, s[98:99]
	v_lshlrev_b64 v[88:89], 13, v[100:101]
	v_lshlrev_b64 v[92:93], 14, v[84:85]
	v_lshl_add_u64 v[88:89], s[2:3], 0, v[88:89]
	v_lshl_add_u64 v[92:93], s[6:7], 0, v[92:93]
	s_mov_b64 s[98:99], 0x2800
	v_lshl_add_u64 v[88:89], v[250:251], 0, s[98:99]
	s_mov_b64 s[98:99], 0x3800
	v_lshl_add_u64 v[92:93], v[248:249], 0, s[98:99]
	s_waitcnt vmcnt(6)
	v_lshlrev_b32_e32 v94, 16, v78
	v_and_b32_e32 v95, 0xffff0000, v78
	v_lshlrev_b32_e32 v78, 16, v79
	v_and_b32_e32 v79, 0xffff0000, v79
	v_lshlrev_b32_e32 v96, 16, v80
	v_and_b32_e32 v97, 0xffff0000, v80
	v_lshlrev_b32_e32 v80, 16, v81
	v_and_b32_e32 v81, 0xffff0000, v81
	v_pk_mul_f32 v[64:65], v[64:65], v[78:79]
	v_pk_mul_f32 v[62:63], v[62:63], v[94:95]
	v_pk_mul_f32 v[78:79], v[60:61], v[80:81]
	v_pk_mul_f32 v[60:61], v[58:59], v[96:97]
	v_cvt_pk_bf16_f32 v58, v62, v63
	v_cvt_pk_bf16_f32 v59, v64, v65
	s_waitcnt vmcnt(4)
	v_lshlrev_b32_e32 v62, 16, v74
	v_and_b32_e32 v63, 0xffff0000, v74
	v_lshlrev_b32_e32 v64, 16, v75
	v_and_b32_e32 v65, 0xffff0000, v75
	v_lshlrev_b32_e32 v74, 16, v76
	v_and_b32_e32 v75, 0xffff0000, v76
	v_lshlrev_b32_e32 v76, 16, v77
	v_and_b32_e32 v77, 0xffff0000, v77
	v_cvt_pk_bf16_f32 v60, v60, v61
	v_cvt_pk_bf16_f32 v61, v78, v79
	global_store_dwordx4 v[86:87], v[58:61], off
	v_pk_mul_f32 v[48:49], v[48:49], v[64:65]
	v_pk_mul_f32 v[46:47], v[46:47], v[62:63]
	v_pk_mul_f32 v[58:59], v[44:45], v[76:77]
	v_pk_mul_f32 v[44:45], v[42:43], v[74:75]
	s_waitcnt vmcnt(3)
; #define PG8_BAR __builtin_amdgcn_s_barrier()
; template <class Epi, class Sched, bool ALIGN_EPI = false, bool SP2 = false, bool I8 = false>
; __device__ __forceinline__ void gemm_phase(PG8_LAS unsigned char* lds, const Gemm g, const Sched& S, const Epi& E) {
;     ...
;         if (!has_next) break;
; #pragma unroll
;         for (int a = 0; a < 2; ++a)
; #pragma unroll
;             for (int b = 0; b < 2; ++b)
; #pragma unroll
;                 for (int m = 0; m < 4; ++m)
; #pragma unroll
;                     for (int n = 0; n < 2; ++n) acc[a][b][m][n] = (typename AccT<I8>::type){0, 0, 0, 0};
;         cur = nxt; cA = nA; cB = nB; ++ui; nt = PG8_NT(cur);
;         if constexpr (ALIGN_EPI) { if (wr == 1) PG8_BAR; }
;     __device__ __forceinline__ void operator()(AccRef acc, const Unit& u, int wr, int wc, int fr, int fq) const {
;     ...
;         for (int s = 0; s < 8; ++s) { const int ai = s >> 2, m = s & 3; const int r = row0 + ai * HALF + m * 16; bf16_t* rowp = O + (size_t)r * ldc + col0;
;                 if (MODE >= 2 && s + 1 < 8) load_row(nxt, row0 + ((s + 1) >> 2) * HALF + ((s + 1) & 3) * 16, col0);
;                 float rs = 1.f; if (MODE == 1) rs = __builtin_amdgcn_rsqf(rstd[r] * (1.0f / 4096.0f) + 1e-6f);
;                 float mx = 0.f;
; #pragma unroll
;                 for (int bj = 0; bj < 2; ++bj) { f32x4 v0 = acc[ai][bj][m][0], v1 = acc[ai][bj][m][1];
;                     if (MODE == 1) { v0 = v0 * rs; v1 = v1 * rs;
; #pragma unroll
;                         for (int j = 0; j < 4; ++j) { const float a = v0[j] > 0.f ? v0[j] : 0.f, b = v1[j] > 0.f ? v1[j] : 0.f; v0[j] = a * a; v1[j] = b * b; } }
;                     if (MODE == 2) { f32x4 g0, g1; unpack8(cur.g[bj], g0, g1); v0 = v0 * g0; v1 = v1 * g1; }
;                     if (MODE == 3) { f32x4 g0, g1, a0, a1; unpack8(cur.g[bj], g0, g1); unpack8(cur.a[bj], a0, a1);
;                         v0 = a0 + v0 * g0; v1 = a1 + v1 * g1;
; #pragma unroll
;                         for (int j = 0; j < 4; ++j) mx = fmaxf(mx, fmaxf(fabsf(v0[j]), fabsf(v1[j]))); }
;                     *(u32x4*)(rowp + bj * HALF) = pack8(v0, v1); }
;                 if (MODE == 3) { mx = fmaxf(mx, __shfl_xor(mx, 16)); mx = fmaxf(mx, __shfl_xor(mx, 32)); if (fq == 0) atomicMax(RM + r, __builtin_bit_cast(unsigned, mx)); }
;                 if (MODE >= 2) cur = nxt; }
	v_lshlrev_b32_e32 v60, 16, v70
	v_and_b32_e32 v61, 0xffff0000, v70
	v_lshlrev_b32_e32 v62, 16, v71
	v_and_b32_e32 v63, 0xffff0000, v71
	v_lshlrev_b32_e32 v64, 16, v72
	v_and_b32_e32 v65, 0xffff0000, v72
	v_lshlrev_b32_e32 v70, 16, v73
	v_cvt_pk_bf16_f32 v42, v46, v47
	v_cvt_pk_bf16_f32 v43, v48, v49
	v_cvt_pk_bf16_f32 v44, v44, v45
	v_cvt_pk_bf16_f32 v45, v58, v59
	global_load_dwordx4 v[46:49], v[90:91], off
	v_and_b32_e32 v71, 0xffff0000, v73
	v_pk_mul_f32 v[56:57], v[56:57], v[62:63]
	v_pk_mul_f32 v[54:55], v[54:55], v[60:61]
	v_pk_mul_f32 v[58:59], v[52:53], v[70:71]
	v_pk_mul_f32 v[52:53], v[50:51], v[64:65]
	global_store_dwordx4 v[86:87], v[42:45], off offset:1024
	s_waitcnt vmcnt(3)
	v_lshlrev_b32_e32 v60, 16, v66
	v_and_b32_e32 v61, 0xffff0000, v66
	v_lshlrev_b32_e32 v62, 16, v67
	v_and_b32_e32 v63, 0xffff0000, v67
	v_lshlrev_b32_e32 v64, 16, v68
	v_and_b32_e32 v65, 0xffff0000, v68
	v_lshlrev_b32_e32 v66, 16, v69
	v_and_b32_e32 v67, 0xffff0000, v69
	global_load_dwordx4 v[42:45], v[90:91], off offset:1024
	v_cvt_pk_bf16_f32 v50, v54, v55
	v_pk_mul_f32 v[40:41], v[40:41], v[62:63]
	v_pk_mul_f32 v[38:39], v[38:39], v[60:61]
	v_pk_mul_f32 v[54:55], v[36:37], v[66:67]
	v_pk_mul_f32 v[36:37], v[34:35], v[64:65]
	v_cvt_pk_bf16_f32 v51, v56, v57
	v_cvt_pk_bf16_f32 v52, v52, v53
	v_cvt_pk_bf16_f32 v53, v58, v59
	global_store_dwordx4 v[88:89], v[50:53], off
	v_cvt_pk_bf16_f32 v34, v38, v39
	v_cvt_pk_bf16_f32 v35, v40, v41
	v_cvt_pk_bf16_f32 v36, v36, v37
	v_cvt_pk_bf16_f32 v37, v54, v55
	global_load_dwordx4 v[38:41], v[92:93], off
	s_nop 0
	v_lshlrev_b64 v[50:51], 13, v[82:83]
	global_store_dwordx4 v[88:89], v[34:37], off offset:1024
	global_load_dwordx4 v[34:37], v[92:93], off offset:1024
	v_lshl_add_u64 v[50:51], s[2:3], 0, v[50:51]
	s_mov_b64 s[98:99], 0x3000
	v_lshl_add_u64 v[50:51], v[250:251], 0, s[98:99]
	v_lshlrev_b64 v[52:53], 13, v[84:85]
	v_lshl_add_u64 v[52:53], s[2:3], 0, v[52:53]
	s_mov_b64 s[98:99], 0x3800
	v_lshl_add_u64 v[52:53], v[250:251], 0, s[98:99]
	s_waitcnt vmcnt(6)
	v_lshlrev_b32_e32 v54, 16, v46
	v_and_b32_e32 v55, 0xffff0000, v46
	v_lshlrev_b32_e32 v46, 16, v47
	v_and_b32_e32 v47, 0xffff0000, v47
	v_lshlrev_b32_e32 v56, 16, v48
	v_and_b32_e32 v57, 0xffff0000, v48
	v_lshlrev_b32_e32 v48, 16, v49
	v_and_b32_e32 v49, 0xffff0000, v49
	v_pk_mul_f32 v[32:33], v[32:33], v[46:47]
	v_pk_mul_f32 v[30:31], v[30:31], v[54:55]
	v_pk_mul_f32 v[46:47], v[28:29], v[48:49]
	v_pk_mul_f32 v[28:29], v[26:27], v[56:57]
	v_cvt_pk_bf16_f32 v26, v30, v31
	v_cvt_pk_bf16_f32 v27, v32, v33
	s_waitcnt vmcnt(4)
	v_lshlrev_b32_e32 v30, 16, v42
	v_cvt_pk_bf16_f32 v28, v28, v29
	v_cvt_pk_bf16_f32 v29, v46, v47
	v_and_b32_e32 v31, 0xffff0000, v42
	v_lshlrev_b32_e32 v32, 16, v43
	v_and_b32_e32 v33, 0xffff0000, v43
	v_lshlrev_b32_e32 v42, 16, v44
	v_and_b32_e32 v43, 0xffff0000, v44
	v_lshlrev_b32_e32 v44, 16, v45
	v_and_b32_e32 v45, 0xffff0000, v45
	global_store_dwordx4 v[50:51], v[26:29], off
	v_pk_mul_f32 v[20:21], v[20:21], v[32:33]
	v_pk_mul_f32 v[18:19], v[18:19], v[30:31]
	v_pk_mul_f32 v[26:27], v[16:17], v[44:45]
	s_waitcnt vmcnt(3)
	v_lshlrev_b32_e32 v28, 16, v38
	v_and_b32_e32 v29, 0xffff0000, v38
	v_lshlrev_b32_e32 v30, 16, v39
	v_and_b32_e32 v31, 0xffff0000, v39
	v_lshlrev_b32_e32 v32, 16, v40
	v_and_b32_e32 v33, 0xffff0000, v40
	v_lshlrev_b32_e32 v38, 16, v41
	v_and_b32_e32 v39, 0xffff0000, v41
	v_pk_mul_f32 v[16:17], v[14:15], v[42:43]
	v_cvt_pk_bf16_f32 v14, v18, v19
	v_cvt_pk_bf16_f32 v15, v20, v21
	v_pk_mul_f32 v[20:21], v[22:23], v[28:29]
	v_pk_mul_f32 v[22:23], v[12:13], v[38:39]
	v_pk_mul_f32 v[12:13], v[10:11], v[32:33]
	v_cvt_pk_bf16_f32 v16, v16, v17
	v_cvt_pk_bf16_f32 v17, v26, v27
	v_pk_mul_f32 v[18:19], v[24:25], v[30:31]
	global_store_dwordx4 v[50:51], v[14:17], off offset:1024
	v_cvt_pk_bf16_f32 v10, v20, v21
	v_cvt_pk_bf16_f32 v11, v18, v19
	v_cvt_pk_bf16_f32 v12, v12, v13
	v_cvt_pk_bf16_f32 v13, v22, v23
	global_store_dwordx4 v[52:53], v[10:13], off
	s_waitcnt vmcnt(3)
	v_lshlrev_b32_e32 v14, 16, v34
	v_and_b32_e32 v15, 0xffff0000, v34
	v_lshlrev_b32_e32 v10, 16, v36
	v_and_b32_e32 v11, 0xffff0000, v36
	v_lshlrev_b32_e32 v12, 16, v37
	v_and_b32_e32 v13, 0xffff0000, v37
	v_lshlrev_b32_e32 v16, 16, v35
	v_and_b32_e32 v17, 0xffff0000, v35
	v_pk_mul_f32 v[12:13], v[4:5], v[12:13]
	v_pk_mul_f32 v[4:5], v[2:3], v[10:11]
	v_pk_mul_f32 v[8:9], v[8:9], v[16:17]
	v_pk_mul_f32 v[6:7], v[6:7], v[14:15]
	s_nop 0
	v_cvt_pk_bf16_f32 v2, v6, v7
	v_cvt_pk_bf16_f32 v3, v8, v9
	v_cvt_pk_bf16_f32 v4, v4, v5
	v_cvt_pk_bf16_f32 v5, v12, v13
	global_store_dwordx4 v[52:53], v[2:5], off offset:1024
	s_cbranch_vccnz .LBB0_1530
	s_andn2_b64 vcc, exec, s[0:1]
	s_cbranch_vccnz .LBB0_1529
	s_barrier
	s_branch .LBB0_1529

; #define PG8_STAGE(bufoff, gbase, voff) do { _Pragma("unroll") for (int _i = 0; _i < 2; ++_i) \
;         __builtin_amdgcn_global_load_lds((const unsigned*)((const char*)(gbase) + (voff)[_i]), (PG8_LAS unsigned*)(lds + (bufoff) + ldsw + _i * 8192), 16, 0, 0); } while (0)
; #define PG8_LDA(dst, b, h) do { _Pragma("unroll") for (int m = 0; m < 4; ++m) _Pragma("unroll") for (int k = 0; k < 2; ++k) dst[m][k] = *(const PG8_LAS bf16x8*)(lds + PG8_SA(b, h) + aoff + m * 2048 + k * 1024); } while (0)
; #define PG8_WAIT_V(n) asm volatile("s_waitcnt vmcnt(" #n ")" ::: "memory")
; #define PG8_WAIT_L(n) asm volatile("s_waitcnt lgkmcnt(" #n ")" ::: "memory")
; #define PG8_BAR __builtin_amdgcn_s_barrier()
; template <class Epi, class Sched, bool ALIGN_EPI = false, bool SP2 = false, bool I8 = false>
; __device__ __forceinline__ void gemm_phase(PG8_LAS unsigned char* lds, const Gemm g, const Sched& S, const Epi& E) {
;     ...
;         for (int t = 0; t < nt; t += 2) {
;             const bool last = (t == nt - 2);
;             const char* a1 = cA + (size_t)(t + 1) * kstep;
;             const char* a2 = last ? nA : cA + (size_t)(t + 2) * kstep; const char* b2 = last ? nB : cB + (size_t)(t + 2) * kstep;
;             const char* a3 = a2 + kstep; const char* b3 = b2 + kstep;
;             if (last && has_next) S.a_ready(nxt);
;             if constexpr (SP2) {
;             PG8_LDB(B0, 0, 0); PG8_LDB(B1, 0, 1); PG8_SCHED; PG8_LDA(At, 0, 0); PG8_STAGE(PG8_SA(1, 1), a1 + hstepA, voffA);
;             PG8_WAIT_V(8); PG8_WAIT_L(0); PG8_BAR; PG8_MMA(0, 0, At, B0); PG8_MMA(0, 1, At, B1); PG8_BAR; PG8_SCHED;
;             PG8_LDA(At, 0, 1); PG8_STAGE(PG8_SB(0, 0), b2, voffB); PG8_STAGE(PG8_SB(0, 1), b2 + hstepB, voffB); PG8_STAGE(PG8_SA(0, 0), a2, voffA);
;             PG8_WAIT_V(8); PG8_WAIT_L(0); PG8_BAR; PG8_MMA(1, 0, At, B0); PG8_MMA(1, 1, At, B1); PG8_BAR; PG8_SCHED;
;             PG8_LDB(B0, 1, 0); PG8_LDB(B1, 1, 1); PG8_SCHED; PG8_LDA(At, 1, 0); PG8_STAGE(PG8_SA(0, 1), a2 + hstepA, voffA);
;             PG8_WAIT_V(8); PG8_WAIT_L(0); PG8_BAR; PG8_MMA(0, 0, At, B0); PG8_MMA(0, 1, At, B1); PG8_BAR; PG8_SCHED;
;             PG8_LDA(At, 1, 1); PG8_STAGE(PG8_SB(1, 0), b3, voffB); PG8_STAGE(PG8_SB(1, 1), b3 + hstepB, voffB); PG8_STAGE(PG8_SA(1, 0), a3, voffA);
;             PG8_WAIT_V(8); PG8_WAIT_L(0); PG8_BAR; PG8_MMA(1, 0, At, B0); PG8_MMA(1, 1, At, B1); PG8_BAR; PG8_SCHED;
.LBB0_1565:
	ds_read_b128 v[130:133], v176
	ds_read_b128 v[134:137], v176 offset:1024
	ds_read_b128 v[138:141], v176 offset:2048
	ds_read_b128 v[142:145], v176 offset:3072
	ds_read_b128 v[162:165], v177
	ds_read_b128 v[166:169], v177 offset:1024
	ds_read_b128 v[170:173], v177 offset:2048
	ds_read_b128 v[180:183], v177 offset:3072
	s_add_u32 s30, s28, 0xfff80080
	s_addc_u32 s31, s29, -1
	s_cmp_eq_u32 s54, 28
	s_cselect_b32 s35, s7, s31
	s_cselect_b32 s34, s21, s30
	s_cselect_b32 s31, s19, s53
	s_cselect_b32 s30, s27, s52
	s_add_i32 m0, s40, 0xc000
	ds_read_b128 v[184:187], v178
	ds_read_b128 v[188:191], v178 offset:1024
	ds_read_b128 v[192:195], v178 offset:2048
	ds_read_b128 v[196:199], v178 offset:3072
	ds_read_b128 v[200:203], v178 offset:4096
	ds_read_b128 v[204:207], v178 offset:5120
	ds_read_b128 v[208:211], v178 offset:6144
	ds_read_b128 v[212:215], v178 offset:7168
	global_load_lds_dwordx4 v154, s[28:29]
	s_add_i32 m0, s40, 0xe000
	s_nop 0
	global_load_lds_dwordx4 v156, s[28:29]
	s_waitcnt vmcnt(8) lgkmcnt(0)
	s_barrier
	v_mfma_f32_16x16x32_bf16 v[126:129], v[130:133], v[184:187], v[126:129]
	v_mfma_f32_16x16x32_bf16 v[122:125], v[138:141], v[184:187], v[122:125]
	v_mfma_f32_16x16x32_bf16 v[110:113], v[130:133], v[192:195], v[110:113]
	v_mfma_f32_16x16x32_bf16 v[106:109], v[138:141], v[192:195], v[106:109]
	v_mfma_f32_16x16x32_bf16 v[94:97], v[130:133], v[200:203], v[94:97]
	v_mfma_f32_16x16x32_bf16 v[90:93], v[138:141], v[200:203], v[90:93]
	v_mfma_f32_16x16x32_bf16 v[78:81], v[130:133], v[208:211], v[78:81]
	v_mfma_f32_16x16x32_bf16 v[74:77], v[138:141], v[208:211], v[74:77]
	v_mfma_f32_16x16x32_bf16 v[126:129], v[134:137], v[188:191], v[126:129]
	v_mfma_f32_16x16x32_bf16 v[122:125], v[142:145], v[188:191], v[122:125]
	v_mfma_f32_16x16x32_bf16 v[110:113], v[134:137], v[196:199], v[110:113]
	v_mfma_f32_16x16x32_bf16 v[106:109], v[142:145], v[196:199], v[106:109]
	v_mfma_f32_16x16x32_bf16 v[94:97], v[134:137], v[204:207], v[94:97]
	v_mfma_f32_16x16x32_bf16 v[90:93], v[142:145], v[204:207], v[90:93]
	v_mfma_f32_16x16x32_bf16 v[78:81], v[134:137], v[212:215], v[78:81]
	v_mfma_f32_16x16x32_bf16 v[74:77], v[142:145], v[212:215], v[74:77]
	v_mfma_f32_16x16x32_bf16 v[118:121], v[162:165], v[184:187], v[118:121]
	v_mfma_f32_16x16x32_bf16 v[114:117], v[170:173], v[184:187], v[114:117]
	v_mfma_f32_16x16x32_bf16 v[102:105], v[162:165], v[192:195], v[102:105]
	v_mfma_f32_16x16x32_bf16 v[98:101], v[170:173], v[192:195], v[98:101]
	v_mfma_f32_16x16x32_bf16 v[86:89], v[162:165], v[200:203], v[86:89]
	v_mfma_f32_16x16x32_bf16 v[82:85], v[170:173], v[200:203], v[82:85]
	v_mfma_f32_16x16x32_bf16 v[70:73], v[162:165], v[208:211], v[70:73]
	v_mfma_f32_16x16x32_bf16 v[66:69], v[170:173], v[208:211], v[66:69]
	v_mfma_f32_16x16x32_bf16 v[118:121], v[166:169], v[188:191], v[118:121]
	v_mfma_f32_16x16x32_bf16 v[114:117], v[180:183], v[188:191], v[114:117]
	v_mfma_f32_16x16x32_bf16 v[102:105], v[166:169], v[196:199], v[102:105]
	v_mfma_f32_16x16x32_bf16 v[98:101], v[180:183], v[196:199], v[98:101]
	v_mfma_f32_16x16x32_bf16 v[86:89], v[166:169], v[204:207], v[86:89]
	v_mfma_f32_16x16x32_bf16 v[82:85], v[180:183], v[204:207], v[82:85]
	v_mfma_f32_16x16x32_bf16 v[70:73], v[166:169], v[212:215], v[70:73]
	v_mfma_f32_16x16x32_bf16 v[66:69], v[180:183], v[212:215], v[66:69]
	s_barrier
	s_add_i32 s55, s50, s39
	s_mov_b64 s[98:99], s[30:31]
	s_mov_b32 m0, s55
	ds_read_b128 v[184:187], v178 offset:16384
	ds_read_b128 v[188:191], v178 offset:17408
	ds_read_b128 v[192:195], v178 offset:18432
	ds_read_b128 v[196:199], v178 offset:19456
	ds_read_b128 v[200:203], v178 offset:20480
	ds_read_b128 v[204:207], v178 offset:21504
	ds_read_b128 v[208:211], v178 offset:22528
	ds_read_b128 v[212:215], v178 offset:23552
	global_load_lds_dwordx4 v148, s[30:31]
	s_add_i32 m0, s55, 0x2000
	s_add_u32 s56, s30, 0x80000
	s_mov_b64 s[98:99], s[30:31]
	s_addc_u32 s57, s31, 0
	s_add_i32 s55, s51, s39
	global_load_lds_dwordx4 v152, s[30:31]
	s_mov_b32 m0, s55
	s_mov_b64 s[100:101], s[34:35]
	global_load_lds_dwordx4 v148, s[56:57]
	s_add_i32 m0, s55, 0x2000
	s_nop 0
	global_load_lds_dwordx4 v152, s[56:57]
	s_mov_b64 s[100:101], s[34:35]
	s_mov_b32 m0, s40
	s_nop 0
	global_load_lds_dwordx4 v146, s[34:35]
	s_mov_b32 m0, s41
	s_nop 0
	global_load_lds_dwordx4 v150, s[34:35]
	s_waitcnt vmcnt(8) lgkmcnt(0)
	s_barrier
	v_mfma_f32_16x16x32_bf16 v[62:65], v[130:133], v[184:187], v[62:65]
	v_mfma_f32_16x16x32_bf16 v[58:61], v[138:141], v[184:187], v[58:61]
	v_mfma_f32_16x16x32_bf16 v[46:49], v[130:133], v[192:195], v[46:49]
	v_mfma_f32_16x16x32_bf16 v[42:45], v[138:141], v[192:195], v[42:45]
	v_mfma_f32_16x16x32_bf16 v[30:33], v[130:133], v[200:203], v[30:33]
	v_mfma_f32_16x16x32_bf16 v[26:29], v[138:141], v[200:203], v[26:29]
	v_mfma_f32_16x16x32_bf16 v[14:17], v[130:133], v[208:211], v[14:17]
	v_mfma_f32_16x16x32_bf16 v[10:13], v[138:141], v[208:211], v[10:13]
	v_mfma_f32_16x16x32_bf16 v[62:65], v[134:137], v[188:191], v[62:65]
	v_mfma_f32_16x16x32_bf16 v[58:61], v[142:145], v[188:191], v[58:61]
	v_mfma_f32_16x16x32_bf16 v[46:49], v[134:137], v[196:199], v[46:49]
	v_mfma_f32_16x16x32_bf16 v[42:45], v[142:145], v[196:199], v[42:45]
	v_mfma_f32_16x16x32_bf16 v[30:33], v[134:137], v[204:207], v[30:33]
	v_mfma_f32_16x16x32_bf16 v[26:29], v[142:145], v[204:207], v[26:29]
	v_mfma_f32_16x16x32_bf16 v[14:17], v[134:137], v[212:215], v[14:17]
	v_mfma_f32_16x16x32_bf16 v[10:13], v[142:145], v[212:215], v[10:13]
	v_mfma_f32_16x16x32_bf16 v[54:57], v[162:165], v[184:187], v[54:57]
	v_mfma_f32_16x16x32_bf16 v[50:53], v[170:173], v[184:187], v[50:53]
	v_mfma_f32_16x16x32_bf16 v[38:41], v[162:165], v[192:195], v[38:41]
	v_mfma_f32_16x16x32_bf16 v[34:37], v[170:173], v[192:195], v[34:37]
	v_mfma_f32_16x16x32_bf16 v[22:25], v[162:165], v[200:203], v[22:25]
	v_mfma_f32_16x16x32_bf16 v[18:21], v[170:173], v[200:203], v[18:21]
	v_mfma_f32_16x16x32_bf16 v[6:9], v[162:165], v[208:211], v[6:9]
	v_mfma_f32_16x16x32_bf16 v[2:5], v[170:173], v[208:211], v[2:5]
	v_mfma_f32_16x16x32_bf16 v[54:57], v[166:169], v[188:191], v[54:57]
	v_mfma_f32_16x16x32_bf16 v[50:53], v[180:183], v[188:191], v[50:53]
	v_mfma_f32_16x16x32_bf16 v[38:41], v[166:169], v[196:199], v[38:41]
	v_mfma_f32_16x16x32_bf16 v[34:37], v[180:183], v[196:199], v[34:37]
	v_mfma_f32_16x16x32_bf16 v[22:25], v[166:169], v[204:207], v[22:25]
	v_mfma_f32_16x16x32_bf16 v[18:21], v[180:183], v[204:207], v[18:21]
	v_mfma_f32_16x16x32_bf16 v[6:9], v[166:169], v[212:215], v[6:9]
	v_mfma_f32_16x16x32_bf16 v[2:5], v[180:183], v[212:215], v[2:5]
	s_barrier
; #define PG8_STAGE(bufoff, gbase, voff) do { _Pragma("unroll") for (int _i = 0; _i < 2; ++_i) \
;         __builtin_amdgcn_global_load_lds((const unsigned*)((const char*)(gbase) + (voff)[_i]), (PG8_LAS unsigned*)(lds + (bufoff) + ldsw + _i * 8192), 16, 0, 0); } while (0)
; #define PG8_LDA(dst, b, h) do { _Pragma("unroll") for (int m = 0; m < 4; ++m) _Pragma("unroll") for (int k = 0; k < 2; ++k) dst[m][k] = *(const PG8_LAS bf16x8*)(lds + PG8_SA(b, h) + aoff + m * 2048 + k * 1024); } while (0)
; #define PG8_WAIT_V(n) asm volatile("s_waitcnt vmcnt(" #n ")" ::: "memory")
; #define PG8_WAIT_L(n) asm volatile("s_waitcnt lgkmcnt(" #n ")" ::: "memory")
; #define PG8_BAR __builtin_amdgcn_s_barrier()
; template <class Epi, class Sched, bool ALIGN_EPI = false, bool SP2 = false, bool I8 = false>
; __device__ __forceinline__ void gemm_phase(PG8_LAS unsigned char* lds, const Gemm g, const Sched& S, const Epi& E) {
;     ...
;         for (int t = 0; t < nt; t += 2) {
;             const bool last = (t == nt - 2);
;             const char* a1 = cA + (size_t)(t + 1) * kstep;
;             const char* a2 = last ? nA : cA + (size_t)(t + 2) * kstep; const char* b2 = last ? nB : cB + (size_t)(t + 2) * kstep;
;             const char* a3 = a2 + kstep; const char* b3 = b2 + kstep;
;             if (last && has_next) S.a_ready(nxt);
;             if constexpr (SP2) {
;             PG8_LDB(B0, 0, 0); PG8_LDB(B1, 0, 1); PG8_SCHED; PG8_LDA(At, 0, 0); PG8_STAGE(PG8_SA(1, 1), a1 + hstepA, voffA);
;             PG8_WAIT_V(8); PG8_WAIT_L(0); PG8_BAR; PG8_MMA(0, 0, At, B0); PG8_MMA(0, 1, At, B1); PG8_BAR; PG8_SCHED;
;             PG8_LDA(At, 0, 1); PG8_STAGE(PG8_SB(0, 0), b2, voffB); PG8_STAGE(PG8_SB(0, 1), b2 + hstepB, voffB); PG8_STAGE(PG8_SA(0, 0), a2, voffA);
;             PG8_WAIT_V(8); PG8_WAIT_L(0); PG8_BAR; PG8_MMA(1, 0, At, B0); PG8_MMA(1, 1, At, B1); PG8_BAR; PG8_SCHED;
;             PG8_LDB(B0, 1, 0); PG8_LDB(B1, 1, 1); PG8_SCHED; PG8_LDA(At, 1, 0); PG8_STAGE(PG8_SA(0, 1), a2 + hstepA, voffA);
;             PG8_WAIT_V(8); PG8_WAIT_L(0); PG8_BAR; PG8_MMA(0, 0, At, B0); PG8_MMA(0, 1, At, B1); PG8_BAR; PG8_SCHED;
;             PG8_LDA(At, 1, 1); PG8_STAGE(PG8_SB(1, 0), b3, voffB); PG8_STAGE(PG8_SB(1, 1), b3 + hstepB, voffB); PG8_STAGE(PG8_SA(1, 0), a3, voffA);
;             PG8_WAIT_V(8); PG8_WAIT_L(0); PG8_BAR; PG8_MMA(1, 0, At, B0); PG8_MMA(1, 1, At, B1); PG8_BAR; PG8_SCHED;
	s_add_i32 s55, 0, 0x18000
	s_add_i32 s56, 0, 0x1c000
	ds_read_b128 v[130:133], v177 offset:16384
	ds_read_b128 v[134:137], v177 offset:17408
	ds_read_b128 v[138:141], v177 offset:18432
	ds_read_b128 v[142:145], v177 offset:19456
	ds_read_b128 v[162:165], v177 offset:32768
	ds_read_b128 v[166:169], v177 offset:33792
	ds_read_b128 v[170:173], v177 offset:34816
	ds_read_b128 v[180:183], v177 offset:35840
	s_add_u32 s34, s34, 0x80000
	s_addc_u32 s35, s35, 0
	s_mov_b32 m0, s42
	ds_read_b128 v[184:187], v178 offset:32768
	ds_read_b128 v[188:191], v178 offset:33792
	ds_read_b128 v[192:195], v178 offset:34816
	ds_read_b128 v[196:199], v178 offset:35840
	ds_read_b128 v[200:203], v178 offset:36864
	ds_read_b128 v[204:207], v178 offset:37888
	ds_read_b128 v[208:211], v178 offset:38912
	ds_read_b128 v[212:215], v178 offset:39936
	global_load_lds_dwordx4 v146, s[34:35]
	s_mov_b32 m0, s43
	s_nop 0
	global_load_lds_dwordx4 v150, s[34:35]
	s_waitcnt vmcnt(8) lgkmcnt(0)
	s_barrier
	v_mfma_f32_16x16x32_bf16 v[126:129], v[130:133], v[184:187], v[126:129]
	v_mfma_f32_16x16x32_bf16 v[122:125], v[138:141], v[184:187], v[122:125]
	v_mfma_f32_16x16x32_bf16 v[110:113], v[130:133], v[192:195], v[110:113]
	v_mfma_f32_16x16x32_bf16 v[106:109], v[138:141], v[192:195], v[106:109]
	v_mfma_f32_16x16x32_bf16 v[94:97], v[130:133], v[200:203], v[94:97]
	v_mfma_f32_16x16x32_bf16 v[90:93], v[138:141], v[200:203], v[90:93]
	v_mfma_f32_16x16x32_bf16 v[78:81], v[130:133], v[208:211], v[78:81]
	v_mfma_f32_16x16x32_bf16 v[74:77], v[138:141], v[208:211], v[74:77]
	v_mfma_f32_16x16x32_bf16 v[126:129], v[134:137], v[188:191], v[126:129]
	v_mfma_f32_16x16x32_bf16 v[122:125], v[142:145], v[188:191], v[122:125]
	v_mfma_f32_16x16x32_bf16 v[110:113], v[134:137], v[196:199], v[110:113]
	v_mfma_f32_16x16x32_bf16 v[106:109], v[142:145], v[196:199], v[106:109]
	v_mfma_f32_16x16x32_bf16 v[94:97], v[134:137], v[204:207], v[94:97]
	v_mfma_f32_16x16x32_bf16 v[90:93], v[142:145], v[204:207], v[90:93]
	v_mfma_f32_16x16x32_bf16 v[78:81], v[134:137], v[212:215], v[78:81]
	v_mfma_f32_16x16x32_bf16 v[74:77], v[142:145], v[212:215], v[74:77]
	v_mfma_f32_16x16x32_bf16 v[118:121], v[162:165], v[184:187], v[118:121]
	v_mfma_f32_16x16x32_bf16 v[114:117], v[170:173], v[184:187], v[114:117]
	v_mfma_f32_16x16x32_bf16 v[102:105], v[162:165], v[192:195], v[102:105]
	v_mfma_f32_16x16x32_bf16 v[98:101], v[170:173], v[192:195], v[98:101]
	v_mfma_f32_16x16x32_bf16 v[86:89], v[162:165], v[200:203], v[86:89]
	v_mfma_f32_16x16x32_bf16 v[82:85], v[170:173], v[200:203], v[82:85]
	v_mfma_f32_16x16x32_bf16 v[70:73], v[162:165], v[208:211], v[70:73]
	v_mfma_f32_16x16x32_bf16 v[66:69], v[170:173], v[208:211], v[66:69]
	v_mfma_f32_16x16x32_bf16 v[118:121], v[166:169], v[188:191], v[118:121]
	v_mfma_f32_16x16x32_bf16 v[114:117], v[180:183], v[188:191], v[114:117]
	v_mfma_f32_16x16x32_bf16 v[102:105], v[166:169], v[196:199], v[102:105]
	v_mfma_f32_16x16x32_bf16 v[98:101], v[180:183], v[196:199], v[98:101]
	v_mfma_f32_16x16x32_bf16 v[86:89], v[166:169], v[204:207], v[86:89]
	v_mfma_f32_16x16x32_bf16 v[82:85], v[180:183], v[204:207], v[82:85]
	v_mfma_f32_16x16x32_bf16 v[70:73], v[166:169], v[212:215], v[70:73]
	v_mfma_f32_16x16x32_bf16 v[66:69], v[180:183], v[212:215], v[66:69]
	s_barrier
	s_add_i32 s34, s55, s39
	s_add_i32 m0, s34, 0xffffff80
	ds_read_b128 v[184:187], v178 offset:49152
	ds_read_b128 v[188:191], v178 offset:50176
	ds_read_b128 v[192:195], v178 offset:51200
	ds_read_b128 v[196:199], v178 offset:52224
	ds_read_b128 v[200:203], v178 offset:53248
	ds_read_b128 v[204:207], v178 offset:54272
	ds_read_b128 v[208:211], v178 offset:55296
	ds_read_b128 v[212:215], v178 offset:56320
	global_load_lds_dwordx4 v148, s[98:99] offset:128
	s_add_i32 m0, s34, 0x1f80
	s_add_u32 s30, s30, 0x80080
	s_addc_u32 s31, s31, 0
	s_add_i32 s34, s56, s39
	global_load_lds_dwordx4 v152, s[98:99] offset:128
	s_mov_b32 m0, s34
	s_nop 0
	global_load_lds_dwordx4 v148, s[30:31]
	s_add_i32 m0, s34, 0x2000
	s_nop 0
	global_load_lds_dwordx4 v152, s[30:31]
	s_add_i32 m0, s46, 0xffffff80
	s_nop 0
	global_load_lds_dwordx4 v146, s[100:101] offset:128
	s_add_i32 m0, s47, 0xffffff80
	s_nop 0
	global_load_lds_dwordx4 v150, s[100:101] offset:128
	s_waitcnt vmcnt(8) lgkmcnt(0)
	s_barrier
	v_mfma_f32_16x16x32_bf16 v[62:65], v[130:133], v[184:187], v[62:65]
	v_mfma_f32_16x16x32_bf16 v[58:61], v[138:141], v[184:187], v[58:61]
	v_mfma_f32_16x16x32_bf16 v[46:49], v[130:133], v[192:195], v[46:49]
	v_mfma_f32_16x16x32_bf16 v[42:45], v[138:141], v[192:195], v[42:45]
	v_mfma_f32_16x16x32_bf16 v[30:33], v[130:133], v[200:203], v[30:33]
	v_mfma_f32_16x16x32_bf16 v[26:29], v[138:141], v[200:203], v[26:29]
	v_mfma_f32_16x16x32_bf16 v[14:17], v[130:133], v[208:211], v[14:17]
	v_mfma_f32_16x16x32_bf16 v[10:13], v[138:141], v[208:211], v[10:13]
	v_mfma_f32_16x16x32_bf16 v[62:65], v[134:137], v[188:191], v[62:65]
	v_mfma_f32_16x16x32_bf16 v[58:61], v[142:145], v[188:191], v[58:61]
	v_mfma_f32_16x16x32_bf16 v[46:49], v[134:137], v[196:199], v[46:49]
	v_mfma_f32_16x16x32_bf16 v[42:45], v[142:145], v[196:199], v[42:45]
	v_mfma_f32_16x16x32_bf16 v[30:33], v[134:137], v[204:207], v[30:33]
	v_mfma_f32_16x16x32_bf16 v[26:29], v[142:145], v[204:207], v[26:29]
	v_mfma_f32_16x16x32_bf16 v[14:17], v[134:137], v[212:215], v[14:17]
	v_mfma_f32_16x16x32_bf16 v[10:13], v[142:145], v[212:215], v[10:13]
	v_mfma_f32_16x16x32_bf16 v[54:57], v[162:165], v[184:187], v[54:57]
	v_mfma_f32_16x16x32_bf16 v[50:53], v[170:173], v[184:187], v[50:53]
	v_mfma_f32_16x16x32_bf16 v[38:41], v[162:165], v[192:195], v[38:41]
	v_mfma_f32_16x16x32_bf16 v[34:37], v[170:173], v[192:195], v[34:37]
	v_mfma_f32_16x16x32_bf16 v[22:25], v[162:165], v[200:203], v[22:25]
	v_mfma_f32_16x16x32_bf16 v[18:21], v[170:173], v[200:203], v[18:21]
	v_mfma_f32_16x16x32_bf16 v[6:9], v[162:165], v[208:211], v[6:9]
	v_mfma_f32_16x16x32_bf16 v[2:5], v[170:173], v[208:211], v[2:5]
	v_mfma_f32_16x16x32_bf16 v[54:57], v[166:169], v[188:191], v[54:57]
	v_mfma_f32_16x16x32_bf16 v[50:53], v[180:183], v[188:191], v[50:53]
	v_mfma_f32_16x16x32_bf16 v[38:41], v[166:169], v[196:199], v[38:41]
	v_mfma_f32_16x16x32_bf16 v[34:37], v[180:183], v[196:199], v[34:37]
	v_mfma_f32_16x16x32_bf16 v[22:25], v[166:169], v[204:207], v[22:25]
	v_mfma_f32_16x16x32_bf16 v[18:21], v[180:183], v[204:207], v[18:21]
	v_mfma_f32_16x16x32_bf16 v[6:9], v[166:169], v[212:215], v[6:9]
	v_mfma_f32_16x16x32_bf16 v[2:5], v[180:183], v[212:215], v[2:5]
	s_barrier
	s_add_i32 s54, s54, 2
	s_add_u32 s28, s28, 0x100
	s_addc_u32 s29, s29, 0
	s_add_u32 s52, s52, 0x100
	s_addc_u32 s53, s53, 0
	s_cmp_gt_u32 s54, 29
	s_cbranch_scc0 .LBB0_1565
	s_and_b64 vcc, exec, s[16:17]
	s_cbranch_vccz .LBB0_1568
	s_barrier
;     __device__ __forceinline__ void load_row(RowIn& R, int r, int col0) const {
; #pragma unroll
;         for (int bj = 0; bj < 2; ++bj) {
;             if (MODE == 2) R.g[bj] = *(const u32x4*)(GT + (size_t)r * 8192 + col0 + bj * HALF);
;             if (MODE == 3) { R.g[bj] = *(const u32x4*)(GT + (size_t)r * 8192 + 4096 + col0 + bj * HALF); R.a[bj] = *(const u32x4*)(AD + (size_t)r * 4096 + col0 + bj * HALF); } }
;     }
;     __device__ __forceinline__ void operator()(AccRef acc, const Unit& u, int wr, int wc, int fr, int fq) const {
;         const int row0 = u.pm * BM + wr * 64 + fr, col0 = u.pn * BM + wc * 32 + 8 * fq;
;         RowIn cur, nxt;
;         if (MODE >= 2) load_row(cur, row0, col0);
; #pragma unroll
;         for (int s = 0; s < 8; ++s) { const int ai = s >> 2, m = s & 3; const int r = row0 + ai * HALF + m * 16; bf16_t* rowp = O + (size_t)r * ldc + col0;
;                 if (MODE >= 2 && s + 1 < 8) load_row(nxt, row0 + ((s + 1) >> 2) * HALF + ((s + 1) & 3) * 16, col0);
;                 float rs = 1.f; if (MODE == 1) rs = __builtin_amdgcn_rsqf(rstd[r] * (1.0f / 4096.0f) + 1e-6f);
;                 float mx = 0.f;
; #pragma unroll
;                 for (int bj = 0; bj < 2; ++bj) { f32x4 v0 = acc[ai][bj][m][0], v1 = acc[ai][bj][m][1];
;                     if (MODE == 1) { v0 = v0 * rs; v1 = v1 * rs;
; #pragma unroll
;                         for (int j = 0; j < 4; ++j) { const float a = v0[j] > 0.f ? v0[j] : 0.f, b = v1[j] > 0.f ? v1[j] : 0.f; v0[j] = a * a; v1[j] = b * b; } }
;                     if (MODE == 2) { f32x4 g0, g1; unpack8(cur.g[bj], g0, g1); v0 = v0 * g0; v1 = v1 * g1; }
;                     if (MODE == 3) { f32x4 g0, g1, a0, a1; unpack8(cur.g[bj], g0, g1); unpack8(cur.a[bj], a0, a1);
;                         v0 = a0 + v0 * g0; v1 = a1 + v1 * g1;
; #pragma unroll
;                         for (int j = 0; j < 4; ++j) mx = fmaxf(mx, fmaxf(fabsf(v0[j]), fabsf(v1[j]))); }
;                     *(u32x4*)(rowp + bj * HALF) = pack8(v0, v1); }
;                 if (MODE == 3) { mx = fmaxf(mx, __shfl_xor(mx, 16)); mx = fmaxf(mx, __shfl_xor(mx, 32)); if (fq == 0) atomicMax(RM + r, __builtin_bit_cast(unsigned, mx)); }
;                 if (MODE >= 2) cur = nxt; }
.LBB0_1568:
	s_lshl_b32 s98, s26, 5
	s_add_i32 s98, s98, s6
	s_add_i32 s98, s98, 16
	s_lshl_b32 s98, s98, 17
	v_and_b32_e32 v248, 63, v0
	v_lshlrev_b32_e32 v248, 4, v248
	v_lshrrev_b32_e32 v249, 6, v0
	v_lshl_add_u32 v248, v249, 14, v248
	v_add_u32_e32 v248, s98, v248
	v_mov_b32_e32 v249, 0
	v_lshl_add_u64 v[248:249], s[8:9], 0, v[248:249]
	s_lshl_b32 s98, s26, 4
	s_add_i32 s98, s98, s6
	s_lshl_b32 s98, s98, 17
	v_and_b32_e32 v250, 63, v0
	v_lshlrev_b32_e32 v250, 4, v250
	v_lshrrev_b32_e32 v251, 6, v0
	v_lshl_add_u32 v250, v251, 14, v250
	v_add_u32_e32 v250, s98, v250
	v_mov_b32_e32 v251, 0
	v_lshl_add_u64 v[250:251], s[10:11], 0, v[250:251]
	v_mov_b32_e32 v130, v0
	s_nop 0
	v_ashrrev_i32_e32 v131, 2, v130
	v_and_b32_e32 v131, 0xffffffc0, v131
	v_lshl_add_u32 v131, s26, 8, v131
	v_bfe_u32 v174, v130, 4, 2
	v_and_or_b32 v166, v130, 15, v131
	v_lshrrev_b32_e32 v130, 1, v130
	v_and_b32_e32 v130, 0x60, v130
	v_lshl_or_b32 v130, s6, 8, v130
	v_lshl_or_b32 v162, v174, 3, v130
	v_ashrrev_i32_e32 v167, 31, v166
	v_ashrrev_i32_e32 v163, 31, v162
	v_lshlrev_b64 v[170:171], 13, v[166:167]
	v_lshlrev_b64 v[164:165], 1, v[162:163]
	v_lshl_add_u64 v[130:131], s[10:11], 0, v[170:171]
	v_lshl_add_u64 v[130:131], v[130:131], 0, v[164:165]
	s_mov_b64 s[98:99], 0x0
	v_lshl_add_u64 v[252:253], v[250:251], 0, s[98:99]
	global_load_dwordx4 v[180:183], v[252:253], off
	global_load_dwordx4 v[184:187], v[252:253], off offset:1024
	v_lshlrev_b64 v[130:131], 14, v[166:167]
	v_lshl_add_u64 v[130:131], s[8:9], 0, v[130:131]
	v_lshl_add_u64 v[130:131], v[130:131], 0, v[164:165]
	v_add_co_u32_e32 v130, vcc, s44, v130
	v_or_b32_e32 v168, 16, v166
	s_nop 0
	v_addc_co_u32_e32 v131, vcc, 0, v131, vcc
	s_mov_b64 s[98:99], 0x0
	v_lshl_add_u64 v[246:247], v[248:249], 0, s[98:99]
	global_load_dwordx4 v[188:191], v[246:247], off
	global_load_dwordx4 v[192:195], v[246:247], off offset:1024
	v_ashrrev_i32_e32 v169, 31, v168
	v_lshlrev_b64 v[130:131], 14, v[168:169]
	v_lshl_add_u64 v[130:131], s[8:9], 0, v[130:131]
	v_lshlrev_b64 v[172:173], 13, v[168:169]
	v_lshl_add_u64 v[130:131], v[130:131], 0, v[164:165]
	v_lshl_add_u64 v[132:133], s[10:11], 0, v[172:173]
	v_add_co_u32_e32 v134, vcc, s44, v130
	v_lshl_add_u64 v[132:133], v[132:133], 0, v[164:165]
	s_nop 0
	v_addc_co_u32_e32 v135, vcc, 0, v131, vcc
	s_mov_b64 s[98:99], 0x800
	v_lshl_add_u64 v[252:253], v[250:251], 0, s[98:99]
	global_load_dwordx4 v[138:141], v[252:253], off
	s_nop 0
	global_load_dwordx4 v[130:133], v[252:253], off offset:1024
	s_nop 0
	s_mov_b64 s[98:99], 0x800
	v_lshl_add_u64 v[246:247], v[248:249], 0, s[98:99]
	global_load_dwordx4 v[142:145], v[246:247], off
	s_nop 0
	global_load_dwordx4 v[134:137], v[246:247], off offset:1024
	v_cmp_eq_u32_e64 s[6:7], 0, v174
	v_lshl_add_u64 v[170:171], s[2:3], 0, v[170:171]
	v_lshl_add_u64 v[170:171], v[170:171], 0, v[164:165]
	s_waitcnt vmcnt(0)
	v_lshlrev_b32_e32 v174, 16, v180
	v_and_b32_e32 v175, 0xffff0000, v180
	v_lshlrev_b32_e32 v196, 16, v182
	v_and_b32_e32 v197, 0xffff0000, v182
	v_lshlrev_b32_e32 v180, 16, v181
	v_and_b32_e32 v181, 0xffff0000, v181
	v_lshlrev_b32_e32 v182, 16, v183
	v_and_b32_e32 v183, 0xffff0000, v183
	v_lshlrev_b32_e32 v200, 16, v186
	v_lshlrev_b32_e32 v202, 16, v188
	v_and_b32_e32 v203, 0xffff0000, v188
	v_lshlrev_b32_e32 v204, 16, v190
	v_and_b32_e32 v205, 0xffff0000, v190
	v_and_b32_e32 v201, 0xffff0000, v186
	v_lshlrev_b32_e32 v186, 16, v187
	v_and_b32_e32 v187, 0xffff0000, v187
	v_lshlrev_b32_e32 v188, 16, v189
	v_and_b32_e32 v189, 0xffff0000, v189
	v_lshlrev_b32_e32 v190, 16, v191
	v_and_b32_e32 v191, 0xffff0000, v191
	v_lshlrev_b32_e32 v208, 16, v194
	v_and_b32_e32 v209, 0xffff0000, v194
	v_lshlrev_b32_e32 v194, 16, v195
	v_and_b32_e32 v195, 0xffff0000, v195
	v_pk_fma_f32 v[126:127], v[126:127], v[202:203], v[174:175]
	v_pk_fma_f32 v[122:123], v[122:123], v[204:205], v[196:197]
	v_lshlrev_b32_e32 v198, 16, v184
	v_and_b32_e32 v199, 0xffff0000, v184
	v_lshlrev_b32_e32 v206, 16, v192
	v_and_b32_e32 v207, 0xffff0000, v192
	v_pk_fma_f32 v[128:129], v[128:129], v[188:189], v[180:181]
	v_pk_fma_f32 v[124:125], v[124:125], v[190:191], v[182:183]
	v_pk_fma_f32 v[174:175], v[116:117], v[194:195], v[186:187]
	v_max_f32_e64 v116, |v126|, |v122|
	v_max_f32_e64 v117, |v127|, |v123|
	v_lshlrev_b32_e32 v184, 16, v185
	v_and_b32_e32 v185, 0xffff0000, v185
	v_lshlrev_b32_e32 v192, 16, v193
	v_and_b32_e32 v193, 0xffff0000, v193
	v_pk_fma_f32 v[118:119], v[118:119], v[206:207], v[198:199]
	v_pk_fma_f32 v[182:183], v[114:115], v[208:209], v[200:201]
	v_max_f32_e64 v180, |v128|, |v124|
	v_max_f32_e64 v181, |v129|, |v125|
	v_max3_f32 v116, v116, 0, v117
	v_pk_fma_f32 v[120:121], v[120:121], v[192:193], v[184:185]
	v_cvt_pk_bf16_f32 v114, v126, v127
	v_max_f32_e64 v126, |v118|, |v182|
	v_max3_f32 v116, v116, v180, v181
	v_max_f32_e64 v117, |v119|, |v183|
	v_max3_f32 v116, v116, v126, v117
	v_max_f32_e64 v117, |v120|, |v174|
	v_max_f32_e64 v126, |v121|, |v175|
	v_max3_f32 v126, v116, v117, v126
	v_and_b32_e32 v117, 64, v179
	v_xor_b32_e32 v116, 16, v179
	v_add_u32_e32 v127, 64, v117
	v_cmp_lt_i32_e32 vcc, v116, v127
	v_cvt_pk_bf16_f32 v115, v128, v129
	s_nop 1
	v_cndmask_b32_e32 v116, v179, v116, vcc
	v_lshlrev_b32_e32 v180, 2, v116
	ds_bpermute_b32 v128, v180, v126
	v_cvt_pk_bf16_f32 v116, v122, v123
	v_cvt_pk_bf16_f32 v117, v124, v125
	global_store_dwordx4 v[170:171], v[114:117], off
	s_nop 1
	v_xor_b32_e32 v115, 32, v179
	v_cmp_lt_i32_e32 vcc, v115, v127
	s_waitcnt lgkmcnt(0)
	v_max_f32_e32 v114, v128, v128
	v_max_f32_e32 v114, v126, v114
	v_cndmask_b32_e32 v115, v179, v115, vcc
	v_lshlrev_b32_e32 v181, 2, v115
	ds_bpermute_b32 v115, v181, v114
	v_cvt_pk_bf16_f32 v116, v118, v119
	v_cvt_pk_bf16_f32 v117, v120, v121
	v_cvt_pk_bf16_f32 v118, v182, v183
	v_cvt_pk_bf16_f32 v119, v174, v175
	global_store_dwordx4 v[170:171], v[116:119], off offset:256
	s_and_saveexec_b64 s[26:27], s[6:7]
	s_cbranch_execz .LBB0_1570
	s_waitcnt lgkmcnt(0)
	v_max_f32_e32 v115, v115, v115
	v_max_f32_e32 v114, v114, v114
	v_lshl_add_u64 v[116:117], v[166:167], 2, s[12:13]
	v_max_f32_e32 v114, v114, v115
	global_atomic_umax v[116:117], v114, off
; __device__ __forceinline__ u32x4 pack8(const f32x4 v0, const f32x4 v1) { u32x4 w; w.x = cvt_pk_bf16(v0[0], v0[1]); w.y = cvt_pk_bf16(v0[2], v0[3]); w.z = cvt_pk_bf16(v1[0], v1[1]); w.w = cvt_pk_bf16(v1[2], v1[3]); return w; }
; __device__ __forceinline__ void unpack8(const u32x4 w, f32x4& v0, f32x4& v1) { v0 = (f32x4){bf_lo(w.x), bf_hi(w.x), bf_lo(w.y), bf_hi(w.y)}; v1 = (f32x4){bf_lo(w.z), bf_hi(w.z), bf_lo(w.w), bf_hi(w.w)}; }
;     __device__ __forceinline__ void operator()(AccRef acc, const Unit& u, int wr, int wc, int fr, int fq) const {
;     ...
;         for (int s = 0; s < 8; ++s) { const int ai = s >> 2, m = s & 3; const int r = row0 + ai * HALF + m * 16; bf16_t* rowp = O + (size_t)r * ldc + col0;
;                 if (MODE >= 2 && s + 1 < 8) load_row(nxt, row0 + ((s + 1) >> 2) * HALF + ((s + 1) & 3) * 16, col0);
;                 float rs = 1.f; if (MODE == 1) rs = __builtin_amdgcn_rsqf(rstd[r] * (1.0f / 4096.0f) + 1e-6f);
;                 float mx = 0.f;
; #pragma unroll
;                 for (int bj = 0; bj < 2; ++bj) { f32x4 v0 = acc[ai][bj][m][0], v1 = acc[ai][bj][m][1];
;                     if (MODE == 1) { v0 = v0 * rs; v1 = v1 * rs;
; #pragma unroll
;                         for (int j = 0; j < 4; ++j) { const float a = v0[j] > 0.f ? v0[j] : 0.f, b = v1[j] > 0.f ? v1[j] : 0.f; v0[j] = a * a; v1[j] = b * b; } }
;                     if (MODE == 2) { f32x4 g0, g1; unpack8(cur.g[bj], g0, g1); v0 = v0 * g0; v1 = v1 * g1; }
;                     if (MODE == 3) { f32x4 g0, g1, a0, a1; unpack8(cur.g[bj], g0, g1); unpack8(cur.a[bj], a0, a1);
;                         v0 = a0 + v0 * g0; v1 = a1 + v1 * g1;
; #pragma unroll
;                         for (int j = 0; j < 4; ++j) mx = fmaxf(mx, fmaxf(fabsf(v0[j]), fabsf(v1[j]))); }
;                     *(u32x4*)(rowp + bj * HALF) = pack8(v0, v1); }
;                 if (MODE == 3) { mx = fmaxf(mx, __shfl_xor(mx, 16)); mx = fmaxf(mx, __shfl_xor(mx, 32)); if (fq == 0) atomicMax(RM + r, __builtin_bit_cast(unsigned, mx)); }
;                 if (MODE >= 2) cur = nxt; }
.LBB0_1570:
	s_or_b64 exec, exec, s[26:27]
	v_or_b32_e32 v170, 32, v166
	v_ashrrev_i32_e32 v171, 31, v170
	s_waitcnt lgkmcnt(0)
	v_lshlrev_b64 v[114:115], 14, v[170:171]
	v_lshl_add_u64 v[114:115], s[8:9], 0, v[114:115]
	v_lshlrev_b64 v[174:175], 13, v[170:171]
	v_lshl_add_u64 v[114:115], v[114:115], 0, v[164:165]
	v_add_co_u32_e32 v114, vcc, 0x2000, v114
	v_lshl_add_u64 v[116:117], s[10:11], 0, v[174:175]
	s_nop 0
	v_addc_co_u32_e32 v115, vcc, 0, v115, vcc
	v_lshl_add_u64 v[116:117], v[116:117], 0, v[164:165]
	s_mov_b64 s[98:99], 0x1000
	v_lshl_add_u64 v[246:247], v[248:249], 0, s[98:99]
	global_load_dwordx4 v[126:129], v[246:247], off
	global_load_dwordx4 v[118:121], v[246:247], off offset:1024
	s_mov_b64 s[98:99], 0x1000
	v_lshl_add_u64 v[252:253], v[250:251], 0, s[98:99]
	global_load_dwordx4 v[122:125], v[252:253], off
	s_nop 0
	global_load_dwordx4 v[114:117], v[252:253], off offset:1024
	v_lshlrev_b32_e32 v182, 16, v142
	v_and_b32_e32 v183, 0xffff0000, v142
	v_lshlrev_b32_e32 v142, 16, v143
	v_and_b32_e32 v143, 0xffff0000, v143
	v_lshlrev_b32_e32 v184, 16, v144
	v_and_b32_e32 v185, 0xffff0000, v144
	v_lshlrev_b32_e32 v144, 16, v145
	v_and_b32_e32 v145, 0xffff0000, v145
	v_lshlrev_b32_e32 v186, 16, v138
	v_and_b32_e32 v187, 0xffff0000, v138
	v_lshlrev_b32_e32 v138, 16, v139
	v_and_b32_e32 v139, 0xffff0000, v139
	v_lshlrev_b32_e32 v188, 16, v140
	v_and_b32_e32 v189, 0xffff0000, v140
	v_lshlrev_b32_e32 v140, 16, v141
	v_and_b32_e32 v141, 0xffff0000, v141
	v_pk_fma_f32 v[112:113], v[112:113], v[142:143], v[138:139]
	v_pk_fma_f32 v[110:111], v[110:111], v[182:183], v[186:187]
	v_pk_fma_f32 v[138:139], v[108:109], v[144:145], v[140:141]
	v_pk_fma_f32 v[108:109], v[106:107], v[184:185], v[188:189]
	v_max_f32_e64 v140, |v113|, |v139|
	v_max_f32_e64 v106, |v110|, |v108|
	v_max_f32_e64 v107, |v111|, |v109|
	v_max3_f32 v106, v106, 0, v107
	v_max_f32_e64 v107, |v112|, |v138|
	v_max3_f32 v144, v106, v107, v140
	v_cvt_pk_bf16_f32 v106, v110, v111
	v_cvt_pk_bf16_f32 v107, v112, v113
	v_lshlrev_b32_e32 v110, 16, v134
	v_and_b32_e32 v111, 0xffff0000, v134
	v_lshlrev_b32_e32 v112, 16, v135
	v_and_b32_e32 v113, 0xffff0000, v135
	v_lshlrev_b32_e32 v134, 16, v136
	v_and_b32_e32 v135, 0xffff0000, v136
	v_lshlrev_b32_e32 v140, 16, v130
	v_and_b32_e32 v141, 0xffff0000, v130
	v_lshlrev_b32_e32 v130, 16, v131
	v_and_b32_e32 v131, 0xffff0000, v131
	v_lshlrev_b32_e32 v142, 16, v132
	v_and_b32_e32 v143, 0xffff0000, v132
	v_lshlrev_b32_e32 v136, 16, v137
	v_and_b32_e32 v137, 0xffff0000, v137
	v_lshlrev_b32_e32 v132, 16, v133
	v_and_b32_e32 v133, 0xffff0000, v133
	v_pk_fma_f32 v[104:105], v[104:105], v[112:113], v[130:131]
	v_pk_fma_f32 v[102:103], v[102:103], v[110:111], v[140:141]
	v_pk_fma_f32 v[112:113], v[98:99], v[134:135], v[142:143]
	v_pk_fma_f32 v[110:111], v[100:101], v[136:137], v[132:133]
	v_max_f32_e64 v98, |v102|, |v112|
	v_max_f32_e64 v99, |v103|, |v113|
	v_max3_f32 v98, v144, v98, v99
	v_max_f32_e64 v99, |v104|, |v110|
	v_max_f32_e64 v100, |v105|, |v111|
	v_max3_f32 v98, v98, v99, v100
	ds_bpermute_b32 v99, v180, v98
	v_lshl_add_u64 v[172:173], s[2:3], 0, v[172:173]
	v_lshl_add_u64 v[172:173], v[172:173], 0, v[164:165]
	v_cvt_pk_bf16_f32 v108, v108, v109
	v_cvt_pk_bf16_f32 v109, v138, v139
	s_waitcnt lgkmcnt(0)
	v_max_f32_e32 v99, v99, v99
	v_max_f32_e32 v98, v98, v99
	ds_bpermute_b32 v99, v181, v98
	global_store_dwordx4 v[172:173], v[106:109], off
	v_cvt_pk_bf16_f32 v100, v102, v103
	v_cvt_pk_bf16_f32 v101, v104, v105
	v_cvt_pk_bf16_f32 v102, v112, v113
	v_cvt_pk_bf16_f32 v103, v110, v111
	global_store_dwordx4 v[172:173], v[100:103], off offset:256
	s_and_saveexec_b64 s[26:27], s[6:7]
	s_cbranch_execz .LBB0_1572
	s_waitcnt lgkmcnt(0)
	v_max_f32_e32 v99, v99, v99
	v_max_f32_e32 v98, v98, v98
	v_lshl_add_u64 v[100:101], v[168:169], 2, s[12:13]
	v_max_f32_e32 v98, v98, v99
	global_atomic_umax v[100:101], v98, off
.LBB0_1572:
	s_or_b64 exec, exec, s[26:27]
	v_or_b32_e32 v130, 48, v166
	v_ashrrev_i32_e32 v131, 31, v130
	s_waitcnt lgkmcnt(0)
	v_lshlrev_b64 v[98:99], 14, v[130:131]
	v_lshl_add_u64 v[98:99], s[8:9], 0, v[98:99]
	v_lshlrev_b64 v[132:133], 13, v[130:131]
	v_lshl_add_u64 v[98:99], v[98:99], 0, v[164:165]
	v_add_co_u32_e32 v98, vcc, 0x2000, v98
	v_lshl_add_u64 v[100:101], s[10:11], 0, v[132:133]
	s_nop 0
	v_addc_co_u32_e32 v99, vcc, 0, v99, vcc
	v_lshl_add_u64 v[100:101], v[100:101], 0, v[164:165]
	s_mov_b64 s[98:99], 0x1800
	v_lshl_add_u64 v[246:247], v[248:249], 0, s[98:99]
	global_load_dwordx4 v[110:113], v[246:247], off
	global_load_dwordx4 v[102:105], v[246:247], off offset:1024
	s_mov_b64 s[98:99], 0x1800
	v_lshl_add_u64 v[252:253], v[250:251], 0, s[98:99]
	global_load_dwordx4 v[106:109], v[252:253], off
	s_nop 0
	global_load_dwordx4 v[98:101], v[252:253], off offset:1024
	s_waitcnt vmcnt(9)
	v_lshlrev_b32_e32 v136, 16, v126
	v_and_b32_e32 v137, 0xffff0000, v126
	v_lshlrev_b32_e32 v126, 16, v127
	v_and_b32_e32 v127, 0xffff0000, v127
	v_lshlrev_b32_e32 v138, 16, v128
	v_and_b32_e32 v139, 0xffff0000, v128
	v_lshlrev_b32_e32 v128, 16, v129
	v_and_b32_e32 v129, 0xffff0000, v129
	s_waitcnt vmcnt(7)
	v_lshlrev_b32_e32 v140, 16, v122
	v_and_b32_e32 v141, 0xffff0000, v122
	v_lshlrev_b32_e32 v122, 16, v123
	v_and_b32_e32 v123, 0xffff0000, v123
	v_lshlrev_b32_e32 v142, 16, v124
	v_and_b32_e32 v143, 0xffff0000, v124
	v_lshlrev_b32_e32 v124, 16, v125
	v_and_b32_e32 v125, 0xffff0000, v125
	v_pk_fma_f32 v[96:97], v[96:97], v[126:127], v[122:123]
	v_pk_fma_f32 v[94:95], v[94:95], v[136:137], v[140:141]
	v_pk_fma_f32 v[122:123], v[92:93], v[128:129], v[124:125]
	v_pk_fma_f32 v[92:93], v[90:91], v[138:139], v[142:143]
	v_max_f32_e64 v124, |v97|, |v123|
	v_max_f32_e64 v90, |v94|, |v92|
	v_max_f32_e64 v91, |v95|, |v93|
	v_max3_f32 v90, v90, 0, v91
	v_max_f32_e64 v91, |v96|, |v122|
	v_max3_f32 v128, v90, v91, v124
	v_cvt_pk_bf16_f32 v90, v94, v95
	v_cvt_pk_bf16_f32 v91, v96, v97
	v_lshlrev_b32_e32 v94, 16, v118
	v_and_b32_e32 v95, 0xffff0000, v118
	v_lshlrev_b32_e32 v96, 16, v119
	v_and_b32_e32 v97, 0xffff0000, v119
	v_lshlrev_b32_e32 v118, 16, v120
	v_and_b32_e32 v119, 0xffff0000, v120
	s_waitcnt vmcnt(6)
; __device__ __forceinline__ u32x4 pack8(const f32x4 v0, const f32x4 v1) { u32x4 w; w.x = cvt_pk_bf16(v0[0], v0[1]); w.y = cvt_pk_bf16(v0[2], v0[3]); w.z = cvt_pk_bf16(v1[0], v1[1]); w.w = cvt_pk_bf16(v1[2], v1[3]); return w; }
; __device__ __forceinline__ void unpack8(const u32x4 w, f32x4& v0, f32x4& v1) { v0 = (f32x4){bf_lo(w.x), bf_hi(w.x), bf_lo(w.y), bf_hi(w.y)}; v1 = (f32x4){bf_lo(w.z), bf_hi(w.z), bf_lo(w.w), bf_hi(w.w)}; }
;     __device__ __forceinline__ void operator()(AccRef acc, const Unit& u, int wr, int wc, int fr, int fq) const {
;     ...
;         for (int s = 0; s < 8; ++s) { const int ai = s >> 2, m = s & 3; const int r = row0 + ai * HALF + m * 16; bf16_t* rowp = O + (size_t)r * ldc + col0;
;                 if (MODE >= 2 && s + 1 < 8) load_row(nxt, row0 + ((s + 1) >> 2) * HALF + ((s + 1) & 3) * 16, col0);
;                 float rs = 1.f; if (MODE == 1) rs = __builtin_amdgcn_rsqf(rstd[r] * (1.0f / 4096.0f) + 1e-6f);
;                 float mx = 0.f;
; #pragma unroll
;                 for (int bj = 0; bj < 2; ++bj) { f32x4 v0 = acc[ai][bj][m][0], v1 = acc[ai][bj][m][1];
;                     if (MODE == 1) { v0 = v0 * rs; v1 = v1 * rs;
; #pragma unroll
;                         for (int j = 0; j < 4; ++j) { const float a = v0[j] > 0.f ? v0[j] : 0.f, b = v1[j] > 0.f ? v1[j] : 0.f; v0[j] = a * a; v1[j] = b * b; } }
;                     if (MODE == 2) { f32x4 g0, g1; unpack8(cur.g[bj], g0, g1); v0 = v0 * g0; v1 = v1 * g1; }
;                     if (MODE == 3) { f32x4 g0, g1, a0, a1; unpack8(cur.g[bj], g0, g1); unpack8(cur.a[bj], a0, a1);
;                         v0 = a0 + v0 * g0; v1 = a1 + v1 * g1;
; #pragma unroll
;                         for (int j = 0; j < 4; ++j) mx = fmaxf(mx, fmaxf(fabsf(v0[j]), fabsf(v1[j]))); }
;                     *(u32x4*)(rowp + bj * HALF) = pack8(v0, v1); }
;                 if (MODE == 3) { mx = fmaxf(mx, __shfl_xor(mx, 16)); mx = fmaxf(mx, __shfl_xor(mx, 32)); if (fq == 0) atomicMax(RM + r, __builtin_bit_cast(unsigned, mx)); }
;                 if (MODE >= 2) cur = nxt; }
	v_lshlrev_b32_e32 v124, 16, v114
	v_and_b32_e32 v125, 0xffff0000, v114
	v_lshlrev_b32_e32 v114, 16, v115
	v_and_b32_e32 v115, 0xffff0000, v115
	v_lshlrev_b32_e32 v126, 16, v116
	v_and_b32_e32 v127, 0xffff0000, v116
	v_lshlrev_b32_e32 v120, 16, v121
	v_and_b32_e32 v121, 0xffff0000, v121
	v_lshlrev_b32_e32 v116, 16, v117
	v_and_b32_e32 v117, 0xffff0000, v117
	v_pk_fma_f32 v[88:89], v[88:89], v[96:97], v[114:115]
	v_pk_fma_f32 v[86:87], v[86:87], v[94:95], v[124:125]
	v_pk_fma_f32 v[96:97], v[82:83], v[118:119], v[126:127]
	v_pk_fma_f32 v[94:95], v[84:85], v[120:121], v[116:117]
	v_max_f32_e64 v82, |v86|, |v96|
	v_max_f32_e64 v83, |v87|, |v97|
	v_max3_f32 v82, v128, v82, v83
	v_max_f32_e64 v83, |v88|, |v94|
	v_max_f32_e64 v84, |v89|, |v95|
	v_max3_f32 v82, v82, v83, v84
	ds_bpermute_b32 v83, v180, v82
	v_lshl_add_u64 v[134:135], s[2:3], 0, v[174:175]
	v_lshl_add_u64 v[134:135], v[134:135], 0, v[164:165]
	v_cvt_pk_bf16_f32 v92, v92, v93
	v_cvt_pk_bf16_f32 v93, v122, v123
	s_waitcnt lgkmcnt(0)
	v_max_f32_e32 v83, v83, v83
	v_max_f32_e32 v82, v82, v83
	ds_bpermute_b32 v83, v181, v82
	global_store_dwordx4 v[134:135], v[90:93], off
	v_cvt_pk_bf16_f32 v84, v86, v87
	v_cvt_pk_bf16_f32 v85, v88, v89
	v_cvt_pk_bf16_f32 v86, v96, v97
	v_cvt_pk_bf16_f32 v87, v94, v95
	global_store_dwordx4 v[134:135], v[84:87], off offset:256
	s_and_saveexec_b64 s[26:27], s[6:7]
	s_cbranch_execz .LBB0_1574
	s_waitcnt lgkmcnt(0)
	v_max_f32_e32 v83, v83, v83
	v_max_f32_e32 v82, v82, v82
	v_lshl_add_u64 v[84:85], v[170:171], 2, s[12:13]
	v_max_f32_e32 v82, v82, v83
	global_atomic_umax v[84:85], v82, off
.LBB0_1574:
	s_or_b64 exec, exec, s[26:27]
	v_add_u32_e32 v114, 0x80, v166
	v_ashrrev_i32_e32 v115, 31, v114
	s_waitcnt lgkmcnt(0)
	v_lshlrev_b64 v[82:83], 14, v[114:115]
	v_lshl_add_u64 v[82:83], s[8:9], 0, v[82:83]
	v_lshlrev_b64 v[116:117], 13, v[114:115]
	v_lshl_add_u64 v[82:83], v[82:83], 0, v[164:165]
	v_add_co_u32_e32 v82, vcc, 0x2000, v82
	v_lshl_add_u64 v[84:85], s[10:11], 0, v[116:117]
	s_nop 0
	v_addc_co_u32_e32 v83, vcc, 0, v83, vcc
	v_lshl_add_u64 v[84:85], v[84:85], 0, v[164:165]
	s_mov_b64 s[98:99], 0x2000
	v_lshl_add_u64 v[246:247], v[248:249], 0, s[98:99]
	global_load_dwordx4 v[94:97], v[246:247], off
	global_load_dwordx4 v[86:89], v[246:247], off offset:1024
	s_mov_b64 s[98:99], 0x2000
	v_lshl_add_u64 v[252:253], v[250:251], 0, s[98:99]
	global_load_dwordx4 v[90:93], v[252:253], off
	s_nop 0
	global_load_dwordx4 v[82:85], v[252:253], off offset:1024
	s_waitcnt vmcnt(9)
	v_lshlrev_b32_e32 v120, 16, v110
	v_and_b32_e32 v121, 0xffff0000, v110
	v_lshlrev_b32_e32 v110, 16, v111
	v_and_b32_e32 v111, 0xffff0000, v111
	v_lshlrev_b32_e32 v122, 16, v112
	v_and_b32_e32 v123, 0xffff0000, v112
	v_lshlrev_b32_e32 v112, 16, v113
	v_and_b32_e32 v113, 0xffff0000, v113
	s_waitcnt vmcnt(7)
	v_lshlrev_b32_e32 v124, 16, v106
	v_and_b32_e32 v125, 0xffff0000, v106
	v_lshlrev_b32_e32 v106, 16, v107
	v_and_b32_e32 v107, 0xffff0000, v107
	v_lshlrev_b32_e32 v126, 16, v108
	v_and_b32_e32 v127, 0xffff0000, v108
	v_lshlrev_b32_e32 v108, 16, v109
	v_and_b32_e32 v109, 0xffff0000, v109
	v_pk_fma_f32 v[80:81], v[80:81], v[110:111], v[106:107]
	v_pk_fma_f32 v[78:79], v[78:79], v[120:121], v[124:125]
	v_pk_fma_f32 v[106:107], v[76:77], v[112:113], v[108:109]
	v_pk_fma_f32 v[76:77], v[74:75], v[122:123], v[126:127]
	v_max_f32_e64 v108, |v81|, |v107|
	v_max_f32_e64 v74, |v78|, |v76|
	v_max_f32_e64 v75, |v79|, |v77|
	v_max3_f32 v74, v74, 0, v75
	v_max_f32_e64 v75, |v80|, |v106|
	v_max3_f32 v112, v74, v75, v108
	v_cvt_pk_bf16_f32 v74, v78, v79
	v_cvt_pk_bf16_f32 v75, v80, v81
	v_lshlrev_b32_e32 v78, 16, v102
	v_and_b32_e32 v79, 0xffff0000, v102
	v_lshlrev_b32_e32 v80, 16, v103
	v_and_b32_e32 v81, 0xffff0000, v103
	v_lshlrev_b32_e32 v102, 16, v104
	v_and_b32_e32 v103, 0xffff0000, v104
	s_waitcnt vmcnt(6)
	v_lshlrev_b32_e32 v108, 16, v98
	v_and_b32_e32 v109, 0xffff0000, v98
	v_lshlrev_b32_e32 v98, 16, v99
	v_and_b32_e32 v99, 0xffff0000, v99
	v_lshlrev_b32_e32 v110, 16, v100
	v_and_b32_e32 v111, 0xffff0000, v100
	v_lshlrev_b32_e32 v104, 16, v105
	v_and_b32_e32 v105, 0xffff0000, v105
	v_lshlrev_b32_e32 v100, 16, v101
	v_and_b32_e32 v101, 0xffff0000, v101
	v_pk_fma_f32 v[72:73], v[72:73], v[80:81], v[98:99]
	v_pk_fma_f32 v[70:71], v[70:71], v[78:79], v[108:109]
	v_pk_fma_f32 v[80:81], v[66:67], v[102:103], v[110:111]
	v_pk_fma_f32 v[78:79], v[68:69], v[104:105], v[100:101]
	v_max_f32_e64 v66, |v70|, |v80|
	v_max_f32_e64 v67, |v71|, |v81|
	v_max3_f32 v66, v112, v66, v67
	v_max_f32_e64 v67, |v72|, |v78|
	v_max_f32_e64 v68, |v73|, |v79|
	v_max3_f32 v66, v66, v67, v68
	ds_bpermute_b32 v67, v180, v66
	v_lshl_add_u64 v[118:119], s[2:3], 0, v[132:133]
	v_lshl_add_u64 v[118:119], v[118:119], 0, v[164:165]
	v_cvt_pk_bf16_f32 v76, v76, v77
	v_cvt_pk_bf16_f32 v77, v106, v107
	s_waitcnt lgkmcnt(0)
	v_max_f32_e32 v67, v67, v67
	v_max_f32_e32 v66, v66, v67
	ds_bpermute_b32 v67, v181, v66
	global_store_dwordx4 v[118:119], v[74:77], off
	v_cvt_pk_bf16_f32 v68, v70, v71
	v_cvt_pk_bf16_f32 v69, v72, v73
	v_cvt_pk_bf16_f32 v70, v80, v81
	v_cvt_pk_bf16_f32 v71, v78, v79
	global_store_dwordx4 v[118:119], v[68:71], off offset:256
	s_and_saveexec_b64 s[26:27], s[6:7]
	s_cbranch_execz .LBB0_1576
	s_waitcnt lgkmcnt(0)
	v_max_f32_e32 v67, v67, v67
	v_max_f32_e32 v66, v66, v66
	v_lshl_add_u64 v[68:69], v[130:131], 2, s[12:13]
	v_max_f32_e32 v66, v66, v67
	global_atomic_umax v[68:69], v66, off
; __device__ __forceinline__ u32x4 pack8(const f32x4 v0, const f32x4 v1) { u32x4 w; w.x = cvt_pk_bf16(v0[0], v0[1]); w.y = cvt_pk_bf16(v0[2], v0[3]); w.z = cvt_pk_bf16(v1[0], v1[1]); w.w = cvt_pk_bf16(v1[2], v1[3]); return w; }
; __device__ __forceinline__ void unpack8(const u32x4 w, f32x4& v0, f32x4& v1) { v0 = (f32x4){bf_lo(w.x), bf_hi(w.x), bf_lo(w.y), bf_hi(w.y)}; v1 = (f32x4){bf_lo(w.z), bf_hi(w.z), bf_lo(w.w), bf_hi(w.w)}; }
;     __device__ __forceinline__ void operator()(AccRef acc, const Unit& u, int wr, int wc, int fr, int fq) const {
;     ...
;         for (int s = 0; s < 8; ++s) { const int ai = s >> 2, m = s & 3; const int r = row0 + ai * HALF + m * 16; bf16_t* rowp = O + (size_t)r * ldc + col0;
;                 if (MODE >= 2 && s + 1 < 8) load_row(nxt, row0 + ((s + 1) >> 2) * HALF + ((s + 1) & 3) * 16, col0);
;                 float rs = 1.f; if (MODE == 1) rs = __builtin_amdgcn_rsqf(rstd[r] * (1.0f / 4096.0f) + 1e-6f);
;                 float mx = 0.f;
; #pragma unroll
;                 for (int bj = 0; bj < 2; ++bj) { f32x4 v0 = acc[ai][bj][m][0], v1 = acc[ai][bj][m][1];
;                     if (MODE == 1) { v0 = v0 * rs; v1 = v1 * rs;
; #pragma unroll
;                         for (int j = 0; j < 4; ++j) { const float a = v0[j] > 0.f ? v0[j] : 0.f, b = v1[j] > 0.f ? v1[j] : 0.f; v0[j] = a * a; v1[j] = b * b; } }
;                     if (MODE == 2) { f32x4 g0, g1; unpack8(cur.g[bj], g0, g1); v0 = v0 * g0; v1 = v1 * g1; }
;                     if (MODE == 3) { f32x4 g0, g1, a0, a1; unpack8(cur.g[bj], g0, g1); unpack8(cur.a[bj], a0, a1);
;                         v0 = a0 + v0 * g0; v1 = a1 + v1 * g1;
; #pragma unroll
;                         for (int j = 0; j < 4; ++j) mx = fmaxf(mx, fmaxf(fabsf(v0[j]), fabsf(v1[j]))); }
;                     *(u32x4*)(rowp + bj * HALF) = pack8(v0, v1); }
;                 if (MODE == 3) { mx = fmaxf(mx, __shfl_xor(mx, 16)); mx = fmaxf(mx, __shfl_xor(mx, 32)); if (fq == 0) atomicMax(RM + r, __builtin_bit_cast(unsigned, mx)); }
;                 if (MODE >= 2) cur = nxt; }
.LBB0_1576:
	s_or_b64 exec, exec, s[26:27]
	v_or_b32_e32 v98, 16, v114
	v_ashrrev_i32_e32 v99, 31, v98
	s_waitcnt lgkmcnt(0)
	v_lshlrev_b64 v[66:67], 14, v[98:99]
	v_lshl_add_u64 v[66:67], s[8:9], 0, v[66:67]
	v_lshlrev_b64 v[100:101], 13, v[98:99]
	v_lshl_add_u64 v[66:67], v[66:67], 0, v[164:165]
	v_add_co_u32_e32 v66, vcc, 0x2000, v66
	v_lshl_add_u64 v[68:69], s[10:11], 0, v[100:101]
	s_nop 0
	v_addc_co_u32_e32 v67, vcc, 0, v67, vcc
	v_lshl_add_u64 v[68:69], v[68:69], 0, v[164:165]
	s_mov_b64 s[98:99], 0x2800
	v_lshl_add_u64 v[246:247], v[248:249], 0, s[98:99]
	global_load_dwordx4 v[78:81], v[246:247], off
	global_load_dwordx4 v[70:73], v[246:247], off offset:1024
	s_mov_b64 s[98:99], 0x2800
	v_lshl_add_u64 v[252:253], v[250:251], 0, s[98:99]
	global_load_dwordx4 v[74:77], v[252:253], off
	s_nop 0
	global_load_dwordx4 v[66:69], v[252:253], off offset:1024
	s_waitcnt vmcnt(9)
	v_lshlrev_b32_e32 v104, 16, v94
	v_and_b32_e32 v105, 0xffff0000, v94
	v_lshlrev_b32_e32 v94, 16, v95
	v_and_b32_e32 v95, 0xffff0000, v95
	v_lshlrev_b32_e32 v106, 16, v96
	v_and_b32_e32 v107, 0xffff0000, v96
	v_lshlrev_b32_e32 v96, 16, v97
	v_and_b32_e32 v97, 0xffff0000, v97
	s_waitcnt vmcnt(7)
	v_lshlrev_b32_e32 v108, 16, v90
	v_and_b32_e32 v109, 0xffff0000, v90
	v_lshlrev_b32_e32 v90, 16, v91
	v_and_b32_e32 v91, 0xffff0000, v91
	v_lshlrev_b32_e32 v110, 16, v92
	v_and_b32_e32 v111, 0xffff0000, v92
	v_lshlrev_b32_e32 v92, 16, v93
	v_and_b32_e32 v93, 0xffff0000, v93
	v_pk_fma_f32 v[64:65], v[64:65], v[94:95], v[90:91]
	v_pk_fma_f32 v[62:63], v[62:63], v[104:105], v[108:109]
	v_pk_fma_f32 v[90:91], v[60:61], v[96:97], v[92:93]
	v_pk_fma_f32 v[60:61], v[58:59], v[106:107], v[110:111]
	v_max_f32_e64 v92, |v65|, |v91|
	v_max_f32_e64 v58, |v62|, |v60|
	v_max_f32_e64 v59, |v63|, |v61|
	v_max3_f32 v58, v58, 0, v59
	v_max_f32_e64 v59, |v64|, |v90|
	v_max3_f32 v96, v58, v59, v92
	v_cvt_pk_bf16_f32 v58, v62, v63
	v_cvt_pk_bf16_f32 v59, v64, v65
	v_lshlrev_b32_e32 v62, 16, v86
	v_and_b32_e32 v63, 0xffff0000, v86
	v_lshlrev_b32_e32 v64, 16, v87
	v_and_b32_e32 v65, 0xffff0000, v87
	v_lshlrev_b32_e32 v86, 16, v88
	v_and_b32_e32 v87, 0xffff0000, v88
	s_waitcnt vmcnt(6)
	v_lshlrev_b32_e32 v92, 16, v82
	v_and_b32_e32 v93, 0xffff0000, v82
	v_lshlrev_b32_e32 v82, 16, v83
	v_and_b32_e32 v83, 0xffff0000, v83
	v_lshlrev_b32_e32 v94, 16, v84
	v_and_b32_e32 v95, 0xffff0000, v84
	v_lshlrev_b32_e32 v88, 16, v89
	v_and_b32_e32 v89, 0xffff0000, v89
	v_lshlrev_b32_e32 v84, 16, v85
	v_and_b32_e32 v85, 0xffff0000, v85
	v_pk_fma_f32 v[56:57], v[56:57], v[64:65], v[82:83]
	v_pk_fma_f32 v[54:55], v[54:55], v[62:63], v[92:93]
	v_pk_fma_f32 v[64:65], v[50:51], v[86:87], v[94:95]
	v_pk_fma_f32 v[62:63], v[52:53], v[88:89], v[84:85]
	v_max_f32_e64 v50, |v54|, |v64|
	v_max_f32_e64 v51, |v55|, |v65|
	v_max3_f32 v50, v96, v50, v51
	v_max_f32_e64 v51, |v56|, |v62|
	v_max_f32_e64 v52, |v57|, |v63|
	v_max3_f32 v50, v50, v51, v52
	ds_bpermute_b32 v51, v180, v50
	v_lshl_add_u64 v[102:103], s[2:3], 0, v[116:117]
	v_lshl_add_u64 v[102:103], v[102:103], 0, v[164:165]
	v_cvt_pk_bf16_f32 v60, v60, v61
	v_cvt_pk_bf16_f32 v61, v90, v91
	s_waitcnt lgkmcnt(0)
	v_max_f32_e32 v51, v51, v51
	v_max_f32_e32 v50, v50, v51
	ds_bpermute_b32 v51, v181, v50
	global_store_dwordx4 v[102:103], v[58:61], off
	v_cvt_pk_bf16_f32 v52, v54, v55
	v_cvt_pk_bf16_f32 v53, v56, v57
	v_cvt_pk_bf16_f32 v54, v64, v65
	v_cvt_pk_bf16_f32 v55, v62, v63
	global_store_dwordx4 v[102:103], v[52:55], off offset:256
	s_and_saveexec_b64 s[26:27], s[6:7]
	s_cbranch_execz .LBB0_1578
	s_waitcnt lgkmcnt(0)
	v_max_f32_e32 v51, v51, v51
	v_max_f32_e32 v50, v50, v50
	v_lshl_add_u64 v[52:53], v[114:115], 2, s[12:13]
	v_max_f32_e32 v50, v50, v51
	global_atomic_umax v[52:53], v50, off
.LBB0_1578:
	s_or_b64 exec, exec, s[26:27]
	v_or_b32_e32 v82, 32, v114
	v_ashrrev_i32_e32 v83, 31, v82
	s_waitcnt lgkmcnt(0)
	v_lshlrev_b64 v[50:51], 14, v[82:83]
	v_lshl_add_u64 v[50:51], s[8:9], 0, v[50:51]
	v_lshlrev_b64 v[84:85], 13, v[82:83]
	v_lshl_add_u64 v[50:51], v[50:51], 0, v[164:165]
	v_add_co_u32_e32 v50, vcc, 0x2000, v50
	v_lshl_add_u64 v[52:53], s[10:11], 0, v[84:85]
	s_nop 0
	v_addc_co_u32_e32 v51, vcc, 0, v51, vcc
	v_lshl_add_u64 v[52:53], v[52:53], 0, v[164:165]
	s_mov_b64 s[98:99], 0x3000
	v_lshl_add_u64 v[246:247], v[248:249], 0, s[98:99]
	global_load_dwordx4 v[62:65], v[246:247], off
	global_load_dwordx4 v[54:57], v[246:247], off offset:1024
	s_mov_b64 s[98:99], 0x3000
	v_lshl_add_u64 v[252:253], v[250:251], 0, s[98:99]
	global_load_dwordx4 v[58:61], v[252:253], off
	s_nop 0
	global_load_dwordx4 v[50:53], v[252:253], off offset:1024
	s_waitcnt vmcnt(9)
	v_lshlrev_b32_e32 v88, 16, v78
	v_and_b32_e32 v89, 0xffff0000, v78
	v_lshlrev_b32_e32 v78, 16, v79
	v_and_b32_e32 v79, 0xffff0000, v79
	v_lshlrev_b32_e32 v90, 16, v80
	v_and_b32_e32 v91, 0xffff0000, v80
	v_lshlrev_b32_e32 v80, 16, v81
	v_and_b32_e32 v81, 0xffff0000, v81
	s_waitcnt vmcnt(7)
	v_lshlrev_b32_e32 v92, 16, v74
	v_and_b32_e32 v93, 0xffff0000, v74
	v_lshlrev_b32_e32 v74, 16, v75
	v_and_b32_e32 v75, 0xffff0000, v75
	v_lshlrev_b32_e32 v94, 16, v76
	v_and_b32_e32 v95, 0xffff0000, v76
	v_lshlrev_b32_e32 v76, 16, v77
	v_and_b32_e32 v77, 0xffff0000, v77
	v_pk_fma_f32 v[48:49], v[48:49], v[78:79], v[74:75]
	v_pk_fma_f32 v[46:47], v[46:47], v[88:89], v[92:93]
	v_pk_fma_f32 v[74:75], v[44:45], v[80:81], v[76:77]
	v_pk_fma_f32 v[44:45], v[42:43], v[90:91], v[94:95]
	v_max_f32_e64 v76, |v49|, |v75|
	v_max_f32_e64 v42, |v46|, |v44|
	v_max_f32_e64 v43, |v47|, |v45|
	v_max3_f32 v42, v42, 0, v43
	v_max_f32_e64 v43, |v48|, |v74|
	v_max3_f32 v80, v42, v43, v76
	v_cvt_pk_bf16_f32 v42, v46, v47
	v_cvt_pk_bf16_f32 v43, v48, v49
	v_lshlrev_b32_e32 v46, 16, v70
	v_and_b32_e32 v47, 0xffff0000, v70
	v_lshlrev_b32_e32 v48, 16, v71
	v_and_b32_e32 v49, 0xffff0000, v71
	v_lshlrev_b32_e32 v70, 16, v72
	v_and_b32_e32 v71, 0xffff0000, v72
	s_waitcnt vmcnt(6)
; __device__ __forceinline__ u32x4 pack8(const f32x4 v0, const f32x4 v1) { u32x4 w; w.x = cvt_pk_bf16(v0[0], v0[1]); w.y = cvt_pk_bf16(v0[2], v0[3]); w.z = cvt_pk_bf16(v1[0], v1[1]); w.w = cvt_pk_bf16(v1[2], v1[3]); return w; }
; __device__ __forceinline__ void unpack8(const u32x4 w, f32x4& v0, f32x4& v1) { v0 = (f32x4){bf_lo(w.x), bf_hi(w.x), bf_lo(w.y), bf_hi(w.y)}; v1 = (f32x4){bf_lo(w.z), bf_hi(w.z), bf_lo(w.w), bf_hi(w.w)}; }
;     __device__ __forceinline__ void operator()(AccRef acc, const Unit& u, int wr, int wc, int fr, int fq) const {
;     ...
;         for (int s = 0; s < 8; ++s) { const int ai = s >> 2, m = s & 3; const int r = row0 + ai * HALF + m * 16; bf16_t* rowp = O + (size_t)r * ldc + col0;
;                 if (MODE >= 2 && s + 1 < 8) load_row(nxt, row0 + ((s + 1) >> 2) * HALF + ((s + 1) & 3) * 16, col0);
;                 float rs = 1.f; if (MODE == 1) rs = __builtin_amdgcn_rsqf(rstd[r] * (1.0f / 4096.0f) + 1e-6f);
;                 float mx = 0.f;
; #pragma unroll
;                 for (int bj = 0; bj < 2; ++bj) { f32x4 v0 = acc[ai][bj][m][0], v1 = acc[ai][bj][m][1];
;                     if (MODE == 1) { v0 = v0 * rs; v1 = v1 * rs;
; #pragma unroll
;                         for (int j = 0; j < 4; ++j) { const float a = v0[j] > 0.f ? v0[j] : 0.f, b = v1[j] > 0.f ? v1[j] : 0.f; v0[j] = a * a; v1[j] = b * b; } }
;                     if (MODE == 2) { f32x4 g0, g1; unpack8(cur.g[bj], g0, g1); v0 = v0 * g0; v1 = v1 * g1; }
;                     if (MODE == 3) { f32x4 g0, g1, a0, a1; unpack8(cur.g[bj], g0, g1); unpack8(cur.a[bj], a0, a1);
;                         v0 = a0 + v0 * g0; v1 = a1 + v1 * g1;
; #pragma unroll
;                         for (int j = 0; j < 4; ++j) mx = fmaxf(mx, fmaxf(fabsf(v0[j]), fabsf(v1[j]))); }
;                     *(u32x4*)(rowp + bj * HALF) = pack8(v0, v1); }
;                 if (MODE == 3) { mx = fmaxf(mx, __shfl_xor(mx, 16)); mx = fmaxf(mx, __shfl_xor(mx, 32)); if (fq == 0) atomicMax(RM + r, __builtin_bit_cast(unsigned, mx)); }
;                 if (MODE >= 2) cur = nxt; }
	v_lshlrev_b32_e32 v76, 16, v66
	v_and_b32_e32 v77, 0xffff0000, v66
	v_lshlrev_b32_e32 v66, 16, v67
	v_and_b32_e32 v67, 0xffff0000, v67
	v_lshlrev_b32_e32 v78, 16, v68
	v_and_b32_e32 v79, 0xffff0000, v68
	v_lshlrev_b32_e32 v72, 16, v73
	v_and_b32_e32 v73, 0xffff0000, v73
	v_lshlrev_b32_e32 v68, 16, v69
	v_and_b32_e32 v69, 0xffff0000, v69
	v_pk_fma_f32 v[40:41], v[40:41], v[48:49], v[66:67]
	v_pk_fma_f32 v[38:39], v[38:39], v[46:47], v[76:77]
	v_pk_fma_f32 v[48:49], v[34:35], v[70:71], v[78:79]
	v_pk_fma_f32 v[46:47], v[36:37], v[72:73], v[68:69]
	v_max_f32_e64 v34, |v38|, |v48|
	v_max_f32_e64 v35, |v39|, |v49|
	v_max3_f32 v34, v80, v34, v35
	v_max_f32_e64 v35, |v40|, |v46|
	v_max_f32_e64 v36, |v41|, |v47|
	v_max3_f32 v34, v34, v35, v36
	ds_bpermute_b32 v35, v180, v34
	v_lshl_add_u64 v[86:87], s[2:3], 0, v[100:101]
	v_lshl_add_u64 v[86:87], v[86:87], 0, v[164:165]
	v_cvt_pk_bf16_f32 v44, v44, v45
	v_cvt_pk_bf16_f32 v45, v74, v75
	s_waitcnt lgkmcnt(0)
	v_max_f32_e32 v35, v35, v35
	v_max_f32_e32 v34, v34, v35
	ds_bpermute_b32 v35, v181, v34
	global_store_dwordx4 v[86:87], v[42:45], off
	v_cvt_pk_bf16_f32 v36, v38, v39
	v_cvt_pk_bf16_f32 v37, v40, v41
	v_cvt_pk_bf16_f32 v38, v48, v49
	v_cvt_pk_bf16_f32 v39, v46, v47
	global_store_dwordx4 v[86:87], v[36:39], off offset:256
	s_and_saveexec_b64 s[26:27], s[6:7]
	s_cbranch_execz .LBB0_1580
	s_waitcnt lgkmcnt(0)
	v_max_f32_e32 v35, v35, v35
	v_max_f32_e32 v34, v34, v34
	v_lshl_add_u64 v[36:37], v[98:99], 2, s[12:13]
	v_max_f32_e32 v34, v34, v35
	global_atomic_umax v[36:37], v34, off
.LBB0_1580:
	s_or_b64 exec, exec, s[26:27]
	v_or_b32_e32 v66, 48, v114
	v_ashrrev_i32_e32 v67, 31, v66
	s_waitcnt lgkmcnt(0)
	v_lshlrev_b64 v[34:35], 14, v[66:67]
	v_lshl_add_u64 v[34:35], s[8:9], 0, v[34:35]
	v_lshlrev_b64 v[68:69], 13, v[66:67]
	v_lshl_add_u64 v[34:35], v[34:35], 0, v[164:165]
	v_add_co_u32_e32 v34, vcc, 0x2000, v34
	v_lshl_add_u64 v[36:37], s[10:11], 0, v[68:69]
	s_nop 0
	v_addc_co_u32_e32 v35, vcc, 0, v35, vcc
	v_lshl_add_u64 v[36:37], v[36:37], 0, v[164:165]
	s_mov_b64 s[98:99], 0x3800
	v_lshl_add_u64 v[246:247], v[248:249], 0, s[98:99]
	global_load_dwordx4 v[46:49], v[246:247], off
	global_load_dwordx4 v[38:41], v[246:247], off offset:1024
	s_mov_b64 s[98:99], 0x3800
	v_lshl_add_u64 v[252:253], v[250:251], 0, s[98:99]
	global_load_dwordx4 v[42:45], v[252:253], off
	s_nop 0
	global_load_dwordx4 v[34:37], v[252:253], off offset:1024
	s_waitcnt vmcnt(9)
	v_lshlrev_b32_e32 v72, 16, v62
	v_and_b32_e32 v73, 0xffff0000, v62
	v_lshlrev_b32_e32 v62, 16, v63
	v_and_b32_e32 v63, 0xffff0000, v63
	v_lshlrev_b32_e32 v74, 16, v64
	v_and_b32_e32 v75, 0xffff0000, v64
	v_lshlrev_b32_e32 v64, 16, v65
	v_and_b32_e32 v65, 0xffff0000, v65
	s_waitcnt vmcnt(7)
	v_lshlrev_b32_e32 v76, 16, v58
	v_and_b32_e32 v77, 0xffff0000, v58
	v_lshlrev_b32_e32 v58, 16, v59
	v_and_b32_e32 v59, 0xffff0000, v59
	v_lshlrev_b32_e32 v78, 16, v60
	v_and_b32_e32 v79, 0xffff0000, v60
	v_lshlrev_b32_e32 v60, 16, v61
	v_and_b32_e32 v61, 0xffff0000, v61
	v_pk_fma_f32 v[32:33], v[32:33], v[62:63], v[58:59]
	v_pk_fma_f32 v[30:31], v[30:31], v[72:73], v[76:77]
	v_pk_fma_f32 v[58:59], v[28:29], v[64:65], v[60:61]
	v_pk_fma_f32 v[28:29], v[26:27], v[74:75], v[78:79]
	v_max_f32_e64 v60, |v33|, |v59|
	v_max_f32_e64 v26, |v30|, |v28|
	v_max_f32_e64 v27, |v31|, |v29|
	v_max3_f32 v26, v26, 0, v27
	v_max_f32_e64 v27, |v32|, |v58|
	v_max3_f32 v64, v26, v27, v60
	v_cvt_pk_bf16_f32 v26, v30, v31
	v_cvt_pk_bf16_f32 v27, v32, v33
	v_lshlrev_b32_e32 v30, 16, v54
	v_and_b32_e32 v31, 0xffff0000, v54
	v_lshlrev_b32_e32 v32, 16, v55
	v_and_b32_e32 v33, 0xffff0000, v55
	v_lshlrev_b32_e32 v54, 16, v56
	v_and_b32_e32 v55, 0xffff0000, v56
	s_waitcnt vmcnt(6)
	v_lshlrev_b32_e32 v60, 16, v50
	v_and_b32_e32 v61, 0xffff0000, v50
	v_lshlrev_b32_e32 v50, 16, v51
	v_and_b32_e32 v51, 0xffff0000, v51
	v_lshlrev_b32_e32 v62, 16, v52
	v_and_b32_e32 v63, 0xffff0000, v52
	v_lshlrev_b32_e32 v56, 16, v57
	v_and_b32_e32 v57, 0xffff0000, v57
	v_lshlrev_b32_e32 v52, 16, v53
	v_and_b32_e32 v53, 0xffff0000, v53
	v_pk_fma_f32 v[24:25], v[24:25], v[32:33], v[50:51]
	v_pk_fma_f32 v[22:23], v[22:23], v[30:31], v[60:61]
	v_pk_fma_f32 v[32:33], v[18:19], v[54:55], v[62:63]
	v_pk_fma_f32 v[30:31], v[20:21], v[56:57], v[52:53]
	v_max_f32_e64 v18, |v22|, |v32|
	v_max_f32_e64 v19, |v23|, |v33|
	v_max3_f32 v18, v64, v18, v19
	v_max_f32_e64 v19, |v24|, |v30|
	v_max_f32_e64 v20, |v25|, |v31|
	v_max3_f32 v18, v18, v19, v20
	ds_bpermute_b32 v19, v180, v18
	v_lshl_add_u64 v[70:71], s[2:3], 0, v[84:85]
	v_lshl_add_u64 v[70:71], v[70:71], 0, v[164:165]
	v_cvt_pk_bf16_f32 v28, v28, v29
	v_cvt_pk_bf16_f32 v29, v58, v59
	s_waitcnt lgkmcnt(0)
	v_max_f32_e32 v19, v19, v19
	v_max_f32_e32 v18, v18, v19
	ds_bpermute_b32 v19, v181, v18
	global_store_dwordx4 v[70:71], v[26:29], off
	v_cvt_pk_bf16_f32 v20, v22, v23
	v_cvt_pk_bf16_f32 v21, v24, v25
	v_cvt_pk_bf16_f32 v22, v32, v33
	v_cvt_pk_bf16_f32 v23, v30, v31
	global_store_dwordx4 v[70:71], v[20:23], off offset:256
	s_and_saveexec_b64 s[26:27], s[6:7]
	s_cbranch_execz .LBB0_1582
	s_waitcnt lgkmcnt(0)
	v_max_f32_e32 v19, v19, v19
	v_max_f32_e32 v18, v18, v18
	v_lshl_add_u64 v[20:21], v[82:83], 2, s[12:13]
	v_max_f32_e32 v18, v18, v19
	global_atomic_umax v[20:21], v18, off
; __device__ __forceinline__ u32x4 pack8(const f32x4 v0, const f32x4 v1) { u32x4 w; w.x = cvt_pk_bf16(v0[0], v0[1]); w.y = cvt_pk_bf16(v0[2], v0[3]); w.z = cvt_pk_bf16(v1[0], v1[1]); w.w = cvt_pk_bf16(v1[2], v1[3]); return w; }
; __device__ __forceinline__ void unpack8(const u32x4 w, f32x4& v0, f32x4& v1) { v0 = (f32x4){bf_lo(w.x), bf_hi(w.x), bf_lo(w.y), bf_hi(w.y)}; v1 = (f32x4){bf_lo(w.z), bf_hi(w.z), bf_lo(w.w), bf_hi(w.w)}; }
;     __device__ __forceinline__ void operator()(AccRef acc, const Unit& u, int wr, int wc, int fr, int fq) const {
;     ...
;         for (int s = 0; s < 8; ++s) { const int ai = s >> 2, m = s & 3; const int r = row0 + ai * HALF + m * 16; bf16_t* rowp = O + (size_t)r * ldc + col0;
;                 if (MODE >= 2 && s + 1 < 8) load_row(nxt, row0 + ((s + 1) >> 2) * HALF + ((s + 1) & 3) * 16, col0);
;                 float rs = 1.f; if (MODE == 1) rs = __builtin_amdgcn_rsqf(rstd[r] * (1.0f / 4096.0f) + 1e-6f);
;                 float mx = 0.f;
; #pragma unroll
;                 for (int bj = 0; bj < 2; ++bj) { f32x4 v0 = acc[ai][bj][m][0], v1 = acc[ai][bj][m][1];
;                     if (MODE == 1) { v0 = v0 * rs; v1 = v1 * rs;
; #pragma unroll
;                         for (int j = 0; j < 4; ++j) { const float a = v0[j] > 0.f ? v0[j] : 0.f, b = v1[j] > 0.f ? v1[j] : 0.f; v0[j] = a * a; v1[j] = b * b; } }
;                     if (MODE == 2) { f32x4 g0, g1; unpack8(cur.g[bj], g0, g1); v0 = v0 * g0; v1 = v1 * g1; }
;                     if (MODE == 3) { f32x4 g0, g1, a0, a1; unpack8(cur.g[bj], g0, g1); unpack8(cur.a[bj], a0, a1);
;                         v0 = a0 + v0 * g0; v1 = a1 + v1 * g1;
; #pragma unroll
;                         for (int j = 0; j < 4; ++j) mx = fmaxf(mx, fmaxf(fabsf(v0[j]), fabsf(v1[j]))); }
;                     *(u32x4*)(rowp + bj * HALF) = pack8(v0, v1); }
;                 if (MODE == 3) { mx = fmaxf(mx, __shfl_xor(mx, 16)); mx = fmaxf(mx, __shfl_xor(mx, 32)); if (fq == 0) atomicMax(RM + r, __builtin_bit_cast(unsigned, mx)); }
;                 if (MODE >= 2) cur = nxt; }
.LBB0_1582:
	s_or_b64 exec, exec, s[26:27]
	s_waitcnt vmcnt(5)
	v_lshlrev_b32_e32 v20, 16, v46
	v_and_b32_e32 v21, 0xffff0000, v46
	v_lshlrev_b32_e32 v24, 16, v48
	v_and_b32_e32 v25, 0xffff0000, v48
	v_lshlrev_b32_e32 v26, 16, v49
	v_and_b32_e32 v27, 0xffff0000, v49
	s_waitcnt vmcnt(3)
	v_lshlrev_b32_e32 v28, 16, v42
	v_and_b32_e32 v29, 0xffff0000, v42
	v_lshlrev_b32_e32 v30, 16, v43
	v_and_b32_e32 v31, 0xffff0000, v43
	v_lshlrev_b32_e32 v32, 16, v44
	v_and_b32_e32 v33, 0xffff0000, v44
	v_lshlrev_b32_e32 v42, 16, v45
	v_and_b32_e32 v43, 0xffff0000, v45
	v_lshlrev_b32_e32 v22, 16, v47
	v_and_b32_e32 v23, 0xffff0000, v47
	v_pk_fma_f32 v[14:15], v[14:15], v[20:21], v[28:29]
	v_pk_fma_f32 v[20:21], v[12:13], v[26:27], v[42:43]
	v_pk_fma_f32 v[12:13], v[10:11], v[24:25], v[32:33]
	v_pk_fma_f32 v[16:17], v[16:17], v[22:23], v[30:31]
	v_max_f32_e64 v10, |v14|, |v12|
	v_max_f32_e64 v11, |v15|, |v13|
	v_max3_f32 v10, v10, 0, v11
	v_max_f32_e64 v11, |v16|, |v20|
	v_max_f32_e64 v22, |v17|, |v21|
	v_max3_f32 v42, v10, v11, v22
	v_cvt_pk_bf16_f32 v10, v14, v15
	v_cvt_pk_bf16_f32 v11, v16, v17
	v_lshlrev_b32_e32 v14, 16, v38
	v_and_b32_e32 v15, 0xffff0000, v38
	v_lshlrev_b32_e32 v16, 16, v39
	v_and_b32_e32 v17, 0xffff0000, v39
	v_lshlrev_b32_e32 v22, 16, v40
	v_and_b32_e32 v23, 0xffff0000, v40
	s_waitcnt vmcnt(2)
	v_lshlrev_b32_e32 v26, 16, v34
	v_and_b32_e32 v27, 0xffff0000, v34
	v_lshlrev_b32_e32 v28, 16, v35
	v_and_b32_e32 v29, 0xffff0000, v35
	v_lshlrev_b32_e32 v30, 16, v36
	v_and_b32_e32 v31, 0xffff0000, v36
	v_lshlrev_b32_e32 v24, 16, v41
	v_and_b32_e32 v25, 0xffff0000, v41
	v_lshlrev_b32_e32 v32, 16, v37
	v_and_b32_e32 v33, 0xffff0000, v37
	v_pk_fma_f32 v[8:9], v[8:9], v[16:17], v[28:29]
	v_pk_fma_f32 v[6:7], v[6:7], v[14:15], v[26:27]
	v_pk_fma_f32 v[16:17], v[2:3], v[22:23], v[30:31]
	v_pk_fma_f32 v[14:15], v[4:5], v[24:25], v[32:33]
	v_max_f32_e64 v2, |v6|, |v16|
	v_max_f32_e64 v3, |v7|, |v17|
	v_max3_f32 v2, v42, v2, v3
	v_max_f32_e64 v3, |v8|, |v14|
	v_max_f32_e64 v4, |v9|, |v15|
	v_max3_f32 v2, v2, v3, v4
	ds_bpermute_b32 v3, v180, v2
	s_waitcnt lgkmcnt(1)
	v_lshl_add_u64 v[18:19], s[2:3], 0, v[68:69]
	v_lshl_add_u64 v[18:19], v[162:163], 1, v[18:19]
	v_cvt_pk_bf16_f32 v12, v12, v13
	v_cvt_pk_bf16_f32 v13, v20, v21
	s_waitcnt lgkmcnt(0)
	v_max_f32_e32 v3, v3, v3
	v_max_f32_e32 v2, v2, v3
	ds_bpermute_b32 v3, v181, v2
	global_store_dwordx4 v[18:19], v[10:13], off
	v_cvt_pk_bf16_f32 v4, v6, v7
	v_cvt_pk_bf16_f32 v5, v8, v9
	v_cvt_pk_bf16_f32 v6, v16, v17
	v_cvt_pk_bf16_f32 v7, v14, v15
	global_store_dwordx4 v[18:19], v[4:7], off offset:256
	s_and_saveexec_b64 s[26:27], s[6:7]
	s_cbranch_execz .LBB0_1584
	s_waitcnt lgkmcnt(0)
	v_max_f32_e32 v3, v3, v3
	v_max_f32_e32 v2, v2, v2
	v_lshl_add_u64 v[4:5], v[66:67], 2, s[12:13]
	v_max_f32_e32 v2, v2, v3
	global_atomic_umax v[4:5], v2, off

; #define PG8_STAGE(bufoff, gbase, voff) do { _Pragma("unroll") for (int _i = 0; _i < 2; ++_i) \
;         __builtin_amdgcn_global_load_lds((const unsigned*)((const char*)(gbase) + (voff)[_i]), (PG8_LAS unsigned*)(lds + (bufoff) + ldsw + _i * 8192), 16, 0, 0); } while (0)
; #define PG8_LDA(dst, b, h) do { _Pragma("unroll") for (int m = 0; m < 4; ++m) _Pragma("unroll") for (int k = 0; k < 2; ++k) dst[m][k] = *(const PG8_LAS bf16x8*)(lds + PG8_SA(b, h) + aoff + m * 2048 + k * 1024); } while (0)
; #define PG8_LDB(dst, b, h) do { _Pragma("unroll") for (int n = 0; n < 2; ++n) _Pragma("unroll") for (int k = 0; k < 2; ++k) dst[n][k] = *(const PG8_LAS bf16x8*)(lds + PG8_SB(b, h) + boff + n * 2048 + k * 1024); } while (0)
; #define PG8_MMA(ai, bj, At, Bt) do { __builtin_amdgcn_s_setprio(1); _Pragma("unroll") for (int m = 0; m < 4; ++m) _Pragma("unroll") for (int n = 0; n < 2; ++n) _Pragma("unroll") for (int k = 0; k < 2; ++k) \
;         acc[ai][bj][m][n] = mma_<I8>(Bt[n][k], At[m][k], acc[ai][bj][m][n]); __builtin_amdgcn_s_setprio(0); } while (0)
; #define PG8_WAIT_V(n) asm volatile("s_waitcnt vmcnt(" #n ")" ::: "memory")
; #define PG8_WAIT_L(n) asm volatile("s_waitcnt lgkmcnt(" #n ")" ::: "memory")
; #define PG8_BAR __builtin_amdgcn_s_barrier()
; #define PG8_SCHED __builtin_amdgcn_sched_barrier(0)
; template <class Epi, class Sched, bool ALIGN_EPI = false, bool SP2 = false, bool I8 = false>
; __device__ __forceinline__ void gemm_phase(PG8_LAS unsigned char* lds, const Gemm g, const Sched& S, const Epi& E) {
;     ...
;             PG8_LDB(B0, 0, 0); PG8_LDB(B1, 0, 1); PG8_SCHED; PG8_LDA(At, 0, 0); PG8_STAGE(PG8_SA(1, 1), a1 + hstepA, voffA);
;             PG8_WAIT_V(8); PG8_WAIT_L(0); PG8_BAR; PG8_MMA(0, 0, At, B0); PG8_MMA(0, 1, At, B1); PG8_BAR; PG8_SCHED;
;             PG8_LDA(At, 0, 1); PG8_STAGE(PG8_SB(0, 0), b2, voffB); PG8_STAGE(PG8_SB(0, 1), b2 + hstepB, voffB); PG8_STAGE(PG8_SA(0, 0), a2, voffA);
;             PG8_WAIT_V(8); PG8_WAIT_L(0); PG8_BAR; PG8_MMA(1, 0, At, B0); PG8_MMA(1, 1, At, B1); PG8_BAR; PG8_SCHED;
.LBB0_1721:
	ds_read_b128 v[34:37], v233
	ds_read_b128 v[38:41], v233 offset:1024
	ds_read_b128 v[42:45], v233 offset:2048
	ds_read_b128 v[62:65], v233 offset:3072
	ds_read_b128 v[146:149], v234
	ds_read_b128 v[150:153], v234 offset:1024
	ds_read_b128 v[154:157], v234 offset:2048
	ds_read_b128 v[158:161], v234 offset:3072
	s_add_u32 s34, s8, 0xfff80080
	s_addc_u32 s35, s9, -1
	s_cmp_eq_u32 s55, 28
	s_cselect_b32 s37, s3, s35
	s_cselect_b32 s36, s7, s34
	s_cselect_b32 s35, s25, s54
	s_cselect_b32 s34, s27, s33
	s_add_i32 m0, s43, 0xc000
	ds_read_b128 v[162:165], v235
	ds_read_b128 v[166:169], v235 offset:1024
	ds_read_b128 v[170:173], v235 offset:2048
	ds_read_b128 v[186:189], v235 offset:3072
	ds_read_b128 v[190:193], v235 offset:4096
	ds_read_b128 v[194:197], v235 offset:5120
	ds_read_b128 v[198:201], v235 offset:6144
	ds_read_b128 v[202:205], v235 offset:7168
	global_load_lds_dwordx4 v178, s[8:9]
	s_add_i32 m0, s43, 0xe000
	s_nop 0
	global_load_lds_dwordx4 v180, s[8:9]
	s_waitcnt vmcnt(8) lgkmcnt(0)
	s_barrier
	v_mfma_i32_16x16x64_i8 v[142:145], v[34:37], v[162:165], v[142:145]
	v_mfma_i32_16x16x64_i8 v[138:141], v[42:45], v[162:165], v[138:141]
	v_mfma_i32_16x16x64_i8 v[126:129], v[34:37], v[170:173], v[126:129]
	v_mfma_i32_16x16x64_i8 v[122:125], v[42:45], v[170:173], v[122:125]
	v_mfma_i32_16x16x64_i8 v[110:113], v[34:37], v[190:193], v[110:113]
	v_mfma_i32_16x16x64_i8 v[106:109], v[42:45], v[190:193], v[106:109]
	v_mfma_i32_16x16x64_i8 v[94:97], v[34:37], v[198:201], v[94:97]
	v_mfma_i32_16x16x64_i8 v[90:93], v[42:45], v[198:201], v[90:93]
	v_mfma_i32_16x16x64_i8 v[142:145], v[38:41], v[166:169], v[142:145]
	v_mfma_i32_16x16x64_i8 v[138:141], v[62:65], v[166:169], v[138:141]
	v_mfma_i32_16x16x64_i8 v[126:129], v[38:41], v[186:189], v[126:129]
	v_mfma_i32_16x16x64_i8 v[122:125], v[62:65], v[186:189], v[122:125]
	v_mfma_i32_16x16x64_i8 v[110:113], v[38:41], v[194:197], v[110:113]
	v_mfma_i32_16x16x64_i8 v[106:109], v[62:65], v[194:197], v[106:109]
	v_mfma_i32_16x16x64_i8 v[94:97], v[38:41], v[202:205], v[94:97]
	v_mfma_i32_16x16x64_i8 v[90:93], v[62:65], v[202:205], v[90:93]
	v_mfma_i32_16x16x64_i8 v[134:137], v[146:149], v[162:165], v[134:137]
	v_mfma_i32_16x16x64_i8 v[130:133], v[154:157], v[162:165], v[130:133]
	v_mfma_i32_16x16x64_i8 v[118:121], v[146:149], v[170:173], v[118:121]
	v_mfma_i32_16x16x64_i8 v[114:117], v[154:157], v[170:173], v[114:117]
	v_mfma_i32_16x16x64_i8 v[102:105], v[146:149], v[190:193], v[102:105]
	v_mfma_i32_16x16x64_i8 v[98:101], v[154:157], v[190:193], v[98:101]
	v_mfma_i32_16x16x64_i8 v[86:89], v[146:149], v[198:201], v[86:89]
	v_mfma_i32_16x16x64_i8 v[82:85], v[154:157], v[198:201], v[82:85]
	v_mfma_i32_16x16x64_i8 v[134:137], v[150:153], v[166:169], v[134:137]
	v_mfma_i32_16x16x64_i8 v[130:133], v[158:161], v[166:169], v[130:133]
	v_mfma_i32_16x16x64_i8 v[118:121], v[150:153], v[186:189], v[118:121]
	v_mfma_i32_16x16x64_i8 v[114:117], v[158:161], v[186:189], v[114:117]
	v_mfma_i32_16x16x64_i8 v[102:105], v[150:153], v[194:197], v[102:105]
	v_mfma_i32_16x16x64_i8 v[98:101], v[158:161], v[194:197], v[98:101]
	v_mfma_i32_16x16x64_i8 v[86:89], v[150:153], v[202:205], v[86:89]
	v_mfma_i32_16x16x64_i8 v[82:85], v[158:161], v[202:205], v[82:85]
	s_barrier
	s_add_i32 s56, s52, s40
	s_mov_b64 s[98:99], s[34:35]
	s_mov_b32 m0, s56
	ds_read_b128 v[162:165], v235 offset:16384
	ds_read_b128 v[166:169], v235 offset:17408
	ds_read_b128 v[170:173], v235 offset:18432
	ds_read_b128 v[186:189], v235 offset:19456
	ds_read_b128 v[190:193], v235 offset:20480
	ds_read_b128 v[194:197], v235 offset:21504
	ds_read_b128 v[198:201], v235 offset:22528
	ds_read_b128 v[202:205], v235 offset:23552
	global_load_lds_dwordx4 v174, s[34:35]
	s_add_i32 m0, s56, 0x2000
	s_add_u32 s56, s34, 0x80000
	s_mov_b64 s[98:99], s[34:35]
	s_addc_u32 s57, s35, 0
	s_add_i32 s58, s53, s40
	global_load_lds_dwordx4 v176, s[34:35]
	s_mov_b32 m0, s58
	s_mov_b64 s[100:101], s[36:37]
	global_load_lds_dwordx4 v174, s[56:57]
	s_add_i32 m0, s58, 0x2000
	s_nop 0
	global_load_lds_dwordx4 v176, s[56:57]
	s_mov_b64 s[100:101], s[36:37]
	s_mov_b32 m0, s43
	s_nop 0
	global_load_lds_dwordx4 v174, s[36:37]
	s_mov_b32 m0, s44
	s_nop 0
	global_load_lds_dwordx4 v176, s[36:37]
	s_waitcnt vmcnt(8) lgkmcnt(0)
	s_barrier
	v_mfma_i32_16x16x64_i8 v[78:81], v[34:37], v[162:165], v[78:81]
	v_mfma_i32_16x16x64_i8 v[74:77], v[42:45], v[162:165], v[74:77]
	v_mfma_i32_16x16x64_i8 v[58:61], v[34:37], v[170:173], v[58:61]
	v_mfma_i32_16x16x64_i8 v[54:57], v[42:45], v[170:173], v[54:57]
	v_mfma_i32_16x16x64_i8 v[30:33], v[34:37], v[190:193], v[30:33]
	v_mfma_i32_16x16x64_i8 v[26:29], v[42:45], v[190:193], v[26:29]
	v_mfma_i32_16x16x64_i8 v[14:17], v[34:37], v[198:201], v[14:17]
	v_mfma_i32_16x16x64_i8 v[10:13], v[42:45], v[198:201], v[10:13]
	v_mfma_i32_16x16x64_i8 v[78:81], v[38:41], v[166:169], v[78:81]
	v_mfma_i32_16x16x64_i8 v[74:77], v[62:65], v[166:169], v[74:77]
	v_mfma_i32_16x16x64_i8 v[58:61], v[38:41], v[186:189], v[58:61]
	v_mfma_i32_16x16x64_i8 v[54:57], v[62:65], v[186:189], v[54:57]
	v_mfma_i32_16x16x64_i8 v[30:33], v[38:41], v[194:197], v[30:33]
	v_mfma_i32_16x16x64_i8 v[26:29], v[62:65], v[194:197], v[26:29]
	v_mfma_i32_16x16x64_i8 v[14:17], v[38:41], v[202:205], v[14:17]
	v_mfma_i32_16x16x64_i8 v[10:13], v[62:65], v[202:205], v[10:13]
	v_mfma_i32_16x16x64_i8 v[46:49], v[154:157], v[170:173], v[46:49]
	v_mfma_i32_16x16x64_i8 v[22:25], v[146:149], v[190:193], v[22:25]
	v_mfma_i32_16x16x64_i8 v[18:21], v[154:157], v[190:193], v[18:21]
	v_mfma_i32_16x16x64_i8 v[6:9], v[146:149], v[198:201], v[6:9]
	v_mfma_i32_16x16x64_i8 v[2:5], v[154:157], v[198:201], v[2:5]
	v_mfma_i32_16x16x64_i8 v[34:37], v[146:149], v[162:165], v[70:73]
	v_mfma_i32_16x16x64_i8 v[38:41], v[154:157], v[162:165], v[66:69]
	v_mfma_i32_16x16x64_i8 v[42:45], v[146:149], v[170:173], v[50:53]
	v_mfma_i32_16x16x64_i8 v[46:49], v[158:161], v[186:189], v[46:49]
	v_mfma_i32_16x16x64_i8 v[22:25], v[150:153], v[194:197], v[22:25]
	v_mfma_i32_16x16x64_i8 v[18:21], v[158:161], v[194:197], v[18:21]
	v_mfma_i32_16x16x64_i8 v[6:9], v[150:153], v[202:205], v[6:9]
	v_mfma_i32_16x16x64_i8 v[2:5], v[158:161], v[202:205], v[2:5]
	v_mfma_i32_16x16x64_i8 v[34:37], v[150:153], v[166:169], v[34:37]
	v_mfma_i32_16x16x64_i8 v[38:41], v[158:161], v[166:169], v[38:41]
	v_mfma_i32_16x16x64_i8 v[42:45], v[150:153], v[186:189], v[42:45]
	s_barrier
; #define PG8_STAGE(bufoff, gbase, voff) do { _Pragma("unroll") for (int _i = 0; _i < 2; ++_i) \
;         __builtin_amdgcn_global_load_lds((const unsigned*)((const char*)(gbase) + (voff)[_i]), (PG8_LAS unsigned*)(lds + (bufoff) + ldsw + _i * 8192), 16, 0, 0); } while (0)
; #define PG8_LDA(dst, b, h) do { _Pragma("unroll") for (int m = 0; m < 4; ++m) _Pragma("unroll") for (int k = 0; k < 2; ++k) dst[m][k] = *(const PG8_LAS bf16x8*)(lds + PG8_SA(b, h) + aoff + m * 2048 + k * 1024); } while (0)
; #define PG8_LDB(dst, b, h) do { _Pragma("unroll") for (int n = 0; n < 2; ++n) _Pragma("unroll") for (int k = 0; k < 2; ++k) dst[n][k] = *(const PG8_LAS bf16x8*)(lds + PG8_SB(b, h) + boff + n * 2048 + k * 1024); } while (0)
; #define PG8_MMA(ai, bj, At, Bt) do { __builtin_amdgcn_s_setprio(1); _Pragma("unroll") for (int m = 0; m < 4; ++m) _Pragma("unroll") for (int n = 0; n < 2; ++n) _Pragma("unroll") for (int k = 0; k < 2; ++k) \
;         acc[ai][bj][m][n] = mma_<I8>(Bt[n][k], At[m][k], acc[ai][bj][m][n]); __builtin_amdgcn_s_setprio(0); } while (0)
; #define PG8_WAIT_V(n) asm volatile("s_waitcnt vmcnt(" #n ")" ::: "memory")
; #define PG8_WAIT_L(n) asm volatile("s_waitcnt lgkmcnt(" #n ")" ::: "memory")
; #define PG8_BAR __builtin_amdgcn_s_barrier()
; #define PG8_SCHED __builtin_amdgcn_sched_barrier(0)
; template <class Epi, class Sched, bool ALIGN_EPI = false, bool SP2 = false, bool I8 = false>
; __device__ __forceinline__ void gemm_phase(PG8_LAS unsigned char* lds, const Gemm g, const Sched& S, const Epi& E) {
;     ...
;             PG8_LDB(B0, 1, 0); PG8_LDB(B1, 1, 1); PG8_SCHED; PG8_LDA(At, 1, 0); PG8_STAGE(PG8_SA(0, 1), a2 + hstepA, voffA);
;             PG8_WAIT_V(8); PG8_WAIT_L(0); PG8_BAR; PG8_MMA(0, 0, At, B0); PG8_MMA(0, 1, At, B1); PG8_BAR; PG8_SCHED;
;             PG8_LDA(At, 1, 1); PG8_STAGE(PG8_SB(1, 0), b3, voffB); PG8_STAGE(PG8_SB(1, 1), b3 + hstepB, voffB); PG8_STAGE(PG8_SA(1, 0), a3, voffA);
;             PG8_WAIT_V(8); PG8_WAIT_L(0); PG8_BAR; PG8_MMA(1, 0, At, B0); PG8_MMA(1, 1, At, B1); PG8_BAR; PG8_SCHED;
	s_add_i32 s56, 0, 0x18000
	s_add_i32 s57, 0, 0x1c000
	ds_read_b128 v[50:53], v234 offset:16384
	ds_read_b128 v[62:65], v234 offset:17408
	ds_read_b128 v[66:69], v234 offset:18432
	ds_read_b128 v[70:73], v234 offset:19456
	ds_read_b128 v[146:149], v234 offset:32768
	ds_read_b128 v[150:153], v234 offset:33792
	ds_read_b128 v[154:157], v234 offset:34816
	ds_read_b128 v[158:161], v234 offset:35840
	s_add_u32 s36, s36, 0x80000
	s_addc_u32 s37, s37, 0
	s_mov_b32 m0, s45
	ds_read_b128 v[162:165], v235 offset:32768
	ds_read_b128 v[166:169], v235 offset:33792
	ds_read_b128 v[170:173], v235 offset:34816
	ds_read_b128 v[186:189], v235 offset:35840
	ds_read_b128 v[190:193], v235 offset:36864
	ds_read_b128 v[194:197], v235 offset:37888
	ds_read_b128 v[198:201], v235 offset:38912
	ds_read_b128 v[202:205], v235 offset:39936
	global_load_lds_dwordx4 v174, s[36:37]
	s_mov_b32 m0, s46
	s_nop 0
	global_load_lds_dwordx4 v176, s[36:37]
	s_waitcnt vmcnt(8) lgkmcnt(0)
	s_barrier
	v_mfma_i32_16x16x64_i8 v[142:145], v[50:53], v[162:165], v[142:145]
	v_mfma_i32_16x16x64_i8 v[138:141], v[66:69], v[162:165], v[138:141]
	v_mfma_i32_16x16x64_i8 v[126:129], v[50:53], v[170:173], v[126:129]
	v_mfma_i32_16x16x64_i8 v[122:125], v[66:69], v[170:173], v[122:125]
	v_mfma_i32_16x16x64_i8 v[110:113], v[50:53], v[190:193], v[110:113]
	v_mfma_i32_16x16x64_i8 v[106:109], v[66:69], v[190:193], v[106:109]
	v_mfma_i32_16x16x64_i8 v[94:97], v[50:53], v[198:201], v[94:97]
	v_mfma_i32_16x16x64_i8 v[90:93], v[66:69], v[198:201], v[90:93]
	v_mfma_i32_16x16x64_i8 v[142:145], v[62:65], v[166:169], v[142:145]
	v_mfma_i32_16x16x64_i8 v[138:141], v[70:73], v[166:169], v[138:141]
	v_mfma_i32_16x16x64_i8 v[126:129], v[62:65], v[186:189], v[126:129]
	v_mfma_i32_16x16x64_i8 v[122:125], v[70:73], v[186:189], v[122:125]
	v_mfma_i32_16x16x64_i8 v[110:113], v[62:65], v[194:197], v[110:113]
	v_mfma_i32_16x16x64_i8 v[106:109], v[70:73], v[194:197], v[106:109]
	v_mfma_i32_16x16x64_i8 v[94:97], v[62:65], v[202:205], v[94:97]
	v_mfma_i32_16x16x64_i8 v[90:93], v[70:73], v[202:205], v[90:93]
	v_mfma_i32_16x16x64_i8 v[134:137], v[146:149], v[162:165], v[134:137]
	v_mfma_i32_16x16x64_i8 v[130:133], v[154:157], v[162:165], v[130:133]
	v_mfma_i32_16x16x64_i8 v[118:121], v[146:149], v[170:173], v[118:121]
	v_mfma_i32_16x16x64_i8 v[114:117], v[154:157], v[170:173], v[114:117]
	v_mfma_i32_16x16x64_i8 v[102:105], v[146:149], v[190:193], v[102:105]
	v_mfma_i32_16x16x64_i8 v[98:101], v[154:157], v[190:193], v[98:101]
	v_mfma_i32_16x16x64_i8 v[86:89], v[146:149], v[198:201], v[86:89]
	v_mfma_i32_16x16x64_i8 v[82:85], v[154:157], v[198:201], v[82:85]
	v_mfma_i32_16x16x64_i8 v[134:137], v[150:153], v[166:169], v[134:137]
	v_mfma_i32_16x16x64_i8 v[130:133], v[158:161], v[166:169], v[130:133]
	v_mfma_i32_16x16x64_i8 v[118:121], v[150:153], v[186:189], v[118:121]
	v_mfma_i32_16x16x64_i8 v[114:117], v[158:161], v[186:189], v[114:117]
	v_mfma_i32_16x16x64_i8 v[102:105], v[150:153], v[194:197], v[102:105]
	v_mfma_i32_16x16x64_i8 v[98:101], v[158:161], v[194:197], v[98:101]
	v_mfma_i32_16x16x64_i8 v[86:89], v[150:153], v[202:205], v[86:89]
	v_mfma_i32_16x16x64_i8 v[82:85], v[158:161], v[202:205], v[82:85]
	s_barrier
	s_add_i32 s36, s56, s40
	s_add_i32 m0, s36, 0xffffff80
	ds_read_b128 v[162:165], v235 offset:49152
	ds_read_b128 v[166:169], v235 offset:50176
	ds_read_b128 v[170:173], v235 offset:51200
	ds_read_b128 v[186:189], v235 offset:52224
	ds_read_b128 v[190:193], v235 offset:53248
	ds_read_b128 v[194:197], v235 offset:54272
	ds_read_b128 v[198:201], v235 offset:55296
	ds_read_b128 v[202:205], v235 offset:56320
	global_load_lds_dwordx4 v174, s[98:99] offset:128
	s_add_i32 m0, s36, 0x1f80
	s_add_u32 s34, s34, 0x80080
	s_addc_u32 s35, s35, 0
	s_add_i32 s36, s57, s40
	global_load_lds_dwordx4 v176, s[98:99] offset:128
	s_mov_b32 m0, s36
	s_nop 0
	global_load_lds_dwordx4 v174, s[34:35]
	s_add_i32 m0, s36, 0x2000
	s_nop 0
	global_load_lds_dwordx4 v176, s[34:35]
	s_add_i32 m0, s48, 0xffffff80
	s_nop 0
	global_load_lds_dwordx4 v174, s[100:101] offset:128
	s_add_i32 m0, s49, 0xffffff80
	s_nop 0
	global_load_lds_dwordx4 v176, s[100:101] offset:128
	s_waitcnt vmcnt(8) lgkmcnt(0)
	s_barrier
	v_mfma_i32_16x16x64_i8 v[78:81], v[50:53], v[162:165], v[78:81]
	v_mfma_i32_16x16x64_i8 v[74:77], v[66:69], v[162:165], v[74:77]
	v_mfma_i32_16x16x64_i8 v[58:61], v[50:53], v[170:173], v[58:61]
	v_mfma_i32_16x16x64_i8 v[54:57], v[66:69], v[170:173], v[54:57]
	v_mfma_i32_16x16x64_i8 v[30:33], v[50:53], v[190:193], v[30:33]
	v_mfma_i32_16x16x64_i8 v[26:29], v[66:69], v[190:193], v[26:29]
	v_mfma_i32_16x16x64_i8 v[14:17], v[50:53], v[198:201], v[14:17]
	v_mfma_i32_16x16x64_i8 v[10:13], v[66:69], v[198:201], v[10:13]
	v_mfma_i32_16x16x64_i8 v[78:81], v[62:65], v[166:169], v[78:81]
	v_mfma_i32_16x16x64_i8 v[74:77], v[70:73], v[166:169], v[74:77]
	v_mfma_i32_16x16x64_i8 v[58:61], v[62:65], v[186:189], v[58:61]
	v_mfma_i32_16x16x64_i8 v[54:57], v[70:73], v[186:189], v[54:57]
	v_mfma_i32_16x16x64_i8 v[30:33], v[62:65], v[194:197], v[30:33]
	v_mfma_i32_16x16x64_i8 v[26:29], v[70:73], v[194:197], v[26:29]
	v_mfma_i32_16x16x64_i8 v[14:17], v[62:65], v[202:205], v[14:17]
	v_mfma_i32_16x16x64_i8 v[10:13], v[70:73], v[202:205], v[10:13]
	v_mfma_i32_16x16x64_i8 v[34:37], v[146:149], v[162:165], v[34:37]
	v_mfma_i32_16x16x64_i8 v[70:73], v[150:153], v[166:169], v[34:37]
	v_mfma_i32_16x16x64_i8 v[34:37], v[154:157], v[162:165], v[38:41]
	v_mfma_i32_16x16x64_i8 v[66:69], v[158:161], v[166:169], v[34:37]
	v_mfma_i32_16x16x64_i8 v[34:37], v[146:149], v[170:173], v[42:45]
	v_mfma_i32_16x16x64_i8 v[50:53], v[150:153], v[186:189], v[34:37]
	v_mfma_i32_16x16x64_i8 v[34:37], v[154:157], v[170:173], v[46:49]
	v_mfma_i32_16x16x64_i8 v[22:25], v[146:149], v[190:193], v[22:25]
	v_mfma_i32_16x16x64_i8 v[18:21], v[154:157], v[190:193], v[18:21]
	v_mfma_i32_16x16x64_i8 v[6:9], v[146:149], v[198:201], v[6:9]
	v_mfma_i32_16x16x64_i8 v[2:5], v[154:157], v[198:201], v[2:5]
	v_mfma_i32_16x16x64_i8 v[46:49], v[158:161], v[186:189], v[34:37]
	v_mfma_i32_16x16x64_i8 v[22:25], v[150:153], v[194:197], v[22:25]
	v_mfma_i32_16x16x64_i8 v[18:21], v[158:161], v[194:197], v[18:21]
	v_mfma_i32_16x16x64_i8 v[6:9], v[150:153], v[202:205], v[6:9]
	v_mfma_i32_16x16x64_i8 v[2:5], v[158:161], v[202:205], v[2:5]
	s_barrier
	s_add_i32 s55, s55, 2
	s_add_u32 s8, s8, 0x100
	s_addc_u32 s9, s9, 0
	s_add_u32 s33, s33, 0x100
	s_addc_u32 s54, s54, 0
	s_cmp_gt_u32 s55, 29
	s_cbranch_scc0 .LBB0_1721
	s_and_b64 vcc, exec, s[20:21]
	s_cbranch_vccz .LBB0_1724
	s_barrier

; #define PG8_STAGE(bufoff, gbase, voff) do { _Pragma("unroll") for (int _i = 0; _i < 2; ++_i) \
;         __builtin_amdgcn_global_load_lds((const unsigned*)((const char*)(gbase) + (voff)[_i]), (PG8_LAS unsigned*)(lds + (bufoff) + ldsw + _i * 8192), 16, 0, 0); } while (0)
; #define PG8_LDA(dst, b, h) do { _Pragma("unroll") for (int m = 0; m < 4; ++m) _Pragma("unroll") for (int k = 0; k < 2; ++k) dst[m][k] = *(const PG8_LAS bf16x8*)(lds + PG8_SA(b, h) + aoff + m * 2048 + k * 1024); } while (0)
; #define PG8_LDB(dst, b, h) do { _Pragma("unroll") for (int n = 0; n < 2; ++n) _Pragma("unroll") for (int k = 0; k < 2; ++k) dst[n][k] = *(const PG8_LAS bf16x8*)(lds + PG8_SB(b, h) + boff + n * 2048 + k * 1024); } while (0)
; #define PG8_MMA(ai, bj, At, Bt) do { __builtin_amdgcn_s_setprio(1); _Pragma("unroll") for (int m = 0; m < 4; ++m) _Pragma("unroll") for (int n = 0; n < 2; ++n) _Pragma("unroll") for (int k = 0; k < 2; ++k) \
;         acc[ai][bj][m][n] = mma_<I8>(Bt[n][k], At[m][k], acc[ai][bj][m][n]); __builtin_amdgcn_s_setprio(0); } while (0)
; #define PG8_WAIT_V(n) asm volatile("s_waitcnt vmcnt(" #n ")" ::: "memory")
; #define PG8_WAIT_L(n) asm volatile("s_waitcnt lgkmcnt(" #n ")" ::: "memory")
; #define PG8_BAR __builtin_amdgcn_s_barrier()
; #define PG8_SCHED __builtin_amdgcn_sched_barrier(0)
; template <class Epi, class Sched, bool ALIGN_EPI = false, bool SP2 = false, bool I8 = false>
; __device__ __forceinline__ void gemm_phase(PG8_LAS unsigned char* lds, const Gemm g, const Sched& S, const Epi& E) {
;     ...
;             PG8_LDB(B0, 0, 0); PG8_LDB(B1, 0, 1); PG8_SCHED; PG8_LDA(At, 0, 0); PG8_STAGE(PG8_SA(1, 1), a1 + hstepA, voffA);
;             PG8_WAIT_V(8); PG8_WAIT_L(0); PG8_BAR; PG8_MMA(0, 0, At, B0); PG8_MMA(0, 1, At, B1); PG8_BAR; PG8_SCHED;
;             PG8_LDA(At, 0, 1); PG8_STAGE(PG8_SB(0, 0), b2, voffB); PG8_STAGE(PG8_SB(0, 1), b2 + hstepB, voffB); PG8_STAGE(PG8_SA(0, 0), a2, voffA);
;             PG8_WAIT_V(8); PG8_WAIT_L(0); PG8_BAR; PG8_MMA(1, 0, At, B0); PG8_MMA(1, 1, At, B1); PG8_BAR; PG8_SCHED;
.LBB0_2014:
	ds_read_b128 v[118:121], v163
	ds_read_b128 v[126:129], v163 offset:1024
	ds_read_b128 v[130:133], v163 offset:2048
	ds_read_b128 v[134:137], v163 offset:3072
	ds_read_b128 v[168:171], v167
	ds_read_b128 v[176:179], v167 offset:1024
	ds_read_b128 v[180:183], v167 offset:2048
	ds_read_b128 v[184:187], v167 offset:3072
	s_add_u32 s38, s36, 0xfff80080
	s_addc_u32 s39, s37, -1
	s_cmp_eq_u32 s65, 28
	s_cselect_b32 s41, s27, s39
	s_cselect_b32 s40, s61, s38
	s_cselect_b32 s39, s25, s64
	s_cselect_b32 s38, s62, s63
	s_add_i32 m0, s35, 0xc000
	ds_read_b128 v[188:191], v173
	ds_read_b128 v[192:195], v173 offset:1024
	ds_read_b128 v[196:199], v173 offset:2048
	ds_read_b128 v[200:203], v173 offset:3072
	ds_read_b128 v[204:207], v173 offset:4096
	ds_read_b128 v[208:211], v173 offset:5120
	ds_read_b128 v[212:215], v173 offset:6144
	ds_read_b128 v[216:219], v173 offset:7168
	global_load_lds_dwordx4 v154, s[36:37]
	s_add_i32 m0, s35, 0xe000
	s_nop 0
	global_load_lds_dwordx4 v156, s[36:37]
	s_waitcnt vmcnt(8) lgkmcnt(0)
	s_barrier
	v_mfma_i32_16x16x64_i8 v[142:145], v[118:121], v[188:191], v[142:145]
	v_mfma_i32_16x16x64_i8 v[138:141], v[130:133], v[188:191], v[138:141]
	v_mfma_i32_16x16x64_i8 v[110:113], v[118:121], v[196:199], v[110:113]
	v_mfma_i32_16x16x64_i8 v[106:109], v[130:133], v[196:199], v[106:109]
	v_mfma_i32_16x16x64_i8 v[94:97], v[118:121], v[204:207], v[94:97]
	v_mfma_i32_16x16x64_i8 v[90:93], v[130:133], v[204:207], v[90:93]
	v_mfma_i32_16x16x64_i8 v[78:81], v[118:121], v[212:215], v[78:81]
	v_mfma_i32_16x16x64_i8 v[74:77], v[130:133], v[212:215], v[74:77]
	v_mfma_i32_16x16x64_i8 v[142:145], v[126:129], v[192:195], v[142:145]
	v_mfma_i32_16x16x64_i8 v[138:141], v[134:137], v[192:195], v[138:141]
	v_mfma_i32_16x16x64_i8 v[110:113], v[126:129], v[200:203], v[110:113]
	v_mfma_i32_16x16x64_i8 v[106:109], v[134:137], v[200:203], v[106:109]
	v_mfma_i32_16x16x64_i8 v[94:97], v[126:129], v[208:211], v[94:97]
	v_mfma_i32_16x16x64_i8 v[90:93], v[134:137], v[208:211], v[90:93]
	v_mfma_i32_16x16x64_i8 v[78:81], v[126:129], v[216:219], v[78:81]
	v_mfma_i32_16x16x64_i8 v[74:77], v[134:137], v[216:219], v[74:77]
	v_mfma_i32_16x16x64_i8 v[122:125], v[168:171], v[188:191], v[122:125]
	v_mfma_i32_16x16x64_i8 v[114:117], v[180:183], v[188:191], v[114:117]
	v_mfma_i32_16x16x64_i8 v[102:105], v[168:171], v[196:199], v[102:105]
	v_mfma_i32_16x16x64_i8 v[98:101], v[180:183], v[196:199], v[98:101]
	v_mfma_i32_16x16x64_i8 v[86:89], v[168:171], v[204:207], v[86:89]
	v_mfma_i32_16x16x64_i8 v[82:85], v[180:183], v[204:207], v[82:85]
	v_mfma_i32_16x16x64_i8 v[70:73], v[168:171], v[212:215], v[70:73]
	v_mfma_i32_16x16x64_i8 v[66:69], v[180:183], v[212:215], v[66:69]
	v_mfma_i32_16x16x64_i8 v[122:125], v[176:179], v[192:195], v[122:125]
	v_mfma_i32_16x16x64_i8 v[114:117], v[184:187], v[192:195], v[114:117]
	v_mfma_i32_16x16x64_i8 v[102:105], v[176:179], v[200:203], v[102:105]
	v_mfma_i32_16x16x64_i8 v[98:101], v[184:187], v[200:203], v[98:101]
	v_mfma_i32_16x16x64_i8 v[86:89], v[176:179], v[208:211], v[86:89]
	v_mfma_i32_16x16x64_i8 v[82:85], v[184:187], v[208:211], v[82:85]
	v_mfma_i32_16x16x64_i8 v[70:73], v[176:179], v[216:219], v[70:73]
	v_mfma_i32_16x16x64_i8 v[66:69], v[184:187], v[216:219], v[66:69]
	s_barrier
	s_add_i32 s66, s54, s46
	s_mov_b64 s[98:99], s[38:39]
	s_mov_b32 m0, s66
	ds_read_b128 v[188:191], v173 offset:16384
	ds_read_b128 v[192:195], v173 offset:17408
	ds_read_b128 v[196:199], v173 offset:18432
	ds_read_b128 v[200:203], v173 offset:19456
	ds_read_b128 v[204:207], v173 offset:20480
	ds_read_b128 v[208:211], v173 offset:21504
	ds_read_b128 v[212:215], v173 offset:22528
	ds_read_b128 v[216:219], v173 offset:23552
	global_load_lds_dwordx4 v148, s[38:39]
	s_add_i32 m0, s66, 0x2000
	s_add_u32 s66, s38, 0x80000
	s_mov_b64 s[98:99], s[38:39]
	s_addc_u32 s67, s39, 0
	s_add_i32 s68, s55, s46
	global_load_lds_dwordx4 v152, s[38:39]
	s_mov_b32 m0, s68
	s_mov_b64 s[100:101], s[40:41]
	global_load_lds_dwordx4 v148, s[66:67]
	s_add_i32 m0, s68, 0x2000
	s_nop 0
	global_load_lds_dwordx4 v152, s[66:67]
	s_mov_b64 s[100:101], s[40:41]
	s_mov_b32 m0, s35
	s_nop 0
	global_load_lds_dwordx4 v146, s[40:41]
	s_mov_b32 m0, s47
	s_nop 0
	global_load_lds_dwordx4 v150, s[40:41]
	s_waitcnt vmcnt(8) lgkmcnt(0)
	s_barrier
	v_mfma_i32_16x16x64_i8 v[62:65], v[118:121], v[188:191], v[62:65]
	v_mfma_i32_16x16x64_i8 v[58:61], v[130:133], v[188:191], v[58:61]
	v_mfma_i32_16x16x64_i8 v[46:49], v[118:121], v[196:199], v[46:49]
	v_mfma_i32_16x16x64_i8 v[42:45], v[130:133], v[196:199], v[42:45]
	v_mfma_i32_16x16x64_i8 v[30:33], v[118:121], v[204:207], v[30:33]
	v_mfma_i32_16x16x64_i8 v[26:29], v[130:133], v[204:207], v[26:29]
	v_mfma_i32_16x16x64_i8 v[14:17], v[118:121], v[212:215], v[14:17]
	v_mfma_i32_16x16x64_i8 v[10:13], v[130:133], v[212:215], v[10:13]
	v_mfma_i32_16x16x64_i8 v[62:65], v[126:129], v[192:195], v[62:65]
	v_mfma_i32_16x16x64_i8 v[58:61], v[134:137], v[192:195], v[58:61]
	v_mfma_i32_16x16x64_i8 v[46:49], v[126:129], v[200:203], v[46:49]
	v_mfma_i32_16x16x64_i8 v[42:45], v[134:137], v[200:203], v[42:45]
	v_mfma_i32_16x16x64_i8 v[30:33], v[126:129], v[208:211], v[30:33]
	v_mfma_i32_16x16x64_i8 v[26:29], v[134:137], v[208:211], v[26:29]
	v_mfma_i32_16x16x64_i8 v[14:17], v[126:129], v[216:219], v[14:17]
	v_mfma_i32_16x16x64_i8 v[10:13], v[134:137], v[216:219], v[10:13]
	v_mfma_i32_16x16x64_i8 v[54:57], v[168:171], v[188:191], v[54:57]
	v_mfma_i32_16x16x64_i8 v[50:53], v[180:183], v[188:191], v[50:53]
	v_mfma_i32_16x16x64_i8 v[38:41], v[168:171], v[196:199], v[38:41]
	v_mfma_i32_16x16x64_i8 v[34:37], v[180:183], v[196:199], v[34:37]
	v_mfma_i32_16x16x64_i8 v[22:25], v[168:171], v[204:207], v[22:25]
	v_mfma_i32_16x16x64_i8 v[18:21], v[180:183], v[204:207], v[18:21]
	v_mfma_i32_16x16x64_i8 v[6:9], v[168:171], v[212:215], v[6:9]
	v_mfma_i32_16x16x64_i8 v[2:5], v[180:183], v[212:215], v[2:5]
	v_mfma_i32_16x16x64_i8 v[54:57], v[176:179], v[192:195], v[54:57]
	v_mfma_i32_16x16x64_i8 v[50:53], v[184:187], v[192:195], v[50:53]
	v_mfma_i32_16x16x64_i8 v[38:41], v[176:179], v[200:203], v[38:41]
	v_mfma_i32_16x16x64_i8 v[34:37], v[184:187], v[200:203], v[34:37]
	v_mfma_i32_16x16x64_i8 v[22:25], v[176:179], v[208:211], v[22:25]
	v_mfma_i32_16x16x64_i8 v[18:21], v[184:187], v[208:211], v[18:21]
	v_mfma_i32_16x16x64_i8 v[6:9], v[176:179], v[216:219], v[6:9]
	v_mfma_i32_16x16x64_i8 v[2:5], v[184:187], v[216:219], v[2:5]
	s_barrier
; #define PG8_STAGE(bufoff, gbase, voff) do { _Pragma("unroll") for (int _i = 0; _i < 2; ++_i) \
;         __builtin_amdgcn_global_load_lds((const unsigned*)((const char*)(gbase) + (voff)[_i]), (PG8_LAS unsigned*)(lds + (bufoff) + ldsw + _i * 8192), 16, 0, 0); } while (0)
; #define PG8_LDA(dst, b, h) do { _Pragma("unroll") for (int m = 0; m < 4; ++m) _Pragma("unroll") for (int k = 0; k < 2; ++k) dst[m][k] = *(const PG8_LAS bf16x8*)(lds + PG8_SA(b, h) + aoff + m * 2048 + k * 1024); } while (0)
; #define PG8_LDB(dst, b, h) do { _Pragma("unroll") for (int n = 0; n < 2; ++n) _Pragma("unroll") for (int k = 0; k < 2; ++k) dst[n][k] = *(const PG8_LAS bf16x8*)(lds + PG8_SB(b, h) + boff + n * 2048 + k * 1024); } while (0)
; #define PG8_MMA(ai, bj, At, Bt) do { __builtin_amdgcn_s_setprio(1); _Pragma("unroll") for (int m = 0; m < 4; ++m) _Pragma("unroll") for (int n = 0; n < 2; ++n) _Pragma("unroll") for (int k = 0; k < 2; ++k) \
;         acc[ai][bj][m][n] = mma_<I8>(Bt[n][k], At[m][k], acc[ai][bj][m][n]); __builtin_amdgcn_s_setprio(0); } while (0)
; #define PG8_WAIT_V(n) asm volatile("s_waitcnt vmcnt(" #n ")" ::: "memory")
; #define PG8_WAIT_L(n) asm volatile("s_waitcnt lgkmcnt(" #n ")" ::: "memory")
; #define PG8_BAR __builtin_amdgcn_s_barrier()
; #define PG8_SCHED __builtin_amdgcn_sched_barrier(0)
; template <class Epi, class Sched, bool ALIGN_EPI = false, bool SP2 = false, bool I8 = false>
; __device__ __forceinline__ void gemm_phase(PG8_LAS unsigned char* lds, const Gemm g, const Sched& S, const Epi& E) {
;     ...
;             PG8_LDB(B0, 1, 0); PG8_LDB(B1, 1, 1); PG8_SCHED; PG8_LDA(At, 1, 0); PG8_STAGE(PG8_SA(0, 1), a2 + hstepA, voffA);
;             PG8_WAIT_V(8); PG8_WAIT_L(0); PG8_BAR; PG8_MMA(0, 0, At, B0); PG8_MMA(0, 1, At, B1); PG8_BAR; PG8_SCHED;
;             PG8_LDA(At, 1, 1); PG8_STAGE(PG8_SB(1, 0), b3, voffB); PG8_STAGE(PG8_SB(1, 1), b3 + hstepB, voffB); PG8_STAGE(PG8_SA(1, 0), a3, voffA);
;             PG8_WAIT_V(8); PG8_WAIT_L(0); PG8_BAR; PG8_MMA(1, 0, At, B0); PG8_MMA(1, 1, At, B1); PG8_BAR; PG8_SCHED;
	s_add_i32 s66, 0, 0x18000
	s_add_i32 s67, 0, 0x1c000
	ds_read_b128 v[118:121], v167 offset:16384
	ds_read_b128 v[126:129], v167 offset:17408
	ds_read_b128 v[130:133], v167 offset:18432
	ds_read_b128 v[134:137], v167 offset:19456
	ds_read_b128 v[168:171], v167 offset:32768
	ds_read_b128 v[176:179], v167 offset:33792
	ds_read_b128 v[180:183], v167 offset:34816
	ds_read_b128 v[184:187], v167 offset:35840
	s_add_u32 s40, s40, 0x80000
	s_addc_u32 s41, s41, 0
	s_mov_b32 m0, s48
	ds_read_b128 v[188:191], v173 offset:32768
	ds_read_b128 v[192:195], v173 offset:33792
	ds_read_b128 v[196:199], v173 offset:34816
	ds_read_b128 v[200:203], v173 offset:35840
	ds_read_b128 v[204:207], v173 offset:36864
	ds_read_b128 v[208:211], v173 offset:37888
	ds_read_b128 v[212:215], v173 offset:38912
	ds_read_b128 v[216:219], v173 offset:39936
	global_load_lds_dwordx4 v146, s[40:41]
	s_mov_b32 m0, s49
	s_nop 0
	global_load_lds_dwordx4 v150, s[40:41]
	s_waitcnt vmcnt(8) lgkmcnt(0)
	s_barrier
	v_mfma_i32_16x16x64_i8 v[142:145], v[118:121], v[188:191], v[142:145]
	v_mfma_i32_16x16x64_i8 v[138:141], v[130:133], v[188:191], v[138:141]
	v_mfma_i32_16x16x64_i8 v[110:113], v[118:121], v[196:199], v[110:113]
	v_mfma_i32_16x16x64_i8 v[106:109], v[130:133], v[196:199], v[106:109]
	v_mfma_i32_16x16x64_i8 v[94:97], v[118:121], v[204:207], v[94:97]
	v_mfma_i32_16x16x64_i8 v[90:93], v[130:133], v[204:207], v[90:93]
	v_mfma_i32_16x16x64_i8 v[78:81], v[118:121], v[212:215], v[78:81]
	v_mfma_i32_16x16x64_i8 v[74:77], v[130:133], v[212:215], v[74:77]
	v_mfma_i32_16x16x64_i8 v[142:145], v[126:129], v[192:195], v[142:145]
	v_mfma_i32_16x16x64_i8 v[138:141], v[134:137], v[192:195], v[138:141]
	v_mfma_i32_16x16x64_i8 v[110:113], v[126:129], v[200:203], v[110:113]
	v_mfma_i32_16x16x64_i8 v[106:109], v[134:137], v[200:203], v[106:109]
	v_mfma_i32_16x16x64_i8 v[94:97], v[126:129], v[208:211], v[94:97]
	v_mfma_i32_16x16x64_i8 v[90:93], v[134:137], v[208:211], v[90:93]
	v_mfma_i32_16x16x64_i8 v[78:81], v[126:129], v[216:219], v[78:81]
	v_mfma_i32_16x16x64_i8 v[74:77], v[134:137], v[216:219], v[74:77]
	v_mfma_i32_16x16x64_i8 v[122:125], v[168:171], v[188:191], v[122:125]
	v_mfma_i32_16x16x64_i8 v[114:117], v[180:183], v[188:191], v[114:117]
	v_mfma_i32_16x16x64_i8 v[102:105], v[168:171], v[196:199], v[102:105]
	v_mfma_i32_16x16x64_i8 v[98:101], v[180:183], v[196:199], v[98:101]
	v_mfma_i32_16x16x64_i8 v[86:89], v[168:171], v[204:207], v[86:89]
	v_mfma_i32_16x16x64_i8 v[82:85], v[180:183], v[204:207], v[82:85]
	v_mfma_i32_16x16x64_i8 v[70:73], v[168:171], v[212:215], v[70:73]
	v_mfma_i32_16x16x64_i8 v[66:69], v[180:183], v[212:215], v[66:69]
	v_mfma_i32_16x16x64_i8 v[122:125], v[176:179], v[192:195], v[122:125]
	v_mfma_i32_16x16x64_i8 v[114:117], v[184:187], v[192:195], v[114:117]
	v_mfma_i32_16x16x64_i8 v[102:105], v[176:179], v[200:203], v[102:105]
	v_mfma_i32_16x16x64_i8 v[98:101], v[184:187], v[200:203], v[98:101]
	v_mfma_i32_16x16x64_i8 v[86:89], v[176:179], v[208:211], v[86:89]
	v_mfma_i32_16x16x64_i8 v[82:85], v[184:187], v[208:211], v[82:85]
	v_mfma_i32_16x16x64_i8 v[70:73], v[176:179], v[216:219], v[70:73]
	v_mfma_i32_16x16x64_i8 v[66:69], v[184:187], v[216:219], v[66:69]
	s_barrier
	s_add_i32 s40, s66, s46
	s_add_i32 m0, s40, 0xffffff80
	ds_read_b128 v[188:191], v173 offset:49152
	ds_read_b128 v[192:195], v173 offset:50176
	ds_read_b128 v[196:199], v173 offset:51200
	ds_read_b128 v[200:203], v173 offset:52224
	ds_read_b128 v[204:207], v173 offset:53248
	ds_read_b128 v[208:211], v173 offset:54272
	ds_read_b128 v[212:215], v173 offset:55296
	ds_read_b128 v[216:219], v173 offset:56320
	global_load_lds_dwordx4 v148, s[98:99] offset:128
	s_add_i32 m0, s40, 0x1f80
	s_add_u32 s38, s38, 0x80080
	s_addc_u32 s39, s39, 0
	s_add_i32 s40, s67, s46
	global_load_lds_dwordx4 v152, s[98:99] offset:128
	s_mov_b32 m0, s40
	s_nop 0
	global_load_lds_dwordx4 v148, s[38:39]
	s_add_i32 m0, s40, 0x2000
	s_nop 0
	global_load_lds_dwordx4 v152, s[38:39]
	s_add_i32 m0, s51, 0xffffff80
	s_nop 0
	global_load_lds_dwordx4 v146, s[100:101] offset:128
	s_add_i32 m0, s52, 0xffffff80
	s_nop 0
	global_load_lds_dwordx4 v150, s[100:101] offset:128
	s_waitcnt vmcnt(8) lgkmcnt(0)
	s_barrier
	v_mfma_i32_16x16x64_i8 v[62:65], v[118:121], v[188:191], v[62:65]
	v_mfma_i32_16x16x64_i8 v[58:61], v[130:133], v[188:191], v[58:61]
	v_mfma_i32_16x16x64_i8 v[46:49], v[118:121], v[196:199], v[46:49]
	v_mfma_i32_16x16x64_i8 v[42:45], v[130:133], v[196:199], v[42:45]
	v_mfma_i32_16x16x64_i8 v[30:33], v[118:121], v[204:207], v[30:33]
	v_mfma_i32_16x16x64_i8 v[26:29], v[130:133], v[204:207], v[26:29]
	v_mfma_i32_16x16x64_i8 v[14:17], v[118:121], v[212:215], v[14:17]
	v_mfma_i32_16x16x64_i8 v[10:13], v[130:133], v[212:215], v[10:13]
	v_mfma_i32_16x16x64_i8 v[62:65], v[126:129], v[192:195], v[62:65]
	v_mfma_i32_16x16x64_i8 v[58:61], v[134:137], v[192:195], v[58:61]
	v_mfma_i32_16x16x64_i8 v[46:49], v[126:129], v[200:203], v[46:49]
	v_mfma_i32_16x16x64_i8 v[42:45], v[134:137], v[200:203], v[42:45]
	v_mfma_i32_16x16x64_i8 v[30:33], v[126:129], v[208:211], v[30:33]
	v_mfma_i32_16x16x64_i8 v[26:29], v[134:137], v[208:211], v[26:29]
	v_mfma_i32_16x16x64_i8 v[14:17], v[126:129], v[216:219], v[14:17]
	v_mfma_i32_16x16x64_i8 v[10:13], v[134:137], v[216:219], v[10:13]
	v_mfma_i32_16x16x64_i8 v[54:57], v[168:171], v[188:191], v[54:57]
	v_mfma_i32_16x16x64_i8 v[50:53], v[180:183], v[188:191], v[50:53]
	v_mfma_i32_16x16x64_i8 v[38:41], v[168:171], v[196:199], v[38:41]
	v_mfma_i32_16x16x64_i8 v[34:37], v[180:183], v[196:199], v[34:37]
	v_mfma_i32_16x16x64_i8 v[22:25], v[168:171], v[204:207], v[22:25]
	v_mfma_i32_16x16x64_i8 v[18:21], v[180:183], v[204:207], v[18:21]
	v_mfma_i32_16x16x64_i8 v[6:9], v[168:171], v[212:215], v[6:9]
	v_mfma_i32_16x16x64_i8 v[2:5], v[180:183], v[212:215], v[2:5]
	v_mfma_i32_16x16x64_i8 v[54:57], v[176:179], v[192:195], v[54:57]
	v_mfma_i32_16x16x64_i8 v[50:53], v[184:187], v[192:195], v[50:53]
	v_mfma_i32_16x16x64_i8 v[38:41], v[176:179], v[200:203], v[38:41]
	v_mfma_i32_16x16x64_i8 v[34:37], v[184:187], v[200:203], v[34:37]
	v_mfma_i32_16x16x64_i8 v[22:25], v[176:179], v[208:211], v[22:25]
	v_mfma_i32_16x16x64_i8 v[18:21], v[184:187], v[208:211], v[18:21]
	v_mfma_i32_16x16x64_i8 v[6:9], v[176:179], v[216:219], v[6:9]
	v_mfma_i32_16x16x64_i8 v[2:5], v[184:187], v[216:219], v[2:5]
	s_barrier
	s_add_i32 s65, s65, 2
	s_add_u32 s36, s36, 0x100
	s_addc_u32 s37, s37, 0
	s_add_u32 s63, s63, 0x100
	s_addc_u32 s64, s64, 0
	s_cmp_gt_u32 s65, 29
	s_cbranch_scc0 .LBB0_2014
	s_and_b64 vcc, exec, s[14:15]
	s_cbranch_vccz .LBB0_2017
	s_barrier
;     __device__ __forceinline__ void operator()(const i32x4 (&acc)[2][2][4][2], const Unit& u, int wr, int wc, int fr, int fq) const {
;         const int row0 = u.pm * BM + wr * 64 + fr, col0 = u.pn * BM + wc * 32 + 8 * fq;
;         f32x4 sv[2][2];
; #pragma unroll
;         for (int bj = 0; bj < 2; ++bj)
; #pragma unroll
;             for (int n = 0; n < 2; ++n) sv[bj][n] = *(const f32x4*)(sw + col0 + bj * HALF + 4 * n);
;         float rsv[2][4];
; #pragma unroll
;         for (int ai = 0; ai < 2; ++ai)
; #pragma unroll
;             for (int m = 0; m < 4; ++m) { const int r = row0 + ai * HALF + m * 16; rsv[ai][m] = __builtin_amdgcn_rsqf(ss[r] * (1.0f / 4096.0f) + 1e-6f) * sx[r]; }
; #pragma unroll
;         for (int ai = 0; ai < 2; ++ai)
; #pragma unroll
;             for (int m = 0; m < 4; ++m) { const int r = row0 + ai * HALF + m * 16; const float rs = rsv[ai][m]; bf16_t* rowp = O + (size_t)r * ldc + col0;
; #pragma unroll
;                 for (int bj = 0; bj < 2; ++bj) { f32x4 v0 = __builtin_convertvector(acc[ai][bj][m][0], f32x4) * rs * sv[bj][0], v1 = __builtin_convertvector(acc[ai][bj][m][1], f32x4) * rs * sv[bj][1];
.LBB0_2017:
	v_mov_b32_e32 v136, v0
	v_cvt_f32_i32_e32 v187, v139
	v_ashrrev_i32_e32 v118, 2, v136
	v_and_b32_e32 v118, 0xffffffc0, v118
	v_lshl_add_u32 v118, s34, 8, v118
	v_and_or_b32 v176, v136, 15, v118
	v_ashrrev_i32_e32 v177, 31, v176
	v_or_b32_e32 v180, 16, v176
	v_or_b32_e32 v164, 48, v176
	v_lshlrev_b64 v[118:119], 2, v[176:177]
	v_ashrrev_i32_e32 v181, 31, v180
	v_or_b32_e32 v170, 32, v176
	v_ashrrev_i32_e32 v165, 31, v164
	v_lshl_add_u64 v[120:121], s[6:7], 0, v[118:119]
	v_lshlrev_b64 v[126:127], 2, v[180:181]
	v_ashrrev_i32_e32 v171, 31, v170
	v_lshlrev_b64 v[134:135], 2, v[164:165]
	v_lshl_add_u64 v[118:119], s[8:9], 0, v[118:119]
	v_lshl_add_u64 v[128:129], s[6:7], 0, v[126:127]
	v_lshlrev_b64 v[130:131], 2, v[170:171]
	global_load_dword v162, v[120:121], off
	global_load_dword v166, v[120:121], off offset:512
	global_load_dword v172, v[118:119], off offset:512
	global_load_dword v175, v[120:121], off offset:576
	global_load_dword v189, v[118:119], off offset:576
	global_load_dword v188, v[120:121], off offset:640
	global_load_dword v190, v[120:121], off offset:704
	v_lshl_add_u64 v[120:121], s[6:7], 0, v[134:135]
	v_lshl_add_u64 v[132:133], s[6:7], 0, v[130:131]
	global_load_dword v191, v[128:129], off
	global_load_dword v192, v[132:133], off
	global_load_dword v193, v[120:121], off
	global_load_dword v194, v[118:119], off
	v_lshl_add_u64 v[120:121], s[8:9], 0, v[126:127]
	v_lshl_add_u64 v[126:127], s[8:9], 0, v[130:131]
	v_lshl_add_u64 v[128:129], s[8:9], 0, v[134:135]
	global_load_dword v195, v[120:121], off
	global_load_dword v196, v[126:127], off
	global_load_dword v197, v[128:129], off
	global_load_dword v198, v[118:119], off offset:640
	global_load_dword v199, v[118:119], off offset:704
	v_lshrrev_b32_e32 v118, 1, v136
	v_and_b32_e32 v118, 0x78, v118
	v_lshl_or_b32 v168, s60, 8, v118
	v_ashrrev_i32_e32 v169, 31, v168
	v_lshl_add_u64 v[118:119], v[168:169], 2, s[10:11]
	global_load_dwordx4 v[134:137], v[118:119], off
	global_load_dwordx4 v[130:133], v[118:119], off offset:16
	global_load_dwordx4 v[126:129], v[118:119], off offset:512
	s_nop 0
	global_load_dwordx4 v[118:121], v[118:119], off offset:528
	v_cvt_f32_i32_e32 v186, v138
	v_lshlrev_b64 v[138:139], 15, v[176:177]
	v_lshlrev_b64 v[168:169], 1, v[168:169]
	v_lshl_add_u64 v[138:139], s[2:3], 0, v[138:139]
	v_cvt_f32_i32_e32 v185, v141
	v_cvt_f32_i32_e32 v184, v140
	v_lshl_add_u64 v[140:141], v[138:139], 0, v[168:169]
	v_cvt_f32_i32_e32 v179, v145
	v_cvt_f32_i32_e32 v178, v144
	v_cvt_f32_i32_e32 v183, v143
	v_cvt_f32_i32_e32 v182, v142
	v_cvt_f32_i32_e32 v117, v117
	v_cvt_f32_i32_e32 v115, v115
	v_cvt_f32_i32_e32 v114, v114
	v_cvt_f32_i32_e32 v116, v116
	v_cvt_f32_i32_e32 v125, v125
	v_cvt_f32_i32_e32 v123, v123
	v_cvt_f32_i32_e32 v122, v122
	v_cvt_f32_i32_e32 v124, v124
	v_cvt_f32_i32_e32 v107, v107
	v_cvt_f32_i32_e32 v106, v106
	v_cvt_f32_i32_e32 v111, v111
	v_cvt_f32_i32_e32 v110, v110
	v_cvt_f32_i32_e32 v109, v109
	v_cvt_f32_i32_e32 v108, v108
	v_cvt_f32_i32_e32 v113, v113
	v_cvt_f32_i32_e32 v112, v112
	v_cvt_f32_i32_e32 v101, v101
	v_cvt_f32_i32_e32 v99, v99
	v_cvt_f32_i32_e32 v98, v98
	v_cvt_f32_i32_e32 v100, v100
	v_cvt_f32_i32_e32 v105, v105
	v_cvt_f32_i32_e32 v103, v103
	v_cvt_f32_i32_e32 v102, v102
	v_cvt_f32_i32_e32 v104, v104
	v_cvt_f32_i32_e32 v91, v91
	v_cvt_f32_i32_e32 v90, v90
	v_cvt_f32_i32_e32 v95, v95
	v_cvt_f32_i32_e32 v94, v94
	v_cvt_f32_i32_e32 v93, v93
	v_cvt_f32_i32_e32 v92, v92
	v_cvt_f32_i32_e32 v97, v97
	v_cvt_f32_i32_e32 v96, v96
	v_cvt_f32_i32_e32 v85, v85
	v_cvt_f32_i32_e32 v83, v83
	v_cvt_f32_i32_e32 v82, v82
	v_cvt_f32_i32_e32 v84, v84
	v_cvt_f32_i32_e32 v89, v89
	v_cvt_f32_i32_e32 v87, v87
	v_cvt_f32_i32_e32 v86, v86
	v_cvt_f32_i32_e32 v88, v88
	v_cvt_f32_i32_e32 v75, v75
	v_cvt_f32_i32_e32 v74, v74
	v_cvt_f32_i32_e32 v79, v79
	v_cvt_f32_i32_e32 v78, v78
	v_cvt_f32_i32_e32 v77, v77
	v_cvt_f32_i32_e32 v76, v76
	v_cvt_f32_i32_e32 v81, v81
	v_cvt_f32_i32_e32 v80, v80
	v_cvt_f32_i32_e32 v69, v69
	s_waitcnt vmcnt(0)
	v_fmamk_f32 v138, v162, 0x39800000, v174
	v_fmamk_f32 v139, v166, 0x39800000, v174
	v_rsq_f32_e32 v138, v138
	v_rsq_f32_e32 v139, v139
	v_fmamk_f32 v142, v175, 0x39800000, v174
	v_fmamk_f32 v143, v188, 0x39800000, v174
	v_fmamk_f32 v145, v191, 0x39800000, v174
	v_fmamk_f32 v162, v192, 0x39800000, v174
	v_rsq_f32_e32 v176, v162
	v_rsq_f32_e32 v145, v145
	v_mul_f32_e32 v188, v194, v138
	v_fmamk_f32 v144, v190, 0x39800000, v174
	v_mul_f32_e32 v162, v172, v139
	v_mul_f32_e32 v172, v196, v176
	v_pk_mul_f32 v[176:177], v[188:189], v[182:183] op_sel_hi:[0,1]
	v_pk_mul_f32 v[178:179], v[188:189], v[178:179] op_sel_hi:[0,1]
	v_rsq_f32_e32 v142, v142
	v_rsq_f32_e32 v143, v143
	v_rsq_f32_e32 v175, v144
	v_pk_mul_f32 v[178:179], v[136:137], v[178:179]
	v_pk_mul_f32 v[176:177], v[134:135], v[176:177]
	v_pk_mul_f32 v[114:115], v[188:189], v[114:115] op_sel_hi:[0,1]
	v_pk_mul_f32 v[116:117], v[188:189], v[116:117] op_sel_hi:[0,1]
	v_pk_mul_f32 v[184:185], v[188:189], v[184:185] op_sel_hi:[0,1]
	v_max_f32_e32 v139, 0, v176
	v_max_f32_e32 v176, 0, v178
	v_pk_mul_f32 v[122:123], v[188:189], v[122:123] op_sel_hi:[0,1]
	v_pk_mul_f32 v[124:125], v[188:189], v[124:125] op_sel_hi:[0,1]
	v_pk_mul_f32 v[116:117], v[120:121], v[116:117]
	v_pk_mul_f32 v[114:115], v[118:119], v[114:115]
	v_mul_f32_e32 v190, v195, v145
	v_pk_mul_f32 v[182:183], v[188:189], v[186:187] op_sel_hi:[0,1]
	v_pk_mul_f32 v[184:185], v[132:133], v[184:185]
	v_max_f32_e32 v145, 0, v177
	v_mul_f32_e32 v139, v139, v139
	v_mul_f32_e32 v178, v176, v176
	v_max_f32_e32 v176, 0, v179
	v_pk_mul_f32 v[124:125], v[128:129], v[124:125]
	v_pk_mul_f32 v[122:123], v[126:127], v[122:123]
; __device__ __forceinline__ u32x4 pack8(const f32x4 v0, const f32x4 v1) { u32x4 w; w.x = cvt_pk_bf16(v0[0], v0[1]); w.y = cvt_pk_bf16(v0[2], v0[3]); w.z = cvt_pk_bf16(v1[0], v1[1]); w.w = cvt_pk_bf16(v1[2], v1[3]); return w; }
;     __device__ __forceinline__ void operator()(const i32x4 (&acc)[2][2][4][2], const Unit& u, int wr, int wc, int fr, int fq) const {
;     ...
;         for (int ai = 0; ai < 2; ++ai)
; #pragma unroll
;             for (int m = 0; m < 4; ++m) { const int r = row0 + ai * HALF + m * 16; const float rs = rsv[ai][m]; bf16_t* rowp = O + (size_t)r * ldc + col0;
; #pragma unroll
;                 for (int bj = 0; bj < 2; ++bj) { f32x4 v0 = __builtin_convertvector(acc[ai][bj][m][0], f32x4) * rs * sv[bj][0], v1 = __builtin_convertvector(acc[ai][bj][m][1], f32x4) * rs * sv[bj][1];
; #pragma unroll
;                     for (int j = 0; j < 4; ++j) { const float a = v0[j] > 0.f ? v0[j] : 0.f, b = v1[j] > 0.f ? v1[j] : 0.f; v0[j] = a * a; v1[j] = b * b; }
;                     *(u32x4*)(rowp + bj * HALF) = pack8(v0, v1); } }
	v_max_f32_e32 v114, 0, v114
	v_max_f32_e32 v115, 0, v115
	v_max_f32_e32 v116, 0, v116
	v_pk_mul_f32 v[182:183], v[130:131], v[182:183]
	v_mul_f32_e32 v145, v145, v145
	v_max_f32_e32 v177, 0, v184
	v_mul_f32_e32 v179, v176, v176
	v_cvt_pk_bf16_f32 v176, v139, v145
	v_mul_f32_e32 v139, v114, v114
	v_max_f32_e32 v114, 0, v123
	v_mul_f32_e32 v123, v115, v115
	v_max_f32_e32 v115, 0, v124
	v_mul_f32_e32 v124, v116, v116
	v_max_f32_e32 v116, 0, v125
	v_pk_mul_f32 v[106:107], v[190:191], v[106:107] op_sel_hi:[0,1]
	v_mul_f32_e32 v144, v189, v142
	v_mul_f32_e32 v142, v198, v143
	v_mul_f32_e32 v138, v199, v175
	v_max_f32_e32 v143, 0, v182
	v_max_f32_e32 v175, 0, v183
	v_mul_f32_e32 v182, v177, v177
	v_max_f32_e32 v177, 0, v185
	v_max_f32_e32 v122, 0, v122
	v_mul_f32_e32 v114, v114, v114
	v_mul_f32_e32 v115, v115, v115
	v_max_f32_e32 v117, 0, v117
	v_mul_f32_e32 v116, v116, v116
	v_pk_mul_f32 v[110:111], v[190:191], v[110:111] op_sel_hi:[0,1]
	v_pk_mul_f32 v[108:109], v[190:191], v[108:109] op_sel_hi:[0,1]
	v_pk_mul_f32 v[106:107], v[130:131], v[106:107]
	v_mul_f32_e32 v143, v143, v143
	v_mul_f32_e32 v175, v175, v175
	v_mul_f32_e32 v183, v177, v177
	v_cvt_pk_bf16_f32 v177, v178, v179
	v_cvt_pk_bf16_f32 v178, v143, v175
	v_cvt_pk_bf16_f32 v179, v182, v183
	global_store_dwordx4 v[140:141], v[176:179], off
	v_mul_f32_e32 v122, v122, v122
	v_mul_f32_e32 v117, v117, v117
	v_cvt_pk_bf16_f32 v114, v122, v114
	v_cvt_pk_bf16_f32 v115, v115, v116
	v_cvt_pk_bf16_f32 v116, v139, v123
	v_pk_mul_f32 v[112:113], v[190:191], v[112:113] op_sel_hi:[0,1]
	v_pk_mul_f32 v[110:111], v[134:135], v[110:111]
	v_pk_mul_f32 v[108:109], v[132:133], v[108:109]
	v_max_f32_e32 v106, 0, v106
	v_cvt_pk_bf16_f32 v117, v124, v117
	global_store_dwordx4 v[140:141], v[114:117], off offset:256
	v_pk_mul_f32 v[112:113], v[136:137], v[112:113]
	v_max_f32_e32 v107, 0, v107
	v_lshlrev_b64 v[114:115], 15, v[180:181]
	v_mul_f32_e32 v116, v106, v106
	v_max_f32_e32 v106, 0, v111
	v_max_f32_e32 v108, 0, v108
	v_pk_mul_f32 v[98:99], v[190:191], v[98:99] op_sel_hi:[0,1]
	v_pk_mul_f32 v[100:101], v[190:191], v[100:101] op_sel_hi:[0,1]
	v_lshl_add_u64 v[114:115], s[2:3], 0, v[114:115]
	v_max_f32_e32 v110, 0, v110
	v_mul_f32_e32 v106, v106, v106
	v_mul_f32_e32 v111, v107, v107
	v_max_f32_e32 v107, 0, v112
	v_mul_f32_e32 v112, v108, v108
	v_max_f32_e32 v108, 0, v113
	v_max_f32_e32 v109, 0, v109
	v_pk_mul_f32 v[102:103], v[190:191], v[102:103] op_sel_hi:[0,1]
	v_pk_mul_f32 v[104:105], v[190:191], v[104:105] op_sel_hi:[0,1]
	v_pk_mul_f32 v[100:101], v[120:121], v[100:101]
	v_pk_mul_f32 v[98:99], v[118:119], v[98:99]
	v_lshl_add_u64 v[114:115], v[114:115], 0, v[168:169]
	v_mul_f32_e32 v110, v110, v110
	v_mul_f32_e32 v107, v107, v107
	v_mul_f32_e32 v108, v108, v108
	v_mul_f32_e32 v109, v109, v109
	v_cvt_pk_bf16_f32 v106, v110, v106
	v_pk_mul_f32 v[104:105], v[128:129], v[104:105]
	v_pk_mul_f32 v[102:103], v[126:127], v[102:103]
	v_max_f32_e32 v98, 0, v98
	v_max_f32_e32 v99, 0, v99
	v_max_f32_e32 v100, 0, v100
	v_fmamk_f32 v166, v193, 0x39800000, v174
	v_cvt_pk_bf16_f32 v107, v107, v108
	v_cvt_pk_bf16_f32 v108, v116, v111
	v_cvt_pk_bf16_f32 v109, v112, v109
	global_store_dwordx4 v[114:115], v[106:109], off
	v_pk_mul_f32 v[90:91], v[172:173], v[90:91] op_sel_hi:[0,1]
	v_rsq_f32_e32 v166, v166
	v_mul_f32_e32 v106, v98, v98
	v_max_f32_e32 v98, 0, v103
	v_mul_f32_e32 v103, v99, v99
	v_max_f32_e32 v99, 0, v104
	v_mul_f32_e32 v104, v100, v100
	v_max_f32_e32 v100, 0, v105
	v_max_f32_e32 v102, 0, v102
	v_mul_f32_e32 v98, v98, v98
	v_mul_f32_e32 v99, v99, v99
	v_max_f32_e32 v101, 0, v101
	v_mul_f32_e32 v100, v100, v100
	v_pk_mul_f32 v[94:95], v[172:173], v[94:95] op_sel_hi:[0,1]
	v_pk_mul_f32 v[92:93], v[172:173], v[92:93] op_sel_hi:[0,1]
	v_pk_mul_f32 v[90:91], v[130:131], v[90:91]
	v_mul_f32_e32 v102, v102, v102
	v_mul_f32_e32 v101, v101, v101
	v_cvt_pk_bf16_f32 v98, v102, v98
	v_cvt_pk_bf16_f32 v99, v99, v100
	v_cvt_pk_bf16_f32 v100, v106, v103
	v_pk_mul_f32 v[96:97], v[172:173], v[96:97] op_sel_hi:[0,1]
	v_pk_mul_f32 v[94:95], v[134:135], v[94:95]
	v_pk_mul_f32 v[92:93], v[132:133], v[92:93]
	v_max_f32_e32 v90, 0, v90
	v_cvt_pk_bf16_f32 v101, v104, v101
	global_store_dwordx4 v[114:115], v[98:101], off offset:256
	v_pk_mul_f32 v[96:97], v[136:137], v[96:97]
	v_max_f32_e32 v91, 0, v91
	v_lshlrev_b64 v[98:99], 15, v[170:171]
	v_mul_f32_e32 v100, v90, v90
	v_max_f32_e32 v90, 0, v95
	v_max_f32_e32 v92, 0, v92
	v_pk_mul_f32 v[82:83], v[172:173], v[82:83] op_sel_hi:[0,1]
	v_pk_mul_f32 v[84:85], v[172:173], v[84:85] op_sel_hi:[0,1]
	v_lshl_add_u64 v[98:99], s[2:3], 0, v[98:99]
	v_max_f32_e32 v94, 0, v94
	v_mul_f32_e32 v90, v90, v90
	v_mul_f32_e32 v95, v91, v91
	v_max_f32_e32 v91, 0, v96
	v_mul_f32_e32 v96, v92, v92
	v_max_f32_e32 v92, 0, v97
	v_max_f32_e32 v93, 0, v93
	v_pk_mul_f32 v[86:87], v[172:173], v[86:87] op_sel_hi:[0,1]
	v_pk_mul_f32 v[88:89], v[172:173], v[88:89] op_sel_hi:[0,1]
	v_pk_mul_f32 v[84:85], v[120:121], v[84:85]
	v_pk_mul_f32 v[82:83], v[118:119], v[82:83]
	v_mul_f32_e32 v166, v197, v166
	v_lshl_add_u64 v[98:99], v[98:99], 0, v[168:169]
	v_mul_f32_e32 v94, v94, v94
	v_mul_f32_e32 v91, v91, v91
	v_mul_f32_e32 v92, v92, v92
	v_mul_f32_e32 v93, v93, v93
	v_cvt_pk_bf16_f32 v90, v94, v90
	v_pk_mul_f32 v[88:89], v[128:129], v[88:89]
	v_pk_mul_f32 v[86:87], v[126:127], v[86:87]
	v_max_f32_e32 v82, 0, v82
	v_max_f32_e32 v83, 0, v83
	v_max_f32_e32 v84, 0, v84
	v_cvt_f32_i32_e32 v67, v67
	v_cvt_f32_i32_e32 v66, v66
	v_cvt_f32_i32_e32 v68, v68
	v_cvt_pk_bf16_f32 v91, v91, v92
	v_cvt_pk_bf16_f32 v92, v100, v95
	v_cvt_pk_bf16_f32 v93, v96, v93
	global_store_dwordx4 v[98:99], v[90:93], off
; __device__ __forceinline__ u32x4 pack8(const f32x4 v0, const f32x4 v1) { u32x4 w; w.x = cvt_pk_bf16(v0[0], v0[1]); w.y = cvt_pk_bf16(v0[2], v0[3]); w.z = cvt_pk_bf16(v1[0], v1[1]); w.w = cvt_pk_bf16(v1[2], v1[3]); return w; }
;     __device__ __forceinline__ void operator()(const i32x4 (&acc)[2][2][4][2], const Unit& u, int wr, int wc, int fr, int fq) const {
;     ...
;         for (int ai = 0; ai < 2; ++ai)
; #pragma unroll
;             for (int m = 0; m < 4; ++m) { const int r = row0 + ai * HALF + m * 16; const float rs = rsv[ai][m]; bf16_t* rowp = O + (size_t)r * ldc + col0;
; #pragma unroll
;                 for (int bj = 0; bj < 2; ++bj) { f32x4 v0 = __builtin_convertvector(acc[ai][bj][m][0], f32x4) * rs * sv[bj][0], v1 = __builtin_convertvector(acc[ai][bj][m][1], f32x4) * rs * sv[bj][1];
; #pragma unroll
;                     for (int j = 0; j < 4; ++j) { const float a = v0[j] > 0.f ? v0[j] : 0.f, b = v1[j] > 0.f ? v1[j] : 0.f; v0[j] = a * a; v1[j] = b * b; }
;                     *(u32x4*)(rowp + bj * HALF) = pack8(v0, v1); } }
	v_pk_mul_f32 v[74:75], v[166:167], v[74:75] op_sel_hi:[0,1]
	v_cvt_f32_i32_e32 v73, v73
	v_mul_f32_e32 v90, v82, v82
	v_max_f32_e32 v82, 0, v87
	v_mul_f32_e32 v87, v83, v83
	v_max_f32_e32 v83, 0, v88
	v_mul_f32_e32 v88, v84, v84
	v_max_f32_e32 v84, 0, v89
	v_cvt_f32_i32_e32 v71, v71
	v_cvt_f32_i32_e32 v70, v70
	v_cvt_f32_i32_e32 v72, v72
	v_max_f32_e32 v86, 0, v86
	v_mul_f32_e32 v82, v82, v82
	v_mul_f32_e32 v83, v83, v83
	v_max_f32_e32 v85, 0, v85
	v_mul_f32_e32 v84, v84, v84
	v_pk_mul_f32 v[78:79], v[166:167], v[78:79] op_sel_hi:[0,1]
	v_pk_mul_f32 v[76:77], v[166:167], v[76:77] op_sel_hi:[0,1]
	v_pk_mul_f32 v[74:75], v[130:131], v[74:75]
	v_mul_f32_e32 v86, v86, v86
	v_mul_f32_e32 v85, v85, v85
	v_cvt_pk_bf16_f32 v82, v86, v82
	v_cvt_pk_bf16_f32 v83, v83, v84
	v_cvt_pk_bf16_f32 v84, v90, v87
	v_pk_mul_f32 v[80:81], v[166:167], v[80:81] op_sel_hi:[0,1]
	v_pk_mul_f32 v[78:79], v[134:135], v[78:79]
	v_pk_mul_f32 v[76:77], v[132:133], v[76:77]
	v_max_f32_e32 v74, 0, v74
	v_cvt_f32_i32_e32 v59, v59
	v_cvt_f32_i32_e32 v58, v58
	v_cvt_pk_bf16_f32 v85, v88, v85
	global_store_dwordx4 v[98:99], v[82:85], off offset:256
	v_pk_mul_f32 v[80:81], v[136:137], v[80:81]
	v_max_f32_e32 v75, 0, v75
	v_lshlrev_b64 v[82:83], 15, v[164:165]
	v_mul_f32_e32 v84, v74, v74
	v_max_f32_e32 v74, 0, v79
	v_max_f32_e32 v76, 0, v76
	v_pk_mul_f32 v[66:67], v[166:167], v[66:67] op_sel_hi:[0,1]
	v_pk_mul_f32 v[68:69], v[166:167], v[68:69] op_sel_hi:[0,1]
	v_cvt_f32_i32_e32 v63, v63
	v_cvt_f32_i32_e32 v62, v62
	v_cvt_f32_i32_e32 v61, v61
	v_cvt_f32_i32_e32 v60, v60
	v_lshl_add_u64 v[82:83], s[2:3], 0, v[82:83]
	v_max_f32_e32 v78, 0, v78
	v_mul_f32_e32 v74, v74, v74
	v_mul_f32_e32 v79, v75, v75
	v_max_f32_e32 v75, 0, v80
	v_mul_f32_e32 v80, v76, v76
	v_max_f32_e32 v76, 0, v81
	v_max_f32_e32 v77, 0, v77
	v_pk_mul_f32 v[70:71], v[166:167], v[70:71] op_sel_hi:[0,1]
	v_pk_mul_f32 v[72:73], v[166:167], v[72:73] op_sel_hi:[0,1]
	v_pk_mul_f32 v[68:69], v[120:121], v[68:69]
	v_pk_mul_f32 v[66:67], v[118:119], v[66:67]
	v_cvt_f32_i32_e32 v65, v65
	v_cvt_f32_i32_e32 v64, v64
	v_lshl_add_u64 v[82:83], v[82:83], 0, v[168:169]
	v_mul_f32_e32 v78, v78, v78
	v_mul_f32_e32 v75, v75, v75
	v_mul_f32_e32 v76, v76, v76
	v_mul_f32_e32 v77, v77, v77
	v_cvt_pk_bf16_f32 v74, v78, v74
	v_pk_mul_f32 v[72:73], v[128:129], v[72:73]
	v_pk_mul_f32 v[70:71], v[126:127], v[70:71]
	v_max_f32_e32 v66, 0, v66
	v_max_f32_e32 v67, 0, v67
	v_max_f32_e32 v68, 0, v68
	v_cvt_pk_bf16_f32 v75, v75, v76
	v_cvt_pk_bf16_f32 v76, v84, v79
	v_cvt_pk_bf16_f32 v77, v80, v77
	global_store_dwordx4 v[82:83], v[74:77], off
	v_pk_mul_f32 v[58:59], v[162:163], v[58:59] op_sel_hi:[0,1]
	v_cvt_f32_i32_e32 v53, v53
	v_mul_f32_e32 v74, v66, v66
	v_max_f32_e32 v66, 0, v71
	v_mul_f32_e32 v71, v67, v67
	v_max_f32_e32 v67, 0, v72
	v_mul_f32_e32 v72, v68, v68
	v_max_f32_e32 v68, 0, v73
	v_cvt_f32_i32_e32 v51, v51
	v_cvt_f32_i32_e32 v50, v50
	v_cvt_f32_i32_e32 v52, v52
	v_max_f32_e32 v70, 0, v70
	v_mul_f32_e32 v66, v66, v66
	v_mul_f32_e32 v67, v67, v67
	v_max_f32_e32 v69, 0, v69
	v_mul_f32_e32 v68, v68, v68
	v_pk_mul_f32 v[62:63], v[162:163], v[62:63] op_sel_hi:[0,1]
	v_pk_mul_f32 v[60:61], v[162:163], v[60:61] op_sel_hi:[0,1]
	v_pk_mul_f32 v[58:59], v[130:131], v[58:59]
	v_cvt_f32_i32_e32 v57, v57
	v_cvt_f32_i32_e32 v56, v56
	v_cvt_f32_i32_e32 v55, v55
	v_cvt_f32_i32_e32 v54, v54
	v_mul_f32_e32 v70, v70, v70
	v_mul_f32_e32 v69, v69, v69
	v_cvt_pk_bf16_f32 v66, v70, v66
	v_cvt_pk_bf16_f32 v67, v67, v68
	v_cvt_pk_bf16_f32 v68, v74, v71
	v_pk_mul_f32 v[64:65], v[162:163], v[64:65] op_sel_hi:[0,1]
	v_pk_mul_f32 v[62:63], v[134:135], v[62:63]
	v_pk_mul_f32 v[60:61], v[132:133], v[60:61]
	v_max_f32_e32 v58, 0, v58
	v_cvt_pk_bf16_f32 v69, v72, v69
	global_store_dwordx4 v[82:83], v[66:69], off offset:256
	v_pk_mul_f32 v[64:65], v[136:137], v[64:65]
	v_max_f32_e32 v62, 0, v62
	v_mul_f32_e32 v68, v58, v58
	v_max_f32_e32 v58, 0, v63
	v_max_f32_e32 v59, 0, v59
	v_max_f32_e32 v60, 0, v60
	v_cvt_f32_i32_e32 v43, v43
	v_cvt_f32_i32_e32 v42, v42
	v_mul_f32_e32 v62, v62, v62
	v_mul_f32_e32 v58, v58, v58
	v_mul_f32_e32 v63, v59, v59
	v_max_f32_e32 v59, 0, v64
	v_mul_f32_e32 v64, v60, v60
	v_max_f32_e32 v60, 0, v65
	v_pk_mul_f32 v[50:51], v[162:163], v[50:51] op_sel_hi:[0,1]
	v_pk_mul_f32 v[52:53], v[162:163], v[52:53] op_sel_hi:[0,1]
	v_cvt_f32_i32_e32 v47, v47
	v_cvt_f32_i32_e32 v46, v46
	v_cvt_f32_i32_e32 v45, v45
	v_cvt_f32_i32_e32 v44, v44
	v_mul_f32_e32 v59, v59, v59
	v_max_f32_e32 v61, 0, v61
	v_mul_f32_e32 v60, v60, v60
	v_cvt_pk_bf16_f32 v58, v62, v58
	v_add_co_u32_e32 v62, vcc, s56, v140
	v_pk_mul_f32 v[54:55], v[162:163], v[54:55] op_sel_hi:[0,1]
	v_pk_mul_f32 v[56:57], v[162:163], v[56:57] op_sel_hi:[0,1]
	v_pk_mul_f32 v[52:53], v[120:121], v[52:53]
	v_pk_mul_f32 v[50:51], v[118:119], v[50:51]
	v_cvt_f32_i32_e32 v49, v49
	v_cvt_f32_i32_e32 v48, v48
	v_mul_f32_e32 v61, v61, v61
	v_cvt_pk_bf16_f32 v59, v59, v60
	v_cvt_pk_bf16_f32 v60, v68, v63
	v_addc_co_u32_e32 v63, vcc, 0, v141, vcc
	v_pk_mul_f32 v[56:57], v[128:129], v[56:57]
	v_pk_mul_f32 v[54:55], v[126:127], v[54:55]
	v_max_f32_e32 v50, 0, v50
	v_max_f32_e32 v51, 0, v51
	v_max_f32_e32 v52, 0, v52
	v_cvt_pk_bf16_f32 v61, v64, v61
	global_store_dwordx4 v[62:63], v[58:61], off
	v_pk_mul_f32 v[42:43], v[144:145], v[42:43] op_sel_hi:[0,1]
	v_cvt_f32_i32_e32 v37, v37
	v_mul_f32_e32 v58, v50, v50
	v_max_f32_e32 v50, 0, v55
	v_mul_f32_e32 v55, v51, v51
	v_max_f32_e32 v51, 0, v56
	v_mul_f32_e32 v56, v52, v52
	v_max_f32_e32 v52, 0, v57
	v_cvt_f32_i32_e32 v35, v35
	v_cvt_f32_i32_e32 v34, v34
	v_cvt_f32_i32_e32 v36, v36
	v_max_f32_e32 v54, 0, v54
	v_mul_f32_e32 v50, v50, v50
	v_mul_f32_e32 v51, v51, v51
; __device__ __forceinline__ u32x4 pack8(const f32x4 v0, const f32x4 v1) { u32x4 w; w.x = cvt_pk_bf16(v0[0], v0[1]); w.y = cvt_pk_bf16(v0[2], v0[3]); w.z = cvt_pk_bf16(v1[0], v1[1]); w.w = cvt_pk_bf16(v1[2], v1[3]); return w; }
;     __device__ __forceinline__ void operator()(const i32x4 (&acc)[2][2][4][2], const Unit& u, int wr, int wc, int fr, int fq) const {
;     ...
;         for (int ai = 0; ai < 2; ++ai)
; #pragma unroll
;             for (int m = 0; m < 4; ++m) { const int r = row0 + ai * HALF + m * 16; const float rs = rsv[ai][m]; bf16_t* rowp = O + (size_t)r * ldc + col0;
; #pragma unroll
;                 for (int bj = 0; bj < 2; ++bj) { f32x4 v0 = __builtin_convertvector(acc[ai][bj][m][0], f32x4) * rs * sv[bj][0], v1 = __builtin_convertvector(acc[ai][bj][m][1], f32x4) * rs * sv[bj][1];
; #pragma unroll
;                     for (int j = 0; j < 4; ++j) { const float a = v0[j] > 0.f ? v0[j] : 0.f, b = v1[j] > 0.f ? v1[j] : 0.f; v0[j] = a * a; v1[j] = b * b; }
;                     *(u32x4*)(rowp + bj * HALF) = pack8(v0, v1); } }
	v_max_f32_e32 v53, 0, v53
	v_mul_f32_e32 v52, v52, v52
	v_pk_mul_f32 v[46:47], v[144:145], v[46:47] op_sel_hi:[0,1]
	v_pk_mul_f32 v[44:45], v[144:145], v[44:45] op_sel_hi:[0,1]
	v_pk_mul_f32 v[42:43], v[130:131], v[42:43]
	v_cvt_f32_i32_e32 v41, v41
	v_cvt_f32_i32_e32 v40, v40
	v_cvt_f32_i32_e32 v39, v39
	v_cvt_f32_i32_e32 v38, v38
	v_lshl_add_u64 v[66:67], v[140:141], 0, s[16:17]
	v_mul_f32_e32 v54, v54, v54
	v_mul_f32_e32 v53, v53, v53
	v_cvt_pk_bf16_f32 v50, v54, v50
	v_cvt_pk_bf16_f32 v51, v51, v52
	v_cvt_pk_bf16_f32 v52, v58, v55
	v_pk_mul_f32 v[48:49], v[144:145], v[48:49] op_sel_hi:[0,1]
	v_pk_mul_f32 v[46:47], v[134:135], v[46:47]
	v_pk_mul_f32 v[44:45], v[132:133], v[44:45]
	v_max_f32_e32 v42, 0, v42
	v_cvt_pk_bf16_f32 v53, v56, v53
	global_store_dwordx4 v[66:67], v[50:53], off offset:256
	v_pk_mul_f32 v[48:49], v[136:137], v[48:49]
	v_max_f32_e32 v46, 0, v46
	v_mul_f32_e32 v52, v42, v42
	v_max_f32_e32 v42, 0, v47
	v_max_f32_e32 v43, 0, v43
	v_max_f32_e32 v44, 0, v44
	v_cvt_f32_i32_e32 v27, v27
	v_cvt_f32_i32_e32 v26, v26
	v_mul_f32_e32 v46, v46, v46
	v_mul_f32_e32 v42, v42, v42
	v_mul_f32_e32 v47, v43, v43
	v_max_f32_e32 v43, 0, v48
	v_mul_f32_e32 v48, v44, v44
	v_max_f32_e32 v44, 0, v49
	v_pk_mul_f32 v[34:35], v[144:145], v[34:35] op_sel_hi:[0,1]
	v_pk_mul_f32 v[36:37], v[144:145], v[36:37] op_sel_hi:[0,1]
	v_cvt_f32_i32_e32 v31, v31
	v_cvt_f32_i32_e32 v30, v30
	v_cvt_f32_i32_e32 v29, v29
	v_cvt_f32_i32_e32 v28, v28
	v_mul_f32_e32 v43, v43, v43
	v_max_f32_e32 v45, 0, v45
	v_mul_f32_e32 v44, v44, v44
	v_cvt_pk_bf16_f32 v42, v46, v42
	v_add_co_u32_e32 v46, vcc, s57, v140
	v_pk_mul_f32 v[38:39], v[144:145], v[38:39] op_sel_hi:[0,1]
	v_pk_mul_f32 v[40:41], v[144:145], v[40:41] op_sel_hi:[0,1]
	v_pk_mul_f32 v[36:37], v[120:121], v[36:37]
	v_pk_mul_f32 v[34:35], v[118:119], v[34:35]
	v_cvt_f32_i32_e32 v33, v33
	v_cvt_f32_i32_e32 v32, v32
	v_mul_f32_e32 v45, v45, v45
	v_cvt_pk_bf16_f32 v43, v43, v44
	v_cvt_pk_bf16_f32 v44, v52, v47
	v_addc_co_u32_e32 v47, vcc, 0, v141, vcc
	v_pk_mul_f32 v[40:41], v[128:129], v[40:41]
	v_pk_mul_f32 v[38:39], v[126:127], v[38:39]
	v_max_f32_e32 v34, 0, v34
	v_max_f32_e32 v35, 0, v35
	v_max_f32_e32 v36, 0, v36
	v_cvt_pk_bf16_f32 v45, v48, v45
	global_store_dwordx4 v[46:47], v[42:45], off
	v_pk_mul_f32 v[26:27], v[142:143], v[26:27] op_sel_hi:[0,1]
	v_cvt_f32_i32_e32 v21, v21
	v_mul_f32_e32 v42, v34, v34
	v_max_f32_e32 v34, 0, v39
	v_mul_f32_e32 v39, v35, v35
	v_max_f32_e32 v35, 0, v40
	v_mul_f32_e32 v40, v36, v36
	v_max_f32_e32 v36, 0, v41
	v_cvt_f32_i32_e32 v19, v19
	v_cvt_f32_i32_e32 v18, v18
	v_cvt_f32_i32_e32 v20, v20
	v_max_f32_e32 v38, 0, v38
	v_mul_f32_e32 v34, v34, v34
	v_mul_f32_e32 v35, v35, v35
	v_max_f32_e32 v37, 0, v37
	v_mul_f32_e32 v36, v36, v36
	v_pk_mul_f32 v[30:31], v[142:143], v[30:31] op_sel_hi:[0,1]
	v_pk_mul_f32 v[28:29], v[142:143], v[28:29] op_sel_hi:[0,1]
	v_pk_mul_f32 v[26:27], v[130:131], v[26:27]
	v_cvt_f32_i32_e32 v25, v25
	v_cvt_f32_i32_e32 v24, v24
	v_cvt_f32_i32_e32 v23, v23
	v_cvt_f32_i32_e32 v22, v22
	v_lshl_add_u64 v[50:51], v[140:141], 0, s[18:19]
	v_mul_f32_e32 v38, v38, v38
	v_mul_f32_e32 v37, v37, v37
	v_cvt_pk_bf16_f32 v34, v38, v34
	v_cvt_pk_bf16_f32 v35, v35, v36
	v_cvt_pk_bf16_f32 v36, v42, v39
	v_pk_mul_f32 v[32:33], v[142:143], v[32:33] op_sel_hi:[0,1]
	v_pk_mul_f32 v[30:31], v[134:135], v[30:31]
	v_pk_mul_f32 v[28:29], v[132:133], v[28:29]
	v_max_f32_e32 v26, 0, v26
	v_cvt_pk_bf16_f32 v37, v40, v37
	global_store_dwordx4 v[50:51], v[34:37], off offset:256
	v_pk_mul_f32 v[32:33], v[136:137], v[32:33]
	v_max_f32_e32 v30, 0, v30
	v_mul_f32_e32 v36, v26, v26
	v_max_f32_e32 v26, 0, v31
	v_max_f32_e32 v27, 0, v27
	v_max_f32_e32 v28, 0, v28
	v_cvt_f32_i32_e32 v11, v11
	v_cvt_f32_i32_e32 v10, v10
	v_mul_f32_e32 v30, v30, v30
	v_mul_f32_e32 v26, v26, v26
	v_mul_f32_e32 v31, v27, v27
	v_max_f32_e32 v27, 0, v32
	v_mul_f32_e32 v32, v28, v28
	v_max_f32_e32 v28, 0, v33
	v_pk_mul_f32 v[18:19], v[142:143], v[18:19] op_sel_hi:[0,1]
	v_pk_mul_f32 v[20:21], v[142:143], v[20:21] op_sel_hi:[0,1]
	v_cvt_f32_i32_e32 v15, v15
; __device__ __forceinline__ u32x4 pack8(const f32x4 v0, const f32x4 v1) { u32x4 w; w.x = cvt_pk_bf16(v0[0], v0[1]); w.y = cvt_pk_bf16(v0[2], v0[3]); w.z = cvt_pk_bf16(v1[0], v1[1]); w.w = cvt_pk_bf16(v1[2], v1[3]); return w; }
;     __device__ __forceinline__ void operator()(const i32x4 (&acc)[2][2][4][2], const Unit& u, int wr, int wc, int fr, int fq) const {
;     ...
;         for (int ai = 0; ai < 2; ++ai)
; #pragma unroll
;             for (int m = 0; m < 4; ++m) { const int r = row0 + ai * HALF + m * 16; const float rs = rsv[ai][m]; bf16_t* rowp = O + (size_t)r * ldc + col0;
; #pragma unroll
;                 for (int bj = 0; bj < 2; ++bj) { f32x4 v0 = __builtin_convertvector(acc[ai][bj][m][0], f32x4) * rs * sv[bj][0], v1 = __builtin_convertvector(acc[ai][bj][m][1], f32x4) * rs * sv[bj][1];
; #pragma unroll
;                     for (int j = 0; j < 4; ++j) { const float a = v0[j] > 0.f ? v0[j] : 0.f, b = v1[j] > 0.f ? v1[j] : 0.f; v0[j] = a * a; v1[j] = b * b; }
;                     *(u32x4*)(rowp + bj * HALF) = pack8(v0, v1); } }
	v_cvt_f32_i32_e32 v14, v14
	v_cvt_f32_i32_e32 v13, v13
	v_cvt_f32_i32_e32 v12, v12
	v_mul_f32_e32 v27, v27, v27
	v_max_f32_e32 v29, 0, v29
	v_mul_f32_e32 v28, v28, v28
	v_cvt_pk_bf16_f32 v26, v30, v26
	v_add_co_u32_e32 v30, vcc, s58, v140
	v_pk_mul_f32 v[22:23], v[142:143], v[22:23] op_sel_hi:[0,1]
	v_pk_mul_f32 v[24:25], v[142:143], v[24:25] op_sel_hi:[0,1]
	v_pk_mul_f32 v[20:21], v[120:121], v[20:21]
	v_pk_mul_f32 v[18:19], v[118:119], v[18:19]
	v_cvt_f32_i32_e32 v17, v17
	v_cvt_f32_i32_e32 v16, v16
	v_mul_f32_e32 v29, v29, v29
	v_cvt_pk_bf16_f32 v27, v27, v28
	v_cvt_pk_bf16_f32 v28, v36, v31
	v_addc_co_u32_e32 v31, vcc, 0, v141, vcc
	v_pk_mul_f32 v[24:25], v[128:129], v[24:25]
	v_pk_mul_f32 v[22:23], v[126:127], v[22:23]
	v_max_f32_e32 v18, 0, v18
	v_max_f32_e32 v19, 0, v19
	v_max_f32_e32 v20, 0, v20
	v_cvt_pk_bf16_f32 v29, v32, v29
	global_store_dwordx4 v[30:31], v[26:29], off
	v_pk_mul_f32 v[10:11], v[138:139], v[10:11] op_sel_hi:[0,1]
	v_cvt_f32_i32_e32 v5, v5
	v_mul_f32_e32 v26, v18, v18
	v_max_f32_e32 v18, 0, v23
	v_mul_f32_e32 v23, v19, v19
	v_max_f32_e32 v19, 0, v24
	v_mul_f32_e32 v24, v20, v20
	v_max_f32_e32 v20, 0, v25
	v_cvt_f32_i32_e32 v3, v3
	v_cvt_f32_i32_e32 v2, v2
	v_cvt_f32_i32_e32 v4, v4
	v_max_f32_e32 v22, 0, v22
	v_mul_f32_e32 v18, v18, v18
	v_mul_f32_e32 v19, v19, v19
	v_max_f32_e32 v21, 0, v21
	v_mul_f32_e32 v20, v20, v20
	v_pk_mul_f32 v[14:15], v[138:139], v[14:15] op_sel_hi:[0,1]
	v_pk_mul_f32 v[12:13], v[138:139], v[12:13] op_sel_hi:[0,1]
	v_pk_mul_f32 v[10:11], v[130:131], v[10:11]
	v_cvt_f32_i32_e32 v9, v9
	v_cvt_f32_i32_e32 v8, v8
	v_cvt_f32_i32_e32 v7, v7
	v_cvt_f32_i32_e32 v6, v6
	v_lshl_add_u64 v[34:35], v[140:141], 0, s[20:21]
	v_mul_f32_e32 v22, v22, v22
	v_mul_f32_e32 v21, v21, v21
	v_cvt_pk_bf16_f32 v18, v22, v18
	v_cvt_pk_bf16_f32 v19, v19, v20
	v_cvt_pk_bf16_f32 v20, v26, v23
	v_pk_mul_f32 v[16:17], v[138:139], v[16:17] op_sel_hi:[0,1]
	v_pk_mul_f32 v[14:15], v[134:135], v[14:15]
	v_pk_mul_f32 v[12:13], v[132:133], v[12:13]
	v_max_f32_e32 v10, 0, v10
	v_cvt_pk_bf16_f32 v21, v24, v21
	global_store_dwordx4 v[34:35], v[18:21], off offset:256
	v_pk_mul_f32 v[16:17], v[136:137], v[16:17]
	v_max_f32_e32 v14, 0, v14
	v_mul_f32_e32 v20, v10, v10
	v_max_f32_e32 v10, 0, v15
	v_max_f32_e32 v11, 0, v11
	v_max_f32_e32 v12, 0, v12
	v_mul_f32_e32 v14, v14, v14
	v_mul_f32_e32 v10, v10, v10
	v_mul_f32_e32 v15, v11, v11
	v_max_f32_e32 v11, 0, v16
	v_mul_f32_e32 v16, v12, v12
	v_max_f32_e32 v12, 0, v17
	v_pk_mul_f32 v[2:3], v[138:139], v[2:3] op_sel_hi:[0,1]
	v_pk_mul_f32 v[4:5], v[138:139], v[4:5] op_sel_hi:[0,1]
	v_mul_f32_e32 v11, v11, v11
	v_max_f32_e32 v13, 0, v13
	v_mul_f32_e32 v12, v12, v12
	v_cvt_pk_bf16_f32 v10, v14, v10
	v_add_co_u32_e32 v14, vcc, s59, v140
	v_pk_mul_f32 v[6:7], v[138:139], v[6:7] op_sel_hi:[0,1]
	v_pk_mul_f32 v[8:9], v[138:139], v[8:9] op_sel_hi:[0,1]
	v_pk_mul_f32 v[4:5], v[120:121], v[4:5]
	v_pk_mul_f32 v[2:3], v[118:119], v[2:3]
	v_mul_f32_e32 v13, v13, v13
	v_cvt_pk_bf16_f32 v11, v11, v12
	v_cvt_pk_bf16_f32 v12, v20, v15
	v_addc_co_u32_e32 v15, vcc, 0, v141, vcc
	v_pk_mul_f32 v[8:9], v[128:129], v[8:9]
	v_pk_mul_f32 v[6:7], v[126:127], v[6:7]
	v_max_f32_e32 v2, 0, v2
	v_max_f32_e32 v3, 0, v3
	v_max_f32_e32 v4, 0, v4
	v_cvt_pk_bf16_f32 v13, v16, v13
	global_store_dwordx4 v[14:15], v[10:13], off
	v_max_f32_e32 v5, 0, v5
	v_lshl_add_u64 v[18:19], v[140:141], 0, s[22:23]
	v_mul_f32_e32 v10, v2, v2
	v_max_f32_e32 v2, 0, v7
	v_mul_f32_e32 v7, v3, v3
	v_max_f32_e32 v3, 0, v8
	v_mul_f32_e32 v8, v4, v4
	v_max_f32_e32 v4, 0, v9
	v_max_f32_e32 v6, 0, v6
	v_mul_f32_e32 v2, v2, v2
	v_mul_f32_e32 v3, v3, v3
	v_mul_f32_e32 v4, v4, v4
	v_mul_f32_e32 v5, v5, v5
	s_andn2_b64 vcc, exec, s[4:5]
	s_mov_b64 s[4:5], -1
	v_mul_f32_e32 v6, v6, v6
	v_cvt_pk_bf16_f32 v2, v6, v2
	v_cvt_pk_bf16_f32 v3, v3, v4
	v_cvt_pk_bf16_f32 v4, v10, v7
	v_cvt_pk_bf16_f32 v5, v8, v5
	global_store_dwordx4 v[18:19], v[2:5], off offset:256
	s_cbranch_vccnz .LBB0_2006
	s_andn2_b64 vcc, exec, s[0:1]
	s_cbranch_vccnz .LBB0_2005
	s_barrier
	s_branch .LBB0_2005

; #define PG8_STAGE(bufoff, gbase, voff) do { _Pragma("unroll") for (int _i = 0; _i < 2; ++_i) \
;         __builtin_amdgcn_global_load_lds((const unsigned*)((const char*)(gbase) + (voff)[_i]), (PG8_LAS unsigned*)(lds + (bufoff) + ldsw + _i * 8192), 16, 0, 0); } while (0)
; #define PG8_LDA(dst, b, h) do { _Pragma("unroll") for (int m = 0; m < 4; ++m) _Pragma("unroll") for (int k = 0; k < 2; ++k) dst[m][k] = *(const PG8_LAS bf16x8*)(lds + PG8_SA(b, h) + aoff + m * 2048 + k * 1024); } while (0)
; #define PG8_LDB(dst, b, h) do { _Pragma("unroll") for (int n = 0; n < 2; ++n) _Pragma("unroll") for (int k = 0; k < 2; ++k) dst[n][k] = *(const PG8_LAS bf16x8*)(lds + PG8_SB(b, h) + boff + n * 2048 + k * 1024); } while (0)
; #define PG8_MMA(ai, bj, At, Bt) do { __builtin_amdgcn_s_setprio(1); _Pragma("unroll") for (int m = 0; m < 4; ++m) _Pragma("unroll") for (int n = 0; n < 2; ++n) _Pragma("unroll") for (int k = 0; k < 2; ++k) \
;         acc[ai][bj][m][n] = mma_<I8>(Bt[n][k], At[m][k], acc[ai][bj][m][n]); __builtin_amdgcn_s_setprio(0); } while (0)
; #define PG8_WAIT_V(n) asm volatile("s_waitcnt vmcnt(" #n ")" ::: "memory")
; #define PG8_WAIT_L(n) asm volatile("s_waitcnt lgkmcnt(" #n ")" ::: "memory")
; #define PG8_BAR __builtin_amdgcn_s_barrier()
; #define PG8_SCHED __builtin_amdgcn_sched_barrier(0)
; template <class Epi, class Sched, bool ALIGN_EPI = false, bool SP2 = false, bool I8 = false>
; __device__ __forceinline__ void gemm_phase(PG8_LAS unsigned char* lds, const Gemm g, const Sched& S, const Epi& E) {
;     ...
;             PG8_LDB(B0, 0, 0); PG8_LDB(B1, 0, 1); PG8_SCHED; PG8_LDA(At, 0, 0); PG8_STAGE(PG8_SA(1, 1), a1 + hstepA, voffA);
;             PG8_WAIT_V(8); PG8_WAIT_L(0); PG8_BAR; PG8_MMA(0, 0, At, B0); PG8_MMA(0, 1, At, B1); PG8_BAR; PG8_SCHED;
;             PG8_LDA(At, 0, 1); PG8_STAGE(PG8_SB(0, 0), b2, voffB); PG8_STAGE(PG8_SB(0, 1), b2 + hstepB, voffB); PG8_STAGE(PG8_SA(0, 0), a2, voffA);
;             PG8_WAIT_V(8); PG8_WAIT_L(0); PG8_BAR; PG8_MMA(1, 0, At, B0); PG8_MMA(1, 1, At, B1); PG8_BAR; PG8_SCHED;
.LBB0_2092:
	ds_read_b128 v[130:133], v192
	ds_read_b128 v[134:137], v192 offset:1024
	ds_read_b128 v[138:141], v192 offset:2048
	ds_read_b128 v[142:145], v192 offset:3072
	ds_read_b128 v[146:149], v193
	ds_read_b128 v[150:153], v193 offset:1024
	ds_read_b128 v[154:157], v193 offset:2048
	ds_read_b128 v[158:161], v193 offset:3072
	s_add_u32 s28, s8, 0xffc00080
	s_addc_u32 s29, s9, -1
	s_cmpk_eq_i32 s51, 0xfc
	s_cselect_b32 s31, s3, s29
	s_cselect_b32 s30, s7, s28
	s_cselect_b32 s29, s21, s50
	s_cselect_b32 s28, s23, s49
	s_add_i32 m0, s38, 0xc000
	ds_read_b128 v[162:165], v194
	ds_read_b128 v[166:169], v194 offset:1024
	ds_read_b128 v[182:185], v194 offset:2048
	ds_read_b128 v[186:189], v194 offset:3072
	ds_read_b128 v[196:199], v194 offset:4096
	ds_read_b128 v[200:203], v194 offset:5120
	ds_read_b128 v[204:207], v194 offset:6144
	ds_read_b128 v[208:211], v194 offset:7168
	global_load_lds_dwordx4 v174, s[8:9]
	s_add_i32 m0, s38, 0xe000
	s_nop 0
	global_load_lds_dwordx4 v176, s[8:9]
	s_waitcnt vmcnt(8) lgkmcnt(0)
	s_barrier
	v_mfma_f32_16x16x32_bf16 v[126:129], v[130:133], v[162:165], v[126:129]
	v_mfma_f32_16x16x32_bf16 v[122:125], v[138:141], v[162:165], v[122:125]
	v_mfma_f32_16x16x32_bf16 v[110:113], v[130:133], v[182:185], v[110:113]
	v_mfma_f32_16x16x32_bf16 v[106:109], v[138:141], v[182:185], v[106:109]
	v_mfma_f32_16x16x32_bf16 v[94:97], v[130:133], v[196:199], v[94:97]
	v_mfma_f32_16x16x32_bf16 v[90:93], v[138:141], v[196:199], v[90:93]
	v_mfma_f32_16x16x32_bf16 v[78:81], v[130:133], v[204:207], v[78:81]
	v_mfma_f32_16x16x32_bf16 v[74:77], v[138:141], v[204:207], v[74:77]
	v_mfma_f32_16x16x32_bf16 v[126:129], v[134:137], v[166:169], v[126:129]
	v_mfma_f32_16x16x32_bf16 v[122:125], v[142:145], v[166:169], v[122:125]
	v_mfma_f32_16x16x32_bf16 v[110:113], v[134:137], v[186:189], v[110:113]
	v_mfma_f32_16x16x32_bf16 v[106:109], v[142:145], v[186:189], v[106:109]
	v_mfma_f32_16x16x32_bf16 v[94:97], v[134:137], v[200:203], v[94:97]
	v_mfma_f32_16x16x32_bf16 v[90:93], v[142:145], v[200:203], v[90:93]
	v_mfma_f32_16x16x32_bf16 v[78:81], v[134:137], v[208:211], v[78:81]
	v_mfma_f32_16x16x32_bf16 v[74:77], v[142:145], v[208:211], v[74:77]
	v_mfma_f32_16x16x32_bf16 v[118:121], v[146:149], v[162:165], v[118:121]
	v_mfma_f32_16x16x32_bf16 v[114:117], v[154:157], v[162:165], v[114:117]
	v_mfma_f32_16x16x32_bf16 v[102:105], v[146:149], v[182:185], v[102:105]
	v_mfma_f32_16x16x32_bf16 v[98:101], v[154:157], v[182:185], v[98:101]
	v_mfma_f32_16x16x32_bf16 v[86:89], v[146:149], v[196:199], v[86:89]
	v_mfma_f32_16x16x32_bf16 v[82:85], v[154:157], v[196:199], v[82:85]
	v_mfma_f32_16x16x32_bf16 v[70:73], v[146:149], v[204:207], v[70:73]
	v_mfma_f32_16x16x32_bf16 v[66:69], v[154:157], v[204:207], v[66:69]
	v_mfma_f32_16x16x32_bf16 v[118:121], v[150:153], v[166:169], v[118:121]
	v_mfma_f32_16x16x32_bf16 v[114:117], v[158:161], v[166:169], v[114:117]
	v_mfma_f32_16x16x32_bf16 v[102:105], v[150:153], v[186:189], v[102:105]
	v_mfma_f32_16x16x32_bf16 v[98:101], v[158:161], v[186:189], v[98:101]
	v_mfma_f32_16x16x32_bf16 v[86:89], v[150:153], v[200:203], v[86:89]
	v_mfma_f32_16x16x32_bf16 v[82:85], v[158:161], v[200:203], v[82:85]
	v_mfma_f32_16x16x32_bf16 v[70:73], v[150:153], v[208:211], v[70:73]
	v_mfma_f32_16x16x32_bf16 v[66:69], v[158:161], v[208:211], v[66:69]
	s_barrier
	s_add_i32 s52, s47, s33
	s_mov_b64 s[98:99], s[28:29]
	s_mov_b32 m0, s52
	ds_read_b128 v[162:165], v194 offset:16384
	ds_read_b128 v[166:169], v194 offset:17408
	ds_read_b128 v[182:185], v194 offset:18432
	ds_read_b128 v[186:189], v194 offset:19456
	ds_read_b128 v[196:199], v194 offset:20480
	ds_read_b128 v[200:203], v194 offset:21504
	ds_read_b128 v[204:207], v194 offset:22528
	ds_read_b128 v[208:211], v194 offset:23552
	global_load_lds_dwordx4 v170, s[28:29]
	s_add_i32 m0, s52, 0x2000
	s_add_u32 s52, s28, 0x400000
	s_mov_b64 s[98:99], s[28:29]
	s_addc_u32 s53, s29, 0
	s_add_i32 s54, s48, s33
	global_load_lds_dwordx4 v172, s[28:29]
	s_mov_b32 m0, s54
	s_mov_b64 s[100:101], s[30:31]
	global_load_lds_dwordx4 v170, s[52:53]
	s_add_i32 m0, s54, 0x2000
	s_nop 0
	global_load_lds_dwordx4 v172, s[52:53]
	s_mov_b64 s[100:101], s[30:31]
	s_mov_b32 m0, s38
	s_nop 0
	global_load_lds_dwordx4 v170, s[30:31]
	s_mov_b32 m0, s39
	s_nop 0
	global_load_lds_dwordx4 v172, s[30:31]
	s_waitcnt vmcnt(8) lgkmcnt(0)
	s_barrier
	v_mfma_f32_16x16x32_bf16 v[62:65], v[130:133], v[162:165], v[62:65]
	v_mfma_f32_16x16x32_bf16 v[58:61], v[138:141], v[162:165], v[58:61]
	v_mfma_f32_16x16x32_bf16 v[46:49], v[130:133], v[182:185], v[46:49]
	v_mfma_f32_16x16x32_bf16 v[42:45], v[138:141], v[182:185], v[42:45]
	v_mfma_f32_16x16x32_bf16 v[30:33], v[130:133], v[196:199], v[30:33]
	v_mfma_f32_16x16x32_bf16 v[26:29], v[138:141], v[196:199], v[26:29]
	v_mfma_f32_16x16x32_bf16 v[22:25], v[130:133], v[204:207], v[22:25]
	v_mfma_f32_16x16x32_bf16 v[10:13], v[138:141], v[204:207], v[10:13]
	v_mfma_f32_16x16x32_bf16 v[62:65], v[134:137], v[166:169], v[62:65]
	v_mfma_f32_16x16x32_bf16 v[58:61], v[142:145], v[166:169], v[58:61]
	v_mfma_f32_16x16x32_bf16 v[46:49], v[134:137], v[186:189], v[46:49]
	v_mfma_f32_16x16x32_bf16 v[42:45], v[142:145], v[186:189], v[42:45]
	v_mfma_f32_16x16x32_bf16 v[30:33], v[134:137], v[200:203], v[30:33]
	v_mfma_f32_16x16x32_bf16 v[26:29], v[142:145], v[200:203], v[26:29]
	v_mfma_f32_16x16x32_bf16 v[22:25], v[134:137], v[208:211], v[22:25]
	v_mfma_f32_16x16x32_bf16 v[10:13], v[142:145], v[208:211], v[10:13]
	v_mfma_f32_16x16x32_bf16 v[54:57], v[146:149], v[162:165], v[54:57]
	v_mfma_f32_16x16x32_bf16 v[50:53], v[154:157], v[162:165], v[50:53]
	v_mfma_f32_16x16x32_bf16 v[38:41], v[146:149], v[182:185], v[38:41]
	v_mfma_f32_16x16x32_bf16 v[34:37], v[154:157], v[182:185], v[34:37]
	v_mfma_f32_16x16x32_bf16 v[18:21], v[146:149], v[196:199], v[18:21]
	v_mfma_f32_16x16x32_bf16 v[14:17], v[154:157], v[196:199], v[14:17]
	v_mfma_f32_16x16x32_bf16 v[6:9], v[146:149], v[204:207], v[6:9]
	v_mfma_f32_16x16x32_bf16 v[2:5], v[154:157], v[204:207], v[2:5]
	v_mfma_f32_16x16x32_bf16 v[54:57], v[150:153], v[166:169], v[54:57]
	v_mfma_f32_16x16x32_bf16 v[50:53], v[158:161], v[166:169], v[50:53]
	v_mfma_f32_16x16x32_bf16 v[38:41], v[150:153], v[186:189], v[38:41]
	v_mfma_f32_16x16x32_bf16 v[34:37], v[158:161], v[186:189], v[34:37]
	v_mfma_f32_16x16x32_bf16 v[18:21], v[150:153], v[200:203], v[18:21]
	v_mfma_f32_16x16x32_bf16 v[14:17], v[158:161], v[200:203], v[14:17]
	v_mfma_f32_16x16x32_bf16 v[6:9], v[150:153], v[208:211], v[6:9]
	v_mfma_f32_16x16x32_bf16 v[2:5], v[158:161], v[208:211], v[2:5]
	s_barrier
; #define PG8_STAGE(bufoff, gbase, voff) do { _Pragma("unroll") for (int _i = 0; _i < 2; ++_i) \
;         __builtin_amdgcn_global_load_lds((const unsigned*)((const char*)(gbase) + (voff)[_i]), (PG8_LAS unsigned*)(lds + (bufoff) + ldsw + _i * 8192), 16, 0, 0); } while (0)
; #define PG8_LDA(dst, b, h) do { _Pragma("unroll") for (int m = 0; m < 4; ++m) _Pragma("unroll") for (int k = 0; k < 2; ++k) dst[m][k] = *(const PG8_LAS bf16x8*)(lds + PG8_SA(b, h) + aoff + m * 2048 + k * 1024); } while (0)
; #define PG8_LDB(dst, b, h) do { _Pragma("unroll") for (int n = 0; n < 2; ++n) _Pragma("unroll") for (int k = 0; k < 2; ++k) dst[n][k] = *(const PG8_LAS bf16x8*)(lds + PG8_SB(b, h) + boff + n * 2048 + k * 1024); } while (0)
; #define PG8_MMA(ai, bj, At, Bt) do { __builtin_amdgcn_s_setprio(1); _Pragma("unroll") for (int m = 0; m < 4; ++m) _Pragma("unroll") for (int n = 0; n < 2; ++n) _Pragma("unroll") for (int k = 0; k < 2; ++k) \
;         acc[ai][bj][m][n] = mma_<I8>(Bt[n][k], At[m][k], acc[ai][bj][m][n]); __builtin_amdgcn_s_setprio(0); } while (0)
; #define PG8_WAIT_V(n) asm volatile("s_waitcnt vmcnt(" #n ")" ::: "memory")
; #define PG8_WAIT_L(n) asm volatile("s_waitcnt lgkmcnt(" #n ")" ::: "memory")
; #define PG8_BAR __builtin_amdgcn_s_barrier()
; #define PG8_SCHED __builtin_amdgcn_sched_barrier(0)
; template <class Epi, class Sched, bool ALIGN_EPI = false, bool SP2 = false, bool I8 = false>
; __device__ __forceinline__ void gemm_phase(PG8_LAS unsigned char* lds, const Gemm g, const Sched& S, const Epi& E) {
;     ...
;             PG8_LDB(B0, 1, 0); PG8_LDB(B1, 1, 1); PG8_SCHED; PG8_LDA(At, 1, 0); PG8_STAGE(PG8_SA(0, 1), a2 + hstepA, voffA);
;             PG8_WAIT_V(8); PG8_WAIT_L(0); PG8_BAR; PG8_MMA(0, 0, At, B0); PG8_MMA(0, 1, At, B1); PG8_BAR; PG8_SCHED;
;             PG8_LDA(At, 1, 1); PG8_STAGE(PG8_SB(1, 0), b3, voffB); PG8_STAGE(PG8_SB(1, 1), b3 + hstepB, voffB); PG8_STAGE(PG8_SA(1, 0), a3, voffA);
;             PG8_WAIT_V(8); PG8_WAIT_L(0); PG8_BAR; PG8_MMA(1, 0, At, B0); PG8_MMA(1, 1, At, B1); PG8_BAR; PG8_SCHED;
	s_add_i32 s52, 0, 0x18000
	s_add_i32 s53, 0, 0x1c000
	ds_read_b128 v[130:133], v193 offset:16384
	ds_read_b128 v[134:137], v193 offset:17408
	ds_read_b128 v[138:141], v193 offset:18432
	ds_read_b128 v[142:145], v193 offset:19456
	ds_read_b128 v[146:149], v193 offset:32768
	ds_read_b128 v[150:153], v193 offset:33792
	ds_read_b128 v[154:157], v193 offset:34816
	ds_read_b128 v[158:161], v193 offset:35840
	s_add_u32 s30, s30, 0x400000
	s_addc_u32 s31, s31, 0
	s_mov_b32 m0, s40
	ds_read_b128 v[162:165], v194 offset:32768
	ds_read_b128 v[166:169], v194 offset:33792
	ds_read_b128 v[182:185], v194 offset:34816
	ds_read_b128 v[186:189], v194 offset:35840
	ds_read_b128 v[196:199], v194 offset:36864
	ds_read_b128 v[200:203], v194 offset:37888
	ds_read_b128 v[204:207], v194 offset:38912
	ds_read_b128 v[208:211], v194 offset:39936
	global_load_lds_dwordx4 v170, s[30:31]
	s_mov_b32 m0, s41
	s_nop 0
	global_load_lds_dwordx4 v172, s[30:31]
	s_waitcnt vmcnt(8) lgkmcnt(0)
	s_barrier
	v_mfma_f32_16x16x32_bf16 v[126:129], v[130:133], v[162:165], v[126:129]
	v_mfma_f32_16x16x32_bf16 v[122:125], v[138:141], v[162:165], v[122:125]
	v_mfma_f32_16x16x32_bf16 v[110:113], v[130:133], v[182:185], v[110:113]
	v_mfma_f32_16x16x32_bf16 v[106:109], v[138:141], v[182:185], v[106:109]
	v_mfma_f32_16x16x32_bf16 v[94:97], v[130:133], v[196:199], v[94:97]
	v_mfma_f32_16x16x32_bf16 v[90:93], v[138:141], v[196:199], v[90:93]
	v_mfma_f32_16x16x32_bf16 v[78:81], v[130:133], v[204:207], v[78:81]
	v_mfma_f32_16x16x32_bf16 v[74:77], v[138:141], v[204:207], v[74:77]
	v_mfma_f32_16x16x32_bf16 v[126:129], v[134:137], v[166:169], v[126:129]
	v_mfma_f32_16x16x32_bf16 v[122:125], v[142:145], v[166:169], v[122:125]
	v_mfma_f32_16x16x32_bf16 v[110:113], v[134:137], v[186:189], v[110:113]
	v_mfma_f32_16x16x32_bf16 v[106:109], v[142:145], v[186:189], v[106:109]
	v_mfma_f32_16x16x32_bf16 v[94:97], v[134:137], v[200:203], v[94:97]
	v_mfma_f32_16x16x32_bf16 v[90:93], v[142:145], v[200:203], v[90:93]
	v_mfma_f32_16x16x32_bf16 v[78:81], v[134:137], v[208:211], v[78:81]
	v_mfma_f32_16x16x32_bf16 v[74:77], v[142:145], v[208:211], v[74:77]
	v_mfma_f32_16x16x32_bf16 v[118:121], v[146:149], v[162:165], v[118:121]
	v_mfma_f32_16x16x32_bf16 v[114:117], v[154:157], v[162:165], v[114:117]
	v_mfma_f32_16x16x32_bf16 v[102:105], v[146:149], v[182:185], v[102:105]
	v_mfma_f32_16x16x32_bf16 v[98:101], v[154:157], v[182:185], v[98:101]
	v_mfma_f32_16x16x32_bf16 v[86:89], v[146:149], v[196:199], v[86:89]
	v_mfma_f32_16x16x32_bf16 v[82:85], v[154:157], v[196:199], v[82:85]
	v_mfma_f32_16x16x32_bf16 v[70:73], v[146:149], v[204:207], v[70:73]
	v_mfma_f32_16x16x32_bf16 v[66:69], v[154:157], v[204:207], v[66:69]
	v_mfma_f32_16x16x32_bf16 v[118:121], v[150:153], v[166:169], v[118:121]
	v_mfma_f32_16x16x32_bf16 v[114:117], v[158:161], v[166:169], v[114:117]
	v_mfma_f32_16x16x32_bf16 v[102:105], v[150:153], v[186:189], v[102:105]
	v_mfma_f32_16x16x32_bf16 v[98:101], v[158:161], v[186:189], v[98:101]
	v_mfma_f32_16x16x32_bf16 v[86:89], v[150:153], v[200:203], v[86:89]
	v_mfma_f32_16x16x32_bf16 v[82:85], v[158:161], v[200:203], v[82:85]
	v_mfma_f32_16x16x32_bf16 v[70:73], v[150:153], v[208:211], v[70:73]
	v_mfma_f32_16x16x32_bf16 v[66:69], v[158:161], v[208:211], v[66:69]
	s_barrier
	s_add_i32 s30, s52, s33
	s_add_i32 m0, s30, 0xffffff80
	ds_read_b128 v[162:165], v194 offset:49152
	ds_read_b128 v[166:169], v194 offset:50176
	ds_read_b128 v[182:185], v194 offset:51200
	ds_read_b128 v[186:189], v194 offset:52224
	ds_read_b128 v[196:199], v194 offset:53248
	ds_read_b128 v[200:203], v194 offset:54272
	ds_read_b128 v[204:207], v194 offset:55296
	ds_read_b128 v[208:211], v194 offset:56320
	global_load_lds_dwordx4 v170, s[98:99] offset:128
	s_add_i32 m0, s30, 0x1f80
	s_add_u32 s28, s28, 0x400080
	s_addc_u32 s29, s29, 0
	s_add_i32 s30, s53, s33
	global_load_lds_dwordx4 v172, s[98:99] offset:128
	s_mov_b32 m0, s30
	s_nop 0
	global_load_lds_dwordx4 v170, s[28:29]
	s_add_i32 m0, s30, 0x2000
	s_nop 0
	global_load_lds_dwordx4 v172, s[28:29]
	s_add_i32 m0, s43, 0xffffff80
	s_nop 0
	global_load_lds_dwordx4 v170, s[100:101] offset:128
	s_add_i32 m0, s44, 0xffffff80
	s_nop 0
	global_load_lds_dwordx4 v172, s[100:101] offset:128
	s_waitcnt vmcnt(8) lgkmcnt(0)
	s_barrier
	v_mfma_f32_16x16x32_bf16 v[62:65], v[130:133], v[162:165], v[62:65]
	v_mfma_f32_16x16x32_bf16 v[58:61], v[138:141], v[162:165], v[58:61]
	v_mfma_f32_16x16x32_bf16 v[46:49], v[130:133], v[182:185], v[46:49]
	v_mfma_f32_16x16x32_bf16 v[42:45], v[138:141], v[182:185], v[42:45]
	v_mfma_f32_16x16x32_bf16 v[30:33], v[130:133], v[196:199], v[30:33]
	v_mfma_f32_16x16x32_bf16 v[26:29], v[138:141], v[196:199], v[26:29]
	v_mfma_f32_16x16x32_bf16 v[22:25], v[130:133], v[204:207], v[22:25]
	v_mfma_f32_16x16x32_bf16 v[10:13], v[138:141], v[204:207], v[10:13]
	v_mfma_f32_16x16x32_bf16 v[62:65], v[134:137], v[166:169], v[62:65]
	v_mfma_f32_16x16x32_bf16 v[58:61], v[142:145], v[166:169], v[58:61]
	v_mfma_f32_16x16x32_bf16 v[46:49], v[134:137], v[186:189], v[46:49]
	v_mfma_f32_16x16x32_bf16 v[42:45], v[142:145], v[186:189], v[42:45]
	v_mfma_f32_16x16x32_bf16 v[30:33], v[134:137], v[200:203], v[30:33]
	v_mfma_f32_16x16x32_bf16 v[26:29], v[142:145], v[200:203], v[26:29]
	v_mfma_f32_16x16x32_bf16 v[22:25], v[134:137], v[208:211], v[22:25]
	v_mfma_f32_16x16x32_bf16 v[10:13], v[142:145], v[208:211], v[10:13]
	v_mfma_f32_16x16x32_bf16 v[54:57], v[146:149], v[162:165], v[54:57]
	v_mfma_f32_16x16x32_bf16 v[50:53], v[154:157], v[162:165], v[50:53]
	v_mfma_f32_16x16x32_bf16 v[38:41], v[146:149], v[182:185], v[38:41]
	v_mfma_f32_16x16x32_bf16 v[34:37], v[154:157], v[182:185], v[34:37]
	v_mfma_f32_16x16x32_bf16 v[18:21], v[146:149], v[196:199], v[18:21]
	v_mfma_f32_16x16x32_bf16 v[14:17], v[154:157], v[196:199], v[14:17]
	v_mfma_f32_16x16x32_bf16 v[6:9], v[146:149], v[204:207], v[6:9]
	v_mfma_f32_16x16x32_bf16 v[2:5], v[154:157], v[204:207], v[2:5]
	v_mfma_f32_16x16x32_bf16 v[54:57], v[150:153], v[166:169], v[54:57]
	v_mfma_f32_16x16x32_bf16 v[50:53], v[158:161], v[166:169], v[50:53]
	v_mfma_f32_16x16x32_bf16 v[38:41], v[150:153], v[186:189], v[38:41]
	v_mfma_f32_16x16x32_bf16 v[34:37], v[158:161], v[186:189], v[34:37]
	v_mfma_f32_16x16x32_bf16 v[18:21], v[150:153], v[200:203], v[18:21]
	v_mfma_f32_16x16x32_bf16 v[14:17], v[158:161], v[200:203], v[14:17]
	v_mfma_f32_16x16x32_bf16 v[6:9], v[150:153], v[208:211], v[6:9]
	v_mfma_f32_16x16x32_bf16 v[2:5], v[158:161], v[208:211], v[2:5]
	s_barrier
	s_add_i32 s51, s51, 2
	s_add_u32 s8, s8, 0x100
	s_addc_u32 s9, s9, 0
	s_add_u32 s49, s49, 0x100
	s_addc_u32 s50, s50, 0
	s_cmpk_gt_u32 s51, 0xfd
	s_cbranch_scc0 .LBB0_2092
	s_and_b64 vcc, exec, s[16:17]
	s_cbranch_vccz .LBB0_2095
	s_barrier

; __device__ __forceinline__ u32x4 pack8(const f32x4 v0, const f32x4 v1) { u32x4 w; w.x = cvt_pk_bf16(v0[0], v0[1]); w.y = cvt_pk_bf16(v0[2], v0[3]); w.z = cvt_pk_bf16(v1[0], v1[1]); w.w = cvt_pk_bf16(v1[2], v1[3]); return w; }
; __device__ __forceinline__ void unpack8(const u32x4 w, f32x4& v0, f32x4& v1) { v0 = (f32x4){bf_lo(w.x), bf_hi(w.x), bf_lo(w.y), bf_hi(w.y)}; v1 = (f32x4){bf_lo(w.z), bf_hi(w.z), bf_lo(w.w), bf_hi(w.w)}; }
;     __device__ __forceinline__ void operator()(AccRef acc, const Unit& u, int wr, int wc, int fr, int fq) const {
;     ...
;         for (int s = 0; s < 8; ++s) { const int ai = s >> 2, m = s & 3; const int r = row0 + ai * HALF + m * 16; bf16_t* rowp = O + (size_t)r * ldc + col0;
;                 if (MODE >= 2 && s + 1 < 8) load_row(nxt, row0 + ((s + 1) >> 2) * HALF + ((s + 1) & 3) * 16, col0);
;                 float rs = 1.f; if (MODE == 1) rs = __builtin_amdgcn_rsqf(rstd[r] * (1.0f / 4096.0f) + 1e-6f);
;                 float mx = 0.f;
; #pragma unroll
;                 for (int bj = 0; bj < 2; ++bj) { f32x4 v0 = acc[ai][bj][m][0], v1 = acc[ai][bj][m][1];
;                     if (MODE == 1) { v0 = v0 * rs; v1 = v1 * rs;
; #pragma unroll
;                         for (int j = 0; j < 4; ++j) { const float a = v0[j] > 0.f ? v0[j] : 0.f, b = v1[j] > 0.f ? v1[j] : 0.f; v0[j] = a * a; v1[j] = b * b; } }
;                     if (MODE == 2) { f32x4 g0, g1; unpack8(cur.g[bj], g0, g1); v0 = v0 * g0; v1 = v1 * g1; }
;                     if (MODE == 3) { f32x4 g0, g1, a0, a1; unpack8(cur.g[bj], g0, g1); unpack8(cur.a[bj], a0, a1);
;                         v0 = a0 + v0 * g0; v1 = a1 + v1 * g1;
; #pragma unroll
;                         for (int j = 0; j < 4; ++j) mx = fmaxf(mx, fmaxf(fabsf(v0[j]), fabsf(v1[j]))); }
;                     *(u32x4*)(rowp + bj * HALF) = pack8(v0, v1); }
.LBB0_2246:
	v_mov_b32_e32 v138, v0
	v_cvt_pk_bf16_f32 v122, v122, v123
	v_cvt_pk_bf16_f32 v123, v124, v125
	v_cvt_pk_bf16_f32 v124, v114, v115
	v_cvt_pk_bf16_f32 v125, v116, v117
	s_nop 0
	v_lshrrev_b32_e32 v139, 6, v138
	v_and_b32_e32 v138, 63, v138
	v_lshlrev_b32_e32 v138, 4, v138
	v_lshl_add_u32 v138, v139, 14, v138
	s_lshl_b32 s98, s26, 4
	s_add_i32 s98, s98, s51
	s_lshl_b32 s98, s98, 17
	v_add_u32_e32 v138, s98, v138
	v_mov_b32_e32 v139, 0
	v_lshl_add_u64 v[138:139], s[2:3], 0, v[138:139]
	global_store_dwordx4 v[138:139], v[122:125], off
	v_cvt_pk_bf16_f32 v114, v126, v127
	v_cvt_pk_bf16_f32 v115, v128, v129
	v_cvt_pk_bf16_f32 v116, v118, v119
	v_cvt_pk_bf16_f32 v117, v120, v121
	global_store_dwordx4 v[138:139], v[114:117], off offset:1024
	v_cvt_pk_bf16_f32 v106, v106, v107
	v_cvt_pk_bf16_f32 v107, v108, v109
	v_cvt_pk_bf16_f32 v108, v98, v99
	v_cvt_pk_bf16_f32 v109, v100, v101
	s_nop 1
	s_mov_b64 s[98:99], 0x800
	v_lshl_add_u64 v[114:115], v[138:139], 0, s[98:99]
	global_store_dwordx4 v[114:115], v[106:109], off
	v_cvt_pk_bf16_f32 v98, v110, v111
	v_cvt_pk_bf16_f32 v99, v112, v113
	v_cvt_pk_bf16_f32 v100, v102, v103
	v_cvt_pk_bf16_f32 v101, v104, v105
	global_store_dwordx4 v[114:115], v[98:101], off offset:1024
	v_cvt_pk_bf16_f32 v90, v90, v91
	v_cvt_pk_bf16_f32 v91, v92, v93
	v_cvt_pk_bf16_f32 v92, v82, v83
	v_cvt_pk_bf16_f32 v93, v84, v85
	s_nop 1
	s_mov_b64 s[98:99], 0x1000
	v_lshl_add_u64 v[98:99], v[138:139], 0, s[98:99]
	global_store_dwordx4 v[98:99], v[90:93], off
	v_cvt_pk_bf16_f32 v82, v94, v95
	v_cvt_pk_bf16_f32 v83, v96, v97
	v_cvt_pk_bf16_f32 v84, v86, v87
	v_cvt_pk_bf16_f32 v85, v88, v89
	global_store_dwordx4 v[98:99], v[82:85], off offset:1024
	v_cvt_pk_bf16_f32 v58, v58, v59
	v_cvt_pk_bf16_f32 v59, v60, v61
	v_cvt_pk_bf16_f32 v60, v50, v51
	v_cvt_pk_bf16_f32 v61, v52, v53
	s_nop 1
	s_mov_b64 s[98:99], 0x1800
	v_lshl_add_u64 v[82:83], v[138:139], 0, s[98:99]
	global_store_dwordx4 v[82:83], v[58:61], off
	v_cvt_pk_bf16_f32 v50, v62, v63
	v_cvt_pk_bf16_f32 v51, v64, v65
	v_cvt_pk_bf16_f32 v52, v54, v55
	v_cvt_pk_bf16_f32 v53, v56, v57
	s_mov_b64 s[98:99], 0x2000
	global_store_dwordx4 v[82:83], v[50:53], off offset:1024
	s_nop 0
	v_lshl_add_u64 v[56:57], v[138:139], 0, s[98:99]
	v_cvt_pk_bf16_f32 v50, v78, v79
	v_lshl_add_u64 v[54:55], v[138:139], 0, s[98:99]
	v_cvt_pk_bf16_f32 v51, v80, v81
	v_cvt_pk_bf16_f32 v52, v70, v71
	v_cvt_pk_bf16_f32 v53, v72, v73
	global_store_dwordx4 v[56:57], v[50:53], off
	s_andn2_b64 vcc, exec, s[4:5]
	s_mov_b64 s[4:5], -1
	v_cvt_pk_bf16_f32 v50, v74, v75
	v_cvt_pk_bf16_f32 v51, v76, v77
	v_cvt_pk_bf16_f32 v52, v66, v67
	v_cvt_pk_bf16_f32 v53, v68, v69
	global_store_dwordx4 v[54:55], v[50:53], off offset:1024
	v_cvt_pk_bf16_f32 v42, v42, v43
	v_cvt_pk_bf16_f32 v43, v44, v45
	v_cvt_pk_bf16_f32 v44, v34, v35
	v_cvt_pk_bf16_f32 v45, v36, v37
	s_nop 1
	s_mov_b64 s[98:99], 0x2800
	v_lshl_add_u64 v[50:51], v[138:139], 0, s[98:99]
	global_store_dwordx4 v[50:51], v[42:45], off
	v_cvt_pk_bf16_f32 v34, v46, v47
	v_cvt_pk_bf16_f32 v35, v48, v49
	v_cvt_pk_bf16_f32 v36, v38, v39
	v_cvt_pk_bf16_f32 v37, v40, v41
	global_store_dwordx4 v[50:51], v[34:37], off offset:1024
	v_cvt_pk_bf16_f32 v26, v26, v27
	v_cvt_pk_bf16_f32 v27, v28, v29
	v_cvt_pk_bf16_f32 v28, v18, v19
	v_cvt_pk_bf16_f32 v29, v20, v21
	s_nop 1
	s_mov_b64 s[98:99], 0x3000
	v_lshl_add_u64 v[34:35], v[138:139], 0, s[98:99]
	global_store_dwordx4 v[34:35], v[26:29], off
	v_cvt_pk_bf16_f32 v18, v30, v31
	v_cvt_pk_bf16_f32 v19, v32, v33
	v_cvt_pk_bf16_f32 v20, v22, v23
	v_cvt_pk_bf16_f32 v21, v24, v25
	global_store_dwordx4 v[34:35], v[18:21], off offset:1024
	v_cvt_pk_bf16_f32 v10, v10, v11
	v_cvt_pk_bf16_f32 v11, v12, v13
	v_cvt_pk_bf16_f32 v12, v2, v3
	v_cvt_pk_bf16_f32 v13, v4, v5
	s_nop 1
	s_mov_b64 s[98:99], 0x3800
	v_lshl_add_u64 v[18:19], v[138:139], 0, s[98:99]
	global_store_dwordx4 v[18:19], v[10:13], off
	v_cvt_pk_bf16_f32 v2, v14, v15
	v_cvt_pk_bf16_f32 v3, v16, v17
	v_cvt_pk_bf16_f32 v4, v6, v7
	v_cvt_pk_bf16_f32 v5, v8, v9
	global_store_dwordx4 v[18:19], v[2:5], off offset:1024
	s_cbranch_vccnz .LBB0_2237
	s_andn2_b64 vcc, exec, s[0:1]
	s_cbranch_vccnz .LBB0_2236
	s_barrier
	s_branch .LBB0_2236

; #define PG8_STAGE(bufoff, gbase, voff) do { _Pragma("unroll") for (int _i = 0; _i < 2; ++_i) \
;         __builtin_amdgcn_global_load_lds((const unsigned*)((const char*)(gbase) + (voff)[_i]), (PG8_LAS unsigned*)(lds + (bufoff) + ldsw + _i * 8192), 16, 0, 0); } while (0)
; #define PG8_LDA(dst, b, h) do { _Pragma("unroll") for (int m = 0; m < 4; ++m) _Pragma("unroll") for (int k = 0; k < 2; ++k) dst[m][k] = *(const PG8_LAS bf16x8*)(lds + PG8_SA(b, h) + aoff + m * 2048 + k * 1024); } while (0)
; #define PG8_LDB(dst, b, h) do { _Pragma("unroll") for (int n = 0; n < 2; ++n) _Pragma("unroll") for (int k = 0; k < 2; ++k) dst[n][k] = *(const PG8_LAS bf16x8*)(lds + PG8_SB(b, h) + boff + n * 2048 + k * 1024); } while (0)
; #define PG8_MMA(ai, bj, At, Bt) do { __builtin_amdgcn_s_setprio(1); _Pragma("unroll") for (int m = 0; m < 4; ++m) _Pragma("unroll") for (int n = 0; n < 2; ++n) _Pragma("unroll") for (int k = 0; k < 2; ++k) \
;         acc[ai][bj][m][n] = mma_<I8>(Bt[n][k], At[m][k], acc[ai][bj][m][n]); __builtin_amdgcn_s_setprio(0); } while (0)
; #define PG8_WAIT_V(n) asm volatile("s_waitcnt vmcnt(" #n ")" ::: "memory")
; #define PG8_WAIT_L(n) asm volatile("s_waitcnt lgkmcnt(" #n ")" ::: "memory")
; #define PG8_BAR __builtin_amdgcn_s_barrier()
; #define PG8_SCHED __builtin_amdgcn_sched_barrier(0)
; template <class Epi, class Sched, bool ALIGN_EPI = false, bool SP2 = false, bool I8 = false>
; __device__ __forceinline__ void gemm_phase(PG8_LAS unsigned char* lds, const Gemm g, const Sched& S, const Epi& E) {
;     ...
;             PG8_LDB(B0, 0, 0); PG8_LDB(B1, 0, 1); PG8_SCHED; PG8_LDA(At, 0, 0); PG8_STAGE(PG8_SA(1, 1), a1 + hstepA, voffA);
;             PG8_WAIT_V(8); PG8_WAIT_L(0); PG8_BAR; PG8_MMA(0, 0, At, B0); PG8_MMA(0, 1, At, B1); PG8_BAR; PG8_SCHED;
;             PG8_LDA(At, 0, 1); PG8_STAGE(PG8_SB(0, 0), b2, voffB); PG8_STAGE(PG8_SB(0, 1), b2 + hstepB, voffB); PG8_STAGE(PG8_SA(0, 0), a2, voffA);
;             PG8_WAIT_V(8); PG8_WAIT_L(0); PG8_BAR; PG8_MMA(1, 0, At, B0); PG8_MMA(1, 1, At, B1); PG8_BAR; PG8_SCHED;
.LBB0_2322:
	ds_read_b128 v[58:61], v183
	ds_read_b128 v[66:69], v183 offset:1024
	ds_read_b128 v[74:77], v183 offset:2048
	ds_read_b128 v[78:81], v183 offset:3072
	ds_read_b128 v[146:149], v189
	ds_read_b128 v[150:153], v189 offset:1024
	ds_read_b128 v[154:157], v189 offset:2048
	ds_read_b128 v[158:161], v189 offset:3072
	s_add_u32 s28, s26, 0xfff80080
	s_addc_u32 s29, s27, -1
	s_cmp_eq_u32 s53, 28
	s_cselect_b32 s31, s21, s29
	s_cselect_b32 s30, s49, s28
	s_cselect_b32 s29, s19, s52
	s_cselect_b32 s28, s50, s51
	s_add_i32 m0, s3, 0xc000
	ds_read_b128 v[162:165], v193
	ds_read_b128 v[178:181], v193 offset:1024
	ds_read_b128 v[184:187], v193 offset:2048
	ds_read_b128 v[198:201], v193 offset:3072
	ds_read_b128 v[202:205], v193 offset:4096
	ds_read_b128 v[206:209], v193 offset:5120
	ds_read_b128 v[210:213], v193 offset:6144
	ds_read_b128 v[214:217], v193 offset:7168
	global_load_lds_dwordx4 v170, s[26:27]
	s_add_i32 m0, s3, 0xe000
	s_nop 0
	global_load_lds_dwordx4 v172, s[26:27]
	s_waitcnt vmcnt(8) lgkmcnt(0)
	s_barrier
	v_mfma_i32_16x16x64_i8 v[142:145], v[58:61], v[162:165], v[142:145]
	v_mfma_i32_16x16x64_i8 v[138:141], v[74:77], v[162:165], v[138:141]
	v_mfma_i32_16x16x64_i8 v[126:129], v[58:61], v[184:187], v[126:129]
	v_mfma_i32_16x16x64_i8 v[122:125], v[74:77], v[184:187], v[122:125]
	v_mfma_i32_16x16x64_i8 v[110:113], v[58:61], v[202:205], v[110:113]
	v_mfma_i32_16x16x64_i8 v[106:109], v[74:77], v[202:205], v[106:109]
	v_mfma_i32_16x16x64_i8 v[94:97], v[58:61], v[210:213], v[94:97]
	v_mfma_i32_16x16x64_i8 v[90:93], v[74:77], v[210:213], v[90:93]
	v_mfma_i32_16x16x64_i8 v[142:145], v[66:69], v[178:181], v[142:145]
	v_mfma_i32_16x16x64_i8 v[138:141], v[78:81], v[178:181], v[138:141]
	v_mfma_i32_16x16x64_i8 v[126:129], v[66:69], v[198:201], v[126:129]
	v_mfma_i32_16x16x64_i8 v[122:125], v[78:81], v[198:201], v[122:125]
	v_mfma_i32_16x16x64_i8 v[110:113], v[66:69], v[206:209], v[110:113]
	v_mfma_i32_16x16x64_i8 v[106:109], v[78:81], v[206:209], v[106:109]
	v_mfma_i32_16x16x64_i8 v[94:97], v[66:69], v[214:217], v[94:97]
	v_mfma_i32_16x16x64_i8 v[90:93], v[78:81], v[214:217], v[90:93]
	v_mfma_i32_16x16x64_i8 v[134:137], v[146:149], v[162:165], v[134:137]
	v_mfma_i32_16x16x64_i8 v[130:133], v[154:157], v[162:165], v[130:133]
	v_mfma_i32_16x16x64_i8 v[118:121], v[146:149], v[184:187], v[118:121]
	v_mfma_i32_16x16x64_i8 v[114:117], v[154:157], v[184:187], v[114:117]
	v_mfma_i32_16x16x64_i8 v[102:105], v[146:149], v[202:205], v[102:105]
	v_mfma_i32_16x16x64_i8 v[98:101], v[154:157], v[202:205], v[98:101]
	v_mfma_i32_16x16x64_i8 v[86:89], v[146:149], v[210:213], v[86:89]
	v_mfma_i32_16x16x64_i8 v[82:85], v[154:157], v[210:213], v[82:85]
	v_mfma_i32_16x16x64_i8 v[134:137], v[150:153], v[178:181], v[134:137]
	v_mfma_i32_16x16x64_i8 v[130:133], v[158:161], v[178:181], v[130:133]
	v_mfma_i32_16x16x64_i8 v[118:121], v[150:153], v[198:201], v[118:121]
	v_mfma_i32_16x16x64_i8 v[114:117], v[158:161], v[198:201], v[114:117]
	v_mfma_i32_16x16x64_i8 v[102:105], v[150:153], v[206:209], v[102:105]
	v_mfma_i32_16x16x64_i8 v[98:101], v[158:161], v[206:209], v[98:101]
	v_mfma_i32_16x16x64_i8 v[86:89], v[150:153], v[214:217], v[86:89]
	v_mfma_i32_16x16x64_i8 v[82:85], v[158:161], v[214:217], v[82:85]
	s_barrier
	s_add_i32 s54, s46, s38
	s_mov_b64 s[98:99], s[28:29]
	s_mov_b32 m0, s54
	ds_read_b128 v[162:165], v193 offset:16384
	ds_read_b128 v[178:181], v193 offset:17408
	ds_read_b128 v[184:187], v193 offset:18432
	ds_read_b128 v[198:201], v193 offset:19456
	ds_read_b128 v[202:205], v193 offset:20480
	ds_read_b128 v[206:209], v193 offset:21504
	ds_read_b128 v[210:213], v193 offset:22528
	ds_read_b128 v[214:217], v193 offset:23552
	global_load_lds_dwordx4 v166, s[28:29]
	s_add_i32 m0, s54, 0x2000
	s_add_u32 s54, s28, 0x80000
	s_mov_b64 s[98:99], s[28:29]
	s_addc_u32 s55, s29, 0
	s_add_i32 s56, s47, s38
	global_load_lds_dwordx4 v168, s[28:29]
	s_mov_b32 m0, s56
	s_mov_b64 s[100:101], s[30:31]
	global_load_lds_dwordx4 v166, s[54:55]
	s_add_i32 m0, s56, 0x2000
	s_nop 0
	global_load_lds_dwordx4 v168, s[54:55]
	s_mov_b64 s[100:101], s[30:31]
	s_mov_b32 m0, s3
	s_nop 0
	global_load_lds_dwordx4 v166, s[30:31]
	s_mov_b32 m0, s39
	s_nop 0
	global_load_lds_dwordx4 v168, s[30:31]
	s_waitcnt vmcnt(8) lgkmcnt(0)
	s_barrier
	v_mfma_i32_16x16x64_i8 v[70:73], v[58:61], v[162:165], v[70:73]
	v_mfma_i32_16x16x64_i8 v[62:65], v[74:77], v[162:165], v[62:65]
	v_mfma_i32_16x16x64_i8 v[46:49], v[58:61], v[184:187], v[46:49]
	v_mfma_i32_16x16x64_i8 v[42:45], v[74:77], v[184:187], v[42:45]
	v_mfma_i32_16x16x64_i8 v[30:33], v[58:61], v[202:205], v[30:33]
	v_mfma_i32_16x16x64_i8 v[26:29], v[74:77], v[202:205], v[26:29]
	v_mfma_i32_16x16x64_i8 v[14:17], v[58:61], v[210:213], v[14:17]
	v_mfma_i32_16x16x64_i8 v[10:13], v[74:77], v[210:213], v[10:13]
	v_mfma_i32_16x16x64_i8 v[70:73], v[66:69], v[178:181], v[70:73]
	v_mfma_i32_16x16x64_i8 v[62:65], v[78:81], v[178:181], v[62:65]
	v_mfma_i32_16x16x64_i8 v[46:49], v[66:69], v[198:201], v[46:49]
	v_mfma_i32_16x16x64_i8 v[42:45], v[78:81], v[198:201], v[42:45]
	v_mfma_i32_16x16x64_i8 v[30:33], v[66:69], v[206:209], v[30:33]
	v_mfma_i32_16x16x64_i8 v[26:29], v[78:81], v[206:209], v[26:29]
	v_mfma_i32_16x16x64_i8 v[14:17], v[66:69], v[214:217], v[14:17]
	v_mfma_i32_16x16x64_i8 v[10:13], v[78:81], v[214:217], v[10:13]
	v_mfma_i32_16x16x64_i8 v[54:57], v[146:149], v[162:165], v[54:57]
	v_mfma_i32_16x16x64_i8 v[50:53], v[154:157], v[162:165], v[50:53]
	v_mfma_i32_16x16x64_i8 v[38:41], v[146:149], v[184:187], v[38:41]
	v_mfma_i32_16x16x64_i8 v[34:37], v[154:157], v[184:187], v[34:37]
	v_mfma_i32_16x16x64_i8 v[22:25], v[146:149], v[202:205], v[22:25]
	v_mfma_i32_16x16x64_i8 v[18:21], v[154:157], v[202:205], v[18:21]
	v_mfma_i32_16x16x64_i8 v[6:9], v[146:149], v[210:213], v[6:9]
	v_mfma_i32_16x16x64_i8 v[2:5], v[154:157], v[210:213], v[2:5]
	v_mfma_i32_16x16x64_i8 v[54:57], v[150:153], v[178:181], v[54:57]
	v_mfma_i32_16x16x64_i8 v[50:53], v[158:161], v[178:181], v[50:53]
	v_mfma_i32_16x16x64_i8 v[38:41], v[150:153], v[198:201], v[38:41]
	v_mfma_i32_16x16x64_i8 v[34:37], v[158:161], v[198:201], v[34:37]
	v_mfma_i32_16x16x64_i8 v[22:25], v[150:153], v[206:209], v[22:25]
	v_mfma_i32_16x16x64_i8 v[18:21], v[158:161], v[206:209], v[18:21]
	v_mfma_i32_16x16x64_i8 v[6:9], v[150:153], v[214:217], v[6:9]
	v_mfma_i32_16x16x64_i8 v[2:5], v[158:161], v[214:217], v[2:5]
	s_barrier
; #define PG8_STAGE(bufoff, gbase, voff) do { _Pragma("unroll") for (int _i = 0; _i < 2; ++_i) \
;         __builtin_amdgcn_global_load_lds((const unsigned*)((const char*)(gbase) + (voff)[_i]), (PG8_LAS unsigned*)(lds + (bufoff) + ldsw + _i * 8192), 16, 0, 0); } while (0)
; #define PG8_LDA(dst, b, h) do { _Pragma("unroll") for (int m = 0; m < 4; ++m) _Pragma("unroll") for (int k = 0; k < 2; ++k) dst[m][k] = *(const PG8_LAS bf16x8*)(lds + PG8_SA(b, h) + aoff + m * 2048 + k * 1024); } while (0)
; #define PG8_LDB(dst, b, h) do { _Pragma("unroll") for (int n = 0; n < 2; ++n) _Pragma("unroll") for (int k = 0; k < 2; ++k) dst[n][k] = *(const PG8_LAS bf16x8*)(lds + PG8_SB(b, h) + boff + n * 2048 + k * 1024); } while (0)
; #define PG8_MMA(ai, bj, At, Bt) do { __builtin_amdgcn_s_setprio(1); _Pragma("unroll") for (int m = 0; m < 4; ++m) _Pragma("unroll") for (int n = 0; n < 2; ++n) _Pragma("unroll") for (int k = 0; k < 2; ++k) \
;         acc[ai][bj][m][n] = mma_<I8>(Bt[n][k], At[m][k], acc[ai][bj][m][n]); __builtin_amdgcn_s_setprio(0); } while (0)
; #define PG8_WAIT_V(n) asm volatile("s_waitcnt vmcnt(" #n ")" ::: "memory")
; #define PG8_WAIT_L(n) asm volatile("s_waitcnt lgkmcnt(" #n ")" ::: "memory")
; #define PG8_BAR __builtin_amdgcn_s_barrier()
; #define PG8_SCHED __builtin_amdgcn_sched_barrier(0)
; template <class Epi, class Sched, bool ALIGN_EPI = false, bool SP2 = false, bool I8 = false>
; __device__ __forceinline__ void gemm_phase(PG8_LAS unsigned char* lds, const Gemm g, const Sched& S, const Epi& E) {
;     ...
;             PG8_LDB(B0, 1, 0); PG8_LDB(B1, 1, 1); PG8_SCHED; PG8_LDA(At, 1, 0); PG8_STAGE(PG8_SA(0, 1), a2 + hstepA, voffA);
;             PG8_WAIT_V(8); PG8_WAIT_L(0); PG8_BAR; PG8_MMA(0, 0, At, B0); PG8_MMA(0, 1, At, B1); PG8_BAR; PG8_SCHED;
;             PG8_LDA(At, 1, 1); PG8_STAGE(PG8_SB(1, 0), b3, voffB); PG8_STAGE(PG8_SB(1, 1), b3 + hstepB, voffB); PG8_STAGE(PG8_SA(1, 0), a3, voffA);
;             PG8_WAIT_V(8); PG8_WAIT_L(0); PG8_BAR; PG8_MMA(1, 0, At, B0); PG8_MMA(1, 1, At, B1); PG8_BAR; PG8_SCHED;
	s_add_i32 s54, 0, 0x18000
	s_add_i32 s55, 0, 0x1c000
	ds_read_b128 v[58:61], v189 offset:16384
	ds_read_b128 v[66:69], v189 offset:17408
	ds_read_b128 v[74:77], v189 offset:18432
	ds_read_b128 v[78:81], v189 offset:19456
	ds_read_b128 v[146:149], v189 offset:32768
	ds_read_b128 v[150:153], v189 offset:33792
	ds_read_b128 v[154:157], v189 offset:34816
	ds_read_b128 v[158:161], v189 offset:35840
	s_add_u32 s30, s30, 0x80000
	s_addc_u32 s31, s31, 0
	s_mov_b32 m0, s40
	ds_read_b128 v[162:165], v193 offset:32768
	ds_read_b128 v[178:181], v193 offset:33792
	ds_read_b128 v[184:187], v193 offset:34816
	ds_read_b128 v[198:201], v193 offset:35840
	ds_read_b128 v[202:205], v193 offset:36864
	ds_read_b128 v[206:209], v193 offset:37888
	ds_read_b128 v[210:213], v193 offset:38912
	ds_read_b128 v[214:217], v193 offset:39936
	global_load_lds_dwordx4 v166, s[30:31]
	s_mov_b32 m0, s41
	s_nop 0
	global_load_lds_dwordx4 v168, s[30:31]
	s_waitcnt vmcnt(8) lgkmcnt(0)
	s_barrier
	v_mfma_i32_16x16x64_i8 v[142:145], v[58:61], v[162:165], v[142:145]
	v_mfma_i32_16x16x64_i8 v[138:141], v[74:77], v[162:165], v[138:141]
	v_mfma_i32_16x16x64_i8 v[126:129], v[58:61], v[184:187], v[126:129]
	v_mfma_i32_16x16x64_i8 v[122:125], v[74:77], v[184:187], v[122:125]
	v_mfma_i32_16x16x64_i8 v[110:113], v[58:61], v[202:205], v[110:113]
	v_mfma_i32_16x16x64_i8 v[106:109], v[74:77], v[202:205], v[106:109]
	v_mfma_i32_16x16x64_i8 v[94:97], v[58:61], v[210:213], v[94:97]
	v_mfma_i32_16x16x64_i8 v[90:93], v[74:77], v[210:213], v[90:93]
	v_mfma_i32_16x16x64_i8 v[142:145], v[66:69], v[178:181], v[142:145]
	v_mfma_i32_16x16x64_i8 v[138:141], v[78:81], v[178:181], v[138:141]
	v_mfma_i32_16x16x64_i8 v[126:129], v[66:69], v[198:201], v[126:129]
	v_mfma_i32_16x16x64_i8 v[122:125], v[78:81], v[198:201], v[122:125]
	v_mfma_i32_16x16x64_i8 v[110:113], v[66:69], v[206:209], v[110:113]
	v_mfma_i32_16x16x64_i8 v[106:109], v[78:81], v[206:209], v[106:109]
	v_mfma_i32_16x16x64_i8 v[94:97], v[66:69], v[214:217], v[94:97]
	v_mfma_i32_16x16x64_i8 v[90:93], v[78:81], v[214:217], v[90:93]
	v_mfma_i32_16x16x64_i8 v[134:137], v[146:149], v[162:165], v[134:137]
	v_mfma_i32_16x16x64_i8 v[130:133], v[154:157], v[162:165], v[130:133]
	v_mfma_i32_16x16x64_i8 v[118:121], v[146:149], v[184:187], v[118:121]
	v_mfma_i32_16x16x64_i8 v[114:117], v[154:157], v[184:187], v[114:117]
	v_mfma_i32_16x16x64_i8 v[102:105], v[146:149], v[202:205], v[102:105]
	v_mfma_i32_16x16x64_i8 v[98:101], v[154:157], v[202:205], v[98:101]
	v_mfma_i32_16x16x64_i8 v[86:89], v[146:149], v[210:213], v[86:89]
	v_mfma_i32_16x16x64_i8 v[82:85], v[154:157], v[210:213], v[82:85]
	v_mfma_i32_16x16x64_i8 v[134:137], v[150:153], v[178:181], v[134:137]
	v_mfma_i32_16x16x64_i8 v[130:133], v[158:161], v[178:181], v[130:133]
	v_mfma_i32_16x16x64_i8 v[118:121], v[150:153], v[198:201], v[118:121]
	v_mfma_i32_16x16x64_i8 v[114:117], v[158:161], v[198:201], v[114:117]
	v_mfma_i32_16x16x64_i8 v[102:105], v[150:153], v[206:209], v[102:105]
	v_mfma_i32_16x16x64_i8 v[98:101], v[158:161], v[206:209], v[98:101]
	v_mfma_i32_16x16x64_i8 v[86:89], v[150:153], v[214:217], v[86:89]
	v_mfma_i32_16x16x64_i8 v[82:85], v[158:161], v[214:217], v[82:85]
	s_barrier
	s_add_i32 s30, s54, s38
	s_add_i32 m0, s30, 0xffffff80
	ds_read_b128 v[162:165], v193 offset:49152
	ds_read_b128 v[178:181], v193 offset:50176
	ds_read_b128 v[184:187], v193 offset:51200
	ds_read_b128 v[198:201], v193 offset:52224
	ds_read_b128 v[202:205], v193 offset:53248
	ds_read_b128 v[206:209], v193 offset:54272
	ds_read_b128 v[210:213], v193 offset:55296
	ds_read_b128 v[214:217], v193 offset:56320
	global_load_lds_dwordx4 v166, s[98:99] offset:128
	s_add_i32 m0, s30, 0x1f80
	s_add_u32 s28, s28, 0x80080
	s_addc_u32 s29, s29, 0
	s_add_i32 s30, s55, s38
	global_load_lds_dwordx4 v168, s[98:99] offset:128
	s_mov_b32 m0, s30
	s_nop 0
	global_load_lds_dwordx4 v166, s[28:29]
	s_add_i32 m0, s30, 0x2000
	s_nop 0
	global_load_lds_dwordx4 v168, s[28:29]
	s_add_i32 m0, s43, 0xffffff80
	s_nop 0
	global_load_lds_dwordx4 v166, s[100:101] offset:128
	s_add_i32 m0, s44, 0xffffff80
	s_nop 0
	global_load_lds_dwordx4 v168, s[100:101] offset:128
	s_waitcnt vmcnt(8) lgkmcnt(0)
	s_barrier
	v_mfma_i32_16x16x64_i8 v[70:73], v[58:61], v[162:165], v[70:73]
	v_mfma_i32_16x16x64_i8 v[62:65], v[74:77], v[162:165], v[62:65]
	v_mfma_i32_16x16x64_i8 v[46:49], v[58:61], v[184:187], v[46:49]
	v_mfma_i32_16x16x64_i8 v[42:45], v[74:77], v[184:187], v[42:45]
	v_mfma_i32_16x16x64_i8 v[30:33], v[58:61], v[202:205], v[30:33]
	v_mfma_i32_16x16x64_i8 v[26:29], v[74:77], v[202:205], v[26:29]
	v_mfma_i32_16x16x64_i8 v[14:17], v[58:61], v[210:213], v[14:17]
	v_mfma_i32_16x16x64_i8 v[10:13], v[74:77], v[210:213], v[10:13]
	v_mfma_i32_16x16x64_i8 v[70:73], v[66:69], v[178:181], v[70:73]
	v_mfma_i32_16x16x64_i8 v[62:65], v[78:81], v[178:181], v[62:65]
	v_mfma_i32_16x16x64_i8 v[46:49], v[66:69], v[198:201], v[46:49]
	v_mfma_i32_16x16x64_i8 v[42:45], v[78:81], v[198:201], v[42:45]
	v_mfma_i32_16x16x64_i8 v[30:33], v[66:69], v[206:209], v[30:33]
	v_mfma_i32_16x16x64_i8 v[26:29], v[78:81], v[206:209], v[26:29]
	v_mfma_i32_16x16x64_i8 v[14:17], v[66:69], v[214:217], v[14:17]
	v_mfma_i32_16x16x64_i8 v[10:13], v[78:81], v[214:217], v[10:13]
	v_mfma_i32_16x16x64_i8 v[54:57], v[146:149], v[162:165], v[54:57]
	v_mfma_i32_16x16x64_i8 v[50:53], v[154:157], v[162:165], v[50:53]
	v_mfma_i32_16x16x64_i8 v[38:41], v[146:149], v[184:187], v[38:41]
	v_mfma_i32_16x16x64_i8 v[34:37], v[154:157], v[184:187], v[34:37]
	v_mfma_i32_16x16x64_i8 v[22:25], v[146:149], v[202:205], v[22:25]
	v_mfma_i32_16x16x64_i8 v[18:21], v[154:157], v[202:205], v[18:21]
	v_mfma_i32_16x16x64_i8 v[6:9], v[146:149], v[210:213], v[6:9]
	v_mfma_i32_16x16x64_i8 v[2:5], v[154:157], v[210:213], v[2:5]
	v_mfma_i32_16x16x64_i8 v[54:57], v[150:153], v[178:181], v[54:57]
	v_mfma_i32_16x16x64_i8 v[50:53], v[158:161], v[178:181], v[50:53]
	v_mfma_i32_16x16x64_i8 v[38:41], v[150:153], v[198:201], v[38:41]
	v_mfma_i32_16x16x64_i8 v[34:37], v[158:161], v[198:201], v[34:37]
	v_mfma_i32_16x16x64_i8 v[22:25], v[150:153], v[206:209], v[22:25]
	v_mfma_i32_16x16x64_i8 v[18:21], v[158:161], v[206:209], v[18:21]
	v_mfma_i32_16x16x64_i8 v[6:9], v[150:153], v[214:217], v[6:9]
	v_mfma_i32_16x16x64_i8 v[2:5], v[158:161], v[214:217], v[2:5]
	s_barrier
	s_add_i32 s53, s53, 2
	s_add_u32 s26, s26, 0x100
	s_addc_u32 s27, s27, 0
	s_add_u32 s51, s51, 0x100
	s_addc_u32 s52, s52, 0
	s_cmp_gt_u32 s53, 29
	s_cbranch_scc0 .LBB0_2322
	s_and_b64 vcc, exec, s[16:17]
	s_cbranch_vccz .LBB0_2325
	s_barrier
